# hazard fix: restore the 8 wait states between the last QK MFMA and the first VALU read of its result (the counted waits removed in the dwordx4 conversion had been supplying one), plus 2 states after t
# speedup vs baseline: 1.0866x; 1.0012x over previous
; template <bool SLC, bool NOMASK> ...
;     const int kq = lane >> 4;
;     const int pos0 = SLC ? (dcur & 0xfffff) : dcur;
;     const int lo = SLC ? ((((dcur >> 20) == qi) | ((dcur >> 20) == 4)) ? 0 : (1 << 30)) : lo_in;
;     load_frag8(nxt, KF, VF, SLC ? (dnext & 0xfffff) : dnext, lane);
;     f32x4 sa[2] = {(f32x4){0.f, 0.f, 0.f, 0.f}, (f32x4){0.f, 0.f, 0.f, 0.f}};
; #pragma unroll
;     for (int T = 0; T < 2; ++T)
; #pragma unroll
;         for (int s2 = 0; s2 < 4; ++s2) sa[T] = __builtin_amdgcn_mfma_f32_16x16x32_fp8_fp8(cur.k[T][s2], qf[s2], sa[T], 0, 0, 0);
;     float sc[8]; bool vd[8]; float mx = -1e30f;
;     const bool act = lo == 0 || !SLC;
;     if (NOMASK) {
; #pragma unroll
;         for (int j = 0; j < 8; ++j) { sc[j] = sa[j >> 2][j & 3]; vd[j] = act; }
;         mx = fmaxf(fmaxf(fmaxf(sc[0], sc[1]), fmaxf(sc[2], sc[3])), fmaxf(fmaxf(sc[4], sc[5]), fmaxf(sc[6], sc[7])));
;         mx = act ? mx : -1e30f;
;     } else {
; #pragma unroll
;         for (int T = 0; T < 2; ++T)
; #pragma unroll
;             for (int r = 0; r < 4; ++r) { const int p = pos0 + 16 * T + 4 * kq + r; const bool v = (p >= lo) & (p <= hi); const float x = sa[T][r];
;                 sc[4 * T + r] = x; vd[4 * T + r] = v; mx = v ? fmaxf(mx, x) : mx; }
;     }
;     if (__builtin_amdgcn_ballot_w64(mx > st.m + 4.f) != 0ull) {
;         mx = fmaxf(mx, __shfl_xor(mx, 16)); mx = fmaxf(mx, __shfl_xor(mx, 32));
;         const float mn = fmaxf(st.m, mx), alpha = __builtin_amdgcn_exp2f(st.m - mn); st.m = mn; st.l *= alpha;
; #pragma unroll
;         for (int j = 0; j < 8; ++j) st.o[j] = st.o[j] * alpha;
;     }
;     f32x4 pa, pb; float ps = 0.f;
;     const float mref = st.m - 4.f;
;     if (NOMASK) {
; #pragma unroll
;         for (int j = 0; j < 4; ++j) { pa[j] = __builtin_amdgcn_exp2f(sc[j] - mref); pb[j] = __builtin_amdgcn_exp2f(sc[4 + j] - mref); }
;         if (SLC) {
; #pragma unroll
;             for (int j = 0; j < 4; ++j) { pa[j] = act ? pa[j] : 0.f; pb[j] = act ? pb[j] : 0.f; }
;         }
; #pragma unroll
;         for (int j = 0; j < 4; ++j) ps += pa[j] + pb[j];
;     } else {
; #pragma unroll
;         for (int j = 0; j < 4; ++j) { pa[j] = vd[j] ? __builtin_amdgcn_exp2f(sc[j] - mref) : 0.f; pb[j] = vd[4 + j] ? __builtin_amdgcn_exp2f(sc[4 + j] - mref) : 0.f; ps += pa[j] + pb[j]; }
;     }
;     st.l += ps;
;     const u32x2 pw = pack8_fp8(pa, pb);
.LBB0_704:
	v_lshl_add_u64 v[244:245], v[198:199], 0, v[98:99]
	global_load_dwordx4 v[180:183], v[244:245], off
	global_load_dwordx4 v[184:187], v[244:245], off offset:1024
	global_load_dwordx4 v[188:191], v[244:245], off offset:2048
	global_load_dwordx4 v[192:195], v[244:245], off offset:3072
	v_lshl_add_u64 v[246:247], v[196:197], 0, v[98:99]
	global_load_dwordx4 v[164:167], v[246:247], off
	global_load_dwordx4 v[168:171], v[246:247], off offset:1024
	global_load_dwordx4 v[172:175], v[246:247], off offset:2048
	global_load_dwordx4 v[176:179], v[246:247], off offset:3072
	s_waitcnt vmcnt(20)
	v_mfma_f32_16x16x32_fp8_fp8 v[2:5], v[132:133], v[74:75], 0
	v_mov_b64_e32 v[72:73], v[48:49]
	v_mov_b64_e32 v[68:69], v[52:53]
	v_mov_b64_e32 v[30:31], v[58:59]
	v_mfma_f32_16x16x32_fp8_fp8 v[6:9], v[140:141], v[74:75], 0
	v_mov_b64_e32 v[26:27], v[62:63]
	v_mov_b64_e32 v[22:23], v[54:55]
	v_mov_b64_e32 v[18:19], v[42:43]
	v_mfma_f32_16x16x32_fp8_fp8 v[2:5], v[134:135], v[76:77], v[2:5]
	v_mov_b64_e32 v[14:15], v[38:39]
	v_mov_b32_e32 v207, v210
	v_mov_b64_e32 v[70:71], v[46:47]
	v_mfma_f32_16x16x32_fp8_fp8 v[6:9], v[142:143], v[76:77], v[6:9]
	v_mov_b64_e32 v[66:67], v[50:51]
	v_mov_b64_e32 v[32:33], v[60:61]
	v_mov_b64_e32 v[28:29], v[64:65]
	v_mfma_f32_16x16x32_fp8_fp8 v[2:5], v[136:137], v[78:79], v[2:5]
	v_mov_b64_e32 v[24:25], v[56:57]
	v_mov_b64_e32 v[20:21], v[44:45]
	v_mov_b64_e32 v[16:17], v[40:41]
	v_mfma_f32_16x16x32_fp8_fp8 v[6:9], v[144:145], v[78:79], v[6:9]
	v_mov_b32_e32 v208, v209
	v_mfma_f32_16x16x32_fp8_fp8 v[2:5], v[138:139], v[80:81], v[2:5]
	v_mfma_f32_16x16x32_fp8_fp8 v[6:9], v[146:147], v[80:81], v[6:9]
	s_nop 6
	v_max_f32_e32 v0, v3, v3
	v_max_f32_e32 v10, v2, v2
	v_max_f32_e32 v0, v10, v0
	v_max_f32_e32 v10, v5, v5
	v_max_f32_e32 v11, v4, v4
	v_max_f32_e32 v10, v11, v10
	v_max_f32_e32 v11, v9, v9
	v_max_f32_e32 v12, v8, v8
	v_max_f32_e32 v11, v12, v11
	v_max3_f32 v11, v6, v7, v11
	v_max3_f32 v0, v0, v10, v11
	v_mov_b64_e32 v[10:11], v[34:35]
	v_cmp_gt_f32_e32 vcc, v0, v211
	v_mov_b64_e32 v[12:13], v[36:37]
	s_cbranch_vccz .LBB0_706
	v_and_b32_e32 v11, 64, v204
	v_xor_b32_e32 v10, 16, v204
	v_add_u32_e32 v11, 64, v11
	v_cmp_lt_i32_e32 vcc, v10, v11
	v_xor_b32_e32 v12, 32, v204
	s_nop 0
	v_cndmask_b32_e32 v10, v204, v10, vcc
	v_lshlrev_b32_e32 v10, 2, v10
	ds_bpermute_b32 v10, v10, v0
	v_max_f32_e32 v0, v0, v0
	v_cmp_lt_i32_e32 vcc, v12, v11
	s_waitcnt lgkmcnt(0)
	v_max_f32_e32 v10, v10, v10
	v_max_f32_e32 v0, v0, v10
	v_cndmask_b32_e32 v10, v204, v12, vcc
	v_lshlrev_b32_e32 v10, 2, v10
	ds_bpermute_b32 v10, v10, v0
	s_waitcnt lgkmcnt(0)
	v_max3_f32 v207, v210, v0, v10
	v_sub_f32_e32 v0, v210, v207
	v_exp_f32_e32 v0, v0
	s_nop 0
	v_mul_f32_e32 v208, v209, v0
	v_pk_mul_f32 v[12:13], v[36:37], v[0:1] op_sel_hi:[1,0]
	v_pk_mul_f32 v[10:11], v[34:35], v[0:1] op_sel_hi:[1,0]
	v_pk_mul_f32 v[16:17], v[40:41], v[0:1] op_sel_hi:[1,0]
	v_pk_mul_f32 v[14:15], v[38:39], v[0:1] op_sel_hi:[1,0]
	v_pk_mul_f32 v[20:21], v[44:45], v[0:1] op_sel_hi:[1,0]
	v_pk_mul_f32 v[18:19], v[42:43], v[0:1] op_sel_hi:[1,0]
	v_pk_mul_f32 v[24:25], v[56:57], v[0:1] op_sel_hi:[1,0]
	v_pk_mul_f32 v[22:23], v[54:55], v[0:1] op_sel_hi:[1,0]
	v_pk_mul_f32 v[28:29], v[64:65], v[0:1] op_sel_hi:[1,0]
	v_pk_mul_f32 v[26:27], v[62:63], v[0:1] op_sel_hi:[1,0]
	v_pk_mul_f32 v[32:33], v[60:61], v[0:1] op_sel_hi:[1,0]
	v_pk_mul_f32 v[30:31], v[58:59], v[0:1] op_sel_hi:[1,0]
	v_pk_mul_f32 v[68:69], v[52:53], v[0:1] op_sel_hi:[1,0]
	v_pk_mul_f32 v[66:67], v[50:51], v[0:1] op_sel_hi:[1,0]
	v_pk_mul_f32 v[72:73], v[48:49], v[0:1] op_sel_hi:[1,0]
	v_pk_mul_f32 v[70:71], v[46:47], v[0:1] op_sel_hi:[1,0]
.LBB0_706:
	v_add_f32_e32 v213, -4.0, v207
	v_sub_f32_e32 v0, v2, v213
	v_exp_f32_e32 v215, v0
	v_sub_f32_e32 v0, v6, v213
	v_exp_f32_e32 v217, v0
	v_sub_f32_e32 v0, v3, v213
	v_exp_f32_e32 v212, v0
	v_sub_f32_e32 v0, v7, v213
	v_exp_f32_e32 v0, v0
	v_sub_f32_e32 v2, v4, v213
	v_exp_f32_e32 v220, v2
	v_sub_f32_e32 v2, v8, v213
	v_exp_f32_e32 v221, v2
	v_sub_f32_e32 v2, v5, v213
	v_exp_f32_e32 v214, v2
	v_sub_f32_e32 v2, v9, v213
	v_mov_b32_e32 v218, v1
	v_mov_b32_e32 v219, v1
	v_exp_f32_e32 v216, v2
	v_cvt_pk_fp8_f32 v218, v215, v212
	v_cvt_pk_fp8_f32 v219, v217, v0
	v_add_f32_e32 v213, v215, v217
	v_add_f32_e32 v215, v220, v221
	v_cvt_pk_fp8_f32 v218, v220, v214 op_sel:[0,0,1]
	v_cvt_pk_fp8_f32 v219, v221, v216 op_sel:[0,0,1]
	s_nop 0
	s_waitcnt vmcnt(19)
	v_mfma_f32_16x16x32_fp8_fp8 v[2:5], v[86:87], v[218:219], v[10:13]
	v_mfma_f32_16x16x32_fp8_fp8 v[10:13], v[90:91], v[218:219], v[18:21]
	s_waitcnt vmcnt(18)
	v_mfma_f32_16x16x32_fp8_fp8 v[18:21], v[94:95], v[218:219], v[26:29]
	s_nop 2
	v_add_f32_e64 v26, v212, v0
	v_add_f32_e64 v27, v213, v1
	v_mfma_f32_16x16x32_fp8_fp8 v[6:9], v[88:89], v[218:219], v[14:17]
	v_pk_add_f32 v[26:27], v[26:27], v[26:27] op_sel_hi:[0,1]
	v_mov_b32_e32 v217, v27
	v_pk_add_f32 v[26:27], v[214:215], v[216:217]
	s_waitcnt vmcnt(17)
	v_mfma_f32_16x16x32_fp8_fp8 v[14:17], v[92:93], v[218:219], v[22:25]
	v_add_f32_e32 v0, v26, v27
	v_add_f32_e32 v208, v0, v208
	v_mfma_f32_16x16x32_fp8_fp8 v[22:25], v[96:97], v[218:219], v[30:33]
	s_waitcnt vmcnt(16)
	v_mfma_f32_16x16x32_fp8_fp8 v[30:33], v[112:113], v[218:219], v[66:69]
	v_mfma_f32_16x16x32_fp8_fp8 v[26:29], v[114:115], v[218:219], v[70:73]
	s_nop 1
	s_branch .LBB0_700
; template <bool SLC, bool NOMASK> ...
;     const int kq = lane >> 4;
;     const int pos0 = SLC ? (dcur & 0xfffff) : dcur;
;     const int lo = SLC ? ((((dcur >> 20) == qi) | ((dcur >> 20) == 4)) ? 0 : (1 << 30)) : lo_in;
;     load_frag8(nxt, KF, VF, SLC ? (dnext & 0xfffff) : dnext, lane);
;     f32x4 sa[2] = {(f32x4){0.f, 0.f, 0.f, 0.f}, (f32x4){0.f, 0.f, 0.f, 0.f}};
; #pragma unroll
;     for (int T = 0; T < 2; ++T)
; #pragma unroll
;         for (int s2 = 0; s2 < 4; ++s2) sa[T] = __builtin_amdgcn_mfma_f32_16x16x32_fp8_fp8(cur.k[T][s2], qf[s2], sa[T], 0, 0, 0);
;     float sc[8]; bool vd[8]; float mx = -1e30f;
;     const bool act = lo == 0 || !SLC;
;     if (NOMASK) {
; #pragma unroll
;         for (int j = 0; j < 8; ++j) { sc[j] = sa[j >> 2][j & 3]; vd[j] = act; }
;         mx = fmaxf(fmaxf(fmaxf(sc[0], sc[1]), fmaxf(sc[2], sc[3])), fmaxf(fmaxf(sc[4], sc[5]), fmaxf(sc[6], sc[7])));
;         mx = act ? mx : -1e30f;
;     } else {
; #pragma unroll
;         for (int T = 0; T < 2; ++T)
; #pragma unroll
;             for (int r = 0; r < 4; ++r) { const int p = pos0 + 16 * T + 4 * kq + r; const bool v = (p >= lo) & (p <= hi); const float x = sa[T][r];
;                 sc[4 * T + r] = x; vd[4 * T + r] = v; mx = v ? fmaxf(mx, x) : mx; }
;     }
;     if (__builtin_amdgcn_ballot_w64(mx > st.m + 4.f) != 0ull) {
;         mx = fmaxf(mx, __shfl_xor(mx, 16)); mx = fmaxf(mx, __shfl_xor(mx, 32));
;         const float mn = fmaxf(st.m, mx), alpha = __builtin_amdgcn_exp2f(st.m - mn); st.m = mn; st.l *= alpha;
; #pragma unroll
;         for (int j = 0; j < 8; ++j) st.o[j] = st.o[j] * alpha;
;     }
;     f32x4 pa, pb; float ps = 0.f;
;     const float mref = st.m - 4.f;
;     if (NOMASK) {
; #pragma unroll
;         for (int j = 0; j < 4; ++j) { pa[j] = __builtin_amdgcn_exp2f(sc[j] - mref); pb[j] = __builtin_amdgcn_exp2f(sc[4 + j] - mref); }
;         if (SLC) {
; #pragma unroll
;             for (int j = 0; j < 4; ++j) { pa[j] = act ? pa[j] : 0.f; pb[j] = act ? pb[j] : 0.f; }
;         }
; #pragma unroll
;         for (int j = 0; j < 4; ++j) ps += pa[j] + pb[j];
;     } else {
; #pragma unroll
;         for (int j = 0; j < 4; ++j) { pa[j] = vd[j] ? __builtin_amdgcn_exp2f(sc[j] - mref) : 0.f; pb[j] = vd[4 + j] ? __builtin_amdgcn_exp2f(sc[4 + j] - mref) : 0.f; ps += pa[j] + pb[j]; }
;     }
;     st.l += ps;
;     const u32x2 pw = pack8_fp8(pa, pb);
.LBB0_707:
	v_lshl_add_u64 v[244:245], v[198:199], 0, v[98:99]
	global_load_dwordx4 v[180:183], v[244:245], off
	global_load_dwordx4 v[184:187], v[244:245], off offset:1024
	global_load_dwordx4 v[188:191], v[244:245], off offset:2048
	global_load_dwordx4 v[192:195], v[244:245], off offset:3072
	v_lshl_add_u64 v[246:247], v[196:197], 0, v[98:99]
	global_load_dwordx4 v[164:167], v[246:247], off
	global_load_dwordx4 v[168:171], v[246:247], off offset:1024
	global_load_dwordx4 v[172:175], v[246:247], off offset:2048
	global_load_dwordx4 v[176:179], v[246:247], off offset:3072
	s_waitcnt vmcnt(20)
	v_mfma_f32_16x16x32_fp8_fp8 v[2:5], v[132:133], v[74:75], 0
	v_or_b32_e32 v0, s75, v203
	v_cmp_ge_i32_e32 vcc, v0, v105
	v_cmp_le_i32_e64 s[4:5], v0, v206
	v_mfma_f32_16x16x32_fp8_fp8 v[2:5], v[134:135], v[76:77], v[2:5]
	s_and_b64 s[10:11], vcc, s[4:5]
	v_or_b32_e32 v11, 1, v0
	v_cmp_ge_i32_e32 vcc, v11, v105
	v_mfma_f32_16x16x32_fp8_fp8 v[2:5], v[136:137], v[78:79], v[2:5]
	v_cmp_lt_i32_e64 s[4:5], v0, v206
	s_and_b64 s[6:7], s[4:5], vcc
	v_mfma_f32_16x16x32_fp8_fp8 v[6:9], v[140:141], v[74:75], 0
	v_mfma_f32_16x16x32_fp8_fp8 v[2:5], v[138:139], v[80:81], v[2:5]
	v_mfma_f32_16x16x32_fp8_fp8 v[6:9], v[142:143], v[76:77], v[6:9]
	v_mfma_f32_16x16x32_fp8_fp8 v[6:9], v[144:145], v[78:79], v[6:9]
	s_nop 5
	v_max_f32_e32 v10, v2, v2
	v_max_f32_e32 v10, 0xf149f2ca, v10
	v_cndmask_b32_e64 v10, v205, v10, s[10:11]
	v_max_f32_e32 v11, v3, v3
	v_max_f32_e32 v11, v10, v11
	v_cndmask_b32_e64 v10, v10, v11, s[6:7]
	v_or_b32_e32 v11, 2, v0
	v_cmp_ge_i32_e32 vcc, v11, v105
	v_cmp_le_i32_e64 s[4:5], v11, v206
	v_max_f32_e32 v11, v4, v4
	v_max_f32_e32 v11, v10, v11
	s_and_b64 s[8:9], vcc, s[4:5]
	v_mfma_f32_16x16x32_fp8_fp8 v[6:9], v[146:147], v[80:81], v[6:9]
	v_cndmask_b32_e64 v10, v10, v11, s[8:9]
	v_or_b32_e32 v11, 3, v0
	v_cmp_ge_i32_e32 vcc, v11, v105
	v_cmp_le_i32_e64 s[4:5], v11, v206
	v_max_f32_e32 v11, v5, v5
	v_max_f32_e32 v11, v10, v11
	s_and_b64 s[4:5], vcc, s[4:5]
	v_cndmask_b32_e64 v10, v10, v11, s[4:5]
	v_or_b32_e32 v11, 16, v0
	v_cmp_ge_i32_e32 vcc, v11, v105
	v_cmp_le_i32_e64 s[12:13], v11, v206
	v_max_f32_e32 v11, v6, v6
	v_max_f32_e32 v11, v10, v11
	s_and_b64 s[18:19], vcc, s[12:13]
	v_cndmask_b32_e64 v10, v10, v11, s[18:19]
	v_or_b32_e32 v11, 17, v0
	v_cmp_ge_i32_e32 vcc, v11, v105
	v_cmp_le_i32_e64 s[12:13], v11, v206
	v_max_f32_e32 v11, v10, v10
	v_max_f32_e32 v12, v7, v7
	v_max_f32_e32 v11, v11, v12
	s_and_b64 s[14:15], vcc, s[12:13]
	v_cndmask_b32_e64 v10, v10, v11, s[14:15]
	v_or_b32_e32 v11, 18, v0
	v_cmp_ge_i32_e32 vcc, v11, v105
	v_cmp_le_i32_e64 s[12:13], v11, v206
	v_max_f32_e32 v11, v10, v10
	v_max_f32_e32 v12, v8, v8
	v_max_f32_e32 v11, v11, v12
	s_and_b64 s[16:17], vcc, s[12:13]
	v_cndmask_b32_e64 v10, v10, v11, s[16:17]
	v_or_b32_e32 v0, 19, v0
	v_cmp_ge_i32_e32 vcc, v0, v105
	v_cmp_le_i32_e64 s[12:13], v0, v206
	v_max_f32_e32 v0, v10, v10
	v_max_f32_e32 v11, v9, v9
	v_max_f32_e32 v0, v0, v11
	s_and_b64 s[12:13], vcc, s[12:13]
	v_cndmask_b32_e64 v0, v10, v0, s[12:13]
	v_cmp_gt_f32_e32 vcc, v0, v211
	s_cbranch_vccz .LBB0_709
	v_and_b32_e32 v11, 64, v204
	v_xor_b32_e32 v10, 16, v204
	v_add_u32_e32 v11, 64, v11
	v_cmp_lt_i32_e32 vcc, v10, v11
	v_xor_b32_e32 v12, 32, v204
	s_nop 0
	v_cndmask_b32_e32 v10, v204, v10, vcc
	v_lshlrev_b32_e32 v10, 2, v10
	ds_bpermute_b32 v10, v10, v0
	v_max_f32_e32 v0, v0, v0
	v_cmp_lt_i32_e32 vcc, v12, v11
	s_waitcnt lgkmcnt(0)
	v_max_f32_e32 v10, v10, v10
	v_max_f32_e32 v0, v0, v10
	v_cndmask_b32_e32 v10, v204, v12, vcc
	v_lshlrev_b32_e32 v10, 2, v10
	ds_bpermute_b32 v10, v10, v0
	s_waitcnt lgkmcnt(0)
	v_max3_f32 v10, v210, v0, v10
	v_sub_f32_e32 v0, v210, v10
	v_exp_f32_e32 v0, v0
	v_mov_b32_e32 v210, v10
	v_mul_f32_e32 v209, v209, v0
	v_pk_mul_f32 v[36:37], v[36:37], v[0:1] op_sel_hi:[1,0]
	v_pk_mul_f32 v[34:35], v[34:35], v[0:1] op_sel_hi:[1,0]
	v_pk_mul_f32 v[40:41], v[40:41], v[0:1] op_sel_hi:[1,0]
	v_pk_mul_f32 v[38:39], v[38:39], v[0:1] op_sel_hi:[1,0]
	v_pk_mul_f32 v[44:45], v[44:45], v[0:1] op_sel_hi:[1,0]
	v_pk_mul_f32 v[42:43], v[42:43], v[0:1] op_sel_hi:[1,0]
	v_pk_mul_f32 v[56:57], v[56:57], v[0:1] op_sel_hi:[1,0]
	v_pk_mul_f32 v[54:55], v[54:55], v[0:1] op_sel_hi:[1,0]
	v_pk_mul_f32 v[64:65], v[64:65], v[0:1] op_sel_hi:[1,0]
	v_pk_mul_f32 v[62:63], v[62:63], v[0:1] op_sel_hi:[1,0]
	v_pk_mul_f32 v[60:61], v[60:61], v[0:1] op_sel_hi:[1,0]
	v_pk_mul_f32 v[58:59], v[58:59], v[0:1] op_sel_hi:[1,0]
	v_pk_mul_f32 v[52:53], v[52:53], v[0:1] op_sel_hi:[1,0]
	v_pk_mul_f32 v[50:51], v[50:51], v[0:1] op_sel_hi:[1,0]
	v_pk_mul_f32 v[48:49], v[48:49], v[0:1] op_sel_hi:[1,0]
	v_pk_mul_f32 v[46:47], v[46:47], v[0:1] op_sel_hi:[1,0]
.LBB0_709:
	v_add_f32_e32 v0, -4.0, v210
	v_sub_f32_e32 v2, v2, v0
	v_exp_f32_e32 v2, v2
	v_sub_f32_e32 v6, v6, v0
	v_exp_f32_e32 v6, v6
	v_sub_f32_e32 v4, v4, v0
	v_cndmask_b32_e64 v22, 0, v2, s[10:11]
	v_sub_f32_e32 v2, v3, v0
	v_exp_f32_e32 v2, v2
	v_sub_f32_e32 v3, v7, v0
	v_exp_f32_e32 v3, v3
	v_cndmask_b32_e64 v23, 0, v6, s[18:19]
	v_sub_f32_e32 v6, v8, v0
	v_cndmask_b32_e64 v24, 0, v2, s[6:7]
	v_sub_f32_e32 v2, v5, v0
	v_sub_f32_e32 v0, v9, v0
	v_exp_f32_e32 v4, v4
	v_exp_f32_e32 v6, v6
	v_cndmask_b32_e64 v25, 0, v3, s[14:15]
	v_exp_f32_e32 v2, v2
	v_exp_f32_e32 v0, v0
	v_mov_b32_e32 v26, v1
	v_mov_b32_e32 v27, v1
	v_cvt_pk_fp8_f32 v26, v22, v24
	v_cvt_pk_fp8_f32 v27, v23, v25
	v_cndmask_b32_e64 v28, 0, v4, s[8:9]
	v_cndmask_b32_e64 v29, 0, v6, s[16:17]
	v_cndmask_b32_e64 v66, 0, v2, s[4:5]
	v_cndmask_b32_e64 v0, 0, v0, s[12:13]
	v_cvt_pk_fp8_f32 v26, v28, v66 op_sel:[0,0,1]
	v_cvt_pk_fp8_f32 v27, v29, v0 op_sel:[0,0,1]
	v_add_f32_e32 v22, v22, v23
	v_add_f32_e32 v30, 0, v22
	v_add_f32_e32 v31, v24, v25
	v_add_f32_e32 v30, v31, v30
	v_add_f32_e32 v28, v28, v29
	v_add_f32_e32 v28, v28, v30
	v_add_f32_e32 v0, v66, v0
	s_waitcnt vmcnt(19)
	v_mfma_f32_16x16x32_fp8_fp8 v[2:5], v[86:87], v[26:27], v[34:37]
	v_add_f32_e32 v0, v0, v28
	v_add_f32_e32 v208, v209, v0
	v_mov_b32_e32 v207, v210
	v_mfma_f32_16x16x32_fp8_fp8 v[6:9], v[88:89], v[26:27], v[38:41]
	s_waitcnt vmcnt(18)
	v_mfma_f32_16x16x32_fp8_fp8 v[10:13], v[90:91], v[26:27], v[42:45]
	v_mfma_f32_16x16x32_fp8_fp8 v[14:17], v[92:93], v[26:27], v[54:57]
	s_waitcnt vmcnt(17)
	v_mfma_f32_16x16x32_fp8_fp8 v[18:21], v[94:95], v[26:27], v[62:65]
	v_mfma_f32_16x16x32_fp8_fp8 v[22:25], v[96:97], v[26:27], v[58:61]
	s_waitcnt vmcnt(16)
	v_mfma_f32_16x16x32_fp8_fp8 v[30:33], v[112:113], v[26:27], v[50:53]
	v_mfma_f32_16x16x32_fp8_fp8 v[26:29], v[114:115], v[26:27], v[46:49]
	s_nop 1
	s_cmp_ge_i32 s66, s74
	s_mov_b64 s[4:5], -1
	s_cbranch_scc0 .LBB0_701

; template <bool SLC, bool NOMASK> ...
;     const int kq = lane >> 4;
;     const int pos0 = SLC ? (dcur & 0xfffff) : dcur;
;     const int lo = SLC ? ((((dcur >> 20) == qi) | ((dcur >> 20) == 4)) ? 0 : (1 << 30)) : lo_in;
;     load_frag8(nxt, KF, VF, SLC ? (dnext & 0xfffff) : dnext, lane);
;     f32x4 sa[2] = {(f32x4){0.f, 0.f, 0.f, 0.f}, (f32x4){0.f, 0.f, 0.f, 0.f}};
; #pragma unroll
;     for (int T = 0; T < 2; ++T)
; #pragma unroll
;         for (int s2 = 0; s2 < 4; ++s2) sa[T] = __builtin_amdgcn_mfma_f32_16x16x32_fp8_fp8(cur.k[T][s2], qf[s2], sa[T], 0, 0, 0);
;     float sc[8]; bool vd[8]; float mx = -1e30f;
;     const bool act = lo == 0 || !SLC;
;     if (NOMASK) {
; #pragma unroll
;         for (int j = 0; j < 8; ++j) { sc[j] = sa[j >> 2][j & 3]; vd[j] = act; }
;         mx = fmaxf(fmaxf(fmaxf(sc[0], sc[1]), fmaxf(sc[2], sc[3])), fmaxf(fmaxf(sc[4], sc[5]), fmaxf(sc[6], sc[7])));
;         mx = act ? mx : -1e30f;
;     } else {
; #pragma unroll
;         for (int T = 0; T < 2; ++T)
; #pragma unroll
;             for (int r = 0; r < 4; ++r) { const int p = pos0 + 16 * T + 4 * kq + r; const bool v = (p >= lo) & (p <= hi); const float x = sa[T][r];
;                 sc[4 * T + r] = x; vd[4 * T + r] = v; mx = v ? fmaxf(mx, x) : mx; }
;     }
;     if (__builtin_amdgcn_ballot_w64(mx > st.m + 4.f) != 0ull) {
;         mx = fmaxf(mx, __shfl_xor(mx, 16)); mx = fmaxf(mx, __shfl_xor(mx, 32));
;         const float mn = fmaxf(st.m, mx), alpha = __builtin_amdgcn_exp2f(st.m - mn); st.m = mn; st.l *= alpha;
; #pragma unroll
;         for (int j = 0; j < 8; ++j) st.o[j] = st.o[j] * alpha;
;     }
;     f32x4 pa, pb; float ps = 0.f;
;     const float mref = st.m - 4.f;
;     if (NOMASK) {
; #pragma unroll
;         for (int j = 0; j < 4; ++j) { pa[j] = __builtin_amdgcn_exp2f(sc[j] - mref); pb[j] = __builtin_amdgcn_exp2f(sc[4 + j] - mref); }
;         if (SLC) {
; #pragma unroll
;             for (int j = 0; j < 4; ++j) { pa[j] = act ? pa[j] : 0.f; pb[j] = act ? pb[j] : 0.f; }
;         }
; #pragma unroll
;         for (int j = 0; j < 4; ++j) ps += pa[j] + pb[j];
;     } else {
; #pragma unroll
;         for (int j = 0; j < 4; ++j) { pa[j] = vd[j] ? __builtin_amdgcn_exp2f(sc[j] - mref) : 0.f; pb[j] = vd[4 + j] ? __builtin_amdgcn_exp2f(sc[4 + j] - mref) : 0.f; ps += pa[j] + pb[j]; }
;     }
;     st.l += ps;
;     const u32x2 pw = pack8_fp8(pa, pb);
.LBB0_711:
	v_lshl_add_u64 v[244:245], v[198:199], 0, v[98:99]
	global_load_dwordx4 v[132:135], v[244:245], off
	global_load_dwordx4 v[136:139], v[244:245], off offset:1024
	global_load_dwordx4 v[140:143], v[244:245], off offset:2048
	global_load_dwordx4 v[144:147], v[244:245], off offset:3072
	v_lshl_add_u64 v[246:247], v[196:197], 0, v[98:99]
	global_load_dwordx4 v[86:89], v[246:247], off
	global_load_dwordx4 v[90:93], v[246:247], off offset:1024
	global_load_dwordx4 v[94:97], v[246:247], off offset:2048
	global_load_dwordx4 v[112:115], v[246:247], off offset:3072
	s_waitcnt vmcnt(20)
	v_mfma_f32_16x16x32_fp8_fp8 v[34:37], v[148:149], v[74:75], 0
	v_mov_b64_e32 v[72:73], v[28:29]
	v_mov_b64_e32 v[68:69], v[32:33]
	v_mov_b64_e32 v[64:65], v[24:25]
	v_mfma_f32_16x16x32_fp8_fp8 v[38:41], v[156:157], v[74:75], 0
	v_mov_b64_e32 v[60:61], v[20:21]
	v_mov_b64_e32 v[56:57], v[16:17]
	v_mov_b64_e32 v[52:53], v[12:13]
	v_mfma_f32_16x16x32_fp8_fp8 v[34:37], v[150:151], v[76:77], v[34:37]
	v_mov_b64_e32 v[48:49], v[8:9]
	v_mov_b32_e32 v209, v207
	v_mov_b64_e32 v[70:71], v[26:27]
	v_mfma_f32_16x16x32_fp8_fp8 v[38:41], v[158:159], v[76:77], v[38:41]
	v_mov_b64_e32 v[66:67], v[30:31]
	v_mov_b64_e32 v[62:63], v[22:23]
	v_mov_b64_e32 v[58:59], v[18:19]
	v_mfma_f32_16x16x32_fp8_fp8 v[34:37], v[152:153], v[78:79], v[34:37]
	v_mov_b64_e32 v[54:55], v[14:15]
	v_mov_b64_e32 v[50:51], v[10:11]
	v_mov_b64_e32 v[46:47], v[6:7]
	v_mfma_f32_16x16x32_fp8_fp8 v[38:41], v[160:161], v[78:79], v[38:41]
	v_mov_b32_e32 v210, v208
	v_mfma_f32_16x16x32_fp8_fp8 v[34:37], v[154:155], v[80:81], v[34:37]
	v_mfma_f32_16x16x32_fp8_fp8 v[38:41], v[162:163], v[80:81], v[38:41]
	s_nop 6
	v_max_f32_e32 v0, v35, v35
	v_max_f32_e32 v42, v34, v34
	v_max_f32_e32 v0, v42, v0
	v_max_f32_e32 v42, v37, v37
	v_max_f32_e32 v43, v36, v36
	v_max_f32_e32 v42, v43, v42
	v_max_f32_e32 v43, v41, v41
	v_max_f32_e32 v44, v40, v40
	v_max_f32_e32 v43, v44, v43
	v_max3_f32 v43, v38, v39, v43
	v_max3_f32 v0, v0, v42, v43
	v_mov_b64_e32 v[44:45], v[4:5]
	v_cmp_gt_f32_e32 vcc, v0, v211
	v_mov_b64_e32 v[42:43], v[2:3]
	s_cbranch_vccz .LBB0_713
	v_and_b32_e32 v43, 64, v204
	v_xor_b32_e32 v42, 16, v204
	v_add_u32_e32 v43, 64, v43
	v_cmp_lt_i32_e32 vcc, v42, v43
	v_xor_b32_e32 v44, 32, v204
	s_nop 0
	v_cndmask_b32_e32 v42, v204, v42, vcc
	v_lshlrev_b32_e32 v42, 2, v42
	ds_bpermute_b32 v42, v42, v0
	v_max_f32_e32 v0, v0, v0
	v_cmp_lt_i32_e32 vcc, v44, v43
	s_waitcnt lgkmcnt(0)
	v_max_f32_e32 v42, v42, v42
	v_max_f32_e32 v0, v0, v42
	v_cndmask_b32_e32 v42, v204, v44, vcc
	v_lshlrev_b32_e32 v42, 2, v42
	ds_bpermute_b32 v42, v42, v0
	s_waitcnt lgkmcnt(0)
	v_max3_f32 v209, v207, v0, v42
	v_sub_f32_e32 v0, v207, v209
	v_exp_f32_e32 v0, v0
	s_nop 0
	v_mul_f32_e32 v210, v208, v0
	v_pk_mul_f32 v[44:45], v[4:5], v[0:1] op_sel_hi:[1,0]
	v_pk_mul_f32 v[42:43], v[2:3], v[0:1] op_sel_hi:[1,0]
	v_pk_mul_f32 v[48:49], v[8:9], v[0:1] op_sel_hi:[1,0]
	v_pk_mul_f32 v[46:47], v[6:7], v[0:1] op_sel_hi:[1,0]
	v_pk_mul_f32 v[52:53], v[12:13], v[0:1] op_sel_hi:[1,0]
	v_pk_mul_f32 v[50:51], v[10:11], v[0:1] op_sel_hi:[1,0]
	v_pk_mul_f32 v[56:57], v[16:17], v[0:1] op_sel_hi:[1,0]
	v_pk_mul_f32 v[54:55], v[14:15], v[0:1] op_sel_hi:[1,0]
	v_pk_mul_f32 v[60:61], v[20:21], v[0:1] op_sel_hi:[1,0]
	v_pk_mul_f32 v[58:59], v[18:19], v[0:1] op_sel_hi:[1,0]
	v_pk_mul_f32 v[64:65], v[24:25], v[0:1] op_sel_hi:[1,0]
	v_pk_mul_f32 v[62:63], v[22:23], v[0:1] op_sel_hi:[1,0]
	v_pk_mul_f32 v[68:69], v[32:33], v[0:1] op_sel_hi:[1,0]
	v_pk_mul_f32 v[66:67], v[30:31], v[0:1] op_sel_hi:[1,0]
	v_pk_mul_f32 v[72:73], v[28:29], v[0:1] op_sel_hi:[1,0]
	v_pk_mul_f32 v[70:71], v[26:27], v[0:1] op_sel_hi:[1,0]
.LBB0_713:
	v_add_f32_e32 v213, -4.0, v209
	v_sub_f32_e32 v0, v34, v213
	v_exp_f32_e32 v215, v0
	v_sub_f32_e32 v0, v38, v213
	v_exp_f32_e32 v217, v0
	v_sub_f32_e32 v0, v35, v213
	v_exp_f32_e32 v212, v0
	v_sub_f32_e32 v0, v39, v213
	v_exp_f32_e32 v0, v0
	v_sub_f32_e32 v34, v36, v213
	v_exp_f32_e32 v220, v34
	v_sub_f32_e32 v34, v40, v213
	v_exp_f32_e32 v221, v34
	v_sub_f32_e32 v34, v37, v213
	v_exp_f32_e32 v214, v34
	v_sub_f32_e32 v34, v41, v213
	v_mov_b32_e32 v218, v1
	v_mov_b32_e32 v219, v1
	v_exp_f32_e32 v216, v34
	v_cvt_pk_fp8_f32 v218, v215, v212
	v_cvt_pk_fp8_f32 v219, v217, v0
	v_add_f32_e32 v213, v215, v217
	v_add_f32_e32 v215, v220, v221
	v_cvt_pk_fp8_f32 v218, v220, v214 op_sel:[0,0,1]
	v_cvt_pk_fp8_f32 v219, v221, v216 op_sel:[0,0,1]
	s_nop 0
	s_waitcnt vmcnt(19)
	v_mfma_f32_16x16x32_fp8_fp8 v[34:37], v[116:117], v[218:219], v[42:45]
	v_mfma_f32_16x16x32_fp8_fp8 v[42:45], v[120:121], v[218:219], v[50:53]
	s_waitcnt vmcnt(18)
	v_mfma_f32_16x16x32_fp8_fp8 v[50:53], v[124:125], v[218:219], v[58:61]
	s_nop 2
	v_add_f32_e64 v58, v212, v0
	v_add_f32_e64 v59, v213, v1
	v_mfma_f32_16x16x32_fp8_fp8 v[38:41], v[118:119], v[218:219], v[46:49]
	v_pk_add_f32 v[58:59], v[58:59], v[58:59] op_sel_hi:[0,1]
	v_mov_b32_e32 v217, v59
	s_waitcnt vmcnt(17)
	v_mfma_f32_16x16x32_fp8_fp8 v[46:49], v[122:123], v[218:219], v[54:57]
	v_mfma_f32_16x16x32_fp8_fp8 v[54:57], v[126:127], v[218:219], v[62:65]
	s_nop 2
	v_add_f32_e64 v62, v214, v216
	v_add_f32_e64 v63, v215, v217
	s_waitcnt vmcnt(16)
	v_mfma_f32_16x16x32_fp8_fp8 v[58:61], v[128:129], v[218:219], v[66:69]
	v_add_f32_e32 v0, v62, v63
	v_add_f32_e32 v210, v0, v210
	v_mfma_f32_16x16x32_fp8_fp8 v[62:65], v[130:131], v[218:219], v[70:73]
	s_nop 1
	s_branch .LBB0_703
; template <bool SLC, bool NOMASK> ...
;     const int kq = lane >> 4;
;     const int pos0 = SLC ? (dcur & 0xfffff) : dcur;
;     const int lo = SLC ? ((((dcur >> 20) == qi) | ((dcur >> 20) == 4)) ? 0 : (1 << 30)) : lo_in;
;     load_frag8(nxt, KF, VF, SLC ? (dnext & 0xfffff) : dnext, lane);
;     f32x4 sa[2] = {(f32x4){0.f, 0.f, 0.f, 0.f}, (f32x4){0.f, 0.f, 0.f, 0.f}};
; #pragma unroll
;     for (int T = 0; T < 2; ++T)
; #pragma unroll
;         for (int s2 = 0; s2 < 4; ++s2) sa[T] = __builtin_amdgcn_mfma_f32_16x16x32_fp8_fp8(cur.k[T][s2], qf[s2], sa[T], 0, 0, 0);
;     float sc[8]; bool vd[8]; float mx = -1e30f;
;     const bool act = lo == 0 || !SLC;
;     if (NOMASK) {
; #pragma unroll
;         for (int j = 0; j < 8; ++j) { sc[j] = sa[j >> 2][j & 3]; vd[j] = act; }
;         mx = fmaxf(fmaxf(fmaxf(sc[0], sc[1]), fmaxf(sc[2], sc[3])), fmaxf(fmaxf(sc[4], sc[5]), fmaxf(sc[6], sc[7])));
;         mx = act ? mx : -1e30f;
;     } else {
; #pragma unroll
;         for (int T = 0; T < 2; ++T)
; #pragma unroll
;             for (int r = 0; r < 4; ++r) { const int p = pos0 + 16 * T + 4 * kq + r; const bool v = (p >= lo) & (p <= hi); const float x = sa[T][r];
;                 sc[4 * T + r] = x; vd[4 * T + r] = v; mx = v ? fmaxf(mx, x) : mx; }
;     }
;     if (__builtin_amdgcn_ballot_w64(mx > st.m + 4.f) != 0ull) {
;         mx = fmaxf(mx, __shfl_xor(mx, 16)); mx = fmaxf(mx, __shfl_xor(mx, 32));
;         const float mn = fmaxf(st.m, mx), alpha = __builtin_amdgcn_exp2f(st.m - mn); st.m = mn; st.l *= alpha;
; #pragma unroll
;         for (int j = 0; j < 8; ++j) st.o[j] = st.o[j] * alpha;
;     }
;     f32x4 pa, pb; float ps = 0.f;
;     const float mref = st.m - 4.f;
;     if (NOMASK) {
; #pragma unroll
;         for (int j = 0; j < 4; ++j) { pa[j] = __builtin_amdgcn_exp2f(sc[j] - mref); pb[j] = __builtin_amdgcn_exp2f(sc[4 + j] - mref); }
;         if (SLC) {
; #pragma unroll
;             for (int j = 0; j < 4; ++j) { pa[j] = act ? pa[j] : 0.f; pb[j] = act ? pb[j] : 0.f; }
;         }
; #pragma unroll
;         for (int j = 0; j < 4; ++j) ps += pa[j] + pb[j];
;     } else {
; #pragma unroll
;         for (int j = 0; j < 4; ++j) { pa[j] = vd[j] ? __builtin_amdgcn_exp2f(sc[j] - mref) : 0.f; pb[j] = vd[4 + j] ? __builtin_amdgcn_exp2f(sc[4 + j] - mref) : 0.f; ps += pa[j] + pb[j]; }
;     }
;     st.l += ps;
;     const u32x2 pw = pack8_fp8(pa, pb);
.LBB0_714:
	v_lshl_add_u64 v[244:245], v[198:199], 0, v[98:99]
	global_load_dwordx4 v[132:135], v[244:245], off
	global_load_dwordx4 v[136:139], v[244:245], off offset:1024
	global_load_dwordx4 v[140:143], v[244:245], off offset:2048
	global_load_dwordx4 v[144:147], v[244:245], off offset:3072
	v_lshl_add_u64 v[246:247], v[196:197], 0, v[98:99]
	global_load_dwordx4 v[86:89], v[246:247], off
	global_load_dwordx4 v[90:93], v[246:247], off offset:1024
	global_load_dwordx4 v[94:97], v[246:247], off offset:2048
	global_load_dwordx4 v[112:115], v[246:247], off offset:3072
	s_waitcnt vmcnt(20)
	v_mfma_f32_16x16x32_fp8_fp8 v[34:37], v[148:149], v[74:75], 0
	v_or_b32_e32 v0, s76, v203
	v_cmp_ge_i32_e32 vcc, v0, v105
	v_cmp_le_i32_e64 s[4:5], v0, v206
	v_mfma_f32_16x16x32_fp8_fp8 v[34:37], v[150:151], v[76:77], v[34:37]
	s_and_b64 s[10:11], vcc, s[4:5]
	v_or_b32_e32 v43, 1, v0
	v_cmp_ge_i32_e32 vcc, v43, v105
	v_mfma_f32_16x16x32_fp8_fp8 v[34:37], v[152:153], v[78:79], v[34:37]
	v_cmp_lt_i32_e64 s[4:5], v0, v206
	s_and_b64 s[6:7], s[4:5], vcc
	v_mfma_f32_16x16x32_fp8_fp8 v[38:41], v[156:157], v[74:75], 0
	v_mfma_f32_16x16x32_fp8_fp8 v[34:37], v[154:155], v[80:81], v[34:37]
	v_mfma_f32_16x16x32_fp8_fp8 v[38:41], v[158:159], v[76:77], v[38:41]
	v_mfma_f32_16x16x32_fp8_fp8 v[38:41], v[160:161], v[78:79], v[38:41]
	s_nop 5
	v_max_f32_e32 v42, v34, v34
	v_max_f32_e32 v42, 0xf149f2ca, v42
	v_cndmask_b32_e64 v42, v205, v42, s[10:11]
	v_max_f32_e32 v43, v35, v35
	v_max_f32_e32 v43, v42, v43
	v_cndmask_b32_e64 v42, v42, v43, s[6:7]
	v_or_b32_e32 v43, 2, v0
	v_cmp_ge_i32_e32 vcc, v43, v105
	v_cmp_le_i32_e64 s[4:5], v43, v206
	v_max_f32_e32 v43, v36, v36
	v_max_f32_e32 v43, v42, v43
	s_and_b64 s[8:9], vcc, s[4:5]
	v_mfma_f32_16x16x32_fp8_fp8 v[38:41], v[162:163], v[80:81], v[38:41]
	v_cndmask_b32_e64 v42, v42, v43, s[8:9]
	v_or_b32_e32 v43, 3, v0
	v_cmp_ge_i32_e32 vcc, v43, v105
	v_cmp_le_i32_e64 s[4:5], v43, v206
	v_max_f32_e32 v43, v37, v37
	v_max_f32_e32 v43, v42, v43
	s_and_b64 s[4:5], vcc, s[4:5]
	v_cndmask_b32_e64 v42, v42, v43, s[4:5]
	v_or_b32_e32 v43, 16, v0
	v_cmp_ge_i32_e32 vcc, v43, v105
	v_cmp_le_i32_e64 s[12:13], v43, v206
	v_max_f32_e32 v43, v38, v38
	v_max_f32_e32 v43, v42, v43
	s_and_b64 s[18:19], vcc, s[12:13]
	v_cndmask_b32_e64 v42, v42, v43, s[18:19]
	v_or_b32_e32 v43, 17, v0
	v_cmp_ge_i32_e32 vcc, v43, v105
	v_cmp_le_i32_e64 s[12:13], v43, v206
	v_max_f32_e32 v43, v42, v42
	v_max_f32_e32 v44, v39, v39
	v_max_f32_e32 v43, v43, v44
	s_and_b64 s[14:15], vcc, s[12:13]
	v_cndmask_b32_e64 v42, v42, v43, s[14:15]
	v_or_b32_e32 v43, 18, v0
	v_cmp_ge_i32_e32 vcc, v43, v105
	v_cmp_le_i32_e64 s[12:13], v43, v206
	v_max_f32_e32 v43, v42, v42
	v_max_f32_e32 v44, v40, v40
	v_max_f32_e32 v43, v43, v44
	s_and_b64 s[16:17], vcc, s[12:13]
	v_cndmask_b32_e64 v42, v42, v43, s[16:17]
	v_or_b32_e32 v0, 19, v0
	v_cmp_ge_i32_e32 vcc, v0, v105
	v_cmp_le_i32_e64 s[12:13], v0, v206
	v_max_f32_e32 v0, v42, v42
	v_max_f32_e32 v43, v41, v41
	v_max_f32_e32 v0, v0, v43
	s_and_b64 s[12:13], vcc, s[12:13]
	v_cndmask_b32_e64 v0, v42, v0, s[12:13]
	v_cmp_gt_f32_e32 vcc, v0, v211
	s_cbranch_vccz .LBB0_716
	v_and_b32_e32 v43, 64, v204
	v_xor_b32_e32 v42, 16, v204
	v_add_u32_e32 v43, 64, v43
	v_cmp_lt_i32_e32 vcc, v42, v43
	v_xor_b32_e32 v44, 32, v204
	s_nop 0
	v_cndmask_b32_e32 v42, v204, v42, vcc
	v_lshlrev_b32_e32 v42, 2, v42
	ds_bpermute_b32 v42, v42, v0
	v_max_f32_e32 v0, v0, v0
	v_cmp_lt_i32_e32 vcc, v44, v43
	s_waitcnt lgkmcnt(0)
	v_max_f32_e32 v42, v42, v42
	v_max_f32_e32 v0, v0, v42
	v_cndmask_b32_e32 v42, v204, v44, vcc
	v_lshlrev_b32_e32 v42, 2, v42
	ds_bpermute_b32 v42, v42, v0
	s_waitcnt lgkmcnt(0)
	v_max3_f32 v42, v207, v0, v42
	v_sub_f32_e32 v0, v207, v42
	v_exp_f32_e32 v0, v0
	v_mov_b32_e32 v207, v42
	v_mul_f32_e32 v208, v208, v0
	v_pk_mul_f32 v[4:5], v[4:5], v[0:1] op_sel_hi:[1,0]
	v_pk_mul_f32 v[2:3], v[2:3], v[0:1] op_sel_hi:[1,0]
	v_pk_mul_f32 v[8:9], v[8:9], v[0:1] op_sel_hi:[1,0]
	v_pk_mul_f32 v[6:7], v[6:7], v[0:1] op_sel_hi:[1,0]
	v_pk_mul_f32 v[12:13], v[12:13], v[0:1] op_sel_hi:[1,0]
	v_pk_mul_f32 v[10:11], v[10:11], v[0:1] op_sel_hi:[1,0]
	v_pk_mul_f32 v[16:17], v[16:17], v[0:1] op_sel_hi:[1,0]
	v_pk_mul_f32 v[14:15], v[14:15], v[0:1] op_sel_hi:[1,0]
	v_pk_mul_f32 v[20:21], v[20:21], v[0:1] op_sel_hi:[1,0]
	v_pk_mul_f32 v[18:19], v[18:19], v[0:1] op_sel_hi:[1,0]
	v_pk_mul_f32 v[24:25], v[24:25], v[0:1] op_sel_hi:[1,0]
	v_pk_mul_f32 v[22:23], v[22:23], v[0:1] op_sel_hi:[1,0]
	v_pk_mul_f32 v[32:33], v[32:33], v[0:1] op_sel_hi:[1,0]
	v_pk_mul_f32 v[30:31], v[30:31], v[0:1] op_sel_hi:[1,0]
	v_pk_mul_f32 v[28:29], v[28:29], v[0:1] op_sel_hi:[1,0]
	v_pk_mul_f32 v[26:27], v[26:27], v[0:1] op_sel_hi:[1,0]
; template <bool SLC, bool NOMASK> ...
;     const int kq = lane >> 4;
;     const int pos0 = SLC ? (dcur & 0xfffff) : dcur;
;     const int lo = SLC ? ((((dcur >> 20) == qi) | ((dcur >> 20) == 4)) ? 0 : (1 << 30)) : lo_in;
;     load_frag8(nxt, KF, VF, SLC ? (dnext & 0xfffff) : dnext, lane);
;     f32x4 sa[2] = {(f32x4){0.f, 0.f, 0.f, 0.f}, (f32x4){0.f, 0.f, 0.f, 0.f}};
; #pragma unroll
;     for (int T = 0; T < 2; ++T)
; #pragma unroll
;         for (int s2 = 0; s2 < 4; ++s2) sa[T] = __builtin_amdgcn_mfma_f32_16x16x32_fp8_fp8(cur.k[T][s2], qf[s2], sa[T], 0, 0, 0);
;     float sc[8]; bool vd[8]; float mx = -1e30f;
;     const bool act = lo == 0 || !SLC;
;     if (NOMASK) {
; #pragma unroll
;         for (int j = 0; j < 8; ++j) { sc[j] = sa[j >> 2][j & 3]; vd[j] = act; }
;         mx = fmaxf(fmaxf(fmaxf(sc[0], sc[1]), fmaxf(sc[2], sc[3])), fmaxf(fmaxf(sc[4], sc[5]), fmaxf(sc[6], sc[7])));
;         mx = act ? mx : -1e30f;
;     } else {
; #pragma unroll
;         for (int T = 0; T < 2; ++T)
; #pragma unroll
;             for (int r = 0; r < 4; ++r) { const int p = pos0 + 16 * T + 4 * kq + r; const bool v = (p >= lo) & (p <= hi); const float x = sa[T][r];
;                 sc[4 * T + r] = x; vd[4 * T + r] = v; mx = v ? fmaxf(mx, x) : mx; }
;     }
;     if (__builtin_amdgcn_ballot_w64(mx > st.m + 4.f) != 0ull) {
;         mx = fmaxf(mx, __shfl_xor(mx, 16)); mx = fmaxf(mx, __shfl_xor(mx, 32));
;         const float mn = fmaxf(st.m, mx), alpha = __builtin_amdgcn_exp2f(st.m - mn); st.m = mn; st.l *= alpha;
; #pragma unroll
;         for (int j = 0; j < 8; ++j) st.o[j] = st.o[j] * alpha;
;     }
;     f32x4 pa, pb; float ps = 0.f;
;     const float mref = st.m - 4.f;
;     if (NOMASK) {
; #pragma unroll
;         for (int j = 0; j < 4; ++j) { pa[j] = __builtin_amdgcn_exp2f(sc[j] - mref); pb[j] = __builtin_amdgcn_exp2f(sc[4 + j] - mref); }
;         if (SLC) {
; #pragma unroll
;             for (int j = 0; j < 4; ++j) { pa[j] = act ? pa[j] : 0.f; pb[j] = act ? pb[j] : 0.f; }
;         }
; #pragma unroll
;         for (int j = 0; j < 4; ++j) ps += pa[j] + pb[j];
;     } else {
; #pragma unroll
;         for (int j = 0; j < 4; ++j) { pa[j] = vd[j] ? __builtin_amdgcn_exp2f(sc[j] - mref) : 0.f; pb[j] = vd[4 + j] ? __builtin_amdgcn_exp2f(sc[4 + j] - mref) : 0.f; ps += pa[j] + pb[j]; }
;     }
;     st.l += ps;
;     const u32x2 pw = pack8_fp8(pa, pb);
.LBB0_716:
	v_add_f32_e32 v0, -4.0, v207
	v_sub_f32_e32 v34, v34, v0
	v_exp_f32_e32 v34, v34
	v_sub_f32_e32 v38, v38, v0
	v_exp_f32_e32 v38, v38
	v_sub_f32_e32 v36, v36, v0
	v_cndmask_b32_e64 v54, 0, v34, s[10:11]
	v_sub_f32_e32 v34, v35, v0
	v_exp_f32_e32 v34, v34
	v_sub_f32_e32 v35, v39, v0
	v_exp_f32_e32 v35, v35
	v_cndmask_b32_e64 v55, 0, v38, s[18:19]
	v_sub_f32_e32 v38, v40, v0
	v_cndmask_b32_e64 v56, 0, v34, s[6:7]
	v_sub_f32_e32 v34, v37, v0
	v_sub_f32_e32 v0, v41, v0
	v_exp_f32_e32 v36, v36
	v_exp_f32_e32 v38, v38
	v_cndmask_b32_e64 v57, 0, v35, s[14:15]
	v_exp_f32_e32 v34, v34
	v_exp_f32_e32 v0, v0
	v_mov_b32_e32 v62, v1
	v_mov_b32_e32 v63, v1
	v_cvt_pk_fp8_f32 v62, v54, v56
	v_cvt_pk_fp8_f32 v63, v55, v57
	v_cndmask_b32_e64 v58, 0, v36, s[8:9]
	v_cndmask_b32_e64 v59, 0, v38, s[16:17]
	v_cndmask_b32_e64 v64, 0, v34, s[4:5]
	v_cndmask_b32_e64 v0, 0, v0, s[12:13]
	v_cvt_pk_fp8_f32 v62, v58, v64 op_sel:[0,0,1]
	v_cvt_pk_fp8_f32 v63, v59, v0 op_sel:[0,0,1]
	v_add_f32_e32 v0, v64, v0
	v_mov_b32_e32 v209, v207
	s_waitcnt vmcnt(19)
	v_mfma_f32_16x16x32_fp8_fp8 v[34:37], v[116:117], v[62:63], v[2:5]
	s_nop 2
	v_add_f32_e32 v2, v54, v55
	v_add_f32_e32 v2, 0, v2
	v_add_f32_e32 v3, v56, v57
	v_mfma_f32_16x16x32_fp8_fp8 v[38:41], v[118:119], v[62:63], v[6:9]
	v_add_f32_e32 v2, v3, v2
	v_add_f32_e32 v3, v58, v59
	v_add_f32_e32 v2, v3, v2
	s_waitcnt vmcnt(18)
	v_mfma_f32_16x16x32_fp8_fp8 v[42:45], v[120:121], v[62:63], v[10:13]
	v_add_f32_e32 v0, v0, v2
	v_add_f32_e32 v210, v208, v0
	v_mfma_f32_16x16x32_fp8_fp8 v[46:49], v[122:123], v[62:63], v[14:17]
	s_waitcnt vmcnt(17)
	v_mfma_f32_16x16x32_fp8_fp8 v[50:53], v[124:125], v[62:63], v[18:21]
	v_mfma_f32_16x16x32_fp8_fp8 v[54:57], v[126:127], v[62:63], v[22:25]
	s_waitcnt vmcnt(16)
	v_mfma_f32_16x16x32_fp8_fp8 v[58:61], v[128:129], v[62:63], v[30:33]
	v_mfma_f32_16x16x32_fp8_fp8 v[62:65], v[130:131], v[62:63], v[26:29]
	s_nop 1
	s_cmp_gt_i32 s77, s74
	s_mov_b64 s[4:5], -1
	s_cbranch_scc1 .LBB0_696
.LBB0_717:
	s_add_i32 s66, s66, 4
	s_min_i32 s4, s66, s74
	s_add_i32 s6, s4, s73
	s_lshl_b32 s76, s6, 5
	s_and_b32 s4, s76, 0x3fffffe0
	s_lshr_b32 s26, s4, 4
	s_lshl_b64 s[4:5], s[26:27], 11
	s_and_b32 s26, s6, 0x1ffffff
	s_and_b32 s8, s42, 0x2000000
	s_lshl_b64 s[6:7], s[26:27], 12
	s_cmp_eq_u32 s8, 0
	v_lshl_add_u64 v[198:199], v[82:83], 0, s[4:5]
	v_lshl_add_u64 v[196:197], v[84:85], 0, s[6:7]
	s_mov_b64 s[4:5], -1
	v_add_f32_e32 v211, 4.0, v209
	s_cbranch_scc1 .LBB0_721
	v_lshl_add_u64 v[244:245], v[198:199], 0, v[98:99]
	global_load_dwordx4 v[148:151], v[244:245], off
	global_load_dwordx4 v[152:155], v[244:245], off offset:1024
	global_load_dwordx4 v[156:159], v[244:245], off offset:2048
	global_load_dwordx4 v[160:163], v[244:245], off offset:3072
	v_lshl_add_u64 v[246:247], v[196:197], 0, v[98:99]
	global_load_dwordx4 v[116:119], v[246:247], off
	global_load_dwordx4 v[120:123], v[246:247], off offset:1024
	global_load_dwordx4 v[124:127], v[246:247], off offset:2048
	global_load_dwordx4 v[128:131], v[246:247], off offset:3072
	s_waitcnt vmcnt(20)
	v_mfma_f32_16x16x32_fp8_fp8 v[2:5], v[180:181], v[74:75], 0
	v_mov_b64_e32 v[72:73], v[64:65]
	v_mov_b64_e32 v[68:69], v[60:61]
	v_mov_b64_e32 v[30:31], v[54:55]
	v_mfma_f32_16x16x32_fp8_fp8 v[6:9], v[188:189], v[74:75], 0
	v_mov_b64_e32 v[26:27], v[50:51]
	v_mov_b64_e32 v[22:23], v[46:47]
	v_mov_b64_e32 v[18:19], v[42:43]
	v_mfma_f32_16x16x32_fp8_fp8 v[2:5], v[182:183], v[76:77], v[2:5]
	v_mov_b64_e32 v[14:15], v[38:39]
	v_mov_b32_e32 v207, v209
	v_mov_b64_e32 v[70:71], v[62:63]
	v_mfma_f32_16x16x32_fp8_fp8 v[6:9], v[190:191], v[76:77], v[6:9]
	v_mov_b64_e32 v[66:67], v[58:59]
	v_mov_b64_e32 v[32:33], v[56:57]
	v_mov_b64_e32 v[28:29], v[52:53]
	v_mfma_f32_16x16x32_fp8_fp8 v[2:5], v[184:185], v[78:79], v[2:5]
	v_mov_b64_e32 v[24:25], v[48:49]
	v_mov_b64_e32 v[20:21], v[44:45]
	v_mov_b64_e32 v[16:17], v[40:41]
	v_mfma_f32_16x16x32_fp8_fp8 v[6:9], v[192:193], v[78:79], v[6:9]
	v_mov_b32_e32 v208, v210
	v_mfma_f32_16x16x32_fp8_fp8 v[2:5], v[186:187], v[80:81], v[2:5]
	v_mfma_f32_16x16x32_fp8_fp8 v[6:9], v[194:195], v[80:81], v[6:9]
	s_nop 6
	v_max_f32_e32 v0, v3, v3
	v_max_f32_e32 v10, v2, v2
	v_max_f32_e32 v0, v10, v0
	v_max_f32_e32 v10, v5, v5
	v_max_f32_e32 v11, v4, v4
	v_max_f32_e32 v10, v11, v10
	v_max_f32_e32 v11, v9, v9
	v_max_f32_e32 v12, v8, v8
	v_max_f32_e32 v11, v12, v11
	v_max3_f32 v11, v6, v7, v11
	v_max3_f32 v0, v0, v10, v11
	v_mov_b64_e32 v[10:11], v[34:35]
	v_cmp_gt_f32_e32 vcc, v0, v211
	v_mov_b64_e32 v[12:13], v[36:37]
	s_cbranch_vccz .LBB0_720
	v_and_b32_e32 v11, 64, v204
	v_xor_b32_e32 v10, 16, v204
	v_add_u32_e32 v11, 64, v11
	v_cmp_lt_i32_e32 vcc, v10, v11
	v_xor_b32_e32 v12, 32, v204
	s_nop 0
	v_cndmask_b32_e32 v10, v204, v10, vcc
	v_lshlrev_b32_e32 v10, 2, v10
	ds_bpermute_b32 v10, v10, v0
	v_max_f32_e32 v0, v0, v0
	v_cmp_lt_i32_e32 vcc, v12, v11
	s_waitcnt lgkmcnt(0)
	v_max_f32_e32 v10, v10, v10
	v_max_f32_e32 v0, v0, v10
	v_cndmask_b32_e32 v10, v204, v12, vcc
	v_lshlrev_b32_e32 v10, 2, v10
	ds_bpermute_b32 v10, v10, v0
	s_waitcnt lgkmcnt(0)
	v_max3_f32 v207, v209, v0, v10
	v_sub_f32_e32 v0, v209, v207
	v_exp_f32_e32 v0, v0
	s_nop 0
	v_mul_f32_e32 v208, v210, v0
	v_pk_mul_f32 v[12:13], v[36:37], v[0:1] op_sel_hi:[1,0]
	v_pk_mul_f32 v[10:11], v[34:35], v[0:1] op_sel_hi:[1,0]
	v_pk_mul_f32 v[16:17], v[40:41], v[0:1] op_sel_hi:[1,0]
	v_pk_mul_f32 v[14:15], v[38:39], v[0:1] op_sel_hi:[1,0]
	v_pk_mul_f32 v[20:21], v[44:45], v[0:1] op_sel_hi:[1,0]
	v_pk_mul_f32 v[18:19], v[42:43], v[0:1] op_sel_hi:[1,0]
	v_pk_mul_f32 v[24:25], v[48:49], v[0:1] op_sel_hi:[1,0]
	v_pk_mul_f32 v[22:23], v[46:47], v[0:1] op_sel_hi:[1,0]
	v_pk_mul_f32 v[28:29], v[52:53], v[0:1] op_sel_hi:[1,0]
	v_pk_mul_f32 v[26:27], v[50:51], v[0:1] op_sel_hi:[1,0]
	v_pk_mul_f32 v[32:33], v[56:57], v[0:1] op_sel_hi:[1,0]
	v_pk_mul_f32 v[30:31], v[54:55], v[0:1] op_sel_hi:[1,0]
	v_pk_mul_f32 v[68:69], v[60:61], v[0:1] op_sel_hi:[1,0]
	v_pk_mul_f32 v[66:67], v[58:59], v[0:1] op_sel_hi:[1,0]
	v_pk_mul_f32 v[72:73], v[64:65], v[0:1] op_sel_hi:[1,0]
	v_pk_mul_f32 v[70:71], v[62:63], v[0:1] op_sel_hi:[1,0]
; template <bool SLC, bool NOMASK> ...
;     const int kq = lane >> 4;
;     const int pos0 = SLC ? (dcur & 0xfffff) : dcur;
;     const int lo = SLC ? ((((dcur >> 20) == qi) | ((dcur >> 20) == 4)) ? 0 : (1 << 30)) : lo_in;
;     load_frag8(nxt, KF, VF, SLC ? (dnext & 0xfffff) : dnext, lane);
;     f32x4 sa[2] = {(f32x4){0.f, 0.f, 0.f, 0.f}, (f32x4){0.f, 0.f, 0.f, 0.f}};
; #pragma unroll
;     for (int T = 0; T < 2; ++T)
; #pragma unroll
;         for (int s2 = 0; s2 < 4; ++s2) sa[T] = __builtin_amdgcn_mfma_f32_16x16x32_fp8_fp8(cur.k[T][s2], qf[s2], sa[T], 0, 0, 0);
;     float sc[8]; bool vd[8]; float mx = -1e30f;
;     const bool act = lo == 0 || !SLC;
;     if (NOMASK) {
; #pragma unroll
;         for (int j = 0; j < 8; ++j) { sc[j] = sa[j >> 2][j & 3]; vd[j] = act; }
;         mx = fmaxf(fmaxf(fmaxf(sc[0], sc[1]), fmaxf(sc[2], sc[3])), fmaxf(fmaxf(sc[4], sc[5]), fmaxf(sc[6], sc[7])));
;         mx = act ? mx : -1e30f;
;     } else {
; #pragma unroll
;         for (int T = 0; T < 2; ++T)
; #pragma unroll
;             for (int r = 0; r < 4; ++r) { const int p = pos0 + 16 * T + 4 * kq + r; const bool v = (p >= lo) & (p <= hi); const float x = sa[T][r];
;                 sc[4 * T + r] = x; vd[4 * T + r] = v; mx = v ? fmaxf(mx, x) : mx; }
;     }
;     if (__builtin_amdgcn_ballot_w64(mx > st.m + 4.f) != 0ull) {
;         mx = fmaxf(mx, __shfl_xor(mx, 16)); mx = fmaxf(mx, __shfl_xor(mx, 32));
;         const float mn = fmaxf(st.m, mx), alpha = __builtin_amdgcn_exp2f(st.m - mn); st.m = mn; st.l *= alpha;
; #pragma unroll
;         for (int j = 0; j < 8; ++j) st.o[j] = st.o[j] * alpha;
;     }
;     f32x4 pa, pb; float ps = 0.f;
;     const float mref = st.m - 4.f;
;     if (NOMASK) {
; #pragma unroll
;         for (int j = 0; j < 4; ++j) { pa[j] = __builtin_amdgcn_exp2f(sc[j] - mref); pb[j] = __builtin_amdgcn_exp2f(sc[4 + j] - mref); }
;         if (SLC) {
; #pragma unroll
;             for (int j = 0; j < 4; ++j) { pa[j] = act ? pa[j] : 0.f; pb[j] = act ? pb[j] : 0.f; }
;         }
; #pragma unroll
;         for (int j = 0; j < 4; ++j) ps += pa[j] + pb[j];
;     } else {
; #pragma unroll
;         for (int j = 0; j < 4; ++j) { pa[j] = vd[j] ? __builtin_amdgcn_exp2f(sc[j] - mref) : 0.f; pb[j] = vd[4 + j] ? __builtin_amdgcn_exp2f(sc[4 + j] - mref) : 0.f; ps += pa[j] + pb[j]; }
;     }
;     st.l += ps;
;     const u32x2 pw = pack8_fp8(pa, pb);
.LBB0_720:
	v_add_f32_e32 v213, -4.0, v207
	v_sub_f32_e32 v0, v2, v213
	v_exp_f32_e32 v215, v0
	v_sub_f32_e32 v0, v6, v213
	v_exp_f32_e32 v217, v0
	v_sub_f32_e32 v0, v3, v213
	v_exp_f32_e32 v212, v0
	v_sub_f32_e32 v0, v7, v213
	v_exp_f32_e32 v0, v0
	v_sub_f32_e32 v2, v4, v213
	v_exp_f32_e32 v220, v2
	v_sub_f32_e32 v2, v8, v213
	v_exp_f32_e32 v221, v2
	v_sub_f32_e32 v2, v5, v213
	v_exp_f32_e32 v214, v2
	v_sub_f32_e32 v2, v9, v213
	v_mov_b32_e32 v218, v1
	v_mov_b32_e32 v219, v1
	v_exp_f32_e32 v216, v2
	v_cvt_pk_fp8_f32 v218, v215, v212
	v_cvt_pk_fp8_f32 v219, v217, v0
	v_add_f32_e32 v213, v215, v217
	v_add_f32_e32 v215, v220, v221
	v_cvt_pk_fp8_f32 v218, v220, v214 op_sel:[0,0,1]
	v_cvt_pk_fp8_f32 v219, v221, v216 op_sel:[0,0,1]
	s_mov_b64 s[4:5], 0
	s_waitcnt vmcnt(19)
	v_mfma_f32_16x16x32_fp8_fp8 v[2:5], v[164:165], v[218:219], v[10:13]
	v_mfma_f32_16x16x32_fp8_fp8 v[10:13], v[168:169], v[218:219], v[18:21]
	s_waitcnt vmcnt(18)
	v_mfma_f32_16x16x32_fp8_fp8 v[18:21], v[172:173], v[218:219], v[26:29]
	s_nop 2
	v_add_f32_e64 v26, v212, v0
	v_add_f32_e64 v27, v213, v1
	v_mfma_f32_16x16x32_fp8_fp8 v[6:9], v[166:167], v[218:219], v[14:17]
	v_pk_add_f32 v[26:27], v[26:27], v[26:27] op_sel_hi:[0,1]
	v_mov_b32_e32 v217, v27
	v_pk_add_f32 v[26:27], v[214:215], v[216:217]
	s_waitcnt vmcnt(17)
	v_mfma_f32_16x16x32_fp8_fp8 v[14:17], v[170:171], v[218:219], v[22:25]
	v_add_f32_e32 v0, v26, v27
	v_add_f32_e32 v208, v0, v208
	v_mfma_f32_16x16x32_fp8_fp8 v[22:25], v[174:175], v[218:219], v[30:33]
	s_waitcnt vmcnt(16)
	v_mfma_f32_16x16x32_fp8_fp8 v[30:33], v[176:177], v[218:219], v[66:69]
	v_mfma_f32_16x16x32_fp8_fp8 v[26:29], v[178:179], v[218:219], v[70:73]
	s_nop 1
.LBB0_721:
	s_and_b64 vcc, exec, s[4:5]
	s_cbranch_vccz .LBB0_725
	v_lshl_add_u64 v[244:245], v[198:199], 0, v[98:99]
	global_load_dwordx4 v[148:151], v[244:245], off
	global_load_dwordx4 v[152:155], v[244:245], off offset:1024
	global_load_dwordx4 v[156:159], v[244:245], off offset:2048
	global_load_dwordx4 v[160:163], v[244:245], off offset:3072
	v_lshl_add_u64 v[246:247], v[196:197], 0, v[98:99]
	global_load_dwordx4 v[116:119], v[246:247], off
	global_load_dwordx4 v[120:123], v[246:247], off offset:1024
	global_load_dwordx4 v[124:127], v[246:247], off offset:2048
	global_load_dwordx4 v[128:131], v[246:247], off offset:3072
	s_waitcnt vmcnt(20)
	v_mfma_f32_16x16x32_fp8_fp8 v[2:5], v[180:181], v[74:75], 0
	v_or_b32_e32 v0, s78, v203
	v_cmp_ge_i32_e32 vcc, v0, v105
	v_cmp_le_i32_e64 s[4:5], v0, v206
	v_mfma_f32_16x16x32_fp8_fp8 v[2:5], v[182:183], v[76:77], v[2:5]
	s_and_b64 s[10:11], vcc, s[4:5]
	v_or_b32_e32 v11, 1, v0
	v_cmp_ge_i32_e32 vcc, v11, v105
	v_mfma_f32_16x16x32_fp8_fp8 v[2:5], v[184:185], v[78:79], v[2:5]
	v_cmp_lt_i32_e64 s[4:5], v0, v206
	s_and_b64 s[6:7], s[4:5], vcc
	v_mfma_f32_16x16x32_fp8_fp8 v[6:9], v[188:189], v[74:75], 0
	v_mfma_f32_16x16x32_fp8_fp8 v[2:5], v[186:187], v[80:81], v[2:5]
	v_mfma_f32_16x16x32_fp8_fp8 v[6:9], v[190:191], v[76:77], v[6:9]
	v_mfma_f32_16x16x32_fp8_fp8 v[6:9], v[192:193], v[78:79], v[6:9]
	s_nop 5
	v_max_f32_e32 v10, v2, v2
	v_max_f32_e32 v10, 0xf149f2ca, v10
	v_cndmask_b32_e64 v10, v205, v10, s[10:11]
	v_max_f32_e32 v11, v3, v3
	v_max_f32_e32 v11, v10, v11
	v_cndmask_b32_e64 v10, v10, v11, s[6:7]
	v_or_b32_e32 v11, 2, v0
	v_cmp_ge_i32_e32 vcc, v11, v105
	v_cmp_le_i32_e64 s[4:5], v11, v206
	v_max_f32_e32 v11, v4, v4
	v_max_f32_e32 v11, v10, v11
	s_and_b64 s[8:9], vcc, s[4:5]
	v_mfma_f32_16x16x32_fp8_fp8 v[6:9], v[194:195], v[80:81], v[6:9]
	v_cndmask_b32_e64 v10, v10, v11, s[8:9]
	v_or_b32_e32 v11, 3, v0
	v_cmp_ge_i32_e32 vcc, v11, v105
	v_cmp_le_i32_e64 s[4:5], v11, v206
	v_max_f32_e32 v11, v5, v5
	v_max_f32_e32 v11, v10, v11
	s_and_b64 s[4:5], vcc, s[4:5]
	v_cndmask_b32_e64 v10, v10, v11, s[4:5]
	v_or_b32_e32 v11, 16, v0
	v_cmp_ge_i32_e32 vcc, v11, v105
	v_cmp_le_i32_e64 s[12:13], v11, v206
	v_max_f32_e32 v11, v6, v6
	v_max_f32_e32 v11, v10, v11
	s_and_b64 s[18:19], vcc, s[12:13]
	v_cndmask_b32_e64 v10, v10, v11, s[18:19]
	v_or_b32_e32 v11, 17, v0
	v_cmp_ge_i32_e32 vcc, v11, v105
	v_cmp_le_i32_e64 s[12:13], v11, v206
	v_max_f32_e32 v11, v10, v10
	v_max_f32_e32 v12, v7, v7
	v_max_f32_e32 v11, v11, v12
	s_and_b64 s[14:15], vcc, s[12:13]
	v_cndmask_b32_e64 v10, v10, v11, s[14:15]
	v_or_b32_e32 v11, 18, v0
	v_cmp_ge_i32_e32 vcc, v11, v105
	v_cmp_le_i32_e64 s[12:13], v11, v206
	v_max_f32_e32 v11, v10, v10
	v_max_f32_e32 v12, v8, v8
	v_max_f32_e32 v11, v11, v12
	s_and_b64 s[16:17], vcc, s[12:13]
	v_cndmask_b32_e64 v10, v10, v11, s[16:17]
	v_or_b32_e32 v0, 19, v0
	v_cmp_ge_i32_e32 vcc, v0, v105
	v_cmp_le_i32_e64 s[12:13], v0, v206
	v_max_f32_e32 v0, v10, v10
	v_max_f32_e32 v11, v9, v9
	v_max_f32_e32 v0, v0, v11
	s_and_b64 s[12:13], vcc, s[12:13]
	v_cndmask_b32_e64 v0, v10, v0, s[12:13]
	v_cmp_gt_f32_e32 vcc, v0, v211
	s_cbranch_vccz .LBB0_724
	v_and_b32_e32 v11, 64, v204
	v_xor_b32_e32 v10, 16, v204
	v_add_u32_e32 v11, 64, v11
	v_cmp_lt_i32_e32 vcc, v10, v11
	v_xor_b32_e32 v12, 32, v204
	s_nop 0
	v_cndmask_b32_e32 v10, v204, v10, vcc
	v_lshlrev_b32_e32 v10, 2, v10
	ds_bpermute_b32 v10, v10, v0
	v_max_f32_e32 v0, v0, v0
	v_cmp_lt_i32_e32 vcc, v12, v11
	s_waitcnt lgkmcnt(0)
	v_max_f32_e32 v10, v10, v10
	v_max_f32_e32 v0, v0, v10
	v_cndmask_b32_e32 v10, v204, v12, vcc
	v_lshlrev_b32_e32 v10, 2, v10
	ds_bpermute_b32 v10, v10, v0
	s_waitcnt lgkmcnt(0)
	v_max3_f32 v10, v209, v0, v10
	v_sub_f32_e32 v0, v209, v10
	v_exp_f32_e32 v0, v0
	v_mov_b32_e32 v209, v10
	v_mul_f32_e32 v210, v210, v0
	v_pk_mul_f32 v[36:37], v[36:37], v[0:1] op_sel_hi:[1,0]
	v_pk_mul_f32 v[34:35], v[34:35], v[0:1] op_sel_hi:[1,0]
	v_pk_mul_f32 v[40:41], v[40:41], v[0:1] op_sel_hi:[1,0]
	v_pk_mul_f32 v[38:39], v[38:39], v[0:1] op_sel_hi:[1,0]
	v_pk_mul_f32 v[44:45], v[44:45], v[0:1] op_sel_hi:[1,0]
	v_pk_mul_f32 v[42:43], v[42:43], v[0:1] op_sel_hi:[1,0]
	v_pk_mul_f32 v[48:49], v[48:49], v[0:1] op_sel_hi:[1,0]
	v_pk_mul_f32 v[46:47], v[46:47], v[0:1] op_sel_hi:[1,0]
	v_pk_mul_f32 v[52:53], v[52:53], v[0:1] op_sel_hi:[1,0]
	v_pk_mul_f32 v[50:51], v[50:51], v[0:1] op_sel_hi:[1,0]
	v_pk_mul_f32 v[56:57], v[56:57], v[0:1] op_sel_hi:[1,0]
	v_pk_mul_f32 v[54:55], v[54:55], v[0:1] op_sel_hi:[1,0]
	v_pk_mul_f32 v[60:61], v[60:61], v[0:1] op_sel_hi:[1,0]
	v_pk_mul_f32 v[58:59], v[58:59], v[0:1] op_sel_hi:[1,0]
	v_pk_mul_f32 v[64:65], v[64:65], v[0:1] op_sel_hi:[1,0]
	v_pk_mul_f32 v[62:63], v[62:63], v[0:1] op_sel_hi:[1,0]
; template <bool SLC, bool NOMASK> ...
;     ...
;     } else {
; #pragma unroll
;         for (int j = 0; j < 4; ++j) { pa[j] = vd[j] ? __builtin_amdgcn_exp2f(sc[j] - mref) : 0.f; pb[j] = vd[4 + j] ? __builtin_amdgcn_exp2f(sc[4 + j] - mref) : 0.f; ps += pa[j] + pb[j]; }
;     }
;     st.l += ps;
;     const u32x2 pw = pack8_fp8(pa, pb);
;     const i64_t pf = __builtin_bit_cast(i64_t, pw);
; #pragma unroll
;     for (int db = 0; db < 8; ++db) st.o[db] = __builtin_amdgcn_mfma_f32_16x16x32_fp8_fp8(cur.v[db], pf, st.o[db], 0, 0, 0);
.LBB0_724:
	v_add_f32_e32 v0, -4.0, v209
	v_sub_f32_e32 v2, v2, v0
	v_exp_f32_e32 v2, v2
	v_sub_f32_e32 v6, v6, v0
	v_exp_f32_e32 v6, v6
	v_sub_f32_e32 v4, v4, v0
	v_cndmask_b32_e64 v22, 0, v2, s[10:11]
	v_sub_f32_e32 v2, v3, v0
	v_exp_f32_e32 v2, v2
	v_sub_f32_e32 v3, v7, v0
	v_exp_f32_e32 v3, v3
	v_cndmask_b32_e64 v23, 0, v6, s[18:19]
	v_sub_f32_e32 v6, v8, v0
	v_cndmask_b32_e64 v24, 0, v2, s[6:7]
	v_sub_f32_e32 v2, v5, v0
	v_sub_f32_e32 v0, v9, v0
	v_exp_f32_e32 v4, v4
	v_exp_f32_e32 v6, v6
	v_cndmask_b32_e64 v25, 0, v3, s[14:15]
	v_exp_f32_e32 v2, v2
	v_exp_f32_e32 v0, v0
	v_mov_b32_e32 v26, v1
	v_mov_b32_e32 v27, v1
	v_cvt_pk_fp8_f32 v26, v22, v24
	v_cvt_pk_fp8_f32 v27, v23, v25
	v_cndmask_b32_e64 v28, 0, v4, s[8:9]
	v_cndmask_b32_e64 v29, 0, v6, s[16:17]
	v_cndmask_b32_e64 v66, 0, v2, s[4:5]
	v_cndmask_b32_e64 v0, 0, v0, s[12:13]
	v_cvt_pk_fp8_f32 v26, v28, v66 op_sel:[0,0,1]
	v_cvt_pk_fp8_f32 v27, v29, v0 op_sel:[0,0,1]
	v_add_f32_e32 v22, v22, v23
	v_add_f32_e32 v30, 0, v22
	v_add_f32_e32 v31, v24, v25
	v_add_f32_e32 v30, v31, v30
	v_add_f32_e32 v28, v28, v29
	v_add_f32_e32 v28, v28, v30
	v_add_f32_e32 v0, v66, v0
	s_waitcnt vmcnt(19)
	v_mfma_f32_16x16x32_fp8_fp8 v[2:5], v[164:165], v[26:27], v[34:37]
	v_add_f32_e32 v0, v0, v28
	v_add_f32_e32 v208, v210, v0
	v_mov_b32_e32 v207, v209
	v_mfma_f32_16x16x32_fp8_fp8 v[6:9], v[166:167], v[26:27], v[38:41]
	s_waitcnt vmcnt(18)
	v_mfma_f32_16x16x32_fp8_fp8 v[10:13], v[168:169], v[26:27], v[42:45]
	v_mfma_f32_16x16x32_fp8_fp8 v[14:17], v[170:171], v[26:27], v[46:49]
	s_waitcnt vmcnt(17)
	v_mfma_f32_16x16x32_fp8_fp8 v[18:21], v[172:173], v[26:27], v[50:53]
	v_mfma_f32_16x16x32_fp8_fp8 v[22:25], v[174:175], v[26:27], v[54:57]
	s_waitcnt vmcnt(16)
	v_mfma_f32_16x16x32_fp8_fp8 v[30:33], v[176:177], v[26:27], v[58:61]
	v_mfma_f32_16x16x32_fp8_fp8 v[26:29], v[178:179], v[26:27], v[62:65]
	s_nop 1

; template <bool SLC, bool NOMASK> ...
;     const int kq = lane >> 4;
;     const int pos0 = SLC ? (dcur & 0xfffff) : dcur;
;     const int lo = SLC ? ((((dcur >> 20) == qi) | ((dcur >> 20) == 4)) ? 0 : (1 << 30)) : lo_in;
;     load_frag8(nxt, KF, VF, SLC ? (dnext & 0xfffff) : dnext, lane);
;     f32x4 sa[2] = {(f32x4){0.f, 0.f, 0.f, 0.f}, (f32x4){0.f, 0.f, 0.f, 0.f}};
; #pragma unroll
;     for (int T = 0; T < 2; ++T)
; #pragma unroll
;         for (int s2 = 0; s2 < 4; ++s2) sa[T] = __builtin_amdgcn_mfma_f32_16x16x32_fp8_fp8(cur.k[T][s2], qf[s2], sa[T], 0, 0, 0);
;     float sc[8]; bool vd[8]; float mx = -1e30f;
;     const bool act = lo == 0 || !SLC;
;     if (NOMASK) {
; #pragma unroll
;         for (int j = 0; j < 8; ++j) { sc[j] = sa[j >> 2][j & 3]; vd[j] = act; }
;         mx = fmaxf(fmaxf(fmaxf(sc[0], sc[1]), fmaxf(sc[2], sc[3])), fmaxf(fmaxf(sc[4], sc[5]), fmaxf(sc[6], sc[7])));
;         mx = act ? mx : -1e30f;
;     } else {
; #pragma unroll
;         for (int T = 0; T < 2; ++T)
; #pragma unroll
;             for (int r = 0; r < 4; ++r) { const int p = pos0 + 16 * T + 4 * kq + r; const bool v = (p >= lo) & (p <= hi); const float x = sa[T][r];
;                 sc[4 * T + r] = x; vd[4 * T + r] = v; mx = v ? fmaxf(mx, x) : mx; }
;     }
;     if (__builtin_amdgcn_ballot_w64(mx > st.m + 4.f) != 0ull) {
;         mx = fmaxf(mx, __shfl_xor(mx, 16)); mx = fmaxf(mx, __shfl_xor(mx, 32));
;         const float mn = fmaxf(st.m, mx), alpha = __builtin_amdgcn_exp2f(st.m - mn); st.m = mn; st.l *= alpha;
; #pragma unroll
;         for (int j = 0; j < 8; ++j) st.o[j] = st.o[j] * alpha;
;     }
;     f32x4 pa, pb; float ps = 0.f;
;     const float mref = st.m - 4.f;
;     if (NOMASK) {
; #pragma unroll
;         for (int j = 0; j < 4; ++j) { pa[j] = __builtin_amdgcn_exp2f(sc[j] - mref); pb[j] = __builtin_amdgcn_exp2f(sc[4 + j] - mref); }
;         if (SLC) {
; #pragma unroll
;             for (int j = 0; j < 4; ++j) { pa[j] = act ? pa[j] : 0.f; pb[j] = act ? pb[j] : 0.f; }
;         }
; #pragma unroll
;         for (int j = 0; j < 4; ++j) ps += pa[j] + pb[j];
;     } else {
; #pragma unroll
;         for (int j = 0; j < 4; ++j) { pa[j] = vd[j] ? __builtin_amdgcn_exp2f(sc[j] - mref) : 0.f; pb[j] = vd[4 + j] ? __builtin_amdgcn_exp2f(sc[4 + j] - mref) : 0.f; ps += pa[j] + pb[j]; }
;     }
;     st.l += ps;
;     const u32x2 pw = pack8_fp8(pa, pb);
.LBB0_745:
	v_lshl_add_u64 v[244:245], v[198:199], 0, v[98:99]
	global_load_dwordx4 v[180:183], v[244:245], off
	global_load_dwordx4 v[184:187], v[244:245], off offset:1024
	global_load_dwordx4 v[188:191], v[244:245], off offset:2048
	global_load_dwordx4 v[192:195], v[244:245], off offset:3072
	v_lshl_add_u64 v[246:247], v[196:197], 0, v[98:99]
	global_load_dwordx4 v[164:167], v[246:247], off
	global_load_dwordx4 v[168:171], v[246:247], off offset:1024
	global_load_dwordx4 v[172:175], v[246:247], off offset:2048
	global_load_dwordx4 v[176:179], v[246:247], off offset:3072
	s_waitcnt vmcnt(20)
	v_mfma_f32_16x16x32_fp8_fp8 v[2:5], v[132:133], v[74:75], 0
	v_mov_b64_e32 v[72:73], v[48:49]
	v_mov_b64_e32 v[68:69], v[52:53]
	v_mov_b64_e32 v[30:31], v[58:59]
	v_mfma_f32_16x16x32_fp8_fp8 v[6:9], v[140:141], v[74:75], 0
	v_mov_b64_e32 v[26:27], v[62:63]
	v_mov_b64_e32 v[22:23], v[54:55]
	v_mov_b64_e32 v[18:19], v[42:43]
	v_mfma_f32_16x16x32_fp8_fp8 v[2:5], v[134:135], v[76:77], v[2:5]
	v_mov_b64_e32 v[14:15], v[38:39]
	v_mov_b32_e32 v205, v208
	v_mov_b64_e32 v[70:71], v[46:47]
	v_mfma_f32_16x16x32_fp8_fp8 v[6:9], v[142:143], v[76:77], v[6:9]
	v_mov_b64_e32 v[66:67], v[50:51]
	v_mov_b64_e32 v[32:33], v[60:61]
	v_mov_b64_e32 v[28:29], v[64:65]
	v_mfma_f32_16x16x32_fp8_fp8 v[2:5], v[136:137], v[78:79], v[2:5]
	v_mov_b64_e32 v[24:25], v[56:57]
	v_mov_b64_e32 v[20:21], v[44:45]
	v_mov_b64_e32 v[16:17], v[40:41]
	v_mfma_f32_16x16x32_fp8_fp8 v[6:9], v[144:145], v[78:79], v[6:9]
	v_mov_b32_e32 v206, v207
	v_mfma_f32_16x16x32_fp8_fp8 v[2:5], v[138:139], v[80:81], v[2:5]
	v_mfma_f32_16x16x32_fp8_fp8 v[6:9], v[146:147], v[80:81], v[6:9]
	s_nop 6
	v_max_f32_e32 v0, v3, v3
	v_max_f32_e32 v10, v2, v2
	v_max_f32_e32 v0, v10, v0
	v_max_f32_e32 v10, v5, v5
	v_max_f32_e32 v11, v4, v4
	v_max_f32_e32 v10, v11, v10
	v_max_f32_e32 v11, v9, v9
	v_max_f32_e32 v12, v8, v8
	v_max_f32_e32 v11, v12, v11
	v_max3_f32 v11, v6, v7, v11
	v_max3_f32 v0, v0, v10, v11
	v_add_f32_e32 v10, 4.0, v208
	v_cmp_gt_f32_e32 vcc, v0, v10
	v_mov_b64_e32 v[10:11], v[34:35]
	v_mov_b64_e32 v[12:13], v[36:37]
	s_cbranch_vccz .LBB0_747
	v_and_b32_e32 v11, 64, v200
	v_xor_b32_e32 v10, 16, v200
	v_add_u32_e32 v11, 64, v11
	v_cmp_lt_i32_e32 vcc, v10, v11
	v_xor_b32_e32 v12, 32, v200
	s_nop 0
	v_cndmask_b32_e32 v10, v200, v10, vcc
	v_lshlrev_b32_e32 v10, 2, v10
	ds_bpermute_b32 v10, v10, v0
	v_max_f32_e32 v0, v0, v0
	v_cmp_lt_i32_e32 vcc, v12, v11
	s_waitcnt lgkmcnt(0)
	v_max_f32_e32 v10, v10, v10
	v_max_f32_e32 v0, v0, v10
	v_cndmask_b32_e32 v10, v200, v12, vcc
	v_lshlrev_b32_e32 v10, 2, v10
	ds_bpermute_b32 v10, v10, v0
	s_waitcnt lgkmcnt(0)
	v_max3_f32 v205, v208, v0, v10
	v_sub_f32_e32 v0, v208, v205
	v_exp_f32_e32 v0, v0
	s_nop 0
	v_mul_f32_e32 v206, v207, v0
	v_pk_mul_f32 v[12:13], v[36:37], v[0:1] op_sel_hi:[1,0]
	v_pk_mul_f32 v[10:11], v[34:35], v[0:1] op_sel_hi:[1,0]
	v_pk_mul_f32 v[16:17], v[40:41], v[0:1] op_sel_hi:[1,0]
	v_pk_mul_f32 v[14:15], v[38:39], v[0:1] op_sel_hi:[1,0]
	v_pk_mul_f32 v[20:21], v[44:45], v[0:1] op_sel_hi:[1,0]
	v_pk_mul_f32 v[18:19], v[42:43], v[0:1] op_sel_hi:[1,0]
	v_pk_mul_f32 v[24:25], v[56:57], v[0:1] op_sel_hi:[1,0]
	v_pk_mul_f32 v[22:23], v[54:55], v[0:1] op_sel_hi:[1,0]
	v_pk_mul_f32 v[28:29], v[64:65], v[0:1] op_sel_hi:[1,0]
	v_pk_mul_f32 v[26:27], v[62:63], v[0:1] op_sel_hi:[1,0]
	v_pk_mul_f32 v[32:33], v[60:61], v[0:1] op_sel_hi:[1,0]
	v_pk_mul_f32 v[30:31], v[58:59], v[0:1] op_sel_hi:[1,0]
	v_pk_mul_f32 v[68:69], v[52:53], v[0:1] op_sel_hi:[1,0]
	v_pk_mul_f32 v[66:67], v[50:51], v[0:1] op_sel_hi:[1,0]
	v_pk_mul_f32 v[72:73], v[48:49], v[0:1] op_sel_hi:[1,0]
	v_pk_mul_f32 v[70:71], v[46:47], v[0:1] op_sel_hi:[1,0]
.LBB0_747:
	v_add_f32_e32 v209, -4.0, v205
	v_sub_f32_e32 v0, v2, v209
	v_exp_f32_e32 v211, v0
	v_sub_f32_e32 v0, v6, v209
	v_exp_f32_e32 v213, v0
	v_sub_f32_e32 v0, v3, v209
	v_exp_f32_e32 v210, v0
	v_sub_f32_e32 v0, v7, v209
	v_exp_f32_e32 v0, v0
	v_sub_f32_e32 v2, v4, v209
	v_exp_f32_e32 v215, v2
	v_sub_f32_e32 v2, v8, v209
	v_exp_f32_e32 v218, v2
	v_sub_f32_e32 v2, v5, v209
	v_exp_f32_e32 v212, v2
	v_sub_f32_e32 v2, v9, v209
	v_mov_b32_e32 v216, v1
	v_mov_b32_e32 v217, v1
	v_exp_f32_e32 v214, v2
	v_cvt_pk_fp8_f32 v216, v211, v210
	v_cvt_pk_fp8_f32 v217, v213, v0
	v_add_f32_e32 v211, v211, v213
	v_add_f32_e32 v213, v215, v218
	v_cvt_pk_fp8_f32 v216, v215, v212 op_sel:[0,0,1]
	v_cvt_pk_fp8_f32 v217, v218, v214 op_sel:[0,0,1]
	s_nop 0
	s_waitcnt vmcnt(19)
	v_mfma_f32_16x16x32_fp8_fp8 v[2:5], v[86:87], v[216:217], v[10:13]
	v_mfma_f32_16x16x32_fp8_fp8 v[10:13], v[90:91], v[216:217], v[18:21]
	s_waitcnt vmcnt(18)
	v_mfma_f32_16x16x32_fp8_fp8 v[18:21], v[94:95], v[216:217], v[26:29]
	s_nop 2
	v_add_f32_e64 v26, v210, v0
	v_add_f32_e64 v27, v211, v1
	v_mfma_f32_16x16x32_fp8_fp8 v[6:9], v[88:89], v[216:217], v[14:17]
	v_pk_add_f32 v[26:27], v[26:27], v[26:27] op_sel_hi:[0,1]
	v_mov_b32_e32 v215, v27
	v_pk_add_f32 v[26:27], v[212:213], v[214:215]
	s_waitcnt vmcnt(17)
	v_mfma_f32_16x16x32_fp8_fp8 v[14:17], v[92:93], v[216:217], v[22:25]
	v_add_f32_e32 v0, v26, v27
	v_add_f32_e32 v206, v0, v206
	v_mfma_f32_16x16x32_fp8_fp8 v[22:25], v[96:97], v[216:217], v[30:33]
	s_waitcnt vmcnt(16)
	v_mfma_f32_16x16x32_fp8_fp8 v[30:33], v[112:113], v[216:217], v[66:69]
	v_mfma_f32_16x16x32_fp8_fp8 v[26:29], v[114:115], v[216:217], v[70:73]
	s_nop 1
	s_branch .LBB0_741
; template <bool SLC, bool NOMASK> ...
;     const int kq = lane >> 4;
;     const int pos0 = SLC ? (dcur & 0xfffff) : dcur;
;     const int lo = SLC ? ((((dcur >> 20) == qi) | ((dcur >> 20) == 4)) ? 0 : (1 << 30)) : lo_in;
;     load_frag8(nxt, KF, VF, SLC ? (dnext & 0xfffff) : dnext, lane);
;     f32x4 sa[2] = {(f32x4){0.f, 0.f, 0.f, 0.f}, (f32x4){0.f, 0.f, 0.f, 0.f}};
; #pragma unroll
;     for (int T = 0; T < 2; ++T)
; #pragma unroll
;         for (int s2 = 0; s2 < 4; ++s2) sa[T] = __builtin_amdgcn_mfma_f32_16x16x32_fp8_fp8(cur.k[T][s2], qf[s2], sa[T], 0, 0, 0);
;     float sc[8]; bool vd[8]; float mx = -1e30f;
;     const bool act = lo == 0 || !SLC;
;     if (NOMASK) {
; #pragma unroll
;         for (int j = 0; j < 8; ++j) { sc[j] = sa[j >> 2][j & 3]; vd[j] = act; }
;         mx = fmaxf(fmaxf(fmaxf(sc[0], sc[1]), fmaxf(sc[2], sc[3])), fmaxf(fmaxf(sc[4], sc[5]), fmaxf(sc[6], sc[7])));
;         mx = act ? mx : -1e30f;
;     } else {
; #pragma unroll
;         for (int T = 0; T < 2; ++T)
; #pragma unroll
;             for (int r = 0; r < 4; ++r) { const int p = pos0 + 16 * T + 4 * kq + r; const bool v = (p >= lo) & (p <= hi); const float x = sa[T][r];
;                 sc[4 * T + r] = x; vd[4 * T + r] = v; mx = v ? fmaxf(mx, x) : mx; }
;     }
;     if (__builtin_amdgcn_ballot_w64(mx > st.m + 4.f) != 0ull) {
;         mx = fmaxf(mx, __shfl_xor(mx, 16)); mx = fmaxf(mx, __shfl_xor(mx, 32));
;         const float mn = fmaxf(st.m, mx), alpha = __builtin_amdgcn_exp2f(st.m - mn); st.m = mn; st.l *= alpha;
; #pragma unroll
;         for (int j = 0; j < 8; ++j) st.o[j] = st.o[j] * alpha;
;     }
;     f32x4 pa, pb; float ps = 0.f;
;     const float mref = st.m - 4.f;
;     if (NOMASK) {
; #pragma unroll
;         for (int j = 0; j < 4; ++j) { pa[j] = __builtin_amdgcn_exp2f(sc[j] - mref); pb[j] = __builtin_amdgcn_exp2f(sc[4 + j] - mref); }
;         if (SLC) {
; #pragma unroll
;             for (int j = 0; j < 4; ++j) { pa[j] = act ? pa[j] : 0.f; pb[j] = act ? pb[j] : 0.f; }
;         }
; #pragma unroll
;         for (int j = 0; j < 4; ++j) ps += pa[j] + pb[j];
;     } else {
; #pragma unroll
;         for (int j = 0; j < 4; ++j) { pa[j] = vd[j] ? __builtin_amdgcn_exp2f(sc[j] - mref) : 0.f; pb[j] = vd[4 + j] ? __builtin_amdgcn_exp2f(sc[4 + j] - mref) : 0.f; ps += pa[j] + pb[j]; }
;     }
;     st.l += ps;
;     const u32x2 pw = pack8_fp8(pa, pb);
.LBB0_748:
	v_lshl_add_u64 v[244:245], v[198:199], 0, v[98:99]
	global_load_dwordx4 v[180:183], v[244:245], off
	global_load_dwordx4 v[184:187], v[244:245], off offset:1024
	global_load_dwordx4 v[188:191], v[244:245], off offset:2048
	global_load_dwordx4 v[192:195], v[244:245], off offset:3072
	v_lshl_add_u64 v[246:247], v[196:197], 0, v[98:99]
	global_load_dwordx4 v[164:167], v[246:247], off
	global_load_dwordx4 v[168:171], v[246:247], off offset:1024
	global_load_dwordx4 v[172:175], v[246:247], off offset:2048
	global_load_dwordx4 v[176:179], v[246:247], off offset:3072
	s_waitcnt vmcnt(20)
	v_mfma_f32_16x16x32_fp8_fp8 v[2:5], v[132:133], v[74:75], 0
	v_or_b32_e32 v0, s62, v107
	v_cmp_ge_i32_e32 vcc, v0, v105
	v_cmp_le_i32_e64 s[4:5], v0, v204
	v_mfma_f32_16x16x32_fp8_fp8 v[2:5], v[134:135], v[76:77], v[2:5]
	s_and_b64 s[10:11], vcc, s[4:5]
	v_or_b32_e32 v11, 1, v0
	v_cmp_ge_i32_e32 vcc, v11, v105
	v_mfma_f32_16x16x32_fp8_fp8 v[2:5], v[136:137], v[78:79], v[2:5]
	v_cmp_lt_i32_e64 s[4:5], v0, v204
	s_and_b64 s[6:7], s[4:5], vcc
	v_mfma_f32_16x16x32_fp8_fp8 v[6:9], v[140:141], v[74:75], 0
	v_mfma_f32_16x16x32_fp8_fp8 v[2:5], v[138:139], v[80:81], v[2:5]
	v_mfma_f32_16x16x32_fp8_fp8 v[6:9], v[142:143], v[76:77], v[6:9]
	v_mfma_f32_16x16x32_fp8_fp8 v[6:9], v[144:145], v[78:79], v[6:9]
	s_nop 5
	v_max_f32_e32 v10, v2, v2
	v_max_f32_e32 v10, 0xf149f2ca, v10
	v_cndmask_b32_e64 v10, v203, v10, s[10:11]
	v_max_f32_e32 v11, v3, v3
	v_max_f32_e32 v11, v10, v11
	v_cndmask_b32_e64 v10, v10, v11, s[6:7]
	v_or_b32_e32 v11, 2, v0
	v_cmp_ge_i32_e32 vcc, v11, v105
	v_cmp_le_i32_e64 s[4:5], v11, v204
	v_max_f32_e32 v11, v4, v4
	v_max_f32_e32 v11, v10, v11
	s_and_b64 s[8:9], vcc, s[4:5]
	v_mfma_f32_16x16x32_fp8_fp8 v[6:9], v[146:147], v[80:81], v[6:9]
	v_cndmask_b32_e64 v10, v10, v11, s[8:9]
	v_or_b32_e32 v11, 3, v0
	v_cmp_ge_i32_e32 vcc, v11, v105
	v_cmp_le_i32_e64 s[4:5], v11, v204
	v_max_f32_e32 v11, v5, v5
	v_max_f32_e32 v11, v10, v11
	s_and_b64 s[4:5], vcc, s[4:5]
	v_cndmask_b32_e64 v10, v10, v11, s[4:5]
	v_or_b32_e32 v11, 16, v0
	v_cmp_ge_i32_e32 vcc, v11, v105
	v_cmp_le_i32_e64 s[12:13], v11, v204
	v_max_f32_e32 v11, v6, v6
	v_max_f32_e32 v11, v10, v11
	s_and_b64 s[18:19], vcc, s[12:13]
	v_cndmask_b32_e64 v10, v10, v11, s[18:19]
	v_or_b32_e32 v11, 17, v0
	v_cmp_ge_i32_e32 vcc, v11, v105
	v_cmp_le_i32_e64 s[12:13], v11, v204
	v_max_f32_e32 v11, v10, v10
	v_max_f32_e32 v12, v7, v7
	v_max_f32_e32 v11, v11, v12
	s_and_b64 s[14:15], vcc, s[12:13]
	v_cndmask_b32_e64 v10, v10, v11, s[14:15]
	v_or_b32_e32 v11, 18, v0
	v_cmp_ge_i32_e32 vcc, v11, v105
	v_cmp_le_i32_e64 s[12:13], v11, v204
	v_max_f32_e32 v11, v10, v10
	v_max_f32_e32 v12, v8, v8
	v_max_f32_e32 v11, v11, v12
	s_and_b64 s[16:17], vcc, s[12:13]
	v_cndmask_b32_e64 v10, v10, v11, s[16:17]
	v_or_b32_e32 v0, 19, v0
	v_cmp_ge_i32_e32 vcc, v0, v105
	v_cmp_le_i32_e64 s[12:13], v0, v204
	v_max_f32_e32 v0, v10, v10
	v_max_f32_e32 v11, v9, v9
	v_max_f32_e32 v0, v0, v11
	s_and_b64 s[12:13], vcc, s[12:13]
	v_cndmask_b32_e64 v0, v10, v0, s[12:13]
	v_add_f32_e32 v10, 4.0, v208
	v_cmp_gt_f32_e32 vcc, v0, v10
	s_cbranch_vccz .LBB0_750
	v_and_b32_e32 v11, 64, v200
	v_xor_b32_e32 v10, 16, v200
	v_add_u32_e32 v11, 64, v11
	v_cmp_lt_i32_e32 vcc, v10, v11
	v_xor_b32_e32 v12, 32, v200
	s_nop 0
	v_cndmask_b32_e32 v10, v200, v10, vcc
	v_lshlrev_b32_e32 v10, 2, v10
	ds_bpermute_b32 v10, v10, v0
	v_max_f32_e32 v0, v0, v0
	v_cmp_lt_i32_e32 vcc, v12, v11
	s_waitcnt lgkmcnt(0)
	v_max_f32_e32 v10, v10, v10
	v_max_f32_e32 v0, v0, v10
	v_cndmask_b32_e32 v10, v200, v12, vcc
	v_lshlrev_b32_e32 v10, 2, v10
	ds_bpermute_b32 v10, v10, v0
	s_waitcnt lgkmcnt(0)
	v_max3_f32 v10, v208, v0, v10
	v_sub_f32_e32 v0, v208, v10
	v_exp_f32_e32 v0, v0
	v_mov_b32_e32 v208, v10
	v_mul_f32_e32 v207, v207, v0
	v_pk_mul_f32 v[36:37], v[36:37], v[0:1] op_sel_hi:[1,0]
	v_pk_mul_f32 v[34:35], v[34:35], v[0:1] op_sel_hi:[1,0]
	v_pk_mul_f32 v[40:41], v[40:41], v[0:1] op_sel_hi:[1,0]
	v_pk_mul_f32 v[38:39], v[38:39], v[0:1] op_sel_hi:[1,0]
	v_pk_mul_f32 v[44:45], v[44:45], v[0:1] op_sel_hi:[1,0]
	v_pk_mul_f32 v[42:43], v[42:43], v[0:1] op_sel_hi:[1,0]
	v_pk_mul_f32 v[56:57], v[56:57], v[0:1] op_sel_hi:[1,0]
	v_pk_mul_f32 v[54:55], v[54:55], v[0:1] op_sel_hi:[1,0]
	v_pk_mul_f32 v[64:65], v[64:65], v[0:1] op_sel_hi:[1,0]
	v_pk_mul_f32 v[62:63], v[62:63], v[0:1] op_sel_hi:[1,0]
	v_pk_mul_f32 v[60:61], v[60:61], v[0:1] op_sel_hi:[1,0]
	v_pk_mul_f32 v[58:59], v[58:59], v[0:1] op_sel_hi:[1,0]
	v_pk_mul_f32 v[52:53], v[52:53], v[0:1] op_sel_hi:[1,0]
	v_pk_mul_f32 v[50:51], v[50:51], v[0:1] op_sel_hi:[1,0]
	v_pk_mul_f32 v[48:49], v[48:49], v[0:1] op_sel_hi:[1,0]
	v_pk_mul_f32 v[46:47], v[46:47], v[0:1] op_sel_hi:[1,0]
.LBB0_750:
	v_add_f32_e32 v0, -4.0, v208
	v_sub_f32_e32 v2, v2, v0
	v_exp_f32_e32 v2, v2
	v_sub_f32_e32 v6, v6, v0
	v_exp_f32_e32 v6, v6
	v_sub_f32_e32 v4, v4, v0
	v_cndmask_b32_e64 v22, 0, v2, s[10:11]
	v_sub_f32_e32 v2, v3, v0
	v_exp_f32_e32 v2, v2
	v_sub_f32_e32 v3, v7, v0
	v_exp_f32_e32 v3, v3
	v_cndmask_b32_e64 v23, 0, v6, s[18:19]
	v_sub_f32_e32 v6, v8, v0
	v_cndmask_b32_e64 v24, 0, v2, s[6:7]
	v_sub_f32_e32 v2, v5, v0
	v_sub_f32_e32 v0, v9, v0
	v_exp_f32_e32 v4, v4
	v_exp_f32_e32 v6, v6
	v_cndmask_b32_e64 v25, 0, v3, s[14:15]
	v_exp_f32_e32 v2, v2
	v_exp_f32_e32 v0, v0
	v_mov_b32_e32 v26, v1
	v_mov_b32_e32 v27, v1
	v_cvt_pk_fp8_f32 v26, v22, v24
	v_cvt_pk_fp8_f32 v27, v23, v25
	v_cndmask_b32_e64 v28, 0, v4, s[8:9]
	v_cndmask_b32_e64 v29, 0, v6, s[16:17]
	v_cndmask_b32_e64 v66, 0, v2, s[4:5]
	v_cndmask_b32_e64 v0, 0, v0, s[12:13]
	v_cvt_pk_fp8_f32 v26, v28, v66 op_sel:[0,0,1]
	v_cvt_pk_fp8_f32 v27, v29, v0 op_sel:[0,0,1]
	v_add_f32_e32 v22, v22, v23
	v_add_f32_e32 v30, 0, v22
	v_add_f32_e32 v31, v24, v25
	v_add_f32_e32 v30, v31, v30
	v_add_f32_e32 v28, v28, v29
	v_add_f32_e32 v28, v28, v30
	v_add_f32_e32 v0, v66, v0
	s_waitcnt vmcnt(19)
	v_mfma_f32_16x16x32_fp8_fp8 v[2:5], v[86:87], v[26:27], v[34:37]
	v_add_f32_e32 v0, v0, v28
	v_add_f32_e32 v206, v207, v0
	v_mov_b32_e32 v205, v208
	v_mfma_f32_16x16x32_fp8_fp8 v[6:9], v[88:89], v[26:27], v[38:41]
	s_waitcnt vmcnt(18)
	v_mfma_f32_16x16x32_fp8_fp8 v[10:13], v[90:91], v[26:27], v[42:45]
	v_mfma_f32_16x16x32_fp8_fp8 v[14:17], v[92:93], v[26:27], v[54:57]
	s_waitcnt vmcnt(17)
	v_mfma_f32_16x16x32_fp8_fp8 v[18:21], v[94:95], v[26:27], v[62:65]
	v_mfma_f32_16x16x32_fp8_fp8 v[22:25], v[96:97], v[26:27], v[58:61]
	s_waitcnt vmcnt(16)
	v_mfma_f32_16x16x32_fp8_fp8 v[30:33], v[112:113], v[26:27], v[50:53]
	v_mfma_f32_16x16x32_fp8_fp8 v[26:29], v[114:115], v[26:27], v[46:49]
	s_nop 1
	s_cmp_ge_i32 s66, s61
	s_mov_b64 s[4:5], -1
	s_cbranch_scc0 .LBB0_742

; template <bool SLC, bool NOMASK> ...
;     const int kq = lane >> 4;
;     const int pos0 = SLC ? (dcur & 0xfffff) : dcur;
;     const int lo = SLC ? ((((dcur >> 20) == qi) | ((dcur >> 20) == 4)) ? 0 : (1 << 30)) : lo_in;
;     load_frag8(nxt, KF, VF, SLC ? (dnext & 0xfffff) : dnext, lane);
;     f32x4 sa[2] = {(f32x4){0.f, 0.f, 0.f, 0.f}, (f32x4){0.f, 0.f, 0.f, 0.f}};
; #pragma unroll
;     for (int T = 0; T < 2; ++T)
; #pragma unroll
;         for (int s2 = 0; s2 < 4; ++s2) sa[T] = __builtin_amdgcn_mfma_f32_16x16x32_fp8_fp8(cur.k[T][s2], qf[s2], sa[T], 0, 0, 0);
;     float sc[8]; bool vd[8]; float mx = -1e30f;
;     const bool act = lo == 0 || !SLC;
;     if (NOMASK) {
; #pragma unroll
;         for (int j = 0; j < 8; ++j) { sc[j] = sa[j >> 2][j & 3]; vd[j] = act; }
;         mx = fmaxf(fmaxf(fmaxf(sc[0], sc[1]), fmaxf(sc[2], sc[3])), fmaxf(fmaxf(sc[4], sc[5]), fmaxf(sc[6], sc[7])));
;         mx = act ? mx : -1e30f;
;     } else {
; #pragma unroll
;         for (int T = 0; T < 2; ++T)
; #pragma unroll
;             for (int r = 0; r < 4; ++r) { const int p = pos0 + 16 * T + 4 * kq + r; const bool v = (p >= lo) & (p <= hi); const float x = sa[T][r];
;                 sc[4 * T + r] = x; vd[4 * T + r] = v; mx = v ? fmaxf(mx, x) : mx; }
;     }
;     if (__builtin_amdgcn_ballot_w64(mx > st.m + 4.f) != 0ull) {
;         mx = fmaxf(mx, __shfl_xor(mx, 16)); mx = fmaxf(mx, __shfl_xor(mx, 32));
;         const float mn = fmaxf(st.m, mx), alpha = __builtin_amdgcn_exp2f(st.m - mn); st.m = mn; st.l *= alpha;
; #pragma unroll
;         for (int j = 0; j < 8; ++j) st.o[j] = st.o[j] * alpha;
;     }
;     f32x4 pa, pb; float ps = 0.f;
;     const float mref = st.m - 4.f;
;     if (NOMASK) {
; #pragma unroll
;         for (int j = 0; j < 4; ++j) { pa[j] = __builtin_amdgcn_exp2f(sc[j] - mref); pb[j] = __builtin_amdgcn_exp2f(sc[4 + j] - mref); }
;         if (SLC) {
; #pragma unroll
;             for (int j = 0; j < 4; ++j) { pa[j] = act ? pa[j] : 0.f; pb[j] = act ? pb[j] : 0.f; }
;         }
; #pragma unroll
;         for (int j = 0; j < 4; ++j) ps += pa[j] + pb[j];
;     } else {
; #pragma unroll
;         for (int j = 0; j < 4; ++j) { pa[j] = vd[j] ? __builtin_amdgcn_exp2f(sc[j] - mref) : 0.f; pb[j] = vd[4 + j] ? __builtin_amdgcn_exp2f(sc[4 + j] - mref) : 0.f; ps += pa[j] + pb[j]; }
;     }
;     st.l += ps;
;     const u32x2 pw = pack8_fp8(pa, pb);
.LBB0_752:
	v_lshl_add_u64 v[244:245], v[198:199], 0, v[98:99]
	global_load_dwordx4 v[132:135], v[244:245], off
	global_load_dwordx4 v[136:139], v[244:245], off offset:1024
	global_load_dwordx4 v[140:143], v[244:245], off offset:2048
	global_load_dwordx4 v[144:147], v[244:245], off offset:3072
	v_lshl_add_u64 v[246:247], v[196:197], 0, v[98:99]
	global_load_dwordx4 v[86:89], v[246:247], off
	global_load_dwordx4 v[90:93], v[246:247], off offset:1024
	global_load_dwordx4 v[94:97], v[246:247], off offset:2048
	global_load_dwordx4 v[112:115], v[246:247], off offset:3072
	s_waitcnt vmcnt(20)
	v_mfma_f32_16x16x32_fp8_fp8 v[34:37], v[148:149], v[74:75], 0
	v_mov_b64_e32 v[72:73], v[28:29]
	v_mov_b64_e32 v[68:69], v[32:33]
	v_mov_b64_e32 v[64:65], v[24:25]
	v_mfma_f32_16x16x32_fp8_fp8 v[38:41], v[156:157], v[74:75], 0
	v_mov_b64_e32 v[60:61], v[20:21]
	v_mov_b64_e32 v[56:57], v[16:17]
	v_mov_b64_e32 v[52:53], v[12:13]
	v_mfma_f32_16x16x32_fp8_fp8 v[34:37], v[150:151], v[76:77], v[34:37]
	v_mov_b64_e32 v[48:49], v[8:9]
	v_mov_b32_e32 v207, v205
	v_mov_b64_e32 v[70:71], v[26:27]
	v_mfma_f32_16x16x32_fp8_fp8 v[38:41], v[158:159], v[76:77], v[38:41]
	v_mov_b64_e32 v[66:67], v[30:31]
	v_mov_b64_e32 v[62:63], v[22:23]
	v_mov_b64_e32 v[58:59], v[18:19]
	v_mfma_f32_16x16x32_fp8_fp8 v[34:37], v[152:153], v[78:79], v[34:37]
	v_mov_b64_e32 v[54:55], v[14:15]
	v_mov_b64_e32 v[50:51], v[10:11]
	v_mov_b64_e32 v[46:47], v[6:7]
	v_mfma_f32_16x16x32_fp8_fp8 v[38:41], v[160:161], v[78:79], v[38:41]
	v_mov_b32_e32 v208, v206
	v_mfma_f32_16x16x32_fp8_fp8 v[34:37], v[154:155], v[80:81], v[34:37]
	v_mfma_f32_16x16x32_fp8_fp8 v[38:41], v[162:163], v[80:81], v[38:41]
	s_nop 6
	v_max_f32_e32 v0, v35, v35
	v_max_f32_e32 v42, v34, v34
	v_max_f32_e32 v0, v42, v0
	v_max_f32_e32 v42, v37, v37
	v_max_f32_e32 v43, v36, v36
	v_max_f32_e32 v42, v43, v42
	v_max_f32_e32 v43, v41, v41
	v_max_f32_e32 v44, v40, v40
	v_max_f32_e32 v43, v44, v43
	v_max3_f32 v43, v38, v39, v43
	v_max3_f32 v0, v0, v42, v43
	v_add_f32_e32 v42, 4.0, v205
	v_cmp_gt_f32_e32 vcc, v0, v42
	v_mov_b64_e32 v[44:45], v[4:5]
	v_mov_b64_e32 v[42:43], v[2:3]
	s_cbranch_vccz .LBB0_754
	v_and_b32_e32 v43, 64, v200
	v_xor_b32_e32 v42, 16, v200
	v_add_u32_e32 v43, 64, v43
	v_cmp_lt_i32_e32 vcc, v42, v43
	v_xor_b32_e32 v44, 32, v200
	s_nop 0
	v_cndmask_b32_e32 v42, v200, v42, vcc
	v_lshlrev_b32_e32 v42, 2, v42
	ds_bpermute_b32 v42, v42, v0
	v_max_f32_e32 v0, v0, v0
	v_cmp_lt_i32_e32 vcc, v44, v43
	s_waitcnt lgkmcnt(0)
	v_max_f32_e32 v42, v42, v42
	v_max_f32_e32 v0, v0, v42
	v_cndmask_b32_e32 v42, v200, v44, vcc
	v_lshlrev_b32_e32 v42, 2, v42
	ds_bpermute_b32 v42, v42, v0
	s_waitcnt lgkmcnt(0)
	v_max3_f32 v207, v205, v0, v42
	v_sub_f32_e32 v0, v205, v207
	v_exp_f32_e32 v0, v0
	s_nop 0
	v_mul_f32_e32 v208, v206, v0
	v_pk_mul_f32 v[44:45], v[4:5], v[0:1] op_sel_hi:[1,0]
	v_pk_mul_f32 v[42:43], v[2:3], v[0:1] op_sel_hi:[1,0]
	v_pk_mul_f32 v[48:49], v[8:9], v[0:1] op_sel_hi:[1,0]
	v_pk_mul_f32 v[46:47], v[6:7], v[0:1] op_sel_hi:[1,0]
	v_pk_mul_f32 v[52:53], v[12:13], v[0:1] op_sel_hi:[1,0]
	v_pk_mul_f32 v[50:51], v[10:11], v[0:1] op_sel_hi:[1,0]
	v_pk_mul_f32 v[56:57], v[16:17], v[0:1] op_sel_hi:[1,0]
	v_pk_mul_f32 v[54:55], v[14:15], v[0:1] op_sel_hi:[1,0]
	v_pk_mul_f32 v[60:61], v[20:21], v[0:1] op_sel_hi:[1,0]
	v_pk_mul_f32 v[58:59], v[18:19], v[0:1] op_sel_hi:[1,0]
	v_pk_mul_f32 v[64:65], v[24:25], v[0:1] op_sel_hi:[1,0]
	v_pk_mul_f32 v[62:63], v[22:23], v[0:1] op_sel_hi:[1,0]
	v_pk_mul_f32 v[68:69], v[32:33], v[0:1] op_sel_hi:[1,0]
	v_pk_mul_f32 v[66:67], v[30:31], v[0:1] op_sel_hi:[1,0]
	v_pk_mul_f32 v[72:73], v[28:29], v[0:1] op_sel_hi:[1,0]
	v_pk_mul_f32 v[70:71], v[26:27], v[0:1] op_sel_hi:[1,0]
.LBB0_754:
	v_add_f32_e32 v209, -4.0, v207
	v_sub_f32_e32 v0, v34, v209
	v_exp_f32_e32 v211, v0
	v_sub_f32_e32 v0, v38, v209
	v_exp_f32_e32 v213, v0
	v_sub_f32_e32 v0, v35, v209
	v_exp_f32_e32 v210, v0
	v_sub_f32_e32 v0, v39, v209
	v_exp_f32_e32 v0, v0
	v_sub_f32_e32 v34, v36, v209
	v_exp_f32_e32 v215, v34
	v_sub_f32_e32 v34, v40, v209
	v_exp_f32_e32 v218, v34
	v_sub_f32_e32 v34, v37, v209
	v_exp_f32_e32 v212, v34
	v_sub_f32_e32 v34, v41, v209
	v_mov_b32_e32 v216, v1
	v_mov_b32_e32 v217, v1
	v_exp_f32_e32 v214, v34
	v_cvt_pk_fp8_f32 v216, v211, v210
	v_cvt_pk_fp8_f32 v217, v213, v0
	v_add_f32_e32 v211, v211, v213
	v_add_f32_e32 v213, v215, v218
	v_cvt_pk_fp8_f32 v216, v215, v212 op_sel:[0,0,1]
	v_cvt_pk_fp8_f32 v217, v218, v214 op_sel:[0,0,1]
	s_nop 0
	s_waitcnt vmcnt(19)
	v_mfma_f32_16x16x32_fp8_fp8 v[34:37], v[116:117], v[216:217], v[42:45]
	v_mfma_f32_16x16x32_fp8_fp8 v[42:45], v[120:121], v[216:217], v[50:53]
	s_waitcnt vmcnt(18)
	v_mfma_f32_16x16x32_fp8_fp8 v[50:53], v[124:125], v[216:217], v[58:61]
	s_nop 2
	v_add_f32_e64 v58, v210, v0
	v_add_f32_e64 v59, v211, v1
	v_mfma_f32_16x16x32_fp8_fp8 v[38:41], v[118:119], v[216:217], v[46:49]
	v_pk_add_f32 v[58:59], v[58:59], v[58:59] op_sel_hi:[0,1]
	v_mov_b32_e32 v215, v59
	s_waitcnt vmcnt(17)
	v_mfma_f32_16x16x32_fp8_fp8 v[46:49], v[122:123], v[216:217], v[54:57]
	v_mfma_f32_16x16x32_fp8_fp8 v[54:57], v[126:127], v[216:217], v[62:65]
	s_nop 2
	v_add_f32_e64 v62, v212, v214
	v_add_f32_e64 v63, v213, v215
	s_waitcnt vmcnt(16)
	v_mfma_f32_16x16x32_fp8_fp8 v[58:61], v[128:129], v[216:217], v[66:69]
	v_add_f32_e32 v0, v62, v63
	v_add_f32_e32 v208, v0, v208
	v_mfma_f32_16x16x32_fp8_fp8 v[62:65], v[130:131], v[216:217], v[70:73]
	s_nop 1
	s_branch .LBB0_744
; template <bool SLC, bool NOMASK> ...
;     const int kq = lane >> 4;
;     const int pos0 = SLC ? (dcur & 0xfffff) : dcur;
;     const int lo = SLC ? ((((dcur >> 20) == qi) | ((dcur >> 20) == 4)) ? 0 : (1 << 30)) : lo_in;
;     load_frag8(nxt, KF, VF, SLC ? (dnext & 0xfffff) : dnext, lane);
;     f32x4 sa[2] = {(f32x4){0.f, 0.f, 0.f, 0.f}, (f32x4){0.f, 0.f, 0.f, 0.f}};
; #pragma unroll
;     for (int T = 0; T < 2; ++T)
; #pragma unroll
;         for (int s2 = 0; s2 < 4; ++s2) sa[T] = __builtin_amdgcn_mfma_f32_16x16x32_fp8_fp8(cur.k[T][s2], qf[s2], sa[T], 0, 0, 0);
;     float sc[8]; bool vd[8]; float mx = -1e30f;
;     const bool act = lo == 0 || !SLC;
;     if (NOMASK) {
; #pragma unroll
;         for (int j = 0; j < 8; ++j) { sc[j] = sa[j >> 2][j & 3]; vd[j] = act; }
;         mx = fmaxf(fmaxf(fmaxf(sc[0], sc[1]), fmaxf(sc[2], sc[3])), fmaxf(fmaxf(sc[4], sc[5]), fmaxf(sc[6], sc[7])));
;         mx = act ? mx : -1e30f;
;     } else {
; #pragma unroll
;         for (int T = 0; T < 2; ++T)
; #pragma unroll
;             for (int r = 0; r < 4; ++r) { const int p = pos0 + 16 * T + 4 * kq + r; const bool v = (p >= lo) & (p <= hi); const float x = sa[T][r];
;                 sc[4 * T + r] = x; vd[4 * T + r] = v; mx = v ? fmaxf(mx, x) : mx; }
;     }
;     if (__builtin_amdgcn_ballot_w64(mx > st.m + 4.f) != 0ull) {
;         mx = fmaxf(mx, __shfl_xor(mx, 16)); mx = fmaxf(mx, __shfl_xor(mx, 32));
;         const float mn = fmaxf(st.m, mx), alpha = __builtin_amdgcn_exp2f(st.m - mn); st.m = mn; st.l *= alpha;
; #pragma unroll
;         for (int j = 0; j < 8; ++j) st.o[j] = st.o[j] * alpha;
;     }
.LBB0_755:
	v_lshl_add_u64 v[244:245], v[198:199], 0, v[98:99]
	global_load_dwordx4 v[132:135], v[244:245], off
	global_load_dwordx4 v[136:139], v[244:245], off offset:1024
	global_load_dwordx4 v[140:143], v[244:245], off offset:2048
	global_load_dwordx4 v[144:147], v[244:245], off offset:3072
	v_lshl_add_u64 v[246:247], v[196:197], 0, v[98:99]
	global_load_dwordx4 v[86:89], v[246:247], off
	global_load_dwordx4 v[90:93], v[246:247], off offset:1024
	global_load_dwordx4 v[94:97], v[246:247], off offset:2048
	global_load_dwordx4 v[112:115], v[246:247], off offset:3072
	s_waitcnt vmcnt(20)
	v_mfma_f32_16x16x32_fp8_fp8 v[34:37], v[148:149], v[74:75], 0
	v_or_b32_e32 v0, s63, v107
	v_cmp_ge_i32_e32 vcc, v0, v105
	v_cmp_le_i32_e64 s[4:5], v0, v204
	v_mfma_f32_16x16x32_fp8_fp8 v[34:37], v[150:151], v[76:77], v[34:37]
	s_and_b64 s[10:11], vcc, s[4:5]
	v_or_b32_e32 v43, 1, v0
	v_cmp_ge_i32_e32 vcc, v43, v105
	v_mfma_f32_16x16x32_fp8_fp8 v[34:37], v[152:153], v[78:79], v[34:37]
	v_cmp_lt_i32_e64 s[4:5], v0, v204
	s_and_b64 s[6:7], s[4:5], vcc
	v_mfma_f32_16x16x32_fp8_fp8 v[38:41], v[156:157], v[74:75], 0
	v_mfma_f32_16x16x32_fp8_fp8 v[34:37], v[154:155], v[80:81], v[34:37]
	v_mfma_f32_16x16x32_fp8_fp8 v[38:41], v[158:159], v[76:77], v[38:41]
	v_mfma_f32_16x16x32_fp8_fp8 v[38:41], v[160:161], v[78:79], v[38:41]
	s_nop 5
	v_max_f32_e32 v42, v34, v34
	v_max_f32_e32 v42, 0xf149f2ca, v42
	v_cndmask_b32_e64 v42, v203, v42, s[10:11]
	v_max_f32_e32 v43, v35, v35
	v_max_f32_e32 v43, v42, v43
	v_cndmask_b32_e64 v42, v42, v43, s[6:7]
	v_or_b32_e32 v43, 2, v0
	v_cmp_ge_i32_e32 vcc, v43, v105
	v_cmp_le_i32_e64 s[4:5], v43, v204
	v_max_f32_e32 v43, v36, v36
	v_max_f32_e32 v43, v42, v43
	s_and_b64 s[8:9], vcc, s[4:5]
	v_mfma_f32_16x16x32_fp8_fp8 v[38:41], v[162:163], v[80:81], v[38:41]
	v_cndmask_b32_e64 v42, v42, v43, s[8:9]
	v_or_b32_e32 v43, 3, v0
	v_cmp_ge_i32_e32 vcc, v43, v105
	v_cmp_le_i32_e64 s[4:5], v43, v204
	v_max_f32_e32 v43, v37, v37
	v_max_f32_e32 v43, v42, v43
	s_and_b64 s[4:5], vcc, s[4:5]
	v_cndmask_b32_e64 v42, v42, v43, s[4:5]
	v_or_b32_e32 v43, 16, v0
	v_cmp_ge_i32_e32 vcc, v43, v105
	v_cmp_le_i32_e64 s[12:13], v43, v204
	v_max_f32_e32 v43, v38, v38
	v_max_f32_e32 v43, v42, v43
	s_and_b64 s[18:19], vcc, s[12:13]
	v_cndmask_b32_e64 v42, v42, v43, s[18:19]
	v_or_b32_e32 v43, 17, v0
	v_cmp_ge_i32_e32 vcc, v43, v105
	v_cmp_le_i32_e64 s[12:13], v43, v204
	v_max_f32_e32 v43, v42, v42
	v_max_f32_e32 v44, v39, v39
	v_max_f32_e32 v43, v43, v44
	s_and_b64 s[14:15], vcc, s[12:13]
	v_cndmask_b32_e64 v42, v42, v43, s[14:15]
	v_or_b32_e32 v43, 18, v0
	v_cmp_ge_i32_e32 vcc, v43, v105
	v_cmp_le_i32_e64 s[12:13], v43, v204
	v_max_f32_e32 v43, v42, v42
	v_max_f32_e32 v44, v40, v40
	v_max_f32_e32 v43, v43, v44
	s_and_b64 s[16:17], vcc, s[12:13]
	v_cndmask_b32_e64 v42, v42, v43, s[16:17]
	v_or_b32_e32 v0, 19, v0
	v_cmp_ge_i32_e32 vcc, v0, v105
	v_cmp_le_i32_e64 s[12:13], v0, v204
	v_max_f32_e32 v0, v42, v42
	v_max_f32_e32 v43, v41, v41
	v_max_f32_e32 v0, v0, v43
	s_and_b64 s[12:13], vcc, s[12:13]
	v_cndmask_b32_e64 v0, v42, v0, s[12:13]
	v_add_f32_e32 v42, 4.0, v205
	v_cmp_gt_f32_e32 vcc, v0, v42
	s_cbranch_vccz .LBB0_757
	v_and_b32_e32 v43, 64, v200
	v_xor_b32_e32 v42, 16, v200
	v_add_u32_e32 v43, 64, v43
	v_cmp_lt_i32_e32 vcc, v42, v43
	v_xor_b32_e32 v44, 32, v200
	s_nop 0
	v_cndmask_b32_e32 v42, v200, v42, vcc
	v_lshlrev_b32_e32 v42, 2, v42
	ds_bpermute_b32 v42, v42, v0
	v_max_f32_e32 v0, v0, v0
	v_cmp_lt_i32_e32 vcc, v44, v43
	s_waitcnt lgkmcnt(0)
	v_max_f32_e32 v42, v42, v42
	v_max_f32_e32 v0, v0, v42
	v_cndmask_b32_e32 v42, v200, v44, vcc
	v_lshlrev_b32_e32 v42, 2, v42
	ds_bpermute_b32 v42, v42, v0
	s_waitcnt lgkmcnt(0)
	v_max3_f32 v42, v205, v0, v42
	v_sub_f32_e32 v0, v205, v42
	v_exp_f32_e32 v0, v0
	v_mov_b32_e32 v205, v42
	v_mul_f32_e32 v206, v206, v0
	v_pk_mul_f32 v[4:5], v[4:5], v[0:1] op_sel_hi:[1,0]
	v_pk_mul_f32 v[2:3], v[2:3], v[0:1] op_sel_hi:[1,0]
	v_pk_mul_f32 v[8:9], v[8:9], v[0:1] op_sel_hi:[1,0]
	v_pk_mul_f32 v[6:7], v[6:7], v[0:1] op_sel_hi:[1,0]
	v_pk_mul_f32 v[12:13], v[12:13], v[0:1] op_sel_hi:[1,0]
	v_pk_mul_f32 v[10:11], v[10:11], v[0:1] op_sel_hi:[1,0]
	v_pk_mul_f32 v[16:17], v[16:17], v[0:1] op_sel_hi:[1,0]
	v_pk_mul_f32 v[14:15], v[14:15], v[0:1] op_sel_hi:[1,0]
	v_pk_mul_f32 v[20:21], v[20:21], v[0:1] op_sel_hi:[1,0]
	v_pk_mul_f32 v[18:19], v[18:19], v[0:1] op_sel_hi:[1,0]
	v_pk_mul_f32 v[24:25], v[24:25], v[0:1] op_sel_hi:[1,0]
	v_pk_mul_f32 v[22:23], v[22:23], v[0:1] op_sel_hi:[1,0]
	v_pk_mul_f32 v[32:33], v[32:33], v[0:1] op_sel_hi:[1,0]
	v_pk_mul_f32 v[30:31], v[30:31], v[0:1] op_sel_hi:[1,0]
	v_pk_mul_f32 v[28:29], v[28:29], v[0:1] op_sel_hi:[1,0]
	v_pk_mul_f32 v[26:27], v[26:27], v[0:1] op_sel_hi:[1,0]
; #define F8_STEP(CUR, NXT2, DC, DN2) do { \
;         if ((DC) & (1 << 30)) step_frag8<SLC, true>(qf, CUR, NXT2, KF, VF, (DC) & NM, (DN2) & NM, lo_in, hi, qi, st, lane); \
;         else step_frag8<SLC, false>(qf, CUR, NXT2, KF, VF, (DC), (DN2) & NM, lo_in, hi, qi, st, lane); } while (0)
; template <bool SLC, bool NOMASK> ...
;     ...
;     } else {
; #pragma unroll
;         for (int j = 0; j < 4; ++j) { pa[j] = vd[j] ? __builtin_amdgcn_exp2f(sc[j] - mref) : 0.f; pb[j] = vd[4 + j] ? __builtin_amdgcn_exp2f(sc[4 + j] - mref) : 0.f; ps += pa[j] + pb[j]; }
;     }
;     st.l += ps;
;     const u32x2 pw = pack8_fp8(pa, pb);
;     const i64_t pf = __builtin_bit_cast(i64_t, pw);
; #pragma unroll
;     for (int db = 0; db < 8; ++db) st.o[db] = __builtin_amdgcn_mfma_f32_16x16x32_fp8_fp8(cur.v[db], pf, st.o[db], 0, 0, 0);
; }
; template <bool SLC, class Desc>
; __device__ __forceinline__ void attn_run_frag8(const i64_t (&qf)[4], const unsigned char* __restrict__ KF, const unsigned char* __restrict__ VF, const Desc& desc, int n,
;                                                int lo_in, int hi, int qi, AState& st, int lane) {
;     ...
;     for (int i = 0; i < n; i += 3) {
;         const int d2 = desc(i + 2 < n ? i + 2 : n - 1);
;         F8_STEP(fa, fc, d0, d2);
;         if (i + 1 >= n) break;
;         const int d3 = desc(i + 3 < n ? i + 3 : n - 1);
;         F8_STEP(fb, fa, d1, d3);
;         if (i + 2 >= n) break;
;         const int d4 = desc(i + 4 < n ? i + 4 : n - 1);
;         F8_STEP(fc, fb, d2, d4);
;         d0 = d3; d1 = d4;
; __device__ __forceinline__ void dilated_unit(int unit, const bf16_t* proj, const bf16_t* kbf, bf16_t* nsaout, int lane) {
;     ...
;         auto desc = [&](int i) { return 32 * (first + i); };
.LBB0_757:
	v_add_f32_e32 v0, -4.0, v205
	v_sub_f32_e32 v34, v34, v0
	v_exp_f32_e32 v34, v34
	v_sub_f32_e32 v38, v38, v0
	v_exp_f32_e32 v38, v38
	v_sub_f32_e32 v36, v36, v0
	v_cndmask_b32_e64 v54, 0, v34, s[10:11]
	v_sub_f32_e32 v34, v35, v0
	v_exp_f32_e32 v34, v34
	v_sub_f32_e32 v35, v39, v0
	v_exp_f32_e32 v35, v35
	v_cndmask_b32_e64 v55, 0, v38, s[18:19]
	v_sub_f32_e32 v38, v40, v0
	v_cndmask_b32_e64 v56, 0, v34, s[6:7]
	v_sub_f32_e32 v34, v37, v0
	v_sub_f32_e32 v0, v41, v0
	v_exp_f32_e32 v36, v36
	v_exp_f32_e32 v38, v38
	v_cndmask_b32_e64 v57, 0, v35, s[14:15]
	v_exp_f32_e32 v34, v34
	v_exp_f32_e32 v0, v0
	v_mov_b32_e32 v62, v1
	v_mov_b32_e32 v63, v1
	v_cvt_pk_fp8_f32 v62, v54, v56
	v_cvt_pk_fp8_f32 v63, v55, v57
	v_cndmask_b32_e64 v58, 0, v36, s[8:9]
	v_cndmask_b32_e64 v59, 0, v38, s[16:17]
	v_cndmask_b32_e64 v64, 0, v34, s[4:5]
	v_cndmask_b32_e64 v0, 0, v0, s[12:13]
	v_cvt_pk_fp8_f32 v62, v58, v64 op_sel:[0,0,1]
	v_cvt_pk_fp8_f32 v63, v59, v0 op_sel:[0,0,1]
	v_add_f32_e32 v0, v64, v0
	v_mov_b32_e32 v207, v205
	s_waitcnt vmcnt(19)
	v_mfma_f32_16x16x32_fp8_fp8 v[34:37], v[116:117], v[62:63], v[2:5]
	s_nop 2
	v_add_f32_e32 v2, v54, v55
	v_add_f32_e32 v2, 0, v2
	v_add_f32_e32 v3, v56, v57
	v_mfma_f32_16x16x32_fp8_fp8 v[38:41], v[118:119], v[62:63], v[6:9]
	v_add_f32_e32 v2, v3, v2
	v_add_f32_e32 v3, v58, v59
	v_add_f32_e32 v2, v3, v2
	s_waitcnt vmcnt(18)
	v_mfma_f32_16x16x32_fp8_fp8 v[42:45], v[120:121], v[62:63], v[10:13]
	v_add_f32_e32 v0, v0, v2
	v_add_f32_e32 v208, v206, v0
	v_mfma_f32_16x16x32_fp8_fp8 v[46:49], v[122:123], v[62:63], v[14:17]
	s_waitcnt vmcnt(17)
	v_mfma_f32_16x16x32_fp8_fp8 v[50:53], v[124:125], v[62:63], v[18:21]
	v_mfma_f32_16x16x32_fp8_fp8 v[54:57], v[126:127], v[62:63], v[22:25]
	s_waitcnt vmcnt(16)
	v_mfma_f32_16x16x32_fp8_fp8 v[58:61], v[128:129], v[62:63], v[30:33]
	v_mfma_f32_16x16x32_fp8_fp8 v[62:65], v[130:131], v[62:63], v[26:29]
	s_nop 1
	s_cmp_gt_i32 s67, s61
	s_mov_b64 s[4:5], -1
	s_cbranch_scc1 .LBB0_737
.LBB0_758:
	s_add_i32 s66, s66, 4
	s_min_i32 s4, s66, s61
	s_add_i32 s6, s4, s60
	s_lshl_b32 s63, s6, 5
	s_and_b32 s4, s63, 0x3fffffe0
	s_lshr_b32 s24, s4, 4
	s_lshl_b64 s[4:5], s[24:25], 11
	s_and_b32 s24, s6, 0x1ffffff
	s_and_b32 s8, s42, 0x2000000
	s_lshl_b64 s[6:7], s[24:25], 12
	s_cmp_eq_u32 s8, 0
	v_lshl_add_u64 v[198:199], v[82:83], 0, s[4:5]
	v_lshl_add_u64 v[196:197], v[84:85], 0, s[6:7]
	s_mov_b64 s[4:5], -1
	v_add_f32_e32 v209, 4.0, v207
	s_cbranch_scc1 .LBB0_762
	v_lshl_add_u64 v[244:245], v[198:199], 0, v[98:99]
	global_load_dwordx4 v[148:151], v[244:245], off
	global_load_dwordx4 v[152:155], v[244:245], off offset:1024
	global_load_dwordx4 v[156:159], v[244:245], off offset:2048
	global_load_dwordx4 v[160:163], v[244:245], off offset:3072
	v_lshl_add_u64 v[246:247], v[196:197], 0, v[98:99]
	global_load_dwordx4 v[116:119], v[246:247], off
	global_load_dwordx4 v[120:123], v[246:247], off offset:1024
	global_load_dwordx4 v[124:127], v[246:247], off offset:2048
	global_load_dwordx4 v[128:131], v[246:247], off offset:3072
	s_waitcnt vmcnt(20)
	v_mfma_f32_16x16x32_fp8_fp8 v[2:5], v[180:181], v[74:75], 0
	v_mov_b64_e32 v[72:73], v[64:65]
	v_mov_b64_e32 v[68:69], v[60:61]
	v_mov_b64_e32 v[30:31], v[54:55]
	v_mfma_f32_16x16x32_fp8_fp8 v[6:9], v[188:189], v[74:75], 0
	v_mov_b64_e32 v[26:27], v[50:51]
	v_mov_b64_e32 v[22:23], v[46:47]
	v_mov_b64_e32 v[18:19], v[42:43]
	v_mfma_f32_16x16x32_fp8_fp8 v[2:5], v[182:183], v[76:77], v[2:5]
	v_mov_b64_e32 v[14:15], v[38:39]
	v_mov_b32_e32 v205, v207
	v_mov_b64_e32 v[70:71], v[62:63]
	v_mfma_f32_16x16x32_fp8_fp8 v[6:9], v[190:191], v[76:77], v[6:9]
	v_mov_b64_e32 v[66:67], v[58:59]
	v_mov_b64_e32 v[32:33], v[56:57]
	v_mov_b64_e32 v[28:29], v[52:53]
	v_mfma_f32_16x16x32_fp8_fp8 v[2:5], v[184:185], v[78:79], v[2:5]
	v_mov_b64_e32 v[24:25], v[48:49]
	v_mov_b64_e32 v[20:21], v[44:45]
	v_mov_b64_e32 v[16:17], v[40:41]
	v_mfma_f32_16x16x32_fp8_fp8 v[6:9], v[192:193], v[78:79], v[6:9]
	v_mov_b32_e32 v206, v208
	v_mfma_f32_16x16x32_fp8_fp8 v[2:5], v[186:187], v[80:81], v[2:5]
	v_mfma_f32_16x16x32_fp8_fp8 v[6:9], v[194:195], v[80:81], v[6:9]
	s_nop 6
	v_max_f32_e32 v0, v3, v3
	v_max_f32_e32 v10, v2, v2
	v_max_f32_e32 v0, v10, v0
	v_max_f32_e32 v10, v5, v5
	v_max_f32_e32 v11, v4, v4
	v_max_f32_e32 v10, v11, v10
	v_max_f32_e32 v11, v9, v9
	v_max_f32_e32 v12, v8, v8
	v_max_f32_e32 v11, v12, v11
	v_max3_f32 v11, v6, v7, v11
	v_max3_f32 v0, v0, v10, v11
	v_mov_b64_e32 v[10:11], v[34:35]
	v_cmp_gt_f32_e32 vcc, v0, v209
	v_mov_b64_e32 v[12:13], v[36:37]
	s_cbranch_vccz .LBB0_761
	v_and_b32_e32 v11, 64, v200
	v_xor_b32_e32 v10, 16, v200
	v_add_u32_e32 v11, 64, v11
	v_cmp_lt_i32_e32 vcc, v10, v11
	v_xor_b32_e32 v12, 32, v200
	s_nop 0
	v_cndmask_b32_e32 v10, v200, v10, vcc
	v_lshlrev_b32_e32 v10, 2, v10
	ds_bpermute_b32 v10, v10, v0
	v_max_f32_e32 v0, v0, v0
	v_cmp_lt_i32_e32 vcc, v12, v11
	s_waitcnt lgkmcnt(0)
	v_max_f32_e32 v10, v10, v10
	v_max_f32_e32 v0, v0, v10
	v_cndmask_b32_e32 v10, v200, v12, vcc
	v_lshlrev_b32_e32 v10, 2, v10
	ds_bpermute_b32 v10, v10, v0
	s_waitcnt lgkmcnt(0)
	v_max3_f32 v205, v207, v0, v10
	v_sub_f32_e32 v0, v207, v205
	v_exp_f32_e32 v0, v0
	s_nop 0
	v_mul_f32_e32 v206, v208, v0
	v_pk_mul_f32 v[12:13], v[36:37], v[0:1] op_sel_hi:[1,0]
	v_pk_mul_f32 v[10:11], v[34:35], v[0:1] op_sel_hi:[1,0]
	v_pk_mul_f32 v[16:17], v[40:41], v[0:1] op_sel_hi:[1,0]
	v_pk_mul_f32 v[14:15], v[38:39], v[0:1] op_sel_hi:[1,0]
	v_pk_mul_f32 v[20:21], v[44:45], v[0:1] op_sel_hi:[1,0]
	v_pk_mul_f32 v[18:19], v[42:43], v[0:1] op_sel_hi:[1,0]
	v_pk_mul_f32 v[24:25], v[48:49], v[0:1] op_sel_hi:[1,0]
	v_pk_mul_f32 v[22:23], v[46:47], v[0:1] op_sel_hi:[1,0]
	v_pk_mul_f32 v[28:29], v[52:53], v[0:1] op_sel_hi:[1,0]
	v_pk_mul_f32 v[26:27], v[50:51], v[0:1] op_sel_hi:[1,0]
	v_pk_mul_f32 v[32:33], v[56:57], v[0:1] op_sel_hi:[1,0]
	v_pk_mul_f32 v[30:31], v[54:55], v[0:1] op_sel_hi:[1,0]
	v_pk_mul_f32 v[68:69], v[60:61], v[0:1] op_sel_hi:[1,0]
	v_pk_mul_f32 v[66:67], v[58:59], v[0:1] op_sel_hi:[1,0]
	v_pk_mul_f32 v[72:73], v[64:65], v[0:1] op_sel_hi:[1,0]
	v_pk_mul_f32 v[70:71], v[62:63], v[0:1] op_sel_hi:[1,0]
; template <bool SLC, bool NOMASK> ...
;     const int kq = lane >> 4;
;     const int pos0 = SLC ? (dcur & 0xfffff) : dcur;
;     const int lo = SLC ? ((((dcur >> 20) == qi) | ((dcur >> 20) == 4)) ? 0 : (1 << 30)) : lo_in;
;     load_frag8(nxt, KF, VF, SLC ? (dnext & 0xfffff) : dnext, lane);
;     f32x4 sa[2] = {(f32x4){0.f, 0.f, 0.f, 0.f}, (f32x4){0.f, 0.f, 0.f, 0.f}};
; #pragma unroll
;     for (int T = 0; T < 2; ++T)
; #pragma unroll
;         for (int s2 = 0; s2 < 4; ++s2) sa[T] = __builtin_amdgcn_mfma_f32_16x16x32_fp8_fp8(cur.k[T][s2], qf[s2], sa[T], 0, 0, 0);
;     float sc[8]; bool vd[8]; float mx = -1e30f;
;     const bool act = lo == 0 || !SLC;
;     if (NOMASK) {
; #pragma unroll
;         for (int j = 0; j < 8; ++j) { sc[j] = sa[j >> 2][j & 3]; vd[j] = act; }
;         mx = fmaxf(fmaxf(fmaxf(sc[0], sc[1]), fmaxf(sc[2], sc[3])), fmaxf(fmaxf(sc[4], sc[5]), fmaxf(sc[6], sc[7])));
;         mx = act ? mx : -1e30f;
;     } else {
; #pragma unroll
;         for (int T = 0; T < 2; ++T)
; #pragma unroll
;             for (int r = 0; r < 4; ++r) { const int p = pos0 + 16 * T + 4 * kq + r; const bool v = (p >= lo) & (p <= hi); const float x = sa[T][r];
;                 sc[4 * T + r] = x; vd[4 * T + r] = v; mx = v ? fmaxf(mx, x) : mx; }
;     }
;     if (__builtin_amdgcn_ballot_w64(mx > st.m + 4.f) != 0ull) {
;         mx = fmaxf(mx, __shfl_xor(mx, 16)); mx = fmaxf(mx, __shfl_xor(mx, 32));
;         const float mn = fmaxf(st.m, mx), alpha = __builtin_amdgcn_exp2f(st.m - mn); st.m = mn; st.l *= alpha;
; #pragma unroll
;         for (int j = 0; j < 8; ++j) st.o[j] = st.o[j] * alpha;
;     }
;     f32x4 pa, pb; float ps = 0.f;
;     const float mref = st.m - 4.f;
;     if (NOMASK) {
; #pragma unroll
;         for (int j = 0; j < 4; ++j) { pa[j] = __builtin_amdgcn_exp2f(sc[j] - mref); pb[j] = __builtin_amdgcn_exp2f(sc[4 + j] - mref); }
;         if (SLC) {
; #pragma unroll
;             for (int j = 0; j < 4; ++j) { pa[j] = act ? pa[j] : 0.f; pb[j] = act ? pb[j] : 0.f; }
;         }
; #pragma unroll
;         for (int j = 0; j < 4; ++j) ps += pa[j] + pb[j];
;     } else {
; #pragma unroll
;         for (int j = 0; j < 4; ++j) { pa[j] = vd[j] ? __builtin_amdgcn_exp2f(sc[j] - mref) : 0.f; pb[j] = vd[4 + j] ? __builtin_amdgcn_exp2f(sc[4 + j] - mref) : 0.f; ps += pa[j] + pb[j]; }
;     }
;     st.l += ps;
;     const u32x2 pw = pack8_fp8(pa, pb);
.LBB0_761:
	v_add_f32_e32 v211, -4.0, v205
	v_sub_f32_e32 v0, v2, v211
	v_exp_f32_e32 v213, v0
	v_sub_f32_e32 v0, v6, v211
	v_exp_f32_e32 v215, v0
	v_sub_f32_e32 v0, v3, v211
	v_exp_f32_e32 v210, v0
	v_sub_f32_e32 v0, v7, v211
	v_exp_f32_e32 v0, v0
	v_sub_f32_e32 v2, v4, v211
	v_exp_f32_e32 v218, v2
	v_sub_f32_e32 v2, v8, v211
	v_exp_f32_e32 v219, v2
	v_sub_f32_e32 v2, v5, v211
	v_exp_f32_e32 v212, v2
	v_sub_f32_e32 v2, v9, v211
	v_mov_b32_e32 v216, v1
	v_mov_b32_e32 v217, v1
	v_exp_f32_e32 v214, v2
	v_cvt_pk_fp8_f32 v216, v213, v210
	v_cvt_pk_fp8_f32 v217, v215, v0
	v_add_f32_e32 v211, v213, v215
	v_add_f32_e32 v213, v218, v219
	v_cvt_pk_fp8_f32 v216, v218, v212 op_sel:[0,0,1]
	v_cvt_pk_fp8_f32 v217, v219, v214 op_sel:[0,0,1]
	s_mov_b64 s[4:5], 0
	s_waitcnt vmcnt(19)
	v_mfma_f32_16x16x32_fp8_fp8 v[2:5], v[164:165], v[216:217], v[10:13]
	v_mfma_f32_16x16x32_fp8_fp8 v[10:13], v[168:169], v[216:217], v[18:21]
	s_waitcnt vmcnt(18)
	v_mfma_f32_16x16x32_fp8_fp8 v[18:21], v[172:173], v[216:217], v[26:29]
	s_nop 2
	v_add_f32_e64 v26, v210, v0
	v_add_f32_e64 v27, v211, v1
	v_mfma_f32_16x16x32_fp8_fp8 v[6:9], v[166:167], v[216:217], v[14:17]
	v_pk_add_f32 v[26:27], v[26:27], v[26:27] op_sel_hi:[0,1]
	v_mov_b32_e32 v215, v27
	v_pk_add_f32 v[26:27], v[212:213], v[214:215]
	s_waitcnt vmcnt(17)
	v_mfma_f32_16x16x32_fp8_fp8 v[14:17], v[170:171], v[216:217], v[22:25]
	v_add_f32_e32 v0, v26, v27
	v_add_f32_e32 v206, v0, v206
	v_mfma_f32_16x16x32_fp8_fp8 v[22:25], v[174:175], v[216:217], v[30:33]
	s_waitcnt vmcnt(16)
	v_mfma_f32_16x16x32_fp8_fp8 v[30:33], v[176:177], v[216:217], v[66:69]
	v_mfma_f32_16x16x32_fp8_fp8 v[26:29], v[178:179], v[216:217], v[70:73]
	s_nop 1
.LBB0_762:
	s_and_b64 vcc, exec, s[4:5]
	s_cbranch_vccz .LBB0_766
	v_lshl_add_u64 v[244:245], v[198:199], 0, v[98:99]
	global_load_dwordx4 v[148:151], v[244:245], off
	global_load_dwordx4 v[152:155], v[244:245], off offset:1024
	global_load_dwordx4 v[156:159], v[244:245], off offset:2048
	global_load_dwordx4 v[160:163], v[244:245], off offset:3072
	v_lshl_add_u64 v[246:247], v[196:197], 0, v[98:99]
	global_load_dwordx4 v[116:119], v[246:247], off
	global_load_dwordx4 v[120:123], v[246:247], off offset:1024
	global_load_dwordx4 v[124:127], v[246:247], off offset:2048
	global_load_dwordx4 v[128:131], v[246:247], off offset:3072
	s_waitcnt vmcnt(20)
	v_mfma_f32_16x16x32_fp8_fp8 v[2:5], v[180:181], v[74:75], 0
	v_or_b32_e32 v0, s68, v107
	v_cmp_ge_i32_e32 vcc, v0, v105
	v_cmp_le_i32_e64 s[4:5], v0, v204
	v_mfma_f32_16x16x32_fp8_fp8 v[2:5], v[182:183], v[76:77], v[2:5]
	s_and_b64 s[10:11], vcc, s[4:5]
	v_or_b32_e32 v11, 1, v0
	v_cmp_ge_i32_e32 vcc, v11, v105
	v_mfma_f32_16x16x32_fp8_fp8 v[2:5], v[184:185], v[78:79], v[2:5]
	v_cmp_lt_i32_e64 s[4:5], v0, v204
	s_and_b64 s[6:7], s[4:5], vcc
	v_mfma_f32_16x16x32_fp8_fp8 v[6:9], v[188:189], v[74:75], 0
	v_mfma_f32_16x16x32_fp8_fp8 v[2:5], v[186:187], v[80:81], v[2:5]
	v_mfma_f32_16x16x32_fp8_fp8 v[6:9], v[190:191], v[76:77], v[6:9]
	v_mfma_f32_16x16x32_fp8_fp8 v[6:9], v[192:193], v[78:79], v[6:9]
	s_nop 5
	v_max_f32_e32 v10, v2, v2
	v_max_f32_e32 v10, 0xf149f2ca, v10
	v_cndmask_b32_e64 v10, v203, v10, s[10:11]
	v_max_f32_e32 v11, v3, v3
	v_max_f32_e32 v11, v10, v11
	v_cndmask_b32_e64 v10, v10, v11, s[6:7]
	v_or_b32_e32 v11, 2, v0
	v_cmp_ge_i32_e32 vcc, v11, v105
	v_cmp_le_i32_e64 s[4:5], v11, v204
	v_max_f32_e32 v11, v4, v4
	v_max_f32_e32 v11, v10, v11
	s_and_b64 s[8:9], vcc, s[4:5]
	v_mfma_f32_16x16x32_fp8_fp8 v[6:9], v[194:195], v[80:81], v[6:9]
	v_cndmask_b32_e64 v10, v10, v11, s[8:9]
	v_or_b32_e32 v11, 3, v0
	v_cmp_ge_i32_e32 vcc, v11, v105
	v_cmp_le_i32_e64 s[4:5], v11, v204
	v_max_f32_e32 v11, v5, v5
	v_max_f32_e32 v11, v10, v11
	s_and_b64 s[4:5], vcc, s[4:5]
	v_cndmask_b32_e64 v10, v10, v11, s[4:5]
	v_or_b32_e32 v11, 16, v0
	v_cmp_ge_i32_e32 vcc, v11, v105
	v_cmp_le_i32_e64 s[12:13], v11, v204
	v_max_f32_e32 v11, v6, v6
	v_max_f32_e32 v11, v10, v11
	s_and_b64 s[18:19], vcc, s[12:13]
	v_cndmask_b32_e64 v10, v10, v11, s[18:19]
	v_or_b32_e32 v11, 17, v0
	v_cmp_ge_i32_e32 vcc, v11, v105
	v_cmp_le_i32_e64 s[12:13], v11, v204
	v_max_f32_e32 v11, v10, v10
	v_max_f32_e32 v12, v7, v7
	v_max_f32_e32 v11, v11, v12
	s_and_b64 s[14:15], vcc, s[12:13]
	v_cndmask_b32_e64 v10, v10, v11, s[14:15]
	v_or_b32_e32 v11, 18, v0
	v_cmp_ge_i32_e32 vcc, v11, v105
	v_cmp_le_i32_e64 s[12:13], v11, v204
	v_max_f32_e32 v11, v10, v10
	v_max_f32_e32 v12, v8, v8
	v_max_f32_e32 v11, v11, v12
	s_and_b64 s[16:17], vcc, s[12:13]
	v_cndmask_b32_e64 v10, v10, v11, s[16:17]
	v_or_b32_e32 v0, 19, v0
	v_cmp_ge_i32_e32 vcc, v0, v105
	v_cmp_le_i32_e64 s[12:13], v0, v204
	v_max_f32_e32 v0, v10, v10
	v_max_f32_e32 v11, v9, v9
	v_max_f32_e32 v0, v0, v11
	s_and_b64 s[12:13], vcc, s[12:13]
	v_cndmask_b32_e64 v0, v10, v0, s[12:13]
	v_cmp_gt_f32_e32 vcc, v0, v209
	s_cbranch_vccz .LBB0_765
	v_and_b32_e32 v11, 64, v200
	v_xor_b32_e32 v10, 16, v200
	v_add_u32_e32 v11, 64, v11
	v_cmp_lt_i32_e32 vcc, v10, v11
	v_xor_b32_e32 v12, 32, v200
	s_nop 0
	v_cndmask_b32_e32 v10, v200, v10, vcc
	v_lshlrev_b32_e32 v10, 2, v10
	ds_bpermute_b32 v10, v10, v0
	v_max_f32_e32 v0, v0, v0
	v_cmp_lt_i32_e32 vcc, v12, v11
	s_waitcnt lgkmcnt(0)
	v_max_f32_e32 v10, v10, v10
	v_max_f32_e32 v0, v0, v10
	v_cndmask_b32_e32 v10, v200, v12, vcc
	v_lshlrev_b32_e32 v10, 2, v10
	ds_bpermute_b32 v10, v10, v0
	s_waitcnt lgkmcnt(0)
	v_max3_f32 v10, v207, v0, v10
	v_sub_f32_e32 v0, v207, v10
	v_exp_f32_e32 v0, v0
	v_mov_b32_e32 v207, v10
	v_mul_f32_e32 v208, v208, v0
	v_pk_mul_f32 v[36:37], v[36:37], v[0:1] op_sel_hi:[1,0]
	v_pk_mul_f32 v[34:35], v[34:35], v[0:1] op_sel_hi:[1,0]
	v_pk_mul_f32 v[40:41], v[40:41], v[0:1] op_sel_hi:[1,0]
	v_pk_mul_f32 v[38:39], v[38:39], v[0:1] op_sel_hi:[1,0]
	v_pk_mul_f32 v[44:45], v[44:45], v[0:1] op_sel_hi:[1,0]
	v_pk_mul_f32 v[42:43], v[42:43], v[0:1] op_sel_hi:[1,0]
	v_pk_mul_f32 v[48:49], v[48:49], v[0:1] op_sel_hi:[1,0]
	v_pk_mul_f32 v[46:47], v[46:47], v[0:1] op_sel_hi:[1,0]
	v_pk_mul_f32 v[52:53], v[52:53], v[0:1] op_sel_hi:[1,0]
	v_pk_mul_f32 v[50:51], v[50:51], v[0:1] op_sel_hi:[1,0]
	v_pk_mul_f32 v[56:57], v[56:57], v[0:1] op_sel_hi:[1,0]
	v_pk_mul_f32 v[54:55], v[54:55], v[0:1] op_sel_hi:[1,0]
	v_pk_mul_f32 v[60:61], v[60:61], v[0:1] op_sel_hi:[1,0]
	v_pk_mul_f32 v[58:59], v[58:59], v[0:1] op_sel_hi:[1,0]
	v_pk_mul_f32 v[64:65], v[64:65], v[0:1] op_sel_hi:[1,0]
	v_pk_mul_f32 v[62:63], v[62:63], v[0:1] op_sel_hi:[1,0]
; template <bool SLC, bool NOMASK> ...
;     ...
;     } else {
; #pragma unroll
;         for (int j = 0; j < 4; ++j) { pa[j] = vd[j] ? __builtin_amdgcn_exp2f(sc[j] - mref) : 0.f; pb[j] = vd[4 + j] ? __builtin_amdgcn_exp2f(sc[4 + j] - mref) : 0.f; ps += pa[j] + pb[j]; }
;     }
;     st.l += ps;
;     const u32x2 pw = pack8_fp8(pa, pb);
;     const i64_t pf = __builtin_bit_cast(i64_t, pw);
; #pragma unroll
;     for (int db = 0; db < 8; ++db) st.o[db] = __builtin_amdgcn_mfma_f32_16x16x32_fp8_fp8(cur.v[db], pf, st.o[db], 0, 0, 0);
.LBB0_765:
	v_add_f32_e32 v0, -4.0, v207
	v_sub_f32_e32 v2, v2, v0
	v_exp_f32_e32 v2, v2
	v_sub_f32_e32 v6, v6, v0
	v_exp_f32_e32 v6, v6
	v_sub_f32_e32 v4, v4, v0
	v_cndmask_b32_e64 v22, 0, v2, s[10:11]
	v_sub_f32_e32 v2, v3, v0
	v_exp_f32_e32 v2, v2
	v_sub_f32_e32 v3, v7, v0
	v_exp_f32_e32 v3, v3
	v_cndmask_b32_e64 v23, 0, v6, s[18:19]
	v_sub_f32_e32 v6, v8, v0
	v_cndmask_b32_e64 v24, 0, v2, s[6:7]
	v_sub_f32_e32 v2, v5, v0
	v_sub_f32_e32 v0, v9, v0
	v_exp_f32_e32 v4, v4
	v_exp_f32_e32 v6, v6
	v_cndmask_b32_e64 v25, 0, v3, s[14:15]
	v_exp_f32_e32 v2, v2
	v_exp_f32_e32 v0, v0
	v_mov_b32_e32 v26, v1
	v_mov_b32_e32 v27, v1
	v_cvt_pk_fp8_f32 v26, v22, v24
	v_cvt_pk_fp8_f32 v27, v23, v25
	v_cndmask_b32_e64 v28, 0, v4, s[8:9]
	v_cndmask_b32_e64 v29, 0, v6, s[16:17]
	v_cndmask_b32_e64 v66, 0, v2, s[4:5]
	v_cndmask_b32_e64 v0, 0, v0, s[12:13]
	v_cvt_pk_fp8_f32 v26, v28, v66 op_sel:[0,0,1]
	v_cvt_pk_fp8_f32 v27, v29, v0 op_sel:[0,0,1]
	v_add_f32_e32 v22, v22, v23
	v_add_f32_e32 v30, 0, v22
	v_add_f32_e32 v31, v24, v25
	v_add_f32_e32 v30, v31, v30
	v_add_f32_e32 v28, v28, v29
	v_add_f32_e32 v28, v28, v30
	v_add_f32_e32 v0, v66, v0
	s_waitcnt vmcnt(19)
	v_mfma_f32_16x16x32_fp8_fp8 v[2:5], v[164:165], v[26:27], v[34:37]
	v_add_f32_e32 v0, v0, v28
	v_add_f32_e32 v206, v208, v0
	v_mov_b32_e32 v205, v207
	v_mfma_f32_16x16x32_fp8_fp8 v[6:9], v[166:167], v[26:27], v[38:41]
	s_waitcnt vmcnt(18)
	v_mfma_f32_16x16x32_fp8_fp8 v[10:13], v[168:169], v[26:27], v[42:45]
	v_mfma_f32_16x16x32_fp8_fp8 v[14:17], v[170:171], v[26:27], v[46:49]
	s_waitcnt vmcnt(17)
	v_mfma_f32_16x16x32_fp8_fp8 v[18:21], v[172:173], v[26:27], v[50:53]
	v_mfma_f32_16x16x32_fp8_fp8 v[22:25], v[174:175], v[26:27], v[54:57]
	s_waitcnt vmcnt(16)
	v_mfma_f32_16x16x32_fp8_fp8 v[30:33], v[176:177], v[26:27], v[58:61]
	v_mfma_f32_16x16x32_fp8_fp8 v[26:29], v[178:179], v[26:27], v[62:65]
	s_nop 1

; template <bool SLC, bool NOMASK> ...
;     const int kq = lane >> 4;
;     const int pos0 = SLC ? (dcur & 0xfffff) : dcur;
;     const int lo = SLC ? ((((dcur >> 20) == qi) | ((dcur >> 20) == 4)) ? 0 : (1 << 30)) : lo_in;
;     load_frag8(nxt, KF, VF, SLC ? (dnext & 0xfffff) : dnext, lane);
;     f32x4 sa[2] = {(f32x4){0.f, 0.f, 0.f, 0.f}, (f32x4){0.f, 0.f, 0.f, 0.f}};
; #pragma unroll
;     for (int T = 0; T < 2; ++T)
; #pragma unroll
;         for (int s2 = 0; s2 < 4; ++s2) sa[T] = __builtin_amdgcn_mfma_f32_16x16x32_fp8_fp8(cur.k[T][s2], qf[s2], sa[T], 0, 0, 0);
;     float sc[8]; bool vd[8]; float mx = -1e30f;
;     const bool act = lo == 0 || !SLC;
;     if (NOMASK) {
; #pragma unroll
;         for (int j = 0; j < 8; ++j) { sc[j] = sa[j >> 2][j & 3]; vd[j] = act; }
;         mx = fmaxf(fmaxf(fmaxf(sc[0], sc[1]), fmaxf(sc[2], sc[3])), fmaxf(fmaxf(sc[4], sc[5]), fmaxf(sc[6], sc[7])));
;         mx = act ? mx : -1e30f;
;     } else {
; #pragma unroll
;         for (int T = 0; T < 2; ++T)
; #pragma unroll
;             for (int r = 0; r < 4; ++r) { const int p = pos0 + 16 * T + 4 * kq + r; const bool v = (p >= lo) & (p <= hi); const float x = sa[T][r];
;                 sc[4 * T + r] = x; vd[4 * T + r] = v; mx = v ? fmaxf(mx, x) : mx; }
;     }
;     if (__builtin_amdgcn_ballot_w64(mx > st.m + 4.f) != 0ull) {
;         mx = fmaxf(mx, __shfl_xor(mx, 16)); mx = fmaxf(mx, __shfl_xor(mx, 32));
;         const float mn = fmaxf(st.m, mx), alpha = __builtin_amdgcn_exp2f(st.m - mn); st.m = mn; st.l *= alpha;
; #pragma unroll
;         for (int j = 0; j < 8; ++j) st.o[j] = st.o[j] * alpha;
;     }
;     f32x4 pa, pb; float ps = 0.f;
;     const float mref = st.m - 4.f;
;     if (NOMASK) {
; #pragma unroll
;         for (int j = 0; j < 4; ++j) { pa[j] = __builtin_amdgcn_exp2f(sc[j] - mref); pb[j] = __builtin_amdgcn_exp2f(sc[4 + j] - mref); }
;         if (SLC) {
; #pragma unroll
;             for (int j = 0; j < 4; ++j) { pa[j] = act ? pa[j] : 0.f; pb[j] = act ? pb[j] : 0.f; }
;         }
; #pragma unroll
;         for (int j = 0; j < 4; ++j) ps += pa[j] + pb[j];
;     } else {
; #pragma unroll
;         for (int j = 0; j < 4; ++j) { pa[j] = vd[j] ? __builtin_amdgcn_exp2f(sc[j] - mref) : 0.f; pb[j] = vd[4 + j] ? __builtin_amdgcn_exp2f(sc[4 + j] - mref) : 0.f; ps += pa[j] + pb[j]; }
;     }
;     st.l += ps;
;     const u32x2 pw = pack8_fp8(pa, pb);
.LBB0_867:
	s_and_b32 s13, s12, 0xfffffbff
	s_cmp_eq_u32 s13, 4
	s_cselect_b64 s[10:11], -1, 0
	s_lshl_b32 s14, s66, 7
	s_and_b32 s50, s14, 0x7fff800
	v_lshl_add_u64 v[10:11], v[86:87], 0, s[50:51]
	s_and_b32 s50, s14, 0x7fff000
	v_lshl_add_u64 v[244:245], v[10:11], 0, v[118:119]
	global_load_dwordx4 v[186:189], v[244:245], off
	global_load_dwordx4 v[190:193], v[244:245], off offset:1024
	global_load_dwordx4 v[194:197], v[244:245], off offset:2048
	global_load_dwordx4 v[198:201], v[244:245], off offset:3072
	v_lshl_add_u64 v[10:11], v[88:89], 0, s[50:51]
	v_lshl_add_u64 v[246:247], v[10:11], 0, v[118:119]
	global_load_dwordx4 v[170:173], v[246:247], off
	global_load_dwordx4 v[174:177], v[246:247], off offset:1024
	global_load_dwordx4 v[178:181], v[246:247], off offset:2048
	global_load_dwordx4 v[182:185], v[246:247], off offset:3072
	s_waitcnt vmcnt(20)
	v_mfma_f32_16x16x32_fp8_fp8 v[2:5], v[138:139], v[78:79], 0
	v_cmp_eq_u32_e32 vcc, s13, v209
	s_or_b64 s[10:11], s[10:11], vcc
	v_mov_b64_e32 v[74:75], v[38:39]
	v_mfma_f32_16x16x32_fp8_fp8 v[6:9], v[146:147], v[78:79], 0
	v_mov_b64_e32 v[70:71], v[42:43]
	v_mov_b64_e32 v[30:31], v[44:45]
	v_mov_b64_e32 v[26:27], v[48:49]
	v_mfma_f32_16x16x32_fp8_fp8 v[2:5], v[140:141], v[80:81], v[2:5]
	v_mov_b64_e32 v[22:23], v[52:53]
	v_mov_b64_e32 v[18:19], v[56:57]
	v_mov_b64_e32 v[14:15], v[60:61]
	v_mfma_f32_16x16x32_fp8_fp8 v[6:9], v[148:149], v[80:81], v[6:9]
	v_mov_b64_e32 v[72:73], v[36:37]
	v_mov_b64_e32 v[68:69], v[40:41]
	v_mov_b64_e32 v[32:33], v[46:47]
	v_mfma_f32_16x16x32_fp8_fp8 v[2:5], v[142:143], v[82:83], v[2:5]
	v_mov_b64_e32 v[28:29], v[50:51]
	v_mov_b64_e32 v[24:25], v[54:55]
	v_mov_b64_e32 v[20:21], v[58:59]
	v_mfma_f32_16x16x32_fp8_fp8 v[6:9], v[150:151], v[82:83], v[6:9]
	v_mov_b64_e32 v[16:17], v[62:63]
	v_mov_b32_e32 v133, v203
	v_mfma_f32_16x16x32_fp8_fp8 v[2:5], v[144:145], v[84:85], v[2:5]
	v_mfma_f32_16x16x32_fp8_fp8 v[6:9], v[152:153], v[84:85], v[6:9]
	s_nop 6
	v_max_f32_e32 v0, v3, v3
	v_max_f32_e32 v10, v2, v2
	v_max_f32_e32 v0, v10, v0
	v_max_f32_e32 v10, v5, v5
	v_max_f32_e32 v11, v4, v4
	v_max_f32_e32 v10, v11, v10
	v_max_f32_e32 v11, v9, v9
	v_max_f32_e32 v12, v8, v8
	v_max_f32_e32 v11, v12, v11
	v_max3_f32 v11, v6, v7, v11
	v_max3_f32 v0, v0, v10, v11
	v_cndmask_b32_e64 v34, v223, v0, s[10:11]
	v_mov_b64_e32 v[10:11], v[64:65]
	v_cmp_gt_f32_e32 vcc, v34, v204
	v_mov_b32_e32 v0, v202
	v_mov_b64_e32 v[12:13], v[66:67]
	s_cbranch_vccz .LBB0_869
	ds_bpermute_b32 v0, v227, v34
	v_max_f32_e32 v10, v34, v34
	s_waitcnt lgkmcnt(0)
	v_max_f32_e32 v0, v0, v0
	v_max_f32_e32 v0, v10, v0
	ds_bpermute_b32 v10, v226, v0
	s_waitcnt lgkmcnt(0)
	v_max3_f32 v0, v202, v0, v10
	v_sub_f32_e32 v10, v202, v0
	v_exp_f32_e32 v34, v10
	s_nop 0
	v_mul_f32_e32 v133, v203, v34
	v_pk_mul_f32 v[12:13], v[66:67], v[34:35] op_sel_hi:[1,0]
	v_pk_mul_f32 v[10:11], v[64:65], v[34:35] op_sel_hi:[1,0]
	v_pk_mul_f32 v[16:17], v[62:63], v[34:35] op_sel_hi:[1,0]
	v_pk_mul_f32 v[14:15], v[60:61], v[34:35] op_sel_hi:[1,0]
	v_pk_mul_f32 v[20:21], v[58:59], v[34:35] op_sel_hi:[1,0]
	v_pk_mul_f32 v[18:19], v[56:57], v[34:35] op_sel_hi:[1,0]
	v_pk_mul_f32 v[24:25], v[54:55], v[34:35] op_sel_hi:[1,0]
	v_pk_mul_f32 v[22:23], v[52:53], v[34:35] op_sel_hi:[1,0]
	v_pk_mul_f32 v[28:29], v[50:51], v[34:35] op_sel_hi:[1,0]
	v_pk_mul_f32 v[26:27], v[48:49], v[34:35] op_sel_hi:[1,0]
	v_pk_mul_f32 v[32:33], v[46:47], v[34:35] op_sel_hi:[1,0]
	v_pk_mul_f32 v[30:31], v[44:45], v[34:35] op_sel_hi:[1,0]
	v_pk_mul_f32 v[70:71], v[42:43], v[34:35] op_sel_hi:[1,0]
	v_pk_mul_f32 v[68:69], v[40:41], v[34:35] op_sel_hi:[1,0]
	v_pk_mul_f32 v[74:75], v[38:39], v[34:35] op_sel_hi:[1,0]
	v_pk_mul_f32 v[72:73], v[36:37], v[34:35] op_sel_hi:[1,0]
.LBB0_869:
	v_add_f32_e32 v34, -4.0, v0
	v_sub_f32_e32 v2, v2, v34
	v_sub_f32_e32 v6, v6, v34
	v_sub_f32_e32 v3, v3, v34
	v_sub_f32_e32 v7, v7, v34
	v_exp_f32_e32 v2, v2
	v_exp_f32_e32 v6, v6
	v_exp_f32_e32 v3, v3
	v_exp_f32_e32 v7, v7
	v_sub_f32_e32 v4, v4, v34
	v_sub_f32_e32 v8, v8, v34
	v_sub_f32_e32 v5, v5, v34
	v_sub_f32_e32 v9, v9, v34
	v_exp_f32_e32 v4, v4
	v_exp_f32_e32 v8, v8
	v_exp_f32_e32 v5, v5
	v_exp_f32_e32 v9, v9
	v_cndmask_b32_e64 v34, 0, v2, s[10:11]
	v_cndmask_b32_e64 v6, 0, v6, s[10:11]
	v_cndmask_b32_e64 v35, 0, v3, s[10:11]
	v_cndmask_b32_e64 v7, 0, v7, s[10:11]
	v_mov_b32_e32 v2, v1
	v_mov_b32_e32 v3, v1
	v_cvt_pk_fp8_f32 v2, v34, v35
	v_cvt_pk_fp8_f32 v3, v6, v7
	v_cndmask_b32_e64 v4, 0, v4, s[10:11]
	v_cndmask_b32_e64 v205, 0, v8, s[10:11]
	v_cndmask_b32_e64 v5, 0, v5, s[10:11]
	v_cndmask_b32_e64 v229, 0, v9, s[10:11]
	v_add_f32_e32 v6, v34, v6
	v_cvt_pk_fp8_f32 v2, v4, v5 op_sel:[0,0,1]
	v_cvt_pk_fp8_f32 v3, v205, v229 op_sel:[0,0,1]
	v_add_f32_e32 v6, 0, v6
	v_add_f32_e32 v7, v35, v7
	v_add_f32_e32 v6, v7, v6
	v_add_f32_e32 v4, v4, v205
	v_add_f32_e32 v4, v4, v6
	v_add_f32_e32 v5, v5, v229
	v_add_f32_e32 v4, v5, v4
	s_waitcnt vmcnt(19)
	v_mfma_f32_16x16x32_fp8_fp8 v[8:11], v[90:91], v[2:3], v[10:13]
	v_add_f32_e32 v133, v133, v4
	v_mfma_f32_16x16x32_fp8_fp8 v[12:15], v[92:93], v[2:3], v[14:17]
	s_waitcnt vmcnt(18)
	v_mfma_f32_16x16x32_fp8_fp8 v[16:19], v[94:95], v[2:3], v[18:21]
	v_mfma_f32_16x16x32_fp8_fp8 v[20:23], v[96:97], v[2:3], v[22:25]
	s_waitcnt vmcnt(17)
	v_mfma_f32_16x16x32_fp8_fp8 v[24:27], v[98:99], v[2:3], v[26:29]
	v_mfma_f32_16x16x32_fp8_fp8 v[32:35], v[100:101], v[2:3], v[30:33]
	s_waitcnt vmcnt(16)
	v_mfma_f32_16x16x32_fp8_fp8 v[28:31], v[102:103], v[2:3], v[68:71]
	v_mfma_f32_16x16x32_fp8_fp8 v[4:7], v[104:105], v[2:3], v[72:75]
	s_nop 1
	s_branch .LBB0_863
; template <bool SLC, bool NOMASK> ...
;     const int kq = lane >> 4;
;     const int pos0 = SLC ? (dcur & 0xfffff) : dcur;
;     const int lo = SLC ? ((((dcur >> 20) == qi) | ((dcur >> 20) == 4)) ? 0 : (1 << 30)) : lo_in;
;     load_frag8(nxt, KF, VF, SLC ? (dnext & 0xfffff) : dnext, lane);
;     f32x4 sa[2] = {(f32x4){0.f, 0.f, 0.f, 0.f}, (f32x4){0.f, 0.f, 0.f, 0.f}};
; #pragma unroll
;     for (int T = 0; T < 2; ++T)
; #pragma unroll
;         for (int s2 = 0; s2 < 4; ++s2) sa[T] = __builtin_amdgcn_mfma_f32_16x16x32_fp8_fp8(cur.k[T][s2], qf[s2], sa[T], 0, 0, 0);
;     float sc[8]; bool vd[8]; float mx = -1e30f;
;     const bool act = lo == 0 || !SLC;
;     if (NOMASK) {
; #pragma unroll
;         for (int j = 0; j < 8; ++j) { sc[j] = sa[j >> 2][j & 3]; vd[j] = act; }
;         mx = fmaxf(fmaxf(fmaxf(sc[0], sc[1]), fmaxf(sc[2], sc[3])), fmaxf(fmaxf(sc[4], sc[5]), fmaxf(sc[6], sc[7])));
;         mx = act ? mx : -1e30f;
;     } else {
; #pragma unroll
;         for (int T = 0; T < 2; ++T)
; #pragma unroll
;             for (int r = 0; r < 4; ++r) { const int p = pos0 + 16 * T + 4 * kq + r; const bool v = (p >= lo) & (p <= hi); const float x = sa[T][r];
;                 sc[4 * T + r] = x; vd[4 * T + r] = v; mx = v ? fmaxf(mx, x) : mx; }
;     }
;     if (__builtin_amdgcn_ballot_w64(mx > st.m + 4.f) != 0ull) {
;         mx = fmaxf(mx, __shfl_xor(mx, 16)); mx = fmaxf(mx, __shfl_xor(mx, 32));
;         const float mn = fmaxf(st.m, mx), alpha = __builtin_amdgcn_exp2f(st.m - mn); st.m = mn; st.l *= alpha;
; #pragma unroll
;         for (int j = 0; j < 8; ++j) st.o[j] = st.o[j] * alpha;
;     }
;     f32x4 pa, pb; float ps = 0.f;
;     const float mref = st.m - 4.f;
;     if (NOMASK) {
; #pragma unroll
;         for (int j = 0; j < 4; ++j) { pa[j] = __builtin_amdgcn_exp2f(sc[j] - mref); pb[j] = __builtin_amdgcn_exp2f(sc[4 + j] - mref); }
;         if (SLC) {
; #pragma unroll
;             for (int j = 0; j < 4; ++j) { pa[j] = act ? pa[j] : 0.f; pb[j] = act ? pb[j] : 0.f; }
;         }
; #pragma unroll
;         for (int j = 0; j < 4; ++j) ps += pa[j] + pb[j];
;     } else {
; #pragma unroll
;         for (int j = 0; j < 4; ++j) { pa[j] = vd[j] ? __builtin_amdgcn_exp2f(sc[j] - mref) : 0.f; pb[j] = vd[4 + j] ? __builtin_amdgcn_exp2f(sc[4 + j] - mref) : 0.f; ps += pa[j] + pb[j]; }
;     }
;     st.l += ps;
;     const u32x2 pw = pack8_fp8(pa, pb);
.LBB0_870:
	s_cmp_eq_u32 s12, 4
	s_cselect_b64 s[10:11], -1, 0
	s_lshl_b32 s13, s66, 7
	s_and_b32 s50, s13, 0x7fff800
	v_lshl_add_u64 v[10:11], v[86:87], 0, s[50:51]
	s_and_b32 s50, s13, 0x7fff000
	v_lshl_add_u64 v[244:245], v[10:11], 0, v[118:119]
	global_load_dwordx4 v[186:189], v[244:245], off
	global_load_dwordx4 v[190:193], v[244:245], off offset:1024
	global_load_dwordx4 v[194:197], v[244:245], off offset:2048
	global_load_dwordx4 v[198:201], v[244:245], off offset:3072
	v_lshl_add_u64 v[10:11], v[88:89], 0, s[50:51]
	v_lshl_add_u64 v[246:247], v[10:11], 0, v[118:119]
	global_load_dwordx4 v[170:173], v[246:247], off
	global_load_dwordx4 v[174:177], v[246:247], off offset:1024
	global_load_dwordx4 v[178:181], v[246:247], off offset:2048
	global_load_dwordx4 v[182:185], v[246:247], off offset:3072
	s_waitcnt vmcnt(20)
	v_mfma_f32_16x16x32_fp8_fp8 v[2:5], v[138:139], v[78:79], 0
	s_and_b32 s13, s59, 0xfffff
	v_cmp_eq_u32_e32 vcc, s12, v209
	v_add_u32_e32 v0, s13, v211
	v_mfma_f32_16x16x32_fp8_fp8 v[2:5], v[140:141], v[80:81], v[2:5]
	s_or_b64 s[18:19], s[10:11], vcc
	v_cmp_le_i32_e32 vcc, v0, v132
	s_and_b64 s[16:17], s[18:19], vcc
	v_mfma_f32_16x16x32_fp8_fp8 v[2:5], v[142:143], v[82:83], v[2:5]
	v_cmp_lt_i32_e32 vcc, v0, v132
	s_and_b64 s[12:13], s[18:19], vcc
	v_mfma_f32_16x16x32_fp8_fp8 v[6:9], v[146:147], v[78:79], 0
	v_mfma_f32_16x16x32_fp8_fp8 v[2:5], v[144:145], v[84:85], v[2:5]
	v_mfma_f32_16x16x32_fp8_fp8 v[6:9], v[148:149], v[80:81], v[6:9]
	v_mfma_f32_16x16x32_fp8_fp8 v[6:9], v[150:151], v[82:83], v[6:9]
	s_nop 5
	v_max_f32_e32 v10, v2, v2
	v_max_f32_e32 v10, 0xf149f2ca, v10
	v_cndmask_b32_e64 v10, v223, v10, s[16:17]
	v_max_f32_e32 v11, v3, v3
	v_max_f32_e32 v11, v10, v11
	v_cndmask_b32_e64 v10, v10, v11, s[12:13]
	v_add_u32_e32 v11, 2, v0
	v_cmp_le_i32_e32 vcc, v11, v132
	v_max_f32_e32 v11, v4, v4
	v_max_f32_e32 v11, v10, v11
	s_and_b64 s[14:15], s[18:19], vcc
	v_mfma_f32_16x16x32_fp8_fp8 v[6:9], v[152:153], v[84:85], v[6:9]
	v_cndmask_b32_e64 v10, v10, v11, s[14:15]
	v_add_u32_e32 v11, 3, v0
	v_cmp_le_i32_e32 vcc, v11, v132
	v_max_f32_e32 v11, v5, v5
	v_max_f32_e32 v11, v10, v11
	s_and_b64 s[10:11], s[18:19], vcc
	v_cndmask_b32_e64 v10, v10, v11, s[10:11]
	v_add_u32_e32 v11, 16, v0
	v_cmp_le_i32_e32 vcc, v11, v132
	v_max_f32_e32 v11, v6, v6
	v_max_f32_e32 v11, v10, v11
	s_and_b64 s[24:25], s[18:19], vcc
	v_cndmask_b32_e64 v10, v10, v11, s[24:25]
	v_add_u32_e32 v11, 17, v0
	v_cmp_le_i32_e32 vcc, v11, v132
	v_max_f32_e32 v11, v10, v10
	v_max_f32_e32 v12, v7, v7
	v_max_f32_e32 v11, v11, v12
	s_and_b64 s[20:21], s[18:19], vcc
	v_cndmask_b32_e64 v10, v10, v11, s[20:21]
	v_add_u32_e32 v11, 18, v0
	v_cmp_le_i32_e32 vcc, v11, v132
	v_max_f32_e32 v11, v10, v10
	v_max_f32_e32 v12, v8, v8
	v_max_f32_e32 v11, v11, v12
	s_and_b64 s[22:23], s[18:19], vcc
	v_cndmask_b32_e64 v10, v10, v11, s[22:23]
	v_add_u32_e32 v0, 19, v0
	v_cmp_le_i32_e32 vcc, v0, v132
	v_max_f32_e32 v0, v10, v10
	v_max_f32_e32 v11, v9, v9
	v_max_f32_e32 v0, v0, v11
	s_and_b64 s[18:19], s[18:19], vcc
	v_cndmask_b32_e64 v0, v10, v0, s[18:19]
	v_cmp_gt_f32_e32 vcc, v0, v204
	s_cbranch_vccz .LBB0_872
	ds_bpermute_b32 v10, v227, v0
	v_max_f32_e32 v0, v0, v0
	s_waitcnt lgkmcnt(0)
	v_max_f32_e32 v10, v10, v10
	v_max_f32_e32 v0, v0, v10
	ds_bpermute_b32 v10, v226, v0
	s_waitcnt lgkmcnt(0)
	v_max3_f32 v10, v202, v0, v10
	v_sub_f32_e32 v0, v202, v10
	v_exp_f32_e32 v0, v0
	v_mov_b32_e32 v202, v10
	v_mul_f32_e32 v203, v203, v0
	v_pk_mul_f32 v[66:67], v[66:67], v[0:1] op_sel_hi:[1,0]
	v_pk_mul_f32 v[64:65], v[64:65], v[0:1] op_sel_hi:[1,0]
	v_pk_mul_f32 v[62:63], v[62:63], v[0:1] op_sel_hi:[1,0]
	v_pk_mul_f32 v[60:61], v[60:61], v[0:1] op_sel_hi:[1,0]
	v_pk_mul_f32 v[58:59], v[58:59], v[0:1] op_sel_hi:[1,0]
	v_pk_mul_f32 v[56:57], v[56:57], v[0:1] op_sel_hi:[1,0]
	v_pk_mul_f32 v[54:55], v[54:55], v[0:1] op_sel_hi:[1,0]
	v_pk_mul_f32 v[52:53], v[52:53], v[0:1] op_sel_hi:[1,0]
	v_pk_mul_f32 v[50:51], v[50:51], v[0:1] op_sel_hi:[1,0]
	v_pk_mul_f32 v[48:49], v[48:49], v[0:1] op_sel_hi:[1,0]
	v_pk_mul_f32 v[46:47], v[46:47], v[0:1] op_sel_hi:[1,0]
	v_pk_mul_f32 v[44:45], v[44:45], v[0:1] op_sel_hi:[1,0]
	v_pk_mul_f32 v[42:43], v[42:43], v[0:1] op_sel_hi:[1,0]
	v_pk_mul_f32 v[40:41], v[40:41], v[0:1] op_sel_hi:[1,0]
	v_pk_mul_f32 v[38:39], v[38:39], v[0:1] op_sel_hi:[1,0]
	v_pk_mul_f32 v[36:37], v[36:37], v[0:1] op_sel_hi:[1,0]
.LBB0_872:
	v_add_f32_e32 v0, -4.0, v202
	v_sub_f32_e32 v2, v2, v0
	v_exp_f32_e32 v2, v2
	v_sub_f32_e32 v6, v6, v0
	v_exp_f32_e32 v6, v6
	v_sub_f32_e32 v4, v4, v0
	v_cndmask_b32_e64 v28, 0, v2, s[16:17]
	v_sub_f32_e32 v2, v3, v0
	v_exp_f32_e32 v2, v2
	v_sub_f32_e32 v3, v7, v0
	v_exp_f32_e32 v3, v3
	v_sub_f32_e32 v7, v8, v0
	v_cndmask_b32_e64 v29, 0, v2, s[12:13]
	v_sub_f32_e32 v2, v5, v0
	v_sub_f32_e32 v0, v9, v0
	v_cndmask_b32_e64 v6, 0, v6, s[24:25]
	v_exp_f32_e32 v4, v4
	v_exp_f32_e32 v7, v7
	v_cndmask_b32_e64 v30, 0, v3, s[20:21]
	v_exp_f32_e32 v5, v2
	v_exp_f32_e32 v0, v0
	v_mov_b32_e32 v2, v1
	v_mov_b32_e32 v3, v1
	v_cvt_pk_fp8_f32 v2, v28, v29
	v_cvt_pk_fp8_f32 v3, v6, v30
	v_cndmask_b32_e64 v4, 0, v4, s[14:15]
	v_cndmask_b32_e64 v7, 0, v7, s[22:23]
	v_cndmask_b32_e64 v5, 0, v5, s[10:11]
	v_cndmask_b32_e64 v0, 0, v0, s[18:19]
	v_cvt_pk_fp8_f32 v2, v4, v5 op_sel:[0,0,1]
	v_cvt_pk_fp8_f32 v3, v7, v0 op_sel:[0,0,1]
	v_add_f32_e32 v6, v28, v6
	v_add_f32_e32 v6, 0, v6
	v_add_f32_e32 v28, v29, v30
	v_add_f32_e32 v6, v28, v6
	v_add_f32_e32 v4, v4, v7
	v_add_f32_e32 v4, v4, v6
	v_add_f32_e32 v0, v5, v0
	s_waitcnt vmcnt(19)
	v_mfma_f32_16x16x32_fp8_fp8 v[8:11], v[90:91], v[2:3], v[64:67]
	v_add_f32_e32 v0, v0, v4
	v_add_f32_e32 v133, v203, v0
	v_mov_b32_e32 v0, v202
	v_mfma_f32_16x16x32_fp8_fp8 v[12:15], v[92:93], v[2:3], v[60:63]
	s_waitcnt vmcnt(18)
	v_mfma_f32_16x16x32_fp8_fp8 v[16:19], v[94:95], v[2:3], v[56:59]
	v_mfma_f32_16x16x32_fp8_fp8 v[20:23], v[96:97], v[2:3], v[52:55]
	s_waitcnt vmcnt(17)
	v_mfma_f32_16x16x32_fp8_fp8 v[24:27], v[98:99], v[2:3], v[48:51]
	v_mfma_f32_16x16x32_fp8_fp8 v[32:35], v[100:101], v[2:3], v[44:47]
	s_waitcnt vmcnt(16)
	v_mfma_f32_16x16x32_fp8_fp8 v[28:31], v[102:103], v[2:3], v[40:43]
	v_mfma_f32_16x16x32_fp8_fp8 v[4:7], v[104:105], v[2:3], v[36:39]
	s_nop 1
	s_add_i32 s10, s58, -3
	s_cmp_ge_u32 s10, s56
	s_mov_b64 s[10:11], -1
	s_cbranch_scc0 .LBB0_864

; template <bool SLC, bool NOMASK> ...
;     const int kq = lane >> 4;
;     const int pos0 = SLC ? (dcur & 0xfffff) : dcur;
;     const int lo = SLC ? ((((dcur >> 20) == qi) | ((dcur >> 20) == 4)) ? 0 : (1 << 30)) : lo_in;
;     load_frag8(nxt, KF, VF, SLC ? (dnext & 0xfffff) : dnext, lane);
;     f32x4 sa[2] = {(f32x4){0.f, 0.f, 0.f, 0.f}, (f32x4){0.f, 0.f, 0.f, 0.f}};
; #pragma unroll
;     for (int T = 0; T < 2; ++T)
; #pragma unroll
;         for (int s2 = 0; s2 < 4; ++s2) sa[T] = __builtin_amdgcn_mfma_f32_16x16x32_fp8_fp8(cur.k[T][s2], qf[s2], sa[T], 0, 0, 0);
;     float sc[8]; bool vd[8]; float mx = -1e30f;
;     const bool act = lo == 0 || !SLC;
;     if (NOMASK) {
; #pragma unroll
;         for (int j = 0; j < 8; ++j) { sc[j] = sa[j >> 2][j & 3]; vd[j] = act; }
;         mx = fmaxf(fmaxf(fmaxf(sc[0], sc[1]), fmaxf(sc[2], sc[3])), fmaxf(fmaxf(sc[4], sc[5]), fmaxf(sc[6], sc[7])));
;         mx = act ? mx : -1e30f;
;     } else {
; #pragma unroll
;         for (int T = 0; T < 2; ++T)
; #pragma unroll
;             for (int r = 0; r < 4; ++r) { const int p = pos0 + 16 * T + 4 * kq + r; const bool v = (p >= lo) & (p <= hi); const float x = sa[T][r];
;                 sc[4 * T + r] = x; vd[4 * T + r] = v; mx = v ? fmaxf(mx, x) : mx; }
;     }
;     if (__builtin_amdgcn_ballot_w64(mx > st.m + 4.f) != 0ull) {
;         mx = fmaxf(mx, __shfl_xor(mx, 16)); mx = fmaxf(mx, __shfl_xor(mx, 32));
;         const float mn = fmaxf(st.m, mx), alpha = __builtin_amdgcn_exp2f(st.m - mn); st.m = mn; st.l *= alpha;
; #pragma unroll
;         for (int j = 0; j < 8; ++j) st.o[j] = st.o[j] * alpha;
;     }
;     f32x4 pa, pb; float ps = 0.f;
;     const float mref = st.m - 4.f;
;     if (NOMASK) {
; #pragma unroll
;         for (int j = 0; j < 4; ++j) { pa[j] = __builtin_amdgcn_exp2f(sc[j] - mref); pb[j] = __builtin_amdgcn_exp2f(sc[4 + j] - mref); }
;         if (SLC) {
; #pragma unroll
;             for (int j = 0; j < 4; ++j) { pa[j] = act ? pa[j] : 0.f; pb[j] = act ? pb[j] : 0.f; }
;         }
; #pragma unroll
;         for (int j = 0; j < 4; ++j) ps += pa[j] + pb[j];
;     } else {
; #pragma unroll
;         for (int j = 0; j < 4; ++j) { pa[j] = vd[j] ? __builtin_amdgcn_exp2f(sc[j] - mref) : 0.f; pb[j] = vd[4 + j] ? __builtin_amdgcn_exp2f(sc[4 + j] - mref) : 0.f; ps += pa[j] + pb[j]; }
;     }
;     st.l += ps;
;     const u32x2 pw = pack8_fp8(pa, pb);
.LBB0_874:
	s_and_b32 s13, s12, 0xfffffbff
	s_cmp_eq_u32 s13, 4
	s_cselect_b64 s[10:11], -1, 0
	s_lshl_b32 s14, s59, 7
	s_and_b32 s50, s14, 0x7fff800
	v_lshl_add_u64 v[44:45], v[86:87], 0, s[50:51]
	s_and_b32 s50, s14, 0x7fff000
	v_lshl_add_u64 v[244:245], v[44:45], 0, v[118:119]
	global_load_dwordx4 v[138:141], v[244:245], off
	global_load_dwordx4 v[142:145], v[244:245], off offset:1024
	global_load_dwordx4 v[146:149], v[244:245], off offset:2048
	global_load_dwordx4 v[150:153], v[244:245], off offset:3072
	v_lshl_add_u64 v[44:45], v[88:89], 0, s[50:51]
	v_lshl_add_u64 v[246:247], v[44:45], 0, v[118:119]
	global_load_dwordx4 v[90:93], v[246:247], off
	global_load_dwordx4 v[94:97], v[246:247], off offset:1024
	global_load_dwordx4 v[98:101], v[246:247], off offset:2048
	global_load_dwordx4 v[102:105], v[246:247], off offset:3072
	s_waitcnt vmcnt(20)
	v_mfma_f32_16x16x32_fp8_fp8 v[36:39], v[154:155], v[78:79], 0
	v_cmp_eq_u32_e32 vcc, s13, v209
	s_or_b64 s[10:11], s[10:11], vcc
	v_mov_b64_e32 v[74:75], v[6:7]
	v_mfma_f32_16x16x32_fp8_fp8 v[40:43], v[162:163], v[78:79], 0
	v_mov_b64_e32 v[70:71], v[30:31]
	v_mov_b64_e32 v[66:67], v[34:35]
	v_mov_b64_e32 v[62:63], v[26:27]
	v_mfma_f32_16x16x32_fp8_fp8 v[36:39], v[156:157], v[80:81], v[36:39]
	v_mov_b64_e32 v[58:59], v[22:23]
	v_mov_b64_e32 v[54:55], v[18:19]
	v_mov_b64_e32 v[50:51], v[14:15]
	v_mfma_f32_16x16x32_fp8_fp8 v[40:43], v[164:165], v[80:81], v[40:43]
	v_mov_b32_e32 v203, v0
	v_mov_b64_e32 v[72:73], v[4:5]
	v_mov_b64_e32 v[68:69], v[28:29]
	v_mfma_f32_16x16x32_fp8_fp8 v[36:39], v[158:159], v[82:83], v[36:39]
	v_mov_b64_e32 v[64:65], v[32:33]
	v_mov_b64_e32 v[60:61], v[24:25]
	v_mov_b64_e32 v[56:57], v[20:21]
	v_mfma_f32_16x16x32_fp8_fp8 v[40:43], v[166:167], v[82:83], v[40:43]
	v_mov_b64_e32 v[52:53], v[16:17]
	v_mov_b64_e32 v[48:49], v[12:13]
	v_mfma_f32_16x16x32_fp8_fp8 v[36:39], v[160:161], v[84:85], v[36:39]
	v_mfma_f32_16x16x32_fp8_fp8 v[40:43], v[168:169], v[84:85], v[40:43]
	s_nop 6
	v_max_f32_e32 v3, v37, v37
	v_max_f32_e32 v44, v36, v36
	v_max_f32_e32 v3, v44, v3
	v_max_f32_e32 v44, v39, v39
	v_max_f32_e32 v45, v38, v38
	v_max_f32_e32 v44, v45, v44
	v_max_f32_e32 v45, v43, v43
	v_max_f32_e32 v46, v42, v42
	v_max_f32_e32 v45, v46, v45
	v_max3_f32 v45, v40, v41, v45
	v_max3_f32 v3, v3, v44, v45
	v_cndmask_b32_e64 v202, v223, v3, s[10:11]
	v_mov_b64_e32 v[46:47], v[10:11]
	v_cmp_gt_f32_e32 vcc, v202, v2
	v_mov_b64_e32 v[44:45], v[8:9]
	v_mov_b32_e32 v3, v133
	s_cbranch_vccz .LBB0_876
	ds_bpermute_b32 v3, v227, v202
	v_max_f32_e32 v44, v202, v202
	s_waitcnt lgkmcnt(0)
	v_max_f32_e32 v3, v3, v3
	v_max_f32_e32 v3, v44, v3
	ds_bpermute_b32 v44, v226, v3
	s_waitcnt lgkmcnt(0)
	v_max3_f32 v203, v0, v3, v44
	v_sub_f32_e32 v3, v0, v203
	v_exp_f32_e32 v72, v3
	s_nop 0
	v_mul_f32_e32 v3, v133, v72
	v_pk_mul_f32 v[46:47], v[10:11], v[72:73] op_sel_hi:[1,0]
	v_pk_mul_f32 v[44:45], v[8:9], v[72:73] op_sel_hi:[1,0]
	v_pk_mul_f32 v[50:51], v[14:15], v[72:73] op_sel_hi:[1,0]
	v_pk_mul_f32 v[48:49], v[12:13], v[72:73] op_sel_hi:[1,0]
	v_pk_mul_f32 v[54:55], v[18:19], v[72:73] op_sel_hi:[1,0]
	v_pk_mul_f32 v[52:53], v[16:17], v[72:73] op_sel_hi:[1,0]
	v_pk_mul_f32 v[58:59], v[22:23], v[72:73] op_sel_hi:[1,0]
	v_pk_mul_f32 v[56:57], v[20:21], v[72:73] op_sel_hi:[1,0]
	v_pk_mul_f32 v[62:63], v[26:27], v[72:73] op_sel_hi:[1,0]
	v_pk_mul_f32 v[60:61], v[24:25], v[72:73] op_sel_hi:[1,0]
	v_pk_mul_f32 v[66:67], v[34:35], v[72:73] op_sel_hi:[1,0]
	v_pk_mul_f32 v[64:65], v[32:33], v[72:73] op_sel_hi:[1,0]
	v_pk_mul_f32 v[70:71], v[30:31], v[72:73] op_sel_hi:[1,0]
	v_pk_mul_f32 v[68:69], v[28:29], v[72:73] op_sel_hi:[1,0]
	v_pk_mul_f32 v[74:75], v[6:7], v[72:73] op_sel_hi:[1,0]
	v_pk_mul_f32 v[72:73], v[4:5], v[72:73] op_sel_hi:[1,0]
.LBB0_876:
	v_add_f32_e32 v202, -4.0, v203
	v_sub_f32_e32 v36, v36, v202
	v_sub_f32_e32 v40, v40, v202
	v_sub_f32_e32 v37, v37, v202
	v_sub_f32_e32 v41, v41, v202
	v_exp_f32_e32 v36, v36
	v_exp_f32_e32 v40, v40
	v_exp_f32_e32 v37, v37
	v_exp_f32_e32 v41, v41
	v_sub_f32_e32 v38, v38, v202
	v_sub_f32_e32 v42, v42, v202
	v_sub_f32_e32 v39, v39, v202
	v_sub_f32_e32 v43, v43, v202
	v_exp_f32_e32 v38, v38
	v_exp_f32_e32 v42, v42
	v_exp_f32_e32 v39, v39
	v_exp_f32_e32 v43, v43
	v_cndmask_b32_e64 v202, 0, v36, s[10:11]
	v_cndmask_b32_e64 v204, 0, v40, s[10:11]
	v_cndmask_b32_e64 v205, 0, v37, s[10:11]
	v_cndmask_b32_e64 v229, 0, v41, s[10:11]
	v_mov_b32_e32 v230, v1
	v_mov_b32_e32 v231, v1
	v_cvt_pk_fp8_f32 v230, v202, v205
	v_cvt_pk_fp8_f32 v231, v204, v229
	v_cndmask_b32_e64 v232, 0, v38, s[10:11]
	v_cndmask_b32_e64 v233, 0, v42, s[10:11]
	v_cndmask_b32_e64 v234, 0, v39, s[10:11]
	v_cndmask_b32_e64 v235, 0, v43, s[10:11]
	v_cvt_pk_fp8_f32 v230, v232, v234 op_sel:[0,0,1]
	v_cvt_pk_fp8_f32 v231, v233, v235 op_sel:[0,0,1]
	s_nop 0
	s_waitcnt vmcnt(19)
	v_mfma_f32_16x16x32_fp8_fp8 v[40:43], v[108:109], v[230:231], v[48:51]
	v_mfma_f32_16x16x32_fp8_fp8 v[48:51], v[112:113], v[230:231], v[56:59]
	s_nop 2
	v_add_f32_e32 v56, v202, v204
	s_waitcnt vmcnt(18)
	v_mfma_f32_16x16x32_fp8_fp8 v[36:39], v[106:107], v[230:231], v[44:47]
	v_mfma_f32_16x16x32_fp8_fp8 v[44:47], v[110:111], v[230:231], v[52:55]
	s_waitcnt vmcnt(17)
	v_mfma_f32_16x16x32_fp8_fp8 v[52:55], v[114:115], v[230:231], v[60:63]
	s_nop 2
	v_add_f32_e32 v60, 0, v56
	v_add_f32_e32 v61, v205, v229
	v_add_f32_e32 v60, v61, v60
	v_add_f32_e32 v61, v232, v233
	v_mfma_f32_16x16x32_fp8_fp8 v[56:59], v[116:117], v[230:231], v[64:67]
	s_nop 2
	v_add_f32_e32 v64, v61, v60
	v_add_f32_e32 v65, v234, v235
	v_add_f32_e32 v64, v65, v64
	s_waitcnt vmcnt(16)
	v_mfma_f32_16x16x32_fp8_fp8 v[60:63], v[134:135], v[230:231], v[68:71]
	v_add_f32_e32 v204, v3, v64
	v_mfma_f32_16x16x32_fp8_fp8 v[64:67], v[136:137], v[230:231], v[72:75]
	s_nop 1
	s_branch .LBB0_866
; template <bool SLC, bool NOMASK> ...
;     const int kq = lane >> 4;
;     const int pos0 = SLC ? (dcur & 0xfffff) : dcur;
;     const int lo = SLC ? ((((dcur >> 20) == qi) | ((dcur >> 20) == 4)) ? 0 : (1 << 30)) : lo_in;
;     load_frag8(nxt, KF, VF, SLC ? (dnext & 0xfffff) : dnext, lane);
;     f32x4 sa[2] = {(f32x4){0.f, 0.f, 0.f, 0.f}, (f32x4){0.f, 0.f, 0.f, 0.f}};
; #pragma unroll
;     for (int T = 0; T < 2; ++T)
; #pragma unroll
;         for (int s2 = 0; s2 < 4; ++s2) sa[T] = __builtin_amdgcn_mfma_f32_16x16x32_fp8_fp8(cur.k[T][s2], qf[s2], sa[T], 0, 0, 0);
;     float sc[8]; bool vd[8]; float mx = -1e30f;
;     const bool act = lo == 0 || !SLC;
;     if (NOMASK) {
; #pragma unroll
;         for (int j = 0; j < 8; ++j) { sc[j] = sa[j >> 2][j & 3]; vd[j] = act; }
;         mx = fmaxf(fmaxf(fmaxf(sc[0], sc[1]), fmaxf(sc[2], sc[3])), fmaxf(fmaxf(sc[4], sc[5]), fmaxf(sc[6], sc[7])));
;         mx = act ? mx : -1e30f;
;     } else {
; #pragma unroll
;         for (int T = 0; T < 2; ++T)
; #pragma unroll
;             for (int r = 0; r < 4; ++r) { const int p = pos0 + 16 * T + 4 * kq + r; const bool v = (p >= lo) & (p <= hi); const float x = sa[T][r];
;                 sc[4 * T + r] = x; vd[4 * T + r] = v; mx = v ? fmaxf(mx, x) : mx; }
;     }
;     if (__builtin_amdgcn_ballot_w64(mx > st.m + 4.f) != 0ull) {
;         mx = fmaxf(mx, __shfl_xor(mx, 16)); mx = fmaxf(mx, __shfl_xor(mx, 32));
;         const float mn = fmaxf(st.m, mx), alpha = __builtin_amdgcn_exp2f(st.m - mn); st.m = mn; st.l *= alpha;
; #pragma unroll
;         for (int j = 0; j < 8; ++j) st.o[j] = st.o[j] * alpha;
;     }
;     f32x4 pa, pb; float ps = 0.f;
;     const float mref = st.m - 4.f;
;     if (NOMASK) {
; #pragma unroll
;         for (int j = 0; j < 4; ++j) { pa[j] = __builtin_amdgcn_exp2f(sc[j] - mref); pb[j] = __builtin_amdgcn_exp2f(sc[4 + j] - mref); }
;         if (SLC) {
; #pragma unroll
;             for (int j = 0; j < 4; ++j) { pa[j] = act ? pa[j] : 0.f; pb[j] = act ? pb[j] : 0.f; }
;         }
; #pragma unroll
;         for (int j = 0; j < 4; ++j) ps += pa[j] + pb[j];
;     } else {
; #pragma unroll
;         for (int j = 0; j < 4; ++j) { pa[j] = vd[j] ? __builtin_amdgcn_exp2f(sc[j] - mref) : 0.f; pb[j] = vd[4 + j] ? __builtin_amdgcn_exp2f(sc[4 + j] - mref) : 0.f; ps += pa[j] + pb[j]; }
;     }
;     st.l += ps;
;     const u32x2 pw = pack8_fp8(pa, pb);
.LBB0_877:
	s_cmp_eq_u32 s12, 4
	s_cselect_b64 s[10:11], -1, 0
	s_lshl_b32 s13, s59, 7
	s_and_b32 s50, s13, 0x7fff800
	v_lshl_add_u64 v[44:45], v[86:87], 0, s[50:51]
	s_and_b32 s50, s13, 0x7fff000
	v_lshl_add_u64 v[244:245], v[44:45], 0, v[118:119]
	global_load_dwordx4 v[138:141], v[244:245], off
	global_load_dwordx4 v[142:145], v[244:245], off offset:1024
	global_load_dwordx4 v[146:149], v[244:245], off offset:2048
	global_load_dwordx4 v[150:153], v[244:245], off offset:3072
	v_lshl_add_u64 v[44:45], v[88:89], 0, s[50:51]
	v_lshl_add_u64 v[246:247], v[44:45], 0, v[118:119]
	global_load_dwordx4 v[90:93], v[246:247], off
	global_load_dwordx4 v[94:97], v[246:247], off offset:1024
	global_load_dwordx4 v[98:101], v[246:247], off offset:2048
	global_load_dwordx4 v[102:105], v[246:247], off offset:3072
	s_waitcnt vmcnt(20)
	v_mfma_f32_16x16x32_fp8_fp8 v[36:39], v[154:155], v[78:79], 0
	s_and_b32 s13, s97, 0xfffff
	v_cmp_eq_u32_e32 vcc, s12, v209
	v_add_u32_e32 v3, s13, v211
	v_mfma_f32_16x16x32_fp8_fp8 v[36:39], v[156:157], v[80:81], v[36:39]
	s_or_b64 s[18:19], s[10:11], vcc
	v_cmp_le_i32_e32 vcc, v3, v132
	s_and_b64 s[16:17], s[18:19], vcc
	v_mfma_f32_16x16x32_fp8_fp8 v[36:39], v[158:159], v[82:83], v[36:39]
	v_cmp_lt_i32_e32 vcc, v3, v132
	s_and_b64 s[12:13], s[18:19], vcc
	v_mfma_f32_16x16x32_fp8_fp8 v[40:43], v[162:163], v[78:79], 0
	v_mfma_f32_16x16x32_fp8_fp8 v[36:39], v[160:161], v[84:85], v[36:39]
	v_mfma_f32_16x16x32_fp8_fp8 v[40:43], v[164:165], v[80:81], v[40:43]
	v_mfma_f32_16x16x32_fp8_fp8 v[40:43], v[166:167], v[82:83], v[40:43]
	s_nop 5
	v_max_f32_e32 v44, v36, v36
	v_max_f32_e32 v44, 0xf149f2ca, v44
	v_cndmask_b32_e64 v44, v223, v44, s[16:17]
	v_max_f32_e32 v45, v37, v37
	v_max_f32_e32 v45, v44, v45
	v_cndmask_b32_e64 v44, v44, v45, s[12:13]
	v_add_u32_e32 v45, 2, v3
	v_cmp_le_i32_e32 vcc, v45, v132
	v_max_f32_e32 v45, v38, v38
	v_max_f32_e32 v45, v44, v45
	s_and_b64 s[14:15], s[18:19], vcc
	v_mfma_f32_16x16x32_fp8_fp8 v[40:43], v[168:169], v[84:85], v[40:43]
	v_cndmask_b32_e64 v44, v44, v45, s[14:15]
	v_add_u32_e32 v45, 3, v3
	v_cmp_le_i32_e32 vcc, v45, v132
	v_max_f32_e32 v45, v39, v39
	v_max_f32_e32 v45, v44, v45
	s_and_b64 s[10:11], s[18:19], vcc
	v_cndmask_b32_e64 v44, v44, v45, s[10:11]
	v_add_u32_e32 v45, 16, v3
	v_cmp_le_i32_e32 vcc, v45, v132
	v_max_f32_e32 v45, v40, v40
	v_max_f32_e32 v45, v44, v45
	s_and_b64 s[24:25], s[18:19], vcc
	v_cndmask_b32_e64 v44, v44, v45, s[24:25]
	v_add_u32_e32 v45, 17, v3
	v_cmp_le_i32_e32 vcc, v45, v132
	v_max_f32_e32 v45, v44, v44
	v_max_f32_e32 v46, v41, v41
	v_max_f32_e32 v45, v45, v46
	s_and_b64 s[20:21], s[18:19], vcc
	v_cndmask_b32_e64 v44, v44, v45, s[20:21]
	v_add_u32_e32 v45, 18, v3
	v_cmp_le_i32_e32 vcc, v45, v132
	v_max_f32_e32 v45, v44, v44
	v_max_f32_e32 v46, v42, v42
	v_max_f32_e32 v45, v45, v46
	s_and_b64 s[22:23], s[18:19], vcc
	v_cndmask_b32_e64 v44, v44, v45, s[22:23]
	v_add_u32_e32 v3, 19, v3
	v_cmp_le_i32_e32 vcc, v3, v132
	v_max_f32_e32 v3, v44, v44
	v_max_f32_e32 v45, v43, v43
	v_max_f32_e32 v3, v3, v45
	s_and_b64 s[18:19], s[18:19], vcc
	v_cndmask_b32_e64 v3, v44, v3, s[18:19]
	v_cmp_gt_f32_e32 vcc, v3, v2
	s_cbranch_vccz .LBB0_879
	ds_bpermute_b32 v2, v227, v3
	v_max_f32_e32 v3, v3, v3
	s_waitcnt lgkmcnt(0)
	v_max_f32_e32 v2, v2, v2
	v_max_f32_e32 v2, v3, v2
	ds_bpermute_b32 v3, v226, v2
	s_waitcnt lgkmcnt(0)
	v_max3_f32 v2, v0, v2, v3
	v_sub_f32_e32 v0, v0, v2
	v_exp_f32_e32 v0, v0
	s_nop 0
	v_mul_f32_e32 v133, v133, v0
	v_pk_mul_f32 v[10:11], v[10:11], v[0:1] op_sel_hi:[1,0]
	v_pk_mul_f32 v[8:9], v[8:9], v[0:1] op_sel_hi:[1,0]
	v_pk_mul_f32 v[14:15], v[14:15], v[0:1] op_sel_hi:[1,0]
	v_pk_mul_f32 v[12:13], v[12:13], v[0:1] op_sel_hi:[1,0]
	v_pk_mul_f32 v[18:19], v[18:19], v[0:1] op_sel_hi:[1,0]
	v_pk_mul_f32 v[16:17], v[16:17], v[0:1] op_sel_hi:[1,0]
	v_pk_mul_f32 v[22:23], v[22:23], v[0:1] op_sel_hi:[1,0]
	v_pk_mul_f32 v[20:21], v[20:21], v[0:1] op_sel_hi:[1,0]
	v_pk_mul_f32 v[26:27], v[26:27], v[0:1] op_sel_hi:[1,0]
	v_pk_mul_f32 v[24:25], v[24:25], v[0:1] op_sel_hi:[1,0]
	v_pk_mul_f32 v[34:35], v[34:35], v[0:1] op_sel_hi:[1,0]
	v_pk_mul_f32 v[32:33], v[32:33], v[0:1] op_sel_hi:[1,0]
	v_pk_mul_f32 v[30:31], v[30:31], v[0:1] op_sel_hi:[1,0]
	v_pk_mul_f32 v[28:29], v[28:29], v[0:1] op_sel_hi:[1,0]
	v_pk_mul_f32 v[6:7], v[6:7], v[0:1] op_sel_hi:[1,0]
	v_pk_mul_f32 v[4:5], v[4:5], v[0:1] op_sel_hi:[1,0]
	v_mov_b32_e32 v0, v2
.LBB0_879:
	v_add_f32_e32 v2, -4.0, v0
	v_sub_f32_e32 v3, v36, v2
	v_exp_f32_e32 v3, v3
	v_sub_f32_e32 v36, v40, v2
	v_exp_f32_e32 v36, v36
	v_mov_b32_e32 v203, v0
	v_cndmask_b32_e64 v56, 0, v3, s[16:17]
	v_sub_f32_e32 v3, v37, v2
	v_cndmask_b32_e64 v57, 0, v36, s[24:25]
	v_exp_f32_e32 v3, v3
	v_sub_f32_e32 v36, v41, v2
	v_sub_f32_e32 v37, v38, v2
	v_exp_f32_e32 v36, v36
	v_exp_f32_e32 v37, v37
	v_sub_f32_e32 v38, v42, v2
	v_cndmask_b32_e64 v58, 0, v3, s[12:13]
	v_sub_f32_e32 v3, v39, v2
	v_sub_f32_e32 v2, v43, v2
	v_exp_f32_e32 v38, v38
	v_cndmask_b32_e64 v59, 0, v36, s[20:21]
	v_cndmask_b32_e64 v60, 0, v37, s[14:15]
	v_exp_f32_e32 v36, v3
	v_exp_f32_e32 v37, v2
	v_mov_b32_e32 v2, v1
	v_mov_b32_e32 v3, v1
	v_cvt_pk_fp8_f32 v2, v56, v58
	v_cvt_pk_fp8_f32 v3, v57, v59
	v_cndmask_b32_e64 v61, 0, v38, s[22:23]
	v_cndmask_b32_e64 v64, 0, v36, s[10:11]
	v_cndmask_b32_e64 v65, 0, v37, s[18:19]
	v_cvt_pk_fp8_f32 v2, v60, v64 op_sel:[0,0,1]
	v_cvt_pk_fp8_f32 v3, v61, v65 op_sel:[0,0,1]
	s_nop 0
	s_waitcnt vmcnt(19)
	v_mfma_f32_16x16x32_fp8_fp8 v[36:39], v[106:107], v[2:3], v[8:11]
	s_nop 2
	v_add_f32_e32 v8, v56, v57
	v_add_f32_e32 v8, 0, v8
	v_add_f32_e32 v9, v58, v59
	v_add_f32_e32 v8, v9, v8
	v_add_f32_e32 v9, v60, v61
	v_mfma_f32_16x16x32_fp8_fp8 v[40:43], v[108:109], v[2:3], v[12:15]
	v_add_f32_e32 v8, v9, v8
	v_add_f32_e32 v9, v64, v65
	v_add_f32_e32 v8, v9, v8
	s_waitcnt vmcnt(18)
	v_mfma_f32_16x16x32_fp8_fp8 v[44:47], v[110:111], v[2:3], v[16:19]
	v_add_f32_e32 v204, v133, v8
	v_mfma_f32_16x16x32_fp8_fp8 v[48:51], v[112:113], v[2:3], v[20:23]
	s_waitcnt vmcnt(17)
	v_mfma_f32_16x16x32_fp8_fp8 v[52:55], v[114:115], v[2:3], v[24:27]
	v_mfma_f32_16x16x32_fp8_fp8 v[56:59], v[116:117], v[2:3], v[32:35]
	s_waitcnt vmcnt(16)
	v_mfma_f32_16x16x32_fp8_fp8 v[60:63], v[134:135], v[2:3], v[28:31]
	v_mfma_f32_16x16x32_fp8_fp8 v[64:67], v[136:137], v[2:3], v[4:7]
	s_nop 1
	s_andn2_b64 vcc, exec, s[26:27]
	s_mov_b64 s[10:11], -1
	s_cbranch_vccnz .LBB0_859
; template <bool SLC, bool NOMASK> ...
;     const int kq = lane >> 4;
;     const int pos0 = SLC ? (dcur & 0xfffff) : dcur;
;     const int lo = SLC ? ((((dcur >> 20) == qi) | ((dcur >> 20) == 4)) ? 0 : (1 << 30)) : lo_in;
;     load_frag8(nxt, KF, VF, SLC ? (dnext & 0xfffff) : dnext, lane);
;     f32x4 sa[2] = {(f32x4){0.f, 0.f, 0.f, 0.f}, (f32x4){0.f, 0.f, 0.f, 0.f}};
; #pragma unroll
;     for (int T = 0; T < 2; ++T)
; #pragma unroll
;         for (int s2 = 0; s2 < 4; ++s2) sa[T] = __builtin_amdgcn_mfma_f32_16x16x32_fp8_fp8(cur.k[T][s2], qf[s2], sa[T], 0, 0, 0);
;     float sc[8]; bool vd[8]; float mx = -1e30f;
;     const bool act = lo == 0 || !SLC;
;     if (NOMASK) {
; #pragma unroll
;         for (int j = 0; j < 8; ++j) { sc[j] = sa[j >> 2][j & 3]; vd[j] = act; }
;         mx = fmaxf(fmaxf(fmaxf(sc[0], sc[1]), fmaxf(sc[2], sc[3])), fmaxf(fmaxf(sc[4], sc[5]), fmaxf(sc[6], sc[7])));
;         mx = act ? mx : -1e30f;
;     } else {
; #pragma unroll
;         for (int T = 0; T < 2; ++T)
; #pragma unroll
;             for (int r = 0; r < 4; ++r) { const int p = pos0 + 16 * T + 4 * kq + r; const bool v = (p >= lo) & (p <= hi); const float x = sa[T][r];
;                 sc[4 * T + r] = x; vd[4 * T + r] = v; mx = v ? fmaxf(mx, x) : mx; }
;     }
;     if (__builtin_amdgcn_ballot_w64(mx > st.m + 4.f) != 0ull) {
;         mx = fmaxf(mx, __shfl_xor(mx, 16)); mx = fmaxf(mx, __shfl_xor(mx, 32));
; template <bool SLC, class Desc>
; __device__ __forceinline__ void attn_run_frag8(const i64_t (&qf)[4], const unsigned char* __restrict__ KF, const unsigned char* __restrict__ VF, const Desc& desc, int n,
;                                                int lo_in, int hi, int qi, AState& st, int lane) {
;     ...
; #pragma unroll 1
;     for (int i = 0; i < n; i += 3) {
;         const int d2 = desc(i + 2 < n ? i + 2 : n - 1);
;         F8_STEP(fa, fc, d0, d2);
;         if (i + 1 >= n) break;
;         const int d3 = desc(i + 3 < n ? i + 3 : n - 1);
;         F8_STEP(fb, fa, d1, d3);
;         if (i + 2 >= n) break;
;         const int d4 = desc(i + 4 < n ? i + 4 : n - 1);
;         F8_STEP(fc, fb, d2, d4);
; __device__ __forceinline__ void nsa_unit(int unit, const bf16_t* proj, const bf16_t* kc, const bf16_t* vc, const bf16_t* gn, const float* cs, const float* sn, ...
;     ...
;     { auto desc = [&](int i) { return __builtin_amdgcn_readfirstlane(list[i]); };
.LBB0_880:
	s_cmp_lt_u32 s58, s56
	s_cselect_b32 s10, s58, s57
	s_lshl_b32 s10, s10, 2
	s_add_i32 s10, s3, s10
	v_mov_b32_e32 v0, s10
	ds_read_b32 v0, v0 offset:13632
	s_and_b32 s13, s66, 2.0
	s_ashr_i32 s12, s66, 20
	s_mov_b64 s[10:11], -1
	s_cmp_eq_u32 s13, 0
	s_waitcnt lgkmcnt(0)
	v_readfirstlane_b32 s97, v0
	v_add_f32_e32 v0, 4.0, v203
	s_cbranch_scc1 .LBB0_884
	s_and_b32 s13, s12, 0xfffffbff
	s_cmp_eq_u32 s13, 4
	s_cselect_b64 s[10:11], -1, 0
	s_lshl_b32 s14, s97, 7
	s_and_b32 s50, s14, 0x7fff800
	v_lshl_add_u64 v[10:11], v[86:87], 0, s[50:51]
	s_and_b32 s50, s14, 0x7fff000
	v_lshl_add_u64 v[244:245], v[10:11], 0, v[118:119]
	global_load_dwordx4 v[154:157], v[244:245], off
	global_load_dwordx4 v[158:161], v[244:245], off offset:1024
	global_load_dwordx4 v[162:165], v[244:245], off offset:2048
	global_load_dwordx4 v[166:169], v[244:245], off offset:3072
	v_lshl_add_u64 v[10:11], v[88:89], 0, s[50:51]
	v_lshl_add_u64 v[246:247], v[10:11], 0, v[118:119]
	global_load_dwordx4 v[106:109], v[246:247], off
	global_load_dwordx4 v[110:113], v[246:247], off offset:1024
	global_load_dwordx4 v[114:117], v[246:247], off offset:2048
	global_load_dwordx4 v[134:137], v[246:247], off offset:3072
	s_waitcnt vmcnt(20)
	v_mfma_f32_16x16x32_fp8_fp8 v[2:5], v[186:187], v[78:79], 0
	v_cmp_eq_u32_e32 vcc, s13, v209
	s_or_b64 s[10:11], s[10:11], vcc
	v_mov_b64_e32 v[74:75], v[66:67]
	v_mfma_f32_16x16x32_fp8_fp8 v[6:9], v[194:195], v[78:79], 0
	v_mov_b64_e32 v[70:71], v[62:63]
	v_mov_b64_e32 v[30:31], v[56:57]
	v_mov_b64_e32 v[26:27], v[52:53]
	v_mfma_f32_16x16x32_fp8_fp8 v[2:5], v[188:189], v[80:81], v[2:5]
	v_mov_b64_e32 v[22:23], v[48:49]
	v_mov_b64_e32 v[18:19], v[44:45]
	v_mov_b64_e32 v[14:15], v[40:41]
	v_mfma_f32_16x16x32_fp8_fp8 v[6:9], v[196:197], v[80:81], v[6:9]
	v_mov_b32_e32 v202, v203
	v_mov_b64_e32 v[72:73], v[64:65]
	v_mov_b64_e32 v[68:69], v[60:61]
	v_mfma_f32_16x16x32_fp8_fp8 v[2:5], v[190:191], v[82:83], v[2:5]
	v_mov_b64_e32 v[32:33], v[58:59]
	v_mov_b64_e32 v[28:29], v[54:55]
	v_mov_b64_e32 v[24:25], v[50:51]
	v_mfma_f32_16x16x32_fp8_fp8 v[6:9], v[198:199], v[82:83], v[6:9]
	v_mov_b64_e32 v[20:21], v[46:47]
	v_mov_b64_e32 v[16:17], v[42:43]
	v_mov_b32_e32 v133, v204
	v_mfma_f32_16x16x32_fp8_fp8 v[2:5], v[192:193], v[84:85], v[2:5]
	v_mfma_f32_16x16x32_fp8_fp8 v[6:9], v[200:201], v[84:85], v[6:9]
	s_nop 6
	v_max_f32_e32 v10, v3, v3
	v_max_f32_e32 v11, v2, v2
	v_max_f32_e32 v10, v11, v10
	v_max_f32_e32 v11, v5, v5
	v_max_f32_e32 v12, v4, v4
	v_max_f32_e32 v11, v12, v11
	v_max_f32_e32 v12, v9, v9
	v_max_f32_e32 v13, v8, v8
	v_max_f32_e32 v12, v13, v12
	v_max3_f32 v12, v6, v7, v12
	v_max3_f32 v10, v10, v11, v12
	v_cndmask_b32_e64 v34, v223, v10, s[10:11]
	v_mov_b64_e32 v[10:11], v[36:37]
	v_cmp_gt_f32_e32 vcc, v34, v0
	v_mov_b64_e32 v[12:13], v[38:39]
	s_cbranch_vccz .LBB0_883
	ds_bpermute_b32 v10, v227, v34
	v_max_f32_e32 v11, v34, v34
	s_waitcnt lgkmcnt(0)
	v_max_f32_e32 v10, v10, v10
	v_max_f32_e32 v10, v11, v10
	ds_bpermute_b32 v11, v226, v10
	s_waitcnt lgkmcnt(0)
	v_max3_f32 v202, v203, v10, v11
	v_sub_f32_e32 v10, v203, v202
	v_exp_f32_e32 v34, v10
	s_nop 0
	v_mul_f32_e32 v133, v204, v34
	v_pk_mul_f32 v[12:13], v[38:39], v[34:35] op_sel_hi:[1,0]
	v_pk_mul_f32 v[10:11], v[36:37], v[34:35] op_sel_hi:[1,0]
	v_pk_mul_f32 v[16:17], v[42:43], v[34:35] op_sel_hi:[1,0]
	v_pk_mul_f32 v[14:15], v[40:41], v[34:35] op_sel_hi:[1,0]
	v_pk_mul_f32 v[20:21], v[46:47], v[34:35] op_sel_hi:[1,0]
	v_pk_mul_f32 v[18:19], v[44:45], v[34:35] op_sel_hi:[1,0]
	v_pk_mul_f32 v[24:25], v[50:51], v[34:35] op_sel_hi:[1,0]
	v_pk_mul_f32 v[22:23], v[48:49], v[34:35] op_sel_hi:[1,0]
	v_pk_mul_f32 v[28:29], v[54:55], v[34:35] op_sel_hi:[1,0]
	v_pk_mul_f32 v[26:27], v[52:53], v[34:35] op_sel_hi:[1,0]
	v_pk_mul_f32 v[32:33], v[58:59], v[34:35] op_sel_hi:[1,0]
	v_pk_mul_f32 v[30:31], v[56:57], v[34:35] op_sel_hi:[1,0]
	v_pk_mul_f32 v[70:71], v[62:63], v[34:35] op_sel_hi:[1,0]
	v_pk_mul_f32 v[68:69], v[60:61], v[34:35] op_sel_hi:[1,0]
	v_pk_mul_f32 v[74:75], v[66:67], v[34:35] op_sel_hi:[1,0]
	v_pk_mul_f32 v[72:73], v[64:65], v[34:35] op_sel_hi:[1,0]
.LBB0_883:
	v_add_f32_e32 v34, -4.0, v202
	v_sub_f32_e32 v2, v2, v34
	v_sub_f32_e32 v6, v6, v34
	v_sub_f32_e32 v3, v3, v34
	v_sub_f32_e32 v7, v7, v34
	v_exp_f32_e32 v2, v2
	v_exp_f32_e32 v6, v6
	v_exp_f32_e32 v3, v3
	v_exp_f32_e32 v7, v7
	v_sub_f32_e32 v4, v4, v34
	v_sub_f32_e32 v8, v8, v34
	v_sub_f32_e32 v5, v5, v34
	v_sub_f32_e32 v9, v9, v34
	v_exp_f32_e32 v4, v4
	v_exp_f32_e32 v8, v8
	v_exp_f32_e32 v5, v5
	v_exp_f32_e32 v9, v9
	v_cndmask_b32_e64 v34, 0, v2, s[10:11]
	v_cndmask_b32_e64 v6, 0, v6, s[10:11]
	v_cndmask_b32_e64 v35, 0, v3, s[10:11]
	v_cndmask_b32_e64 v7, 0, v7, s[10:11]
	v_mov_b32_e32 v2, v1
	v_mov_b32_e32 v3, v1
	v_cvt_pk_fp8_f32 v2, v34, v35
	v_cvt_pk_fp8_f32 v3, v6, v7
	v_cndmask_b32_e64 v4, 0, v4, s[10:11]
	v_cndmask_b32_e64 v205, 0, v8, s[10:11]
	v_cndmask_b32_e64 v5, 0, v5, s[10:11]
	v_cndmask_b32_e64 v229, 0, v9, s[10:11]
	v_add_f32_e32 v6, v34, v6
	v_cvt_pk_fp8_f32 v2, v4, v5 op_sel:[0,0,1]
	v_cvt_pk_fp8_f32 v3, v205, v229 op_sel:[0,0,1]
	v_add_f32_e32 v6, 0, v6
	v_add_f32_e32 v7, v35, v7
	v_add_f32_e32 v6, v7, v6
	v_add_f32_e32 v4, v4, v205
	v_add_f32_e32 v4, v4, v6
	v_add_f32_e32 v5, v5, v229
	v_add_f32_e32 v4, v5, v4
	s_waitcnt vmcnt(19)
	v_mfma_f32_16x16x32_fp8_fp8 v[8:11], v[170:171], v[2:3], v[10:13]
	v_add_f32_e32 v133, v133, v4
	s_mov_b64 s[10:11], 0
	v_mfma_f32_16x16x32_fp8_fp8 v[12:15], v[172:173], v[2:3], v[14:17]
	s_waitcnt vmcnt(18)
	v_mfma_f32_16x16x32_fp8_fp8 v[16:19], v[174:175], v[2:3], v[18:21]
	v_mfma_f32_16x16x32_fp8_fp8 v[20:23], v[176:177], v[2:3], v[22:25]
	s_waitcnt vmcnt(17)
	v_mfma_f32_16x16x32_fp8_fp8 v[24:27], v[178:179], v[2:3], v[26:29]
	v_mfma_f32_16x16x32_fp8_fp8 v[32:35], v[180:181], v[2:3], v[30:33]
	s_waitcnt vmcnt(16)
	v_mfma_f32_16x16x32_fp8_fp8 v[28:31], v[182:183], v[2:3], v[68:71]
	v_mfma_f32_16x16x32_fp8_fp8 v[4:7], v[184:185], v[2:3], v[72:75]
	s_nop 1
; template <bool SLC, bool NOMASK> ...
;     const int kq = lane >> 4;
;     const int pos0 = SLC ? (dcur & 0xfffff) : dcur;
;     const int lo = SLC ? ((((dcur >> 20) == qi) | ((dcur >> 20) == 4)) ? 0 : (1 << 30)) : lo_in;
;     load_frag8(nxt, KF, VF, SLC ? (dnext & 0xfffff) : dnext, lane);
;     f32x4 sa[2] = {(f32x4){0.f, 0.f, 0.f, 0.f}, (f32x4){0.f, 0.f, 0.f, 0.f}};
; #pragma unroll
;     for (int T = 0; T < 2; ++T)
; #pragma unroll
;         for (int s2 = 0; s2 < 4; ++s2) sa[T] = __builtin_amdgcn_mfma_f32_16x16x32_fp8_fp8(cur.k[T][s2], qf[s2], sa[T], 0, 0, 0);
;     float sc[8]; bool vd[8]; float mx = -1e30f;
;     const bool act = lo == 0 || !SLC;
;     if (NOMASK) {
; #pragma unroll
;         for (int j = 0; j < 8; ++j) { sc[j] = sa[j >> 2][j & 3]; vd[j] = act; }
;         mx = fmaxf(fmaxf(fmaxf(sc[0], sc[1]), fmaxf(sc[2], sc[3])), fmaxf(fmaxf(sc[4], sc[5]), fmaxf(sc[6], sc[7])));
;         mx = act ? mx : -1e30f;
;     } else {
; #pragma unroll
;         for (int T = 0; T < 2; ++T)
; #pragma unroll
;             for (int r = 0; r < 4; ++r) { const int p = pos0 + 16 * T + 4 * kq + r; const bool v = (p >= lo) & (p <= hi); const float x = sa[T][r];
;                 sc[4 * T + r] = x; vd[4 * T + r] = v; mx = v ? fmaxf(mx, x) : mx; }
;     }
;     if (__builtin_amdgcn_ballot_w64(mx > st.m + 4.f) != 0ull) {
;         mx = fmaxf(mx, __shfl_xor(mx, 16)); mx = fmaxf(mx, __shfl_xor(mx, 32));
;         const float mn = fmaxf(st.m, mx), alpha = __builtin_amdgcn_exp2f(st.m - mn); st.m = mn; st.l *= alpha;
; #pragma unroll
;         for (int j = 0; j < 8; ++j) st.o[j] = st.o[j] * alpha;
;     }
;     f32x4 pa, pb; float ps = 0.f;
;     const float mref = st.m - 4.f;
;     if (NOMASK) {
; #pragma unroll
;         for (int j = 0; j < 4; ++j) { pa[j] = __builtin_amdgcn_exp2f(sc[j] - mref); pb[j] = __builtin_amdgcn_exp2f(sc[4 + j] - mref); }
;         if (SLC) {
; #pragma unroll
;             for (int j = 0; j < 4; ++j) { pa[j] = act ? pa[j] : 0.f; pb[j] = act ? pb[j] : 0.f; }
;         }
; #pragma unroll
;         for (int j = 0; j < 4; ++j) ps += pa[j] + pb[j];
;     } else {
; #pragma unroll
;         for (int j = 0; j < 4; ++j) { pa[j] = vd[j] ? __builtin_amdgcn_exp2f(sc[j] - mref) : 0.f; pb[j] = vd[4 + j] ? __builtin_amdgcn_exp2f(sc[4 + j] - mref) : 0.f; ps += pa[j] + pb[j]; }
;     }
;     st.l += ps;
;     const u32x2 pw = pack8_fp8(pa, pb);
.LBB0_884:
	s_and_b64 vcc, exec, s[10:11]
	s_cbranch_vccz .LBB0_888
	s_cmp_eq_u32 s12, 4
	s_cselect_b64 s[10:11], -1, 0
	s_lshl_b32 s13, s97, 7
	s_and_b32 s50, s13, 0x7fff800
	v_lshl_add_u64 v[10:11], v[86:87], 0, s[50:51]
	s_and_b32 s50, s13, 0x7fff000
	v_lshl_add_u64 v[244:245], v[10:11], 0, v[118:119]
	global_load_dwordx4 v[154:157], v[244:245], off
	global_load_dwordx4 v[158:161], v[244:245], off offset:1024
	global_load_dwordx4 v[162:165], v[244:245], off offset:2048
	global_load_dwordx4 v[166:169], v[244:245], off offset:3072
	v_lshl_add_u64 v[10:11], v[88:89], 0, s[50:51]
	v_lshl_add_u64 v[246:247], v[10:11], 0, v[118:119]
	global_load_dwordx4 v[106:109], v[246:247], off
	global_load_dwordx4 v[110:113], v[246:247], off offset:1024
	global_load_dwordx4 v[114:117], v[246:247], off offset:2048
	global_load_dwordx4 v[134:137], v[246:247], off offset:3072
	s_waitcnt vmcnt(20)
	v_mfma_f32_16x16x32_fp8_fp8 v[2:5], v[186:187], v[78:79], 0
	s_and_b32 s13, s66, 0xfffff
	v_cmp_eq_u32_e32 vcc, s12, v209
	v_add_u32_e32 v10, s13, v211
	v_mfma_f32_16x16x32_fp8_fp8 v[2:5], v[188:189], v[80:81], v[2:5]
	s_or_b64 s[18:19], s[10:11], vcc
	v_cmp_le_i32_e32 vcc, v10, v132
	s_and_b64 s[16:17], s[18:19], vcc
	v_mfma_f32_16x16x32_fp8_fp8 v[2:5], v[190:191], v[82:83], v[2:5]
	v_cmp_lt_i32_e32 vcc, v10, v132
	s_and_b64 s[12:13], s[18:19], vcc
	v_mfma_f32_16x16x32_fp8_fp8 v[6:9], v[194:195], v[78:79], 0
	v_mfma_f32_16x16x32_fp8_fp8 v[2:5], v[192:193], v[84:85], v[2:5]
	v_mfma_f32_16x16x32_fp8_fp8 v[6:9], v[196:197], v[80:81], v[6:9]
	v_mfma_f32_16x16x32_fp8_fp8 v[6:9], v[198:199], v[82:83], v[6:9]
	s_nop 5
	v_max_f32_e32 v11, v2, v2
	v_max_f32_e32 v11, 0xf149f2ca, v11
	v_cndmask_b32_e64 v11, v223, v11, s[16:17]
	v_max_f32_e32 v12, v3, v3
	v_max_f32_e32 v12, v11, v12
	v_cndmask_b32_e64 v11, v11, v12, s[12:13]
	v_add_u32_e32 v12, 2, v10
	v_cmp_le_i32_e32 vcc, v12, v132
	v_max_f32_e32 v12, v4, v4
	v_max_f32_e32 v12, v11, v12
	s_and_b64 s[14:15], s[18:19], vcc
	v_mfma_f32_16x16x32_fp8_fp8 v[6:9], v[200:201], v[84:85], v[6:9]
	v_cndmask_b32_e64 v11, v11, v12, s[14:15]
	v_add_u32_e32 v12, 3, v10
	v_cmp_le_i32_e32 vcc, v12, v132
	v_max_f32_e32 v12, v5, v5
	v_max_f32_e32 v12, v11, v12
	s_and_b64 s[10:11], s[18:19], vcc
	v_cndmask_b32_e64 v11, v11, v12, s[10:11]
	v_add_u32_e32 v12, 16, v10
	v_cmp_le_i32_e32 vcc, v12, v132
	v_max_f32_e32 v12, v6, v6
	v_max_f32_e32 v12, v11, v12
	s_and_b64 s[24:25], s[18:19], vcc
	v_cndmask_b32_e64 v11, v11, v12, s[24:25]
	v_add_u32_e32 v12, 17, v10
	v_cmp_le_i32_e32 vcc, v12, v132
	v_max_f32_e32 v12, v11, v11
	v_max_f32_e32 v13, v7, v7
	v_max_f32_e32 v12, v12, v13
	s_and_b64 s[20:21], s[18:19], vcc
	v_cndmask_b32_e64 v11, v11, v12, s[20:21]
	v_add_u32_e32 v12, 18, v10
	v_cmp_le_i32_e32 vcc, v12, v132
	v_max_f32_e32 v12, v11, v11
	v_max_f32_e32 v13, v8, v8
	v_max_f32_e32 v12, v12, v13
	s_and_b64 s[22:23], s[18:19], vcc
	v_cndmask_b32_e64 v11, v11, v12, s[22:23]
	v_add_u32_e32 v10, 19, v10
	v_cmp_le_i32_e32 vcc, v10, v132
	v_max_f32_e32 v10, v11, v11
	v_max_f32_e32 v12, v9, v9
	v_max_f32_e32 v10, v10, v12
	s_and_b64 s[18:19], s[18:19], vcc
	v_cndmask_b32_e64 v10, v11, v10, s[18:19]
	v_cmp_gt_f32_e32 vcc, v10, v0
	s_cbranch_vccz .LBB0_887
	ds_bpermute_b32 v0, v227, v10
	v_max_f32_e32 v10, v10, v10
	s_waitcnt lgkmcnt(0)
	v_max_f32_e32 v0, v0, v0
	v_max_f32_e32 v0, v10, v0
	ds_bpermute_b32 v10, v226, v0
	s_waitcnt lgkmcnt(0)
	v_max3_f32 v10, v203, v0, v10
	v_sub_f32_e32 v0, v203, v10
	v_exp_f32_e32 v0, v0
	v_mov_b32_e32 v203, v10
	v_mul_f32_e32 v204, v204, v0
	v_pk_mul_f32 v[38:39], v[38:39], v[0:1] op_sel_hi:[1,0]
	v_pk_mul_f32 v[36:37], v[36:37], v[0:1] op_sel_hi:[1,0]
	v_pk_mul_f32 v[42:43], v[42:43], v[0:1] op_sel_hi:[1,0]
	v_pk_mul_f32 v[40:41], v[40:41], v[0:1] op_sel_hi:[1,0]
	v_pk_mul_f32 v[46:47], v[46:47], v[0:1] op_sel_hi:[1,0]
	v_pk_mul_f32 v[44:45], v[44:45], v[0:1] op_sel_hi:[1,0]
	v_pk_mul_f32 v[50:51], v[50:51], v[0:1] op_sel_hi:[1,0]
	v_pk_mul_f32 v[48:49], v[48:49], v[0:1] op_sel_hi:[1,0]
	v_pk_mul_f32 v[54:55], v[54:55], v[0:1] op_sel_hi:[1,0]
	v_pk_mul_f32 v[52:53], v[52:53], v[0:1] op_sel_hi:[1,0]
	v_pk_mul_f32 v[58:59], v[58:59], v[0:1] op_sel_hi:[1,0]
	v_pk_mul_f32 v[56:57], v[56:57], v[0:1] op_sel_hi:[1,0]
	v_pk_mul_f32 v[62:63], v[62:63], v[0:1] op_sel_hi:[1,0]
	v_pk_mul_f32 v[60:61], v[60:61], v[0:1] op_sel_hi:[1,0]
	v_pk_mul_f32 v[66:67], v[66:67], v[0:1] op_sel_hi:[1,0]
	v_pk_mul_f32 v[64:65], v[64:65], v[0:1] op_sel_hi:[1,0]
.LBB0_887:
	v_add_f32_e32 v0, -4.0, v203
	v_sub_f32_e32 v2, v2, v0
	v_exp_f32_e32 v2, v2
	v_sub_f32_e32 v6, v6, v0
	v_exp_f32_e32 v6, v6
	v_sub_f32_e32 v4, v4, v0
	v_cndmask_b32_e64 v28, 0, v2, s[16:17]
	v_sub_f32_e32 v2, v3, v0
	v_exp_f32_e32 v2, v2
	v_sub_f32_e32 v3, v7, v0
	v_exp_f32_e32 v3, v3
	v_sub_f32_e32 v7, v8, v0
	v_cndmask_b32_e64 v29, 0, v2, s[12:13]
	v_sub_f32_e32 v2, v5, v0
	v_sub_f32_e32 v0, v9, v0
	v_cndmask_b32_e64 v6, 0, v6, s[24:25]
	v_exp_f32_e32 v4, v4
	v_exp_f32_e32 v7, v7
	v_cndmask_b32_e64 v30, 0, v3, s[20:21]
	v_exp_f32_e32 v5, v2
	v_exp_f32_e32 v0, v0
	v_mov_b32_e32 v2, v1
	v_mov_b32_e32 v3, v1
	v_cvt_pk_fp8_f32 v2, v28, v29
	v_cvt_pk_fp8_f32 v3, v6, v30
	v_cndmask_b32_e64 v4, 0, v4, s[14:15]
	v_cndmask_b32_e64 v7, 0, v7, s[22:23]
	v_cndmask_b32_e64 v5, 0, v5, s[10:11]
	v_cndmask_b32_e64 v0, 0, v0, s[18:19]
	v_cvt_pk_fp8_f32 v2, v4, v5 op_sel:[0,0,1]
	v_cvt_pk_fp8_f32 v3, v7, v0 op_sel:[0,0,1]
	v_add_f32_e32 v6, v28, v6
	v_add_f32_e32 v6, 0, v6
	v_add_f32_e32 v28, v29, v30
	v_add_f32_e32 v6, v28, v6
	v_add_f32_e32 v4, v4, v7
	v_add_f32_e32 v4, v4, v6
	v_add_f32_e32 v0, v5, v0
	s_waitcnt vmcnt(19)
	v_mfma_f32_16x16x32_fp8_fp8 v[8:11], v[170:171], v[2:3], v[36:39]
	v_add_f32_e32 v0, v0, v4
	v_add_f32_e32 v133, v204, v0
	v_mov_b32_e32 v202, v203
	v_mfma_f32_16x16x32_fp8_fp8 v[12:15], v[172:173], v[2:3], v[40:43]
	s_waitcnt vmcnt(18)
	v_mfma_f32_16x16x32_fp8_fp8 v[16:19], v[174:175], v[2:3], v[44:47]
	v_mfma_f32_16x16x32_fp8_fp8 v[20:23], v[176:177], v[2:3], v[48:51]
	s_waitcnt vmcnt(17)
	v_mfma_f32_16x16x32_fp8_fp8 v[24:27], v[178:179], v[2:3], v[52:55]
	v_mfma_f32_16x16x32_fp8_fp8 v[32:35], v[180:181], v[2:3], v[56:59]
	s_waitcnt vmcnt(16)
	v_mfma_f32_16x16x32_fp8_fp8 v[28:31], v[182:183], v[2:3], v[60:63]
	v_mfma_f32_16x16x32_fp8_fp8 v[4:7], v[184:185], v[2:3], v[64:67]
	s_nop 1

; template <bool SLC, bool NOMASK> ...
;     const int kq = lane >> 4;
;     const int pos0 = SLC ? (dcur & 0xfffff) : dcur;
;     const int lo = SLC ? ((((dcur >> 20) == qi) | ((dcur >> 20) == 4)) ? 0 : (1 << 30)) : lo_in;
;     load_frag8(nxt, KF, VF, SLC ? (dnext & 0xfffff) : dnext, lane);
;     f32x4 sa[2] = {(f32x4){0.f, 0.f, 0.f, 0.f}, (f32x4){0.f, 0.f, 0.f, 0.f}};
; #pragma unroll
;     for (int T = 0; T < 2; ++T)
; #pragma unroll
;         for (int s2 = 0; s2 < 4; ++s2) sa[T] = __builtin_amdgcn_mfma_f32_16x16x32_fp8_fp8(cur.k[T][s2], qf[s2], sa[T], 0, 0, 0);
;     float sc[8]; bool vd[8]; float mx = -1e30f;
;     const bool act = lo == 0 || !SLC;
;     if (NOMASK) {
; #pragma unroll
;         for (int j = 0; j < 8; ++j) { sc[j] = sa[j >> 2][j & 3]; vd[j] = act; }
;         mx = fmaxf(fmaxf(fmaxf(sc[0], sc[1]), fmaxf(sc[2], sc[3])), fmaxf(fmaxf(sc[4], sc[5]), fmaxf(sc[6], sc[7])));
;         mx = act ? mx : -1e30f;
;     } else {
; #pragma unroll
;         for (int T = 0; T < 2; ++T)
; #pragma unroll
;             for (int r = 0; r < 4; ++r) { const int p = pos0 + 16 * T + 4 * kq + r; const bool v = (p >= lo) & (p <= hi); const float x = sa[T][r];
;                 sc[4 * T + r] = x; vd[4 * T + r] = v; mx = v ? fmaxf(mx, x) : mx; }
;     }
;     if (__builtin_amdgcn_ballot_w64(mx > st.m + 4.f) != 0ull) {
;         mx = fmaxf(mx, __shfl_xor(mx, 16)); mx = fmaxf(mx, __shfl_xor(mx, 32));
;         const float mn = fmaxf(st.m, mx), alpha = __builtin_amdgcn_exp2f(st.m - mn); st.m = mn; st.l *= alpha;
; #pragma unroll
;         for (int j = 0; j < 8; ++j) st.o[j] = st.o[j] * alpha;
;     }
;     f32x4 pa, pb; float ps = 0.f;
;     const float mref = st.m - 4.f;
;     if (NOMASK) {
; #pragma unroll
;         for (int j = 0; j < 4; ++j) { pa[j] = __builtin_amdgcn_exp2f(sc[j] - mref); pb[j] = __builtin_amdgcn_exp2f(sc[4 + j] - mref); }
;         if (SLC) {
; #pragma unroll
;             for (int j = 0; j < 4; ++j) { pa[j] = act ? pa[j] : 0.f; pb[j] = act ? pb[j] : 0.f; }
;         }
; #pragma unroll
;         for (int j = 0; j < 4; ++j) ps += pa[j] + pb[j];
;     } else {
; #pragma unroll
;         for (int j = 0; j < 4; ++j) { pa[j] = vd[j] ? __builtin_amdgcn_exp2f(sc[j] - mref) : 0.f; pb[j] = vd[4 + j] ? __builtin_amdgcn_exp2f(sc[4 + j] - mref) : 0.f; ps += pa[j] + pb[j]; }
;     }
;     st.l += ps;
;     const u32x2 pw = pack8_fp8(pa, pb);
.LBB0_900:
	v_lshl_add_u64 v[244:245], v[204:205], 0, v[118:119]
	global_load_dwordx4 v[186:189], v[244:245], off
	global_load_dwordx4 v[190:193], v[244:245], off offset:1024
	global_load_dwordx4 v[194:197], v[244:245], off offset:2048
	global_load_dwordx4 v[198:201], v[244:245], off offset:3072
	v_lshl_add_u64 v[246:247], v[202:203], 0, v[118:119]
	global_load_dwordx4 v[170:173], v[246:247], off
	global_load_dwordx4 v[174:177], v[246:247], off offset:1024
	global_load_dwordx4 v[178:181], v[246:247], off offset:2048
	global_load_dwordx4 v[182:185], v[246:247], off offset:3072
	s_waitcnt vmcnt(20)
	v_mfma_f32_16x16x32_fp8_fp8 v[2:5], v[138:139], v[78:79], 0
	v_mov_b64_e32 v[74:75], v[38:39]
	v_mov_b64_e32 v[70:71], v[42:43]
	v_mov_b64_e32 v[30:31], v[44:45]
	v_mfma_f32_16x16x32_fp8_fp8 v[6:9], v[146:147], v[78:79], 0
	v_mov_b64_e32 v[26:27], v[48:49]
	v_mov_b64_e32 v[22:23], v[52:53]
	v_mov_b64_e32 v[18:19], v[56:57]
	v_mfma_f32_16x16x32_fp8_fp8 v[2:5], v[140:141], v[80:81], v[2:5]
	v_mov_b64_e32 v[14:15], v[60:61]
	v_mov_b32_e32 v229, v133
	v_mov_b64_e32 v[72:73], v[36:37]
	v_mfma_f32_16x16x32_fp8_fp8 v[6:9], v[148:149], v[80:81], v[6:9]
	v_mov_b64_e32 v[68:69], v[40:41]
	v_mov_b64_e32 v[32:33], v[46:47]
	v_mov_b64_e32 v[28:29], v[50:51]
	v_mfma_f32_16x16x32_fp8_fp8 v[2:5], v[142:143], v[82:83], v[2:5]
	v_mov_b64_e32 v[24:25], v[54:55]
	v_mov_b64_e32 v[20:21], v[58:59]
	v_mov_b64_e32 v[16:17], v[62:63]
	v_mfma_f32_16x16x32_fp8_fp8 v[6:9], v[150:151], v[82:83], v[6:9]
	v_mov_b32_e32 v34, v230
	v_mfma_f32_16x16x32_fp8_fp8 v[2:5], v[144:145], v[84:85], v[2:5]
	v_mfma_f32_16x16x32_fp8_fp8 v[6:9], v[152:153], v[84:85], v[6:9]
	s_nop 6
	v_max_f32_e32 v0, v3, v3
	v_max_f32_e32 v10, v2, v2
	v_max_f32_e32 v0, v10, v0
	v_max_f32_e32 v10, v5, v5
	v_max_f32_e32 v11, v4, v4
	v_max_f32_e32 v10, v11, v10
	v_max_f32_e32 v11, v9, v9
	v_max_f32_e32 v12, v8, v8
	v_max_f32_e32 v11, v12, v11
	v_max3_f32 v11, v6, v7, v11
	v_max3_f32 v0, v0, v10, v11
	v_mov_b64_e32 v[10:11], v[64:65]
	v_cmp_gt_f32_e32 vcc, v0, v231
	v_mov_b64_e32 v[12:13], v[66:67]
	s_cbranch_vccz .LBB0_902
	ds_bpermute_b32 v10, v227, v0
	v_max_f32_e32 v0, v0, v0
	s_waitcnt lgkmcnt(0)
	v_max_f32_e32 v10, v10, v10
	v_max_f32_e32 v0, v0, v10
	ds_bpermute_b32 v10, v226, v0
	s_waitcnt lgkmcnt(0)
	v_max3_f32 v229, v133, v0, v10
	v_sub_f32_e32 v0, v133, v229
	v_exp_f32_e32 v0, v0
	s_nop 0
	v_mul_f32_e32 v34, v230, v0
	v_pk_mul_f32 v[12:13], v[66:67], v[0:1] op_sel_hi:[1,0]
	v_pk_mul_f32 v[10:11], v[64:65], v[0:1] op_sel_hi:[1,0]
	v_pk_mul_f32 v[16:17], v[62:63], v[0:1] op_sel_hi:[1,0]
	v_pk_mul_f32 v[14:15], v[60:61], v[0:1] op_sel_hi:[1,0]
	v_pk_mul_f32 v[20:21], v[58:59], v[0:1] op_sel_hi:[1,0]
	v_pk_mul_f32 v[18:19], v[56:57], v[0:1] op_sel_hi:[1,0]
	v_pk_mul_f32 v[24:25], v[54:55], v[0:1] op_sel_hi:[1,0]
	v_pk_mul_f32 v[22:23], v[52:53], v[0:1] op_sel_hi:[1,0]
	v_pk_mul_f32 v[28:29], v[50:51], v[0:1] op_sel_hi:[1,0]
	v_pk_mul_f32 v[26:27], v[48:49], v[0:1] op_sel_hi:[1,0]
	v_pk_mul_f32 v[32:33], v[46:47], v[0:1] op_sel_hi:[1,0]
	v_pk_mul_f32 v[30:31], v[44:45], v[0:1] op_sel_hi:[1,0]
	v_pk_mul_f32 v[70:71], v[42:43], v[0:1] op_sel_hi:[1,0]
	v_pk_mul_f32 v[68:69], v[40:41], v[0:1] op_sel_hi:[1,0]
	v_pk_mul_f32 v[74:75], v[38:39], v[0:1] op_sel_hi:[1,0]
	v_pk_mul_f32 v[72:73], v[36:37], v[0:1] op_sel_hi:[1,0]
.LBB0_902:
	v_add_f32_e32 v232, -4.0, v229
	v_sub_f32_e32 v0, v2, v232
	v_exp_f32_e32 v233, v0
	v_sub_f32_e32 v0, v6, v232
	v_exp_f32_e32 v236, v0
	v_sub_f32_e32 v0, v3, v232
	v_exp_f32_e32 v2, v0
	v_sub_f32_e32 v0, v7, v232
	v_exp_f32_e32 v0, v0
	v_sub_f32_e32 v3, v4, v232
	v_exp_f32_e32 v237, v3
	v_sub_f32_e32 v3, v8, v232
	v_exp_f32_e32 v238, v3
	v_sub_f32_e32 v3, v5, v232
	v_exp_f32_e32 v4, v3
	v_sub_f32_e32 v3, v9, v232
	v_mov_b32_e32 v234, v1
	v_mov_b32_e32 v235, v1
	v_exp_f32_e32 v232, v3
	v_cvt_pk_fp8_f32 v234, v233, v2
	v_cvt_pk_fp8_f32 v235, v236, v0
	v_add_f32_e32 v3, v233, v236
	v_pk_add_f32 v[2:3], v[2:3], v[0:1]
	v_cvt_pk_fp8_f32 v234, v237, v4 op_sel:[0,0,1]
	v_cvt_pk_fp8_f32 v235, v238, v232 op_sel:[0,0,1]
	v_pk_add_f32 v[2:3], v[2:3], v[2:3] op_sel_hi:[0,1]
	v_add_f32_e32 v5, v237, v238
	v_mov_b32_e32 v233, v3
	v_pk_add_f32 v[2:3], v[4:5], v[232:233]
	s_waitcnt vmcnt(19)
	v_mfma_f32_16x16x32_fp8_fp8 v[6:9], v[90:91], v[234:235], v[10:13]
	v_add_f32_e32 v0, v2, v3
	v_add_f32_e32 v34, v0, v34
	v_mfma_f32_16x16x32_fp8_fp8 v[10:13], v[92:93], v[234:235], v[14:17]
	s_waitcnt vmcnt(18)
	v_mfma_f32_16x16x32_fp8_fp8 v[14:17], v[94:95], v[234:235], v[18:21]
	v_mfma_f32_16x16x32_fp8_fp8 v[18:21], v[96:97], v[234:235], v[22:25]
	s_waitcnt vmcnt(17)
	v_mfma_f32_16x16x32_fp8_fp8 v[22:25], v[98:99], v[234:235], v[26:29]
	v_mfma_f32_16x16x32_fp8_fp8 v[26:29], v[100:101], v[234:235], v[30:33]
	s_waitcnt vmcnt(16)
	v_mfma_f32_16x16x32_fp8_fp8 v[30:33], v[102:103], v[234:235], v[68:71]
	v_mfma_f32_16x16x32_fp8_fp8 v[2:5], v[104:105], v[234:235], v[72:75]
	s_nop 1
	s_branch .LBB0_896
; template <bool SLC, bool NOMASK> ...
;     const int kq = lane >> 4;
;     const int pos0 = SLC ? (dcur & 0xfffff) : dcur;
;     const int lo = SLC ? ((((dcur >> 20) == qi) | ((dcur >> 20) == 4)) ? 0 : (1 << 30)) : lo_in;
;     load_frag8(nxt, KF, VF, SLC ? (dnext & 0xfffff) : dnext, lane);
;     f32x4 sa[2] = {(f32x4){0.f, 0.f, 0.f, 0.f}, (f32x4){0.f, 0.f, 0.f, 0.f}};
; #pragma unroll
;     for (int T = 0; T < 2; ++T)
; #pragma unroll
;         for (int s2 = 0; s2 < 4; ++s2) sa[T] = __builtin_amdgcn_mfma_f32_16x16x32_fp8_fp8(cur.k[T][s2], qf[s2], sa[T], 0, 0, 0);
;     float sc[8]; bool vd[8]; float mx = -1e30f;
;     const bool act = lo == 0 || !SLC;
;     if (NOMASK) {
; #pragma unroll
;         for (int j = 0; j < 8; ++j) { sc[j] = sa[j >> 2][j & 3]; vd[j] = act; }
;         mx = fmaxf(fmaxf(fmaxf(sc[0], sc[1]), fmaxf(sc[2], sc[3])), fmaxf(fmaxf(sc[4], sc[5]), fmaxf(sc[6], sc[7])));
;         mx = act ? mx : -1e30f;
;     } else {
; #pragma unroll
;         for (int T = 0; T < 2; ++T)
; #pragma unroll
;             for (int r = 0; r < 4; ++r) { const int p = pos0 + 16 * T + 4 * kq + r; const bool v = (p >= lo) & (p <= hi); const float x = sa[T][r];
;                 sc[4 * T + r] = x; vd[4 * T + r] = v; mx = v ? fmaxf(mx, x) : mx; }
;     }
;     if (__builtin_amdgcn_ballot_w64(mx > st.m + 4.f) != 0ull) {
;         mx = fmaxf(mx, __shfl_xor(mx, 16)); mx = fmaxf(mx, __shfl_xor(mx, 32));
;         const float mn = fmaxf(st.m, mx), alpha = __builtin_amdgcn_exp2f(st.m - mn); st.m = mn; st.l *= alpha;
; #pragma unroll
;         for (int j = 0; j < 8; ++j) st.o[j] = st.o[j] * alpha;
;     }
;     f32x4 pa, pb; float ps = 0.f;
;     const float mref = st.m - 4.f;
;     if (NOMASK) {
; #pragma unroll
;         for (int j = 0; j < 4; ++j) { pa[j] = __builtin_amdgcn_exp2f(sc[j] - mref); pb[j] = __builtin_amdgcn_exp2f(sc[4 + j] - mref); }
;         if (SLC) {
; #pragma unroll
;             for (int j = 0; j < 4; ++j) { pa[j] = act ? pa[j] : 0.f; pb[j] = act ? pb[j] : 0.f; }
;         }
; #pragma unroll
;         for (int j = 0; j < 4; ++j) ps += pa[j] + pb[j];
;     } else {
; #pragma unroll
;         for (int j = 0; j < 4; ++j) { pa[j] = vd[j] ? __builtin_amdgcn_exp2f(sc[j] - mref) : 0.f; pb[j] = vd[4 + j] ? __builtin_amdgcn_exp2f(sc[4 + j] - mref) : 0.f; ps += pa[j] + pb[j]; }
;     }
;     st.l += ps;
;     const u32x2 pw = pack8_fp8(pa, pb);
.LBB0_903:
	v_lshl_add_u64 v[244:245], v[204:205], 0, v[118:119]
	global_load_dwordx4 v[186:189], v[244:245], off
	global_load_dwordx4 v[190:193], v[244:245], off offset:1024
	global_load_dwordx4 v[194:197], v[244:245], off offset:2048
	global_load_dwordx4 v[198:201], v[244:245], off offset:3072
	v_lshl_add_u64 v[246:247], v[202:203], 0, v[118:119]
	global_load_dwordx4 v[170:173], v[246:247], off
	global_load_dwordx4 v[174:177], v[246:247], off offset:1024
	global_load_dwordx4 v[178:181], v[246:247], off offset:2048
	global_load_dwordx4 v[182:185], v[246:247], off offset:3072
	s_waitcnt vmcnt(20)
	v_mfma_f32_16x16x32_fp8_fp8 v[2:5], v[138:139], v[78:79], 0
	v_add_u32_e32 v0, s14, v211
	v_cmp_ge_i32_e32 vcc, v0, v35
	v_cmp_le_i32_e64 s[10:11], v0, v132
	v_mfma_f32_16x16x32_fp8_fp8 v[2:5], v[140:141], v[80:81], v[2:5]
	s_and_b64 s[16:17], vcc, s[10:11]
	v_add_u32_e32 v11, 1, v0
	v_cmp_ge_i32_e32 vcc, v11, v35
	v_mfma_f32_16x16x32_fp8_fp8 v[2:5], v[142:143], v[82:83], v[2:5]
	v_cmp_lt_i32_e64 s[10:11], v0, v132
	s_and_b64 s[12:13], s[10:11], vcc
	v_mfma_f32_16x16x32_fp8_fp8 v[6:9], v[146:147], v[78:79], 0
	v_mfma_f32_16x16x32_fp8_fp8 v[2:5], v[144:145], v[84:85], v[2:5]
	v_mfma_f32_16x16x32_fp8_fp8 v[6:9], v[148:149], v[80:81], v[6:9]
	v_mfma_f32_16x16x32_fp8_fp8 v[6:9], v[150:151], v[82:83], v[6:9]
	s_nop 5
	v_max_f32_e32 v10, v2, v2
	v_max_f32_e32 v10, 0xf149f2ca, v10
	v_cndmask_b32_e64 v10, v223, v10, s[16:17]
	v_max_f32_e32 v11, v3, v3
	v_max_f32_e32 v11, v10, v11
	v_cndmask_b32_e64 v10, v10, v11, s[12:13]
	v_add_u32_e32 v11, 2, v0
	v_cmp_ge_i32_e32 vcc, v11, v35
	v_cmp_le_i32_e64 s[10:11], v11, v132
	v_max_f32_e32 v11, v4, v4
	v_max_f32_e32 v11, v10, v11
	s_and_b64 s[14:15], vcc, s[10:11]
	v_mfma_f32_16x16x32_fp8_fp8 v[6:9], v[152:153], v[84:85], v[6:9]
	v_cndmask_b32_e64 v10, v10, v11, s[14:15]
	v_add_u32_e32 v11, 3, v0
	v_cmp_ge_i32_e32 vcc, v11, v35
	v_cmp_le_i32_e64 s[10:11], v11, v132
	v_max_f32_e32 v11, v5, v5
	v_max_f32_e32 v11, v10, v11
	s_and_b64 s[10:11], vcc, s[10:11]
	v_cndmask_b32_e64 v10, v10, v11, s[10:11]
	v_add_u32_e32 v11, 16, v0
	v_cmp_ge_i32_e32 vcc, v11, v35
	v_cmp_le_i32_e64 s[18:19], v11, v132
	v_max_f32_e32 v11, v6, v6
	v_max_f32_e32 v11, v10, v11
	s_and_b64 s[24:25], vcc, s[18:19]
	v_cndmask_b32_e64 v10, v10, v11, s[24:25]
	v_add_u32_e32 v11, 17, v0
	v_cmp_ge_i32_e32 vcc, v11, v35
	v_cmp_le_i32_e64 s[18:19], v11, v132
	v_max_f32_e32 v11, v10, v10
	v_max_f32_e32 v12, v7, v7
	v_max_f32_e32 v11, v11, v12
	s_and_b64 s[20:21], vcc, s[18:19]
	v_cndmask_b32_e64 v10, v10, v11, s[20:21]
	v_add_u32_e32 v11, 18, v0
	v_cmp_ge_i32_e32 vcc, v11, v35
	v_cmp_le_i32_e64 s[18:19], v11, v132
	v_max_f32_e32 v11, v10, v10
	v_max_f32_e32 v12, v8, v8
	v_max_f32_e32 v11, v11, v12
	s_and_b64 s[22:23], vcc, s[18:19]
	v_cndmask_b32_e64 v10, v10, v11, s[22:23]
	v_add_u32_e32 v0, 19, v0
	v_cmp_ge_i32_e32 vcc, v0, v35
	v_cmp_le_i32_e64 s[18:19], v0, v132
	v_max_f32_e32 v0, v10, v10
	v_max_f32_e32 v11, v9, v9
	v_max_f32_e32 v0, v0, v11
	s_and_b64 s[18:19], vcc, s[18:19]
	v_cndmask_b32_e64 v0, v10, v0, s[18:19]
	v_cmp_gt_f32_e32 vcc, v0, v231
	s_cbranch_vccz .LBB0_905
	ds_bpermute_b32 v10, v227, v0
	v_max_f32_e32 v0, v0, v0
	s_waitcnt lgkmcnt(0)
	v_max_f32_e32 v10, v10, v10
	v_max_f32_e32 v0, v0, v10
	ds_bpermute_b32 v10, v226, v0
	s_waitcnt lgkmcnt(0)
	v_max3_f32 v10, v133, v0, v10
	v_sub_f32_e32 v0, v133, v10
	v_exp_f32_e32 v0, v0
	v_mov_b32_e32 v133, v10
	v_mul_f32_e32 v230, v230, v0
	v_pk_mul_f32 v[66:67], v[66:67], v[0:1] op_sel_hi:[1,0]
	v_pk_mul_f32 v[64:65], v[64:65], v[0:1] op_sel_hi:[1,0]
	v_pk_mul_f32 v[62:63], v[62:63], v[0:1] op_sel_hi:[1,0]
	v_pk_mul_f32 v[60:61], v[60:61], v[0:1] op_sel_hi:[1,0]
	v_pk_mul_f32 v[58:59], v[58:59], v[0:1] op_sel_hi:[1,0]
	v_pk_mul_f32 v[56:57], v[56:57], v[0:1] op_sel_hi:[1,0]
	v_pk_mul_f32 v[54:55], v[54:55], v[0:1] op_sel_hi:[1,0]
	v_pk_mul_f32 v[52:53], v[52:53], v[0:1] op_sel_hi:[1,0]
	v_pk_mul_f32 v[50:51], v[50:51], v[0:1] op_sel_hi:[1,0]
	v_pk_mul_f32 v[48:49], v[48:49], v[0:1] op_sel_hi:[1,0]
	v_pk_mul_f32 v[46:47], v[46:47], v[0:1] op_sel_hi:[1,0]
	v_pk_mul_f32 v[44:45], v[44:45], v[0:1] op_sel_hi:[1,0]
	v_pk_mul_f32 v[42:43], v[42:43], v[0:1] op_sel_hi:[1,0]
	v_pk_mul_f32 v[40:41], v[40:41], v[0:1] op_sel_hi:[1,0]
	v_pk_mul_f32 v[38:39], v[38:39], v[0:1] op_sel_hi:[1,0]
	v_pk_mul_f32 v[36:37], v[36:37], v[0:1] op_sel_hi:[1,0]
.LBB0_905:
	v_add_f32_e32 v0, -4.0, v133
	v_sub_f32_e32 v2, v2, v0
	v_exp_f32_e32 v2, v2
	v_sub_f32_e32 v6, v6, v0
	v_exp_f32_e32 v6, v6
	v_sub_f32_e32 v4, v4, v0
	v_cndmask_b32_e64 v26, 0, v2, s[16:17]
	v_sub_f32_e32 v2, v3, v0
	v_exp_f32_e32 v2, v2
	v_sub_f32_e32 v3, v7, v0
	v_exp_f32_e32 v3, v3
	v_cndmask_b32_e64 v27, 0, v6, s[24:25]
	v_sub_f32_e32 v6, v8, v0
	v_cndmask_b32_e64 v28, 0, v2, s[12:13]
	v_sub_f32_e32 v2, v5, v0
	v_sub_f32_e32 v0, v9, v0
	v_exp_f32_e32 v4, v4
	v_exp_f32_e32 v6, v6
	v_cndmask_b32_e64 v29, 0, v3, s[20:21]
	v_exp_f32_e32 v5, v2
	v_exp_f32_e32 v0, v0
	v_mov_b32_e32 v2, v1
	v_mov_b32_e32 v3, v1
	v_cvt_pk_fp8_f32 v2, v26, v28
	v_cvt_pk_fp8_f32 v3, v27, v29
	v_cndmask_b32_e64 v4, 0, v4, s[14:15]
	v_cndmask_b32_e64 v30, 0, v6, s[22:23]
	v_cndmask_b32_e64 v5, 0, v5, s[10:11]
	v_cndmask_b32_e64 v0, 0, v0, s[18:19]
	v_cvt_pk_fp8_f32 v2, v4, v5 op_sel:[0,0,1]
	v_cvt_pk_fp8_f32 v3, v30, v0 op_sel:[0,0,1]
	v_add_f32_e32 v26, v26, v27
	v_add_f32_e32 v31, 0, v26
	v_add_f32_e32 v32, v28, v29
	v_add_f32_e32 v31, v32, v31
	v_add_f32_e32 v4, v4, v30
	v_add_f32_e32 v4, v4, v31
	v_add_f32_e32 v0, v5, v0
	s_waitcnt vmcnt(19)
	v_mfma_f32_16x16x32_fp8_fp8 v[6:9], v[90:91], v[2:3], v[64:67]
	v_add_f32_e32 v0, v0, v4
	v_add_f32_e32 v34, v230, v0
	v_mov_b32_e32 v229, v133
	v_mfma_f32_16x16x32_fp8_fp8 v[10:13], v[92:93], v[2:3], v[60:63]
	s_waitcnt vmcnt(18)
	v_mfma_f32_16x16x32_fp8_fp8 v[14:17], v[94:95], v[2:3], v[56:59]
	v_mfma_f32_16x16x32_fp8_fp8 v[18:21], v[96:97], v[2:3], v[52:55]
	s_waitcnt vmcnt(17)
	v_mfma_f32_16x16x32_fp8_fp8 v[22:25], v[98:99], v[2:3], v[48:51]
	v_mfma_f32_16x16x32_fp8_fp8 v[26:29], v[100:101], v[2:3], v[44:47]
	s_waitcnt vmcnt(16)
	v_mfma_f32_16x16x32_fp8_fp8 v[30:33], v[102:103], v[2:3], v[40:43]
	v_mfma_f32_16x16x32_fp8_fp8 v[2:5], v[104:105], v[2:3], v[36:39]
	s_nop 1
	s_cmp_ge_i32 s58, s27
	s_mov_b64 s[10:11], -1
	s_cbranch_scc0 .LBB0_897

; template <bool SLC, bool NOMASK> ...
;     const int kq = lane >> 4;
;     const int pos0 = SLC ? (dcur & 0xfffff) : dcur;
;     const int lo = SLC ? ((((dcur >> 20) == qi) | ((dcur >> 20) == 4)) ? 0 : (1 << 30)) : lo_in;
;     load_frag8(nxt, KF, VF, SLC ? (dnext & 0xfffff) : dnext, lane);
;     f32x4 sa[2] = {(f32x4){0.f, 0.f, 0.f, 0.f}, (f32x4){0.f, 0.f, 0.f, 0.f}};
; #pragma unroll
;     for (int T = 0; T < 2; ++T)
; #pragma unroll
;         for (int s2 = 0; s2 < 4; ++s2) sa[T] = __builtin_amdgcn_mfma_f32_16x16x32_fp8_fp8(cur.k[T][s2], qf[s2], sa[T], 0, 0, 0);
;     float sc[8]; bool vd[8]; float mx = -1e30f;
;     const bool act = lo == 0 || !SLC;
;     if (NOMASK) {
; #pragma unroll
;         for (int j = 0; j < 8; ++j) { sc[j] = sa[j >> 2][j & 3]; vd[j] = act; }
;         mx = fmaxf(fmaxf(fmaxf(sc[0], sc[1]), fmaxf(sc[2], sc[3])), fmaxf(fmaxf(sc[4], sc[5]), fmaxf(sc[6], sc[7])));
;         mx = act ? mx : -1e30f;
;     } else {
; #pragma unroll
;         for (int T = 0; T < 2; ++T)
; #pragma unroll
;             for (int r = 0; r < 4; ++r) { const int p = pos0 + 16 * T + 4 * kq + r; const bool v = (p >= lo) & (p <= hi); const float x = sa[T][r];
;                 sc[4 * T + r] = x; vd[4 * T + r] = v; mx = v ? fmaxf(mx, x) : mx; }
;     }
;     if (__builtin_amdgcn_ballot_w64(mx > st.m + 4.f) != 0ull) {
;         mx = fmaxf(mx, __shfl_xor(mx, 16)); mx = fmaxf(mx, __shfl_xor(mx, 32));
;         const float mn = fmaxf(st.m, mx), alpha = __builtin_amdgcn_exp2f(st.m - mn); st.m = mn; st.l *= alpha;
; #pragma unroll
;         for (int j = 0; j < 8; ++j) st.o[j] = st.o[j] * alpha;
;     }
;     f32x4 pa, pb; float ps = 0.f;
;     const float mref = st.m - 4.f;
;     if (NOMASK) {
; #pragma unroll
;         for (int j = 0; j < 4; ++j) { pa[j] = __builtin_amdgcn_exp2f(sc[j] - mref); pb[j] = __builtin_amdgcn_exp2f(sc[4 + j] - mref); }
;         if (SLC) {
; #pragma unroll
;             for (int j = 0; j < 4; ++j) { pa[j] = act ? pa[j] : 0.f; pb[j] = act ? pb[j] : 0.f; }
;         }
; #pragma unroll
;         for (int j = 0; j < 4; ++j) ps += pa[j] + pb[j];
;     } else {
; #pragma unroll
;         for (int j = 0; j < 4; ++j) { pa[j] = vd[j] ? __builtin_amdgcn_exp2f(sc[j] - mref) : 0.f; pb[j] = vd[4 + j] ? __builtin_amdgcn_exp2f(sc[4 + j] - mref) : 0.f; ps += pa[j] + pb[j]; }
;     }
;     st.l += ps;
;     const u32x2 pw = pack8_fp8(pa, pb);
.LBB0_907:
	v_lshl_add_u64 v[244:245], v[204:205], 0, v[118:119]
	global_load_dwordx4 v[138:141], v[244:245], off
	global_load_dwordx4 v[142:145], v[244:245], off offset:1024
	global_load_dwordx4 v[146:149], v[244:245], off offset:2048
	global_load_dwordx4 v[150:153], v[244:245], off offset:3072
	v_lshl_add_u64 v[246:247], v[202:203], 0, v[118:119]
	global_load_dwordx4 v[90:93], v[246:247], off
	global_load_dwordx4 v[94:97], v[246:247], off offset:1024
	global_load_dwordx4 v[98:101], v[246:247], off offset:2048
	global_load_dwordx4 v[102:105], v[246:247], off offset:3072
	s_waitcnt vmcnt(20)
	v_mfma_f32_16x16x32_fp8_fp8 v[36:39], v[154:155], v[78:79], 0
	v_mov_b64_e32 v[74:75], v[4:5]
	v_mov_b64_e32 v[70:71], v[32:33]
	v_mov_b64_e32 v[66:67], v[28:29]
	v_mfma_f32_16x16x32_fp8_fp8 v[40:43], v[162:163], v[78:79], 0
	v_mov_b64_e32 v[62:63], v[24:25]
	v_mov_b64_e32 v[58:59], v[20:21]
	v_mov_b64_e32 v[54:55], v[16:17]
	v_mfma_f32_16x16x32_fp8_fp8 v[36:39], v[156:157], v[80:81], v[36:39]
	v_mov_b64_e32 v[50:51], v[12:13]
	v_mov_b32_e32 v230, v229
	v_mov_b64_e32 v[72:73], v[2:3]
	v_mfma_f32_16x16x32_fp8_fp8 v[40:43], v[164:165], v[80:81], v[40:43]
	v_mov_b64_e32 v[68:69], v[30:31]
	v_mov_b64_e32 v[64:65], v[26:27]
	v_mov_b64_e32 v[60:61], v[22:23]
	v_mfma_f32_16x16x32_fp8_fp8 v[36:39], v[158:159], v[82:83], v[36:39]
	v_mov_b64_e32 v[56:57], v[18:19]
	v_mov_b64_e32 v[52:53], v[14:15]
	v_mov_b64_e32 v[48:49], v[10:11]
	v_mfma_f32_16x16x32_fp8_fp8 v[40:43], v[166:167], v[82:83], v[40:43]
	v_mov_b32_e32 v231, v34
	v_mfma_f32_16x16x32_fp8_fp8 v[36:39], v[160:161], v[84:85], v[36:39]
	v_mfma_f32_16x16x32_fp8_fp8 v[40:43], v[168:169], v[84:85], v[40:43]
	s_nop 6
	v_max_f32_e32 v0, v37, v37
	v_max_f32_e32 v44, v36, v36
	v_max_f32_e32 v0, v44, v0
	v_max_f32_e32 v44, v39, v39
	v_max_f32_e32 v45, v38, v38
	v_max_f32_e32 v44, v45, v44
	v_max_f32_e32 v45, v43, v43
	v_max_f32_e32 v46, v42, v42
	v_max_f32_e32 v45, v46, v45
	v_max3_f32 v45, v40, v41, v45
	v_max3_f32 v0, v0, v44, v45
	v_mov_b64_e32 v[46:47], v[8:9]
	v_cmp_gt_f32_e32 vcc, v0, v133
	v_mov_b64_e32 v[44:45], v[6:7]
	s_cbranch_vccz .LBB0_909
	ds_bpermute_b32 v44, v227, v0
	v_max_f32_e32 v0, v0, v0
	s_waitcnt lgkmcnt(0)
	v_max_f32_e32 v44, v44, v44
	v_max_f32_e32 v0, v0, v44
	ds_bpermute_b32 v44, v226, v0
	s_waitcnt lgkmcnt(0)
	v_max3_f32 v230, v229, v0, v44
	v_sub_f32_e32 v0, v229, v230
	v_exp_f32_e32 v0, v0
	s_nop 0
	v_mul_f32_e32 v231, v34, v0
	v_pk_mul_f32 v[46:47], v[8:9], v[0:1] op_sel_hi:[1,0]
	v_pk_mul_f32 v[44:45], v[6:7], v[0:1] op_sel_hi:[1,0]
	v_pk_mul_f32 v[50:51], v[12:13], v[0:1] op_sel_hi:[1,0]
	v_pk_mul_f32 v[48:49], v[10:11], v[0:1] op_sel_hi:[1,0]
	v_pk_mul_f32 v[54:55], v[16:17], v[0:1] op_sel_hi:[1,0]
	v_pk_mul_f32 v[52:53], v[14:15], v[0:1] op_sel_hi:[1,0]
	v_pk_mul_f32 v[58:59], v[20:21], v[0:1] op_sel_hi:[1,0]
	v_pk_mul_f32 v[56:57], v[18:19], v[0:1] op_sel_hi:[1,0]
	v_pk_mul_f32 v[62:63], v[24:25], v[0:1] op_sel_hi:[1,0]
	v_pk_mul_f32 v[60:61], v[22:23], v[0:1] op_sel_hi:[1,0]
	v_pk_mul_f32 v[66:67], v[28:29], v[0:1] op_sel_hi:[1,0]
	v_pk_mul_f32 v[64:65], v[26:27], v[0:1] op_sel_hi:[1,0]
	v_pk_mul_f32 v[70:71], v[32:33], v[0:1] op_sel_hi:[1,0]
	v_pk_mul_f32 v[68:69], v[30:31], v[0:1] op_sel_hi:[1,0]
	v_pk_mul_f32 v[74:75], v[4:5], v[0:1] op_sel_hi:[1,0]
	v_pk_mul_f32 v[72:73], v[2:3], v[0:1] op_sel_hi:[1,0]
.LBB0_909:
	v_add_f32_e32 v233, -4.0, v230
	v_sub_f32_e32 v0, v36, v233
	v_exp_f32_e32 v235, v0
	v_sub_f32_e32 v0, v40, v233
	v_exp_f32_e32 v237, v0
	v_sub_f32_e32 v0, v37, v233
	v_exp_f32_e32 v232, v0
	v_sub_f32_e32 v0, v41, v233
	v_exp_f32_e32 v0, v0
	v_sub_f32_e32 v36, v38, v233
	v_exp_f32_e32 v240, v36
	v_sub_f32_e32 v36, v42, v233
	v_exp_f32_e32 v241, v36
	v_sub_f32_e32 v36, v39, v233
	v_exp_f32_e32 v234, v36
	v_sub_f32_e32 v36, v43, v233
	v_mov_b32_e32 v238, v1
	v_mov_b32_e32 v239, v1
	v_exp_f32_e32 v236, v36
	v_cvt_pk_fp8_f32 v238, v235, v232
	v_cvt_pk_fp8_f32 v239, v237, v0
	v_add_f32_e32 v233, v235, v237
	v_add_f32_e32 v235, v240, v241
	v_cvt_pk_fp8_f32 v238, v240, v234 op_sel:[0,0,1]
	v_cvt_pk_fp8_f32 v239, v241, v236 op_sel:[0,0,1]
	s_nop 0
	s_waitcnt vmcnt(19)
	v_mfma_f32_16x16x32_fp8_fp8 v[36:39], v[106:107], v[238:239], v[44:47]
	v_mfma_f32_16x16x32_fp8_fp8 v[44:47], v[110:111], v[238:239], v[52:55]
	s_waitcnt vmcnt(18)
	v_mfma_f32_16x16x32_fp8_fp8 v[52:55], v[114:115], v[238:239], v[60:63]
	s_nop 2
	v_add_f32_e64 v60, v232, v0
	v_add_f32_e64 v61, v233, v1
	v_mfma_f32_16x16x32_fp8_fp8 v[40:43], v[108:109], v[238:239], v[48:51]
	v_pk_add_f32 v[60:61], v[60:61], v[60:61] op_sel_hi:[0,1]
	v_mov_b32_e32 v237, v61
	s_waitcnt vmcnt(17)
	v_mfma_f32_16x16x32_fp8_fp8 v[48:51], v[112:113], v[238:239], v[56:59]
	v_mfma_f32_16x16x32_fp8_fp8 v[56:59], v[116:117], v[238:239], v[64:67]
	s_nop 2
	v_add_f32_e64 v64, v234, v236
	v_add_f32_e64 v65, v235, v237
	s_waitcnt vmcnt(16)
	v_mfma_f32_16x16x32_fp8_fp8 v[60:63], v[134:135], v[238:239], v[68:71]
	v_add_f32_e32 v0, v64, v65
	v_add_f32_e32 v231, v0, v231
	v_mfma_f32_16x16x32_fp8_fp8 v[64:67], v[136:137], v[238:239], v[72:75]
	s_nop 1
	s_branch .LBB0_899
; template <bool SLC, bool NOMASK> ...
;     const int kq = lane >> 4;
;     const int pos0 = SLC ? (dcur & 0xfffff) : dcur;
;     const int lo = SLC ? ((((dcur >> 20) == qi) | ((dcur >> 20) == 4)) ? 0 : (1 << 30)) : lo_in;
;     load_frag8(nxt, KF, VF, SLC ? (dnext & 0xfffff) : dnext, lane);
;     f32x4 sa[2] = {(f32x4){0.f, 0.f, 0.f, 0.f}, (f32x4){0.f, 0.f, 0.f, 0.f}};
; #pragma unroll
;     for (int T = 0; T < 2; ++T)
; #pragma unroll
;         for (int s2 = 0; s2 < 4; ++s2) sa[T] = __builtin_amdgcn_mfma_f32_16x16x32_fp8_fp8(cur.k[T][s2], qf[s2], sa[T], 0, 0, 0);
;     float sc[8]; bool vd[8]; float mx = -1e30f;
;     const bool act = lo == 0 || !SLC;
;     if (NOMASK) {
; #pragma unroll
;         for (int j = 0; j < 8; ++j) { sc[j] = sa[j >> 2][j & 3]; vd[j] = act; }
;         mx = fmaxf(fmaxf(fmaxf(sc[0], sc[1]), fmaxf(sc[2], sc[3])), fmaxf(fmaxf(sc[4], sc[5]), fmaxf(sc[6], sc[7])));
;         mx = act ? mx : -1e30f;
;     } else {
; #pragma unroll
;         for (int T = 0; T < 2; ++T)
; #pragma unroll
;             for (int r = 0; r < 4; ++r) { const int p = pos0 + 16 * T + 4 * kq + r; const bool v = (p >= lo) & (p <= hi); const float x = sa[T][r];
;                 sc[4 * T + r] = x; vd[4 * T + r] = v; mx = v ? fmaxf(mx, x) : mx; }
;     }
;     if (__builtin_amdgcn_ballot_w64(mx > st.m + 4.f) != 0ull) {
;         mx = fmaxf(mx, __shfl_xor(mx, 16)); mx = fmaxf(mx, __shfl_xor(mx, 32));
;         const float mn = fmaxf(st.m, mx), alpha = __builtin_amdgcn_exp2f(st.m - mn); st.m = mn; st.l *= alpha;
; #pragma unroll
;         for (int j = 0; j < 8; ++j) st.o[j] = st.o[j] * alpha;
;     }
;     f32x4 pa, pb; float ps = 0.f;
;     const float mref = st.m - 4.f;
;     if (NOMASK) {
; #pragma unroll
;         for (int j = 0; j < 4; ++j) { pa[j] = __builtin_amdgcn_exp2f(sc[j] - mref); pb[j] = __builtin_amdgcn_exp2f(sc[4 + j] - mref); }
;         if (SLC) {
; #pragma unroll
;             for (int j = 0; j < 4; ++j) { pa[j] = act ? pa[j] : 0.f; pb[j] = act ? pb[j] : 0.f; }
;         }
; #pragma unroll
;         for (int j = 0; j < 4; ++j) ps += pa[j] + pb[j];
;     } else {
; #pragma unroll
;         for (int j = 0; j < 4; ++j) { pa[j] = vd[j] ? __builtin_amdgcn_exp2f(sc[j] - mref) : 0.f; pb[j] = vd[4 + j] ? __builtin_amdgcn_exp2f(sc[4 + j] - mref) : 0.f; ps += pa[j] + pb[j]; }
;     }
;     st.l += ps;
;     const u32x2 pw = pack8_fp8(pa, pb);
.LBB0_910:
	v_lshl_add_u64 v[244:245], v[204:205], 0, v[118:119]
	global_load_dwordx4 v[138:141], v[244:245], off
	global_load_dwordx4 v[142:145], v[244:245], off offset:1024
	global_load_dwordx4 v[146:149], v[244:245], off offset:2048
	global_load_dwordx4 v[150:153], v[244:245], off offset:3072
	v_lshl_add_u64 v[246:247], v[202:203], 0, v[118:119]
	global_load_dwordx4 v[90:93], v[246:247], off
	global_load_dwordx4 v[94:97], v[246:247], off offset:1024
	global_load_dwordx4 v[98:101], v[246:247], off offset:2048
	global_load_dwordx4 v[102:105], v[246:247], off offset:3072
	s_waitcnt vmcnt(20)
	v_mfma_f32_16x16x32_fp8_fp8 v[36:39], v[154:155], v[78:79], 0
	v_add_u32_e32 v0, s66, v211
	v_cmp_ge_i32_e32 vcc, v0, v35
	v_cmp_le_i32_e64 s[10:11], v0, v132
	v_mfma_f32_16x16x32_fp8_fp8 v[36:39], v[156:157], v[80:81], v[36:39]
	s_and_b64 s[16:17], vcc, s[10:11]
	v_add_u32_e32 v45, 1, v0
	v_cmp_ge_i32_e32 vcc, v45, v35
	v_mfma_f32_16x16x32_fp8_fp8 v[36:39], v[158:159], v[82:83], v[36:39]
	v_cmp_lt_i32_e64 s[10:11], v0, v132
	s_and_b64 s[12:13], s[10:11], vcc
	v_mfma_f32_16x16x32_fp8_fp8 v[40:43], v[162:163], v[78:79], 0
	v_mfma_f32_16x16x32_fp8_fp8 v[36:39], v[160:161], v[84:85], v[36:39]
	v_mfma_f32_16x16x32_fp8_fp8 v[40:43], v[164:165], v[80:81], v[40:43]
	v_mfma_f32_16x16x32_fp8_fp8 v[40:43], v[166:167], v[82:83], v[40:43]
	s_nop 5
	v_max_f32_e32 v44, v36, v36
	v_max_f32_e32 v44, 0xf149f2ca, v44
	v_cndmask_b32_e64 v44, v223, v44, s[16:17]
	v_max_f32_e32 v45, v37, v37
	v_max_f32_e32 v45, v44, v45
	v_cndmask_b32_e64 v44, v44, v45, s[12:13]
	v_add_u32_e32 v45, 2, v0
	v_cmp_ge_i32_e32 vcc, v45, v35
	v_cmp_le_i32_e64 s[10:11], v45, v132
	v_max_f32_e32 v45, v38, v38
	v_max_f32_e32 v45, v44, v45
	s_and_b64 s[14:15], vcc, s[10:11]
	v_mfma_f32_16x16x32_fp8_fp8 v[40:43], v[168:169], v[84:85], v[40:43]
	v_cndmask_b32_e64 v44, v44, v45, s[14:15]
	v_add_u32_e32 v45, 3, v0
	v_cmp_ge_i32_e32 vcc, v45, v35
	v_cmp_le_i32_e64 s[10:11], v45, v132
	v_max_f32_e32 v45, v39, v39
	v_max_f32_e32 v45, v44, v45
	s_and_b64 s[10:11], vcc, s[10:11]
	v_cndmask_b32_e64 v44, v44, v45, s[10:11]
	v_add_u32_e32 v45, 16, v0
	v_cmp_ge_i32_e32 vcc, v45, v35
	v_cmp_le_i32_e64 s[18:19], v45, v132
	v_max_f32_e32 v45, v40, v40
	v_max_f32_e32 v45, v44, v45
	s_and_b64 s[24:25], vcc, s[18:19]
	v_cndmask_b32_e64 v44, v44, v45, s[24:25]
	v_add_u32_e32 v45, 17, v0
	v_cmp_ge_i32_e32 vcc, v45, v35
	v_cmp_le_i32_e64 s[18:19], v45, v132
	v_max_f32_e32 v45, v44, v44
	v_max_f32_e32 v46, v41, v41
	v_max_f32_e32 v45, v45, v46
	s_and_b64 s[20:21], vcc, s[18:19]
	v_cndmask_b32_e64 v44, v44, v45, s[20:21]
	v_add_u32_e32 v45, 18, v0
	v_cmp_ge_i32_e32 vcc, v45, v35
	v_cmp_le_i32_e64 s[18:19], v45, v132
	v_max_f32_e32 v45, v44, v44
	v_max_f32_e32 v46, v42, v42
	v_max_f32_e32 v45, v45, v46
	s_and_b64 s[22:23], vcc, s[18:19]
	v_cndmask_b32_e64 v44, v44, v45, s[22:23]
	v_add_u32_e32 v0, 19, v0
	v_cmp_ge_i32_e32 vcc, v0, v35
	v_cmp_le_i32_e64 s[18:19], v0, v132
	v_max_f32_e32 v0, v44, v44
	v_max_f32_e32 v45, v43, v43
	v_max_f32_e32 v0, v0, v45
	s_and_b64 s[18:19], vcc, s[18:19]
	v_cndmask_b32_e64 v0, v44, v0, s[18:19]
	v_cmp_gt_f32_e32 vcc, v0, v133
	s_cbranch_vccz .LBB0_912
	ds_bpermute_b32 v44, v227, v0
	v_max_f32_e32 v0, v0, v0
	s_waitcnt lgkmcnt(0)
	v_max_f32_e32 v44, v44, v44
	v_max_f32_e32 v0, v0, v44
	ds_bpermute_b32 v44, v226, v0
	s_waitcnt lgkmcnt(0)
	v_max3_f32 v44, v229, v0, v44
	v_sub_f32_e32 v0, v229, v44
	v_exp_f32_e32 v0, v0
	v_mov_b32_e32 v229, v44
	v_mul_f32_e32 v34, v34, v0
	v_pk_mul_f32 v[8:9], v[8:9], v[0:1] op_sel_hi:[1,0]
	v_pk_mul_f32 v[6:7], v[6:7], v[0:1] op_sel_hi:[1,0]
	v_pk_mul_f32 v[12:13], v[12:13], v[0:1] op_sel_hi:[1,0]
	v_pk_mul_f32 v[10:11], v[10:11], v[0:1] op_sel_hi:[1,0]
	v_pk_mul_f32 v[16:17], v[16:17], v[0:1] op_sel_hi:[1,0]
	v_pk_mul_f32 v[14:15], v[14:15], v[0:1] op_sel_hi:[1,0]
	v_pk_mul_f32 v[20:21], v[20:21], v[0:1] op_sel_hi:[1,0]
	v_pk_mul_f32 v[18:19], v[18:19], v[0:1] op_sel_hi:[1,0]
	v_pk_mul_f32 v[24:25], v[24:25], v[0:1] op_sel_hi:[1,0]
	v_pk_mul_f32 v[22:23], v[22:23], v[0:1] op_sel_hi:[1,0]
	v_pk_mul_f32 v[28:29], v[28:29], v[0:1] op_sel_hi:[1,0]
	v_pk_mul_f32 v[26:27], v[26:27], v[0:1] op_sel_hi:[1,0]
	v_pk_mul_f32 v[32:33], v[32:33], v[0:1] op_sel_hi:[1,0]
	v_pk_mul_f32 v[30:31], v[30:31], v[0:1] op_sel_hi:[1,0]
	v_pk_mul_f32 v[4:5], v[4:5], v[0:1] op_sel_hi:[1,0]
	v_pk_mul_f32 v[2:3], v[2:3], v[0:1] op_sel_hi:[1,0]
.LBB0_912:
	v_add_f32_e32 v0, -4.0, v229
	v_sub_f32_e32 v36, v36, v0
	v_exp_f32_e32 v36, v36
	v_sub_f32_e32 v40, v40, v0
	v_exp_f32_e32 v40, v40
	v_sub_f32_e32 v38, v38, v0
	v_cndmask_b32_e64 v56, 0, v36, s[16:17]
	v_sub_f32_e32 v36, v37, v0
	v_exp_f32_e32 v36, v36
	v_sub_f32_e32 v37, v41, v0
	v_exp_f32_e32 v37, v37
	v_cndmask_b32_e64 v57, 0, v40, s[24:25]
	v_sub_f32_e32 v40, v42, v0
	v_cndmask_b32_e64 v58, 0, v36, s[12:13]
	v_sub_f32_e32 v36, v39, v0
	v_sub_f32_e32 v0, v43, v0
	v_exp_f32_e32 v38, v38
	v_exp_f32_e32 v40, v40
	v_cndmask_b32_e64 v59, 0, v37, s[20:21]
	v_exp_f32_e32 v36, v36
	v_exp_f32_e32 v0, v0
	v_mov_b32_e32 v64, v1
	v_mov_b32_e32 v65, v1
	v_cvt_pk_fp8_f32 v64, v56, v58
	v_cvt_pk_fp8_f32 v65, v57, v59
	v_cndmask_b32_e64 v60, 0, v38, s[14:15]
	v_cndmask_b32_e64 v61, 0, v40, s[22:23]
	v_cndmask_b32_e64 v66, 0, v36, s[10:11]
	v_cndmask_b32_e64 v0, 0, v0, s[18:19]
	v_cvt_pk_fp8_f32 v64, v60, v66 op_sel:[0,0,1]
	v_cvt_pk_fp8_f32 v65, v61, v0 op_sel:[0,0,1]
	v_add_f32_e32 v0, v66, v0
	v_mov_b32_e32 v230, v229
	s_waitcnt vmcnt(19)
	v_mfma_f32_16x16x32_fp8_fp8 v[36:39], v[106:107], v[64:65], v[6:9]
	s_nop 2
	v_add_f32_e32 v6, v56, v57
	v_add_f32_e32 v6, 0, v6
	v_add_f32_e32 v7, v58, v59
	v_mfma_f32_16x16x32_fp8_fp8 v[40:43], v[108:109], v[64:65], v[10:13]
	v_add_f32_e32 v6, v7, v6
	v_add_f32_e32 v7, v60, v61
	v_add_f32_e32 v6, v7, v6
	s_waitcnt vmcnt(18)
	v_mfma_f32_16x16x32_fp8_fp8 v[44:47], v[110:111], v[64:65], v[14:17]
	v_add_f32_e32 v0, v0, v6
	v_add_f32_e32 v231, v34, v0
	v_mfma_f32_16x16x32_fp8_fp8 v[48:51], v[112:113], v[64:65], v[18:21]
	s_waitcnt vmcnt(17)
	v_mfma_f32_16x16x32_fp8_fp8 v[52:55], v[114:115], v[64:65], v[22:25]
	v_mfma_f32_16x16x32_fp8_fp8 v[56:59], v[116:117], v[64:65], v[26:29]
	s_waitcnt vmcnt(16)
	v_mfma_f32_16x16x32_fp8_fp8 v[60:63], v[134:135], v[64:65], v[30:33]
	v_mfma_f32_16x16x32_fp8_fp8 v[64:67], v[136:137], v[64:65], v[2:5]
	s_nop 1
	s_cmp_gt_i32 s57, s27
	s_mov_b64 s[10:11], -1
	s_cbranch_scc1 .LBB0_892
; template <bool SLC, bool NOMASK> ...
;     const int kq = lane >> 4;
;     const int pos0 = SLC ? (dcur & 0xfffff) : dcur;
;     const int lo = SLC ? ((((dcur >> 20) == qi) | ((dcur >> 20) == 4)) ? 0 : (1 << 30)) : lo_in;
;     load_frag8(nxt, KF, VF, SLC ? (dnext & 0xfffff) : dnext, lane);
;     f32x4 sa[2] = {(f32x4){0.f, 0.f, 0.f, 0.f}, (f32x4){0.f, 0.f, 0.f, 0.f}};
; #pragma unroll
;     for (int T = 0; T < 2; ++T)
; #pragma unroll
;         for (int s2 = 0; s2 < 4; ++s2) sa[T] = __builtin_amdgcn_mfma_f32_16x16x32_fp8_fp8(cur.k[T][s2], qf[s2], sa[T], 0, 0, 0);
;     float sc[8]; bool vd[8]; float mx = -1e30f;
;     const bool act = lo == 0 || !SLC;
;     if (NOMASK) {
; #pragma unroll
;         for (int j = 0; j < 8; ++j) { sc[j] = sa[j >> 2][j & 3]; vd[j] = act; }
;         mx = fmaxf(fmaxf(fmaxf(sc[0], sc[1]), fmaxf(sc[2], sc[3])), fmaxf(fmaxf(sc[4], sc[5]), fmaxf(sc[6], sc[7])));
;         mx = act ? mx : -1e30f;
;     } else {
; #pragma unroll
;         for (int T = 0; T < 2; ++T)
; #pragma unroll
;             for (int r = 0; r < 4; ++r) { const int p = pos0 + 16 * T + 4 * kq + r; const bool v = (p >= lo) & (p <= hi); const float x = sa[T][r];
;                 sc[4 * T + r] = x; vd[4 * T + r] = v; mx = v ? fmaxf(mx, x) : mx; }
;     }
;     if (__builtin_amdgcn_ballot_w64(mx > st.m + 4.f) != 0ull) {
; template <bool SLC, class Desc>
; __device__ __forceinline__ void attn_run_frag8(const i64_t (&qf)[4], const unsigned char* __restrict__ KF, const unsigned char* __restrict__ VF, const Desc& desc, int n,
;                                                int lo_in, int hi, int qi, AState& st, int lane) {
;     ...
; #pragma unroll 1
;     for (int i = 0; i < n; i += 3) {
;         const int d2 = desc(i + 2 < n ? i + 2 : n - 1);
;         F8_STEP(fa, fc, d0, d2);
;         if (i + 1 >= n) break;
;         const int d3 = desc(i + 3 < n ? i + 3 : n - 1);
;         F8_STEP(fb, fa, d1, d3);
;         if (i + 2 >= n) break;
;         const int d4 = desc(i + 4 < n ? i + 4 : n - 1);
;         F8_STEP(fc, fb, d2, d4);
;         d0 = d3; d1 = d4;
; __device__ __forceinline__ void nsa_unit(int unit, const bf16_t* proj, const bf16_t* kc, const bf16_t* vc, const bf16_t* gn, const float* cs, const float* sn, ...
;     ...
;       auto desc = [&](int i) { const int p0 = 32 * (first + i); return p0 | ((p0 >= t0 + 3 - 511 && p0 + 31 <= t0) ? (1 << 30) : 0); };
.LBB0_913:
	s_cmp_lt_i32 s59, s56
	s_cselect_b64 s[10:11], -1, 0
	s_or_b32 s12, s59, 31
	s_cmp_gt_i32 s12, s96
	s_cselect_b64 s[12:13], -1, 0
	s_or_b64 s[10:11], s[10:11], s[12:13]
	s_and_b64 s[10:11], s[10:11], exec
	s_cselect_b32 s10, 0, 2.0
	s_add_i32 s58, s58, 4
	s_or_b32 s14, s10, s59
	s_min_i32 s10, s58, s27
	s_add_i32 s12, s10, s26
	s_lshl_b32 s43, s12, 5
	s_and_b32 s10, s43, 0x3fffffe0
	s_lshr_b32 s50, s10, 4
	s_lshl_b64 s[10:11], s[50:51], 11
	s_and_b32 s50, s12, 0x1ffffff
	s_lshl_b64 s[12:13], s[50:51], 12
	s_cmp_lt_u32 s14, 2.0
	v_lshl_add_u64 v[204:205], v[86:87], 0, s[10:11]
	v_lshl_add_u64 v[202:203], v[88:89], 0, s[12:13]
	s_mov_b64 s[10:11], -1
	v_add_f32_e32 v229, 4.0, v230
	s_cbranch_scc1 .LBB0_917
	v_lshl_add_u64 v[244:245], v[204:205], 0, v[118:119]
	global_load_dwordx4 v[154:157], v[244:245], off
	global_load_dwordx4 v[158:161], v[244:245], off offset:1024
	global_load_dwordx4 v[162:165], v[244:245], off offset:2048
	global_load_dwordx4 v[166:169], v[244:245], off offset:3072
	v_lshl_add_u64 v[246:247], v[202:203], 0, v[118:119]
	global_load_dwordx4 v[106:109], v[246:247], off
	global_load_dwordx4 v[110:113], v[246:247], off offset:1024
	global_load_dwordx4 v[114:117], v[246:247], off offset:2048
	global_load_dwordx4 v[134:137], v[246:247], off offset:3072
	s_waitcnt vmcnt(20)
	v_mfma_f32_16x16x32_fp8_fp8 v[2:5], v[186:187], v[78:79], 0
	v_mov_b64_e32 v[74:75], v[66:67]
	v_mov_b64_e32 v[70:71], v[62:63]
	v_mov_b64_e32 v[30:31], v[56:57]
	v_mfma_f32_16x16x32_fp8_fp8 v[6:9], v[194:195], v[78:79], 0
	v_mov_b64_e32 v[26:27], v[52:53]
	v_mov_b64_e32 v[22:23], v[48:49]
	v_mov_b64_e32 v[18:19], v[44:45]
	v_mfma_f32_16x16x32_fp8_fp8 v[2:5], v[188:189], v[80:81], v[2:5]
	v_mov_b64_e32 v[14:15], v[40:41]
	v_mov_b32_e32 v133, v230
	v_mov_b64_e32 v[72:73], v[64:65]
	v_mfma_f32_16x16x32_fp8_fp8 v[6:9], v[196:197], v[80:81], v[6:9]
	v_mov_b64_e32 v[68:69], v[60:61]
	v_mov_b64_e32 v[32:33], v[58:59]
	v_mov_b64_e32 v[28:29], v[54:55]
	v_mfma_f32_16x16x32_fp8_fp8 v[2:5], v[190:191], v[82:83], v[2:5]
	v_mov_b64_e32 v[24:25], v[50:51]
	v_mov_b64_e32 v[20:21], v[46:47]
	v_mov_b64_e32 v[16:17], v[42:43]
	v_mfma_f32_16x16x32_fp8_fp8 v[6:9], v[198:199], v[82:83], v[6:9]
	v_mov_b32_e32 v34, v231
	v_mfma_f32_16x16x32_fp8_fp8 v[2:5], v[192:193], v[84:85], v[2:5]
	v_mfma_f32_16x16x32_fp8_fp8 v[6:9], v[200:201], v[84:85], v[6:9]
	s_nop 6
	v_max_f32_e32 v0, v3, v3
	v_max_f32_e32 v10, v2, v2
	v_max_f32_e32 v0, v10, v0
	v_max_f32_e32 v10, v5, v5
	v_max_f32_e32 v11, v4, v4
	v_max_f32_e32 v10, v11, v10
	v_max_f32_e32 v11, v9, v9
	v_max_f32_e32 v12, v8, v8
	v_max_f32_e32 v11, v12, v11
	v_max3_f32 v11, v6, v7, v11
	v_max3_f32 v0, v0, v10, v11
	v_mov_b64_e32 v[10:11], v[36:37]
	v_cmp_gt_f32_e32 vcc, v0, v229
	v_mov_b64_e32 v[12:13], v[38:39]
	s_cbranch_vccz .LBB0_916
	ds_bpermute_b32 v10, v227, v0
	v_max_f32_e32 v0, v0, v0
	s_waitcnt lgkmcnt(0)
	v_max_f32_e32 v10, v10, v10
	v_max_f32_e32 v0, v0, v10
	ds_bpermute_b32 v10, v226, v0
	s_waitcnt lgkmcnt(0)
	v_max3_f32 v133, v230, v0, v10
	v_sub_f32_e32 v0, v230, v133
	v_exp_f32_e32 v0, v0
	s_nop 0
	v_mul_f32_e32 v34, v231, v0
	v_pk_mul_f32 v[12:13], v[38:39], v[0:1] op_sel_hi:[1,0]
	v_pk_mul_f32 v[10:11], v[36:37], v[0:1] op_sel_hi:[1,0]
	v_pk_mul_f32 v[16:17], v[42:43], v[0:1] op_sel_hi:[1,0]
	v_pk_mul_f32 v[14:15], v[40:41], v[0:1] op_sel_hi:[1,0]
	v_pk_mul_f32 v[20:21], v[46:47], v[0:1] op_sel_hi:[1,0]
	v_pk_mul_f32 v[18:19], v[44:45], v[0:1] op_sel_hi:[1,0]
	v_pk_mul_f32 v[24:25], v[50:51], v[0:1] op_sel_hi:[1,0]
	v_pk_mul_f32 v[22:23], v[48:49], v[0:1] op_sel_hi:[1,0]
	v_pk_mul_f32 v[28:29], v[54:55], v[0:1] op_sel_hi:[1,0]
	v_pk_mul_f32 v[26:27], v[52:53], v[0:1] op_sel_hi:[1,0]
	v_pk_mul_f32 v[32:33], v[58:59], v[0:1] op_sel_hi:[1,0]
	v_pk_mul_f32 v[30:31], v[56:57], v[0:1] op_sel_hi:[1,0]
	v_pk_mul_f32 v[70:71], v[62:63], v[0:1] op_sel_hi:[1,0]
	v_pk_mul_f32 v[68:69], v[60:61], v[0:1] op_sel_hi:[1,0]
	v_pk_mul_f32 v[74:75], v[66:67], v[0:1] op_sel_hi:[1,0]
	v_pk_mul_f32 v[72:73], v[64:65], v[0:1] op_sel_hi:[1,0]
.LBB0_916:
	v_add_f32_e32 v232, -4.0, v133
	v_sub_f32_e32 v0, v2, v232
	v_exp_f32_e32 v233, v0
	v_sub_f32_e32 v0, v6, v232
	v_exp_f32_e32 v236, v0
	v_sub_f32_e32 v0, v3, v232
	v_exp_f32_e32 v2, v0
	v_sub_f32_e32 v0, v7, v232
	v_exp_f32_e32 v0, v0
	v_sub_f32_e32 v3, v4, v232
	v_exp_f32_e32 v237, v3
	v_sub_f32_e32 v3, v8, v232
	v_exp_f32_e32 v238, v3
	v_sub_f32_e32 v3, v5, v232
	v_exp_f32_e32 v4, v3
	v_sub_f32_e32 v3, v9, v232
	v_mov_b32_e32 v234, v1
	v_mov_b32_e32 v235, v1
	v_exp_f32_e32 v232, v3
	v_cvt_pk_fp8_f32 v234, v233, v2
	v_cvt_pk_fp8_f32 v235, v236, v0
	v_add_f32_e32 v3, v233, v236
	v_pk_add_f32 v[2:3], v[2:3], v[0:1]
	v_cvt_pk_fp8_f32 v234, v237, v4 op_sel:[0,0,1]
	v_cvt_pk_fp8_f32 v235, v238, v232 op_sel:[0,0,1]
	v_pk_add_f32 v[2:3], v[2:3], v[2:3] op_sel_hi:[0,1]
	v_add_f32_e32 v5, v237, v238
	v_mov_b32_e32 v233, v3
	v_pk_add_f32 v[2:3], v[4:5], v[232:233]
	s_waitcnt vmcnt(19)
	v_mfma_f32_16x16x32_fp8_fp8 v[6:9], v[170:171], v[234:235], v[10:13]
	v_add_f32_e32 v0, v2, v3
	v_add_f32_e32 v34, v0, v34
	s_mov_b64 s[10:11], 0
	v_mfma_f32_16x16x32_fp8_fp8 v[10:13], v[172:173], v[234:235], v[14:17]
	s_waitcnt vmcnt(18)
	v_mfma_f32_16x16x32_fp8_fp8 v[14:17], v[174:175], v[234:235], v[18:21]
	v_mfma_f32_16x16x32_fp8_fp8 v[18:21], v[176:177], v[234:235], v[22:25]
	s_waitcnt vmcnt(17)
	v_mfma_f32_16x16x32_fp8_fp8 v[22:25], v[178:179], v[234:235], v[26:29]
	v_mfma_f32_16x16x32_fp8_fp8 v[26:29], v[180:181], v[234:235], v[30:33]
	s_waitcnt vmcnt(16)
	v_mfma_f32_16x16x32_fp8_fp8 v[30:33], v[182:183], v[234:235], v[68:71]
	v_mfma_f32_16x16x32_fp8_fp8 v[2:5], v[184:185], v[234:235], v[72:75]
	s_nop 1
; template <bool SLC, bool NOMASK> ...
;     const int kq = lane >> 4;
;     const int pos0 = SLC ? (dcur & 0xfffff) : dcur;
;     const int lo = SLC ? ((((dcur >> 20) == qi) | ((dcur >> 20) == 4)) ? 0 : (1 << 30)) : lo_in;
;     load_frag8(nxt, KF, VF, SLC ? (dnext & 0xfffff) : dnext, lane);
;     f32x4 sa[2] = {(f32x4){0.f, 0.f, 0.f, 0.f}, (f32x4){0.f, 0.f, 0.f, 0.f}};
; #pragma unroll
;     for (int T = 0; T < 2; ++T)
; #pragma unroll
;         for (int s2 = 0; s2 < 4; ++s2) sa[T] = __builtin_amdgcn_mfma_f32_16x16x32_fp8_fp8(cur.k[T][s2], qf[s2], sa[T], 0, 0, 0);
;     float sc[8]; bool vd[8]; float mx = -1e30f;
;     const bool act = lo == 0 || !SLC;
;     if (NOMASK) {
; #pragma unroll
;         for (int j = 0; j < 8; ++j) { sc[j] = sa[j >> 2][j & 3]; vd[j] = act; }
;         mx = fmaxf(fmaxf(fmaxf(sc[0], sc[1]), fmaxf(sc[2], sc[3])), fmaxf(fmaxf(sc[4], sc[5]), fmaxf(sc[6], sc[7])));
;         mx = act ? mx : -1e30f;
;     } else {
; #pragma unroll
;         for (int T = 0; T < 2; ++T)
; #pragma unroll
;             for (int r = 0; r < 4; ++r) { const int p = pos0 + 16 * T + 4 * kq + r; const bool v = (p >= lo) & (p <= hi); const float x = sa[T][r];
;                 sc[4 * T + r] = x; vd[4 * T + r] = v; mx = v ? fmaxf(mx, x) : mx; }
;     }
;     if (__builtin_amdgcn_ballot_w64(mx > st.m + 4.f) != 0ull) {
;         mx = fmaxf(mx, __shfl_xor(mx, 16)); mx = fmaxf(mx, __shfl_xor(mx, 32));
;         const float mn = fmaxf(st.m, mx), alpha = __builtin_amdgcn_exp2f(st.m - mn); st.m = mn; st.l *= alpha;
; #pragma unroll
;         for (int j = 0; j < 8; ++j) st.o[j] = st.o[j] * alpha;
;     }
;     f32x4 pa, pb; float ps = 0.f;
;     const float mref = st.m - 4.f;
;     if (NOMASK) {
; #pragma unroll
;         for (int j = 0; j < 4; ++j) { pa[j] = __builtin_amdgcn_exp2f(sc[j] - mref); pb[j] = __builtin_amdgcn_exp2f(sc[4 + j] - mref); }
;         if (SLC) {
; #pragma unroll
;             for (int j = 0; j < 4; ++j) { pa[j] = act ? pa[j] : 0.f; pb[j] = act ? pb[j] : 0.f; }
;         }
; #pragma unroll
;         for (int j = 0; j < 4; ++j) ps += pa[j] + pb[j];
;     } else {
; #pragma unroll
;         for (int j = 0; j < 4; ++j) { pa[j] = vd[j] ? __builtin_amdgcn_exp2f(sc[j] - mref) : 0.f; pb[j] = vd[4 + j] ? __builtin_amdgcn_exp2f(sc[4 + j] - mref) : 0.f; ps += pa[j] + pb[j]; }
;     }
;     st.l += ps;
;     const u32x2 pw = pack8_fp8(pa, pb);
.LBB0_917:
	s_and_b64 vcc, exec, s[10:11]
	s_cbranch_vccz .LBB0_921
	v_lshl_add_u64 v[244:245], v[204:205], 0, v[118:119]
	global_load_dwordx4 v[154:157], v[244:245], off
	global_load_dwordx4 v[158:161], v[244:245], off offset:1024
	global_load_dwordx4 v[162:165], v[244:245], off offset:2048
	global_load_dwordx4 v[166:169], v[244:245], off offset:3072
	v_lshl_add_u64 v[246:247], v[202:203], 0, v[118:119]
	global_load_dwordx4 v[106:109], v[246:247], off
	global_load_dwordx4 v[110:113], v[246:247], off offset:1024
	global_load_dwordx4 v[114:117], v[246:247], off offset:2048
	global_load_dwordx4 v[134:137], v[246:247], off offset:3072
	s_waitcnt vmcnt(20)
	v_mfma_f32_16x16x32_fp8_fp8 v[2:5], v[186:187], v[78:79], 0
	v_or_b32_e32 v0, s59, v211
	v_cmp_ge_i32_e32 vcc, v0, v35
	v_cmp_le_i32_e64 s[10:11], v0, v132
	v_mfma_f32_16x16x32_fp8_fp8 v[2:5], v[188:189], v[80:81], v[2:5]
	s_and_b64 s[16:17], vcc, s[10:11]
	v_or_b32_e32 v11, 1, v0
	v_cmp_ge_i32_e32 vcc, v11, v35
	v_mfma_f32_16x16x32_fp8_fp8 v[2:5], v[190:191], v[82:83], v[2:5]
	v_cmp_lt_i32_e64 s[10:11], v0, v132
	s_and_b64 s[12:13], s[10:11], vcc
	v_mfma_f32_16x16x32_fp8_fp8 v[6:9], v[194:195], v[78:79], 0
	v_mfma_f32_16x16x32_fp8_fp8 v[2:5], v[192:193], v[84:85], v[2:5]
	v_mfma_f32_16x16x32_fp8_fp8 v[6:9], v[196:197], v[80:81], v[6:9]
	v_mfma_f32_16x16x32_fp8_fp8 v[6:9], v[198:199], v[82:83], v[6:9]
	s_nop 5
	v_max_f32_e32 v10, v2, v2
	v_max_f32_e32 v10, 0xf149f2ca, v10
	v_cndmask_b32_e64 v10, v223, v10, s[16:17]
	v_max_f32_e32 v11, v3, v3
	v_max_f32_e32 v11, v10, v11
	v_cndmask_b32_e64 v10, v10, v11, s[12:13]
	v_or_b32_e32 v11, 2, v0
	v_cmp_ge_i32_e32 vcc, v11, v35
	v_cmp_le_i32_e64 s[10:11], v11, v132
	v_max_f32_e32 v11, v4, v4
	v_max_f32_e32 v11, v10, v11
	s_and_b64 s[14:15], vcc, s[10:11]
	v_mfma_f32_16x16x32_fp8_fp8 v[6:9], v[200:201], v[84:85], v[6:9]
	v_cndmask_b32_e64 v10, v10, v11, s[14:15]
	v_or_b32_e32 v11, 3, v0
	v_cmp_ge_i32_e32 vcc, v11, v35
	v_cmp_le_i32_e64 s[10:11], v11, v132
	v_max_f32_e32 v11, v5, v5
	v_max_f32_e32 v11, v10, v11
	s_and_b64 s[10:11], vcc, s[10:11]
	v_cndmask_b32_e64 v10, v10, v11, s[10:11]
	v_or_b32_e32 v11, 16, v0
	v_cmp_ge_i32_e32 vcc, v11, v35
	v_cmp_le_i32_e64 s[18:19], v11, v132
	v_max_f32_e32 v11, v6, v6
	v_max_f32_e32 v11, v10, v11
	s_and_b64 s[24:25], vcc, s[18:19]
	v_cndmask_b32_e64 v10, v10, v11, s[24:25]
	v_or_b32_e32 v11, 17, v0
	v_cmp_ge_i32_e32 vcc, v11, v35
	v_cmp_le_i32_e64 s[18:19], v11, v132
	v_max_f32_e32 v11, v10, v10
	v_max_f32_e32 v12, v7, v7
	v_max_f32_e32 v11, v11, v12
	s_and_b64 s[20:21], vcc, s[18:19]
	v_cndmask_b32_e64 v10, v10, v11, s[20:21]
	v_or_b32_e32 v11, 18, v0
	v_cmp_ge_i32_e32 vcc, v11, v35
	v_cmp_le_i32_e64 s[18:19], v11, v132
	v_max_f32_e32 v11, v10, v10
	v_max_f32_e32 v12, v8, v8
	v_max_f32_e32 v11, v11, v12
	s_and_b64 s[22:23], vcc, s[18:19]
	v_cndmask_b32_e64 v10, v10, v11, s[22:23]
	v_or_b32_e32 v0, 19, v0
	v_cmp_ge_i32_e32 vcc, v0, v35
	v_cmp_le_i32_e64 s[18:19], v0, v132
	v_max_f32_e32 v0, v10, v10
	v_max_f32_e32 v11, v9, v9
	v_max_f32_e32 v0, v0, v11
	s_and_b64 s[18:19], vcc, s[18:19]
	v_cndmask_b32_e64 v0, v10, v0, s[18:19]
	v_cmp_gt_f32_e32 vcc, v0, v229
	s_cbranch_vccz .LBB0_920
	ds_bpermute_b32 v10, v227, v0
	v_max_f32_e32 v0, v0, v0
	s_waitcnt lgkmcnt(0)
	v_max_f32_e32 v10, v10, v10
	v_max_f32_e32 v0, v0, v10
	ds_bpermute_b32 v10, v226, v0
	s_waitcnt lgkmcnt(0)
	v_max3_f32 v10, v230, v0, v10
	v_sub_f32_e32 v0, v230, v10
	v_exp_f32_e32 v0, v0
	v_mov_b32_e32 v230, v10
	v_mul_f32_e32 v231, v231, v0
	v_pk_mul_f32 v[38:39], v[38:39], v[0:1] op_sel_hi:[1,0]
	v_pk_mul_f32 v[36:37], v[36:37], v[0:1] op_sel_hi:[1,0]
	v_pk_mul_f32 v[42:43], v[42:43], v[0:1] op_sel_hi:[1,0]
	v_pk_mul_f32 v[40:41], v[40:41], v[0:1] op_sel_hi:[1,0]
	v_pk_mul_f32 v[46:47], v[46:47], v[0:1] op_sel_hi:[1,0]
	v_pk_mul_f32 v[44:45], v[44:45], v[0:1] op_sel_hi:[1,0]
	v_pk_mul_f32 v[50:51], v[50:51], v[0:1] op_sel_hi:[1,0]
	v_pk_mul_f32 v[48:49], v[48:49], v[0:1] op_sel_hi:[1,0]
	v_pk_mul_f32 v[54:55], v[54:55], v[0:1] op_sel_hi:[1,0]
	v_pk_mul_f32 v[52:53], v[52:53], v[0:1] op_sel_hi:[1,0]
	v_pk_mul_f32 v[58:59], v[58:59], v[0:1] op_sel_hi:[1,0]
	v_pk_mul_f32 v[56:57], v[56:57], v[0:1] op_sel_hi:[1,0]
	v_pk_mul_f32 v[62:63], v[62:63], v[0:1] op_sel_hi:[1,0]
	v_pk_mul_f32 v[60:61], v[60:61], v[0:1] op_sel_hi:[1,0]
	v_pk_mul_f32 v[66:67], v[66:67], v[0:1] op_sel_hi:[1,0]
	v_pk_mul_f32 v[64:65], v[64:65], v[0:1] op_sel_hi:[1,0]
.LBB0_920:
	v_add_f32_e32 v0, -4.0, v230
	v_sub_f32_e32 v2, v2, v0
	v_exp_f32_e32 v2, v2
	v_sub_f32_e32 v6, v6, v0
	v_exp_f32_e32 v6, v6
	v_sub_f32_e32 v4, v4, v0
	v_cndmask_b32_e64 v26, 0, v2, s[16:17]
	v_sub_f32_e32 v2, v3, v0
	v_exp_f32_e32 v2, v2
	v_sub_f32_e32 v3, v7, v0
	v_exp_f32_e32 v3, v3
	v_cndmask_b32_e64 v27, 0, v6, s[24:25]
	v_sub_f32_e32 v6, v8, v0
	v_cndmask_b32_e64 v28, 0, v2, s[12:13]
	v_sub_f32_e32 v2, v5, v0
	v_sub_f32_e32 v0, v9, v0
	v_exp_f32_e32 v4, v4
	v_exp_f32_e32 v6, v6
	v_cndmask_b32_e64 v29, 0, v3, s[20:21]
	v_exp_f32_e32 v5, v2
	v_exp_f32_e32 v0, v0
	v_mov_b32_e32 v2, v1
	v_mov_b32_e32 v3, v1
	v_cvt_pk_fp8_f32 v2, v26, v28
	v_cvt_pk_fp8_f32 v3, v27, v29
	v_cndmask_b32_e64 v4, 0, v4, s[14:15]
	v_cndmask_b32_e64 v30, 0, v6, s[22:23]
	v_cndmask_b32_e64 v5, 0, v5, s[10:11]
	v_cndmask_b32_e64 v0, 0, v0, s[18:19]
	v_cvt_pk_fp8_f32 v2, v4, v5 op_sel:[0,0,1]
	v_cvt_pk_fp8_f32 v3, v30, v0 op_sel:[0,0,1]
	v_add_f32_e32 v26, v26, v27
	v_add_f32_e32 v31, 0, v26
	v_add_f32_e32 v32, v28, v29
	v_add_f32_e32 v31, v32, v31
	v_add_f32_e32 v4, v4, v30
	v_add_f32_e32 v4, v4, v31
	v_add_f32_e32 v0, v5, v0
	s_waitcnt vmcnt(19)
	v_mfma_f32_16x16x32_fp8_fp8 v[6:9], v[170:171], v[2:3], v[36:39]
	v_add_f32_e32 v0, v0, v4
	v_add_f32_e32 v34, v231, v0
	v_mov_b32_e32 v133, v230
	v_mfma_f32_16x16x32_fp8_fp8 v[10:13], v[172:173], v[2:3], v[40:43]
	s_waitcnt vmcnt(18)
	v_mfma_f32_16x16x32_fp8_fp8 v[14:17], v[174:175], v[2:3], v[44:47]
	v_mfma_f32_16x16x32_fp8_fp8 v[18:21], v[176:177], v[2:3], v[48:51]
	s_waitcnt vmcnt(17)
	v_mfma_f32_16x16x32_fp8_fp8 v[22:25], v[178:179], v[2:3], v[52:55]
	v_mfma_f32_16x16x32_fp8_fp8 v[26:29], v[180:181], v[2:3], v[56:59]
	s_waitcnt vmcnt(16)
	v_mfma_f32_16x16x32_fp8_fp8 v[30:33], v[182:183], v[2:3], v[60:63]
	v_mfma_f32_16x16x32_fp8_fp8 v[2:5], v[184:185], v[2:3], v[64:67]
	s_nop 1

; template <bool SLC, bool NOMASK> ...
;     const int kq = lane >> 4;
;     const int pos0 = SLC ? (dcur & 0xfffff) : dcur;
;     const int lo = SLC ? ((((dcur >> 20) == qi) | ((dcur >> 20) == 4)) ? 0 : (1 << 30)) : lo_in;
;     load_frag8(nxt, KF, VF, SLC ? (dnext & 0xfffff) : dnext, lane);
;     f32x4 sa[2] = {(f32x4){0.f, 0.f, 0.f, 0.f}, (f32x4){0.f, 0.f, 0.f, 0.f}};
; #pragma unroll
;     for (int T = 0; T < 2; ++T)
; #pragma unroll
;         for (int s2 = 0; s2 < 4; ++s2) sa[T] = __builtin_amdgcn_mfma_f32_16x16x32_fp8_fp8(cur.k[T][s2], qf[s2], sa[T], 0, 0, 0);
;     float sc[8]; bool vd[8]; float mx = -1e30f;
;     const bool act = lo == 0 || !SLC;
;     if (NOMASK) {
; #pragma unroll
;         for (int j = 0; j < 8; ++j) { sc[j] = sa[j >> 2][j & 3]; vd[j] = act; }
;         mx = fmaxf(fmaxf(fmaxf(sc[0], sc[1]), fmaxf(sc[2], sc[3])), fmaxf(fmaxf(sc[4], sc[5]), fmaxf(sc[6], sc[7])));
;         mx = act ? mx : -1e30f;
;     } else {
; #pragma unroll
;         for (int T = 0; T < 2; ++T)
; #pragma unroll
;             for (int r = 0; r < 4; ++r) { const int p = pos0 + 16 * T + 4 * kq + r; const bool v = (p >= lo) & (p <= hi); const float x = sa[T][r];
;                 sc[4 * T + r] = x; vd[4 * T + r] = v; mx = v ? fmaxf(mx, x) : mx; }
;     }
;     if (__builtin_amdgcn_ballot_w64(mx > st.m + 4.f) != 0ull) {
;         mx = fmaxf(mx, __shfl_xor(mx, 16)); mx = fmaxf(mx, __shfl_xor(mx, 32));
;         const float mn = fmaxf(st.m, mx), alpha = __builtin_amdgcn_exp2f(st.m - mn); st.m = mn; st.l *= alpha;
; #pragma unroll
;         for (int j = 0; j < 8; ++j) st.o[j] = st.o[j] * alpha;
;     }
;     f32x4 pa, pb; float ps = 0.f;
;     const float mref = st.m - 4.f;
;     if (NOMASK) {
; #pragma unroll
;         for (int j = 0; j < 4; ++j) { pa[j] = __builtin_amdgcn_exp2f(sc[j] - mref); pb[j] = __builtin_amdgcn_exp2f(sc[4 + j] - mref); }
;         if (SLC) {
; #pragma unroll
;             for (int j = 0; j < 4; ++j) { pa[j] = act ? pa[j] : 0.f; pb[j] = act ? pb[j] : 0.f; }
;         }
; #pragma unroll
;         for (int j = 0; j < 4; ++j) ps += pa[j] + pb[j];
;     } else {
; #pragma unroll
;         for (int j = 0; j < 4; ++j) { pa[j] = vd[j] ? __builtin_amdgcn_exp2f(sc[j] - mref) : 0.f; pb[j] = vd[4 + j] ? __builtin_amdgcn_exp2f(sc[4 + j] - mref) : 0.f; ps += pa[j] + pb[j]; }
;     }
;     st.l += ps;
;     const u32x2 pw = pack8_fp8(pa, pb);
.LBB0_969:
	s_and_b32 s13, s12, 0xfffffbff
	s_cmp_eq_u32 s13, 4
	s_cselect_b64 s[10:11], -1, 0
	s_lshl_b32 s14, s66, 7
	s_and_b32 s50, s14, 0x7fff800
	v_lshl_add_u64 v[10:11], v[86:87], 0, s[50:51]
	s_and_b32 s50, s14, 0x7fff000
	v_lshl_add_u64 v[246:247], v[10:11], 0, v[120:121]
	global_load_dwordx4 v[186:189], v[246:247], off
	global_load_dwordx4 v[190:193], v[246:247], off offset:1024
	global_load_dwordx4 v[194:197], v[246:247], off offset:2048
	global_load_dwordx4 v[198:201], v[246:247], off offset:3072
	v_lshl_add_u64 v[10:11], v[88:89], 0, s[50:51]
	v_lshl_add_u64 v[244:245], v[10:11], 0, v[120:121]
	global_load_dwordx4 v[170:173], v[244:245], off
	global_load_dwordx4 v[174:177], v[244:245], off offset:1024
	global_load_dwordx4 v[178:181], v[244:245], off offset:2048
	global_load_dwordx4 v[182:185], v[244:245], off offset:3072
	s_waitcnt vmcnt(20)
	v_mfma_f32_16x16x32_fp8_fp8 v[2:5], v[138:139], v[78:79], 0
	v_cmp_eq_u32_e32 vcc, s13, v209
	s_or_b64 s[10:11], s[10:11], vcc
	v_mov_b64_e32 v[74:75], v[38:39]
	v_mfma_f32_16x16x32_fp8_fp8 v[6:9], v[146:147], v[78:79], 0
	v_mov_b64_e32 v[70:71], v[42:43]
	v_mov_b64_e32 v[30:31], v[44:45]
	v_mov_b64_e32 v[26:27], v[48:49]
	v_mfma_f32_16x16x32_fp8_fp8 v[2:5], v[140:141], v[80:81], v[2:5]
	v_mov_b64_e32 v[22:23], v[52:53]
	v_mov_b64_e32 v[18:19], v[56:57]
	v_mov_b64_e32 v[14:15], v[60:61]
	v_mfma_f32_16x16x32_fp8_fp8 v[6:9], v[148:149], v[80:81], v[6:9]
	v_mov_b64_e32 v[72:73], v[36:37]
	v_mov_b64_e32 v[68:69], v[40:41]
	v_mov_b64_e32 v[32:33], v[46:47]
	v_mfma_f32_16x16x32_fp8_fp8 v[2:5], v[142:143], v[82:83], v[2:5]
	v_mov_b64_e32 v[28:29], v[50:51]
	v_mov_b64_e32 v[24:25], v[54:55]
	v_mov_b64_e32 v[20:21], v[58:59]
	v_mfma_f32_16x16x32_fp8_fp8 v[6:9], v[150:151], v[82:83], v[6:9]
	v_mov_b64_e32 v[16:17], v[62:63]
	v_mov_b32_e32 v133, v203
	v_mfma_f32_16x16x32_fp8_fp8 v[2:5], v[144:145], v[84:85], v[2:5]
	v_mfma_f32_16x16x32_fp8_fp8 v[6:9], v[152:153], v[84:85], v[6:9]
	s_nop 6
	v_max_f32_e32 v0, v3, v3
	v_max_f32_e32 v10, v2, v2
	v_max_f32_e32 v0, v10, v0
	v_max_f32_e32 v10, v5, v5
	v_max_f32_e32 v11, v4, v4
	v_max_f32_e32 v10, v11, v10
	v_max_f32_e32 v11, v9, v9
	v_max_f32_e32 v12, v8, v8
	v_max_f32_e32 v11, v12, v11
	v_max3_f32 v11, v6, v7, v11
	v_max3_f32 v0, v0, v10, v11
	v_cndmask_b32_e64 v34, v220, v0, s[10:11]
	v_mov_b64_e32 v[10:11], v[64:65]
	v_cmp_gt_f32_e32 vcc, v34, v204
	v_mov_b32_e32 v0, v202
	v_mov_b64_e32 v[12:13], v[66:67]
	s_cbranch_vccz .LBB0_971
	ds_bpermute_b32 v0, v225, v34
	v_max_f32_e32 v10, v34, v34
	s_waitcnt lgkmcnt(0)
	v_max_f32_e32 v0, v0, v0
	v_max_f32_e32 v0, v10, v0
	ds_bpermute_b32 v10, v224, v0
	s_waitcnt lgkmcnt(0)
	v_max3_f32 v0, v202, v0, v10
	v_sub_f32_e32 v10, v202, v0
	v_exp_f32_e32 v34, v10
	s_nop 0
	v_mul_f32_e32 v133, v203, v34
	v_pk_mul_f32 v[12:13], v[66:67], v[34:35] op_sel_hi:[1,0]
	v_pk_mul_f32 v[10:11], v[64:65], v[34:35] op_sel_hi:[1,0]
	v_pk_mul_f32 v[16:17], v[62:63], v[34:35] op_sel_hi:[1,0]
	v_pk_mul_f32 v[14:15], v[60:61], v[34:35] op_sel_hi:[1,0]
	v_pk_mul_f32 v[20:21], v[58:59], v[34:35] op_sel_hi:[1,0]
	v_pk_mul_f32 v[18:19], v[56:57], v[34:35] op_sel_hi:[1,0]
	v_pk_mul_f32 v[24:25], v[54:55], v[34:35] op_sel_hi:[1,0]
	v_pk_mul_f32 v[22:23], v[52:53], v[34:35] op_sel_hi:[1,0]
	v_pk_mul_f32 v[28:29], v[50:51], v[34:35] op_sel_hi:[1,0]
	v_pk_mul_f32 v[26:27], v[48:49], v[34:35] op_sel_hi:[1,0]
	v_pk_mul_f32 v[32:33], v[46:47], v[34:35] op_sel_hi:[1,0]
	v_pk_mul_f32 v[30:31], v[44:45], v[34:35] op_sel_hi:[1,0]
	v_pk_mul_f32 v[70:71], v[42:43], v[34:35] op_sel_hi:[1,0]
	v_pk_mul_f32 v[68:69], v[40:41], v[34:35] op_sel_hi:[1,0]
	v_pk_mul_f32 v[74:75], v[38:39], v[34:35] op_sel_hi:[1,0]
	v_pk_mul_f32 v[72:73], v[36:37], v[34:35] op_sel_hi:[1,0]
.LBB0_971:
	v_add_f32_e32 v34, -4.0, v0
	v_sub_f32_e32 v2, v2, v34
	v_sub_f32_e32 v6, v6, v34
	v_sub_f32_e32 v3, v3, v34
	v_sub_f32_e32 v7, v7, v34
	v_exp_f32_e32 v2, v2
	v_exp_f32_e32 v6, v6
	v_exp_f32_e32 v3, v3
	v_exp_f32_e32 v7, v7
	v_sub_f32_e32 v4, v4, v34
	v_sub_f32_e32 v8, v8, v34
	v_sub_f32_e32 v5, v5, v34
	v_sub_f32_e32 v9, v9, v34
	v_exp_f32_e32 v4, v4
	v_exp_f32_e32 v8, v8
	v_exp_f32_e32 v5, v5
	v_exp_f32_e32 v9, v9
	v_cndmask_b32_e64 v34, 0, v2, s[10:11]
	v_cndmask_b32_e64 v6, 0, v6, s[10:11]
	v_cndmask_b32_e64 v35, 0, v3, s[10:11]
	v_cndmask_b32_e64 v7, 0, v7, s[10:11]
	v_mov_b32_e32 v2, v1
	v_mov_b32_e32 v3, v1
	v_cvt_pk_fp8_f32 v2, v34, v35
	v_cvt_pk_fp8_f32 v3, v6, v7
	v_cndmask_b32_e64 v4, 0, v4, s[10:11]
	v_cndmask_b32_e64 v205, 0, v8, s[10:11]
	v_cndmask_b32_e64 v5, 0, v5, s[10:11]
	v_cndmask_b32_e64 v227, 0, v9, s[10:11]
	v_add_f32_e32 v6, v34, v6
	v_cvt_pk_fp8_f32 v2, v4, v5 op_sel:[0,0,1]
	v_cvt_pk_fp8_f32 v3, v205, v227 op_sel:[0,0,1]
	v_add_f32_e32 v6, 0, v6
	v_add_f32_e32 v7, v35, v7
	v_add_f32_e32 v6, v7, v6
	v_add_f32_e32 v4, v4, v205
	v_add_f32_e32 v4, v4, v6
	v_add_f32_e32 v5, v5, v227
	v_add_f32_e32 v4, v5, v4
	s_waitcnt vmcnt(19)
	v_mfma_f32_16x16x32_fp8_fp8 v[8:11], v[90:91], v[2:3], v[10:13]
	v_add_f32_e32 v133, v133, v4
	v_mfma_f32_16x16x32_fp8_fp8 v[12:15], v[92:93], v[2:3], v[14:17]
	s_waitcnt vmcnt(18)
	v_mfma_f32_16x16x32_fp8_fp8 v[16:19], v[94:95], v[2:3], v[18:21]
	v_mfma_f32_16x16x32_fp8_fp8 v[20:23], v[96:97], v[2:3], v[22:25]
	s_waitcnt vmcnt(17)
	v_mfma_f32_16x16x32_fp8_fp8 v[24:27], v[98:99], v[2:3], v[26:29]
	v_mfma_f32_16x16x32_fp8_fp8 v[32:35], v[100:101], v[2:3], v[30:33]
	s_waitcnt vmcnt(16)
	v_mfma_f32_16x16x32_fp8_fp8 v[28:31], v[102:103], v[2:3], v[68:71]
	v_mfma_f32_16x16x32_fp8_fp8 v[4:7], v[104:105], v[2:3], v[72:75]
	s_nop 1
	s_branch .LBB0_965
; template <bool SLC, bool NOMASK> ...
;     const int kq = lane >> 4;
;     const int pos0 = SLC ? (dcur & 0xfffff) : dcur;
;     const int lo = SLC ? ((((dcur >> 20) == qi) | ((dcur >> 20) == 4)) ? 0 : (1 << 30)) : lo_in;
;     load_frag8(nxt, KF, VF, SLC ? (dnext & 0xfffff) : dnext, lane);
;     f32x4 sa[2] = {(f32x4){0.f, 0.f, 0.f, 0.f}, (f32x4){0.f, 0.f, 0.f, 0.f}};
; #pragma unroll
;     for (int T = 0; T < 2; ++T)
; #pragma unroll
;         for (int s2 = 0; s2 < 4; ++s2) sa[T] = __builtin_amdgcn_mfma_f32_16x16x32_fp8_fp8(cur.k[T][s2], qf[s2], sa[T], 0, 0, 0);
;     float sc[8]; bool vd[8]; float mx = -1e30f;
;     const bool act = lo == 0 || !SLC;
;     if (NOMASK) {
; #pragma unroll
;         for (int j = 0; j < 8; ++j) { sc[j] = sa[j >> 2][j & 3]; vd[j] = act; }
;         mx = fmaxf(fmaxf(fmaxf(sc[0], sc[1]), fmaxf(sc[2], sc[3])), fmaxf(fmaxf(sc[4], sc[5]), fmaxf(sc[6], sc[7])));
;         mx = act ? mx : -1e30f;
;     } else {
; #pragma unroll
;         for (int T = 0; T < 2; ++T)
; #pragma unroll
;             for (int r = 0; r < 4; ++r) { const int p = pos0 + 16 * T + 4 * kq + r; const bool v = (p >= lo) & (p <= hi); const float x = sa[T][r];
;                 sc[4 * T + r] = x; vd[4 * T + r] = v; mx = v ? fmaxf(mx, x) : mx; }
;     }
;     if (__builtin_amdgcn_ballot_w64(mx > st.m + 4.f) != 0ull) {
;         mx = fmaxf(mx, __shfl_xor(mx, 16)); mx = fmaxf(mx, __shfl_xor(mx, 32));
;         const float mn = fmaxf(st.m, mx), alpha = __builtin_amdgcn_exp2f(st.m - mn); st.m = mn; st.l *= alpha;
; #pragma unroll
;         for (int j = 0; j < 8; ++j) st.o[j] = st.o[j] * alpha;
;     }
;     f32x4 pa, pb; float ps = 0.f;
;     const float mref = st.m - 4.f;
;     if (NOMASK) {
; #pragma unroll
;         for (int j = 0; j < 4; ++j) { pa[j] = __builtin_amdgcn_exp2f(sc[j] - mref); pb[j] = __builtin_amdgcn_exp2f(sc[4 + j] - mref); }
;         if (SLC) {
; #pragma unroll
;             for (int j = 0; j < 4; ++j) { pa[j] = act ? pa[j] : 0.f; pb[j] = act ? pb[j] : 0.f; }
;         }
; #pragma unroll
;         for (int j = 0; j < 4; ++j) ps += pa[j] + pb[j];
;     } else {
; #pragma unroll
;         for (int j = 0; j < 4; ++j) { pa[j] = vd[j] ? __builtin_amdgcn_exp2f(sc[j] - mref) : 0.f; pb[j] = vd[4 + j] ? __builtin_amdgcn_exp2f(sc[4 + j] - mref) : 0.f; ps += pa[j] + pb[j]; }
;     }
;     st.l += ps;
;     const u32x2 pw = pack8_fp8(pa, pb);
.LBB0_972:
	s_cmp_eq_u32 s12, 4
	s_cselect_b64 s[10:11], -1, 0
	s_lshl_b32 s13, s66, 7
	s_and_b32 s50, s13, 0x7fff800
	v_lshl_add_u64 v[10:11], v[86:87], 0, s[50:51]
	s_and_b32 s50, s13, 0x7fff000
	v_lshl_add_u64 v[246:247], v[10:11], 0, v[120:121]
	global_load_dwordx4 v[186:189], v[246:247], off
	global_load_dwordx4 v[190:193], v[246:247], off offset:1024
	global_load_dwordx4 v[194:197], v[246:247], off offset:2048
	global_load_dwordx4 v[198:201], v[246:247], off offset:3072
	v_lshl_add_u64 v[10:11], v[88:89], 0, s[50:51]
	v_lshl_add_u64 v[244:245], v[10:11], 0, v[120:121]
	global_load_dwordx4 v[170:173], v[244:245], off
	global_load_dwordx4 v[174:177], v[244:245], off offset:1024
	global_load_dwordx4 v[178:181], v[244:245], off offset:2048
	global_load_dwordx4 v[182:185], v[244:245], off offset:3072
	s_waitcnt vmcnt(20)
	v_mfma_f32_16x16x32_fp8_fp8 v[2:5], v[138:139], v[78:79], 0
	s_and_b32 s13, s57, 0xfffff
	v_cmp_eq_u32_e32 vcc, s12, v209
	v_add_u32_e32 v0, s13, v210
	v_mfma_f32_16x16x32_fp8_fp8 v[2:5], v[140:141], v[80:81], v[2:5]
	s_or_b64 s[18:19], s[10:11], vcc
	v_cmp_le_i32_e32 vcc, v0, v132
	s_and_b64 s[16:17], s[18:19], vcc
	v_mfma_f32_16x16x32_fp8_fp8 v[2:5], v[142:143], v[82:83], v[2:5]
	v_cmp_lt_i32_e32 vcc, v0, v132
	s_and_b64 s[12:13], s[18:19], vcc
	v_mfma_f32_16x16x32_fp8_fp8 v[6:9], v[146:147], v[78:79], 0
	v_mfma_f32_16x16x32_fp8_fp8 v[2:5], v[144:145], v[84:85], v[2:5]
	v_mfma_f32_16x16x32_fp8_fp8 v[6:9], v[148:149], v[80:81], v[6:9]
	v_mfma_f32_16x16x32_fp8_fp8 v[6:9], v[150:151], v[82:83], v[6:9]
	s_nop 5
	v_max_f32_e32 v10, v2, v2
	v_max_f32_e32 v10, 0xf149f2ca, v10
	v_cndmask_b32_e64 v10, v220, v10, s[16:17]
	v_max_f32_e32 v11, v3, v3
	v_max_f32_e32 v11, v10, v11
	v_cndmask_b32_e64 v10, v10, v11, s[12:13]
	v_add_u32_e32 v11, 2, v0
	v_cmp_le_i32_e32 vcc, v11, v132
	v_max_f32_e32 v11, v4, v4
	v_max_f32_e32 v11, v10, v11
	s_and_b64 s[14:15], s[18:19], vcc
	v_mfma_f32_16x16x32_fp8_fp8 v[6:9], v[152:153], v[84:85], v[6:9]
	v_cndmask_b32_e64 v10, v10, v11, s[14:15]
	v_add_u32_e32 v11, 3, v0
	v_cmp_le_i32_e32 vcc, v11, v132
	v_max_f32_e32 v11, v5, v5
	v_max_f32_e32 v11, v10, v11
	s_and_b64 s[10:11], s[18:19], vcc
	v_cndmask_b32_e64 v10, v10, v11, s[10:11]
	v_add_u32_e32 v11, 16, v0
	v_cmp_le_i32_e32 vcc, v11, v132
	v_max_f32_e32 v11, v6, v6
	v_max_f32_e32 v11, v10, v11
	s_and_b64 s[24:25], s[18:19], vcc
	v_cndmask_b32_e64 v10, v10, v11, s[24:25]
	v_add_u32_e32 v11, 17, v0
	v_cmp_le_i32_e32 vcc, v11, v132
	v_max_f32_e32 v11, v10, v10
	v_max_f32_e32 v12, v7, v7
	v_max_f32_e32 v11, v11, v12
	s_and_b64 s[20:21], s[18:19], vcc
	v_cndmask_b32_e64 v10, v10, v11, s[20:21]
	v_add_u32_e32 v11, 18, v0
	v_cmp_le_i32_e32 vcc, v11, v132
	v_max_f32_e32 v11, v10, v10
	v_max_f32_e32 v12, v8, v8
	v_max_f32_e32 v11, v11, v12
	s_and_b64 s[22:23], s[18:19], vcc
	v_cndmask_b32_e64 v10, v10, v11, s[22:23]
	v_add_u32_e32 v0, 19, v0
	v_cmp_le_i32_e32 vcc, v0, v132
	v_max_f32_e32 v0, v10, v10
	v_max_f32_e32 v11, v9, v9
	v_max_f32_e32 v0, v0, v11
	s_and_b64 s[18:19], s[18:19], vcc
	v_cndmask_b32_e64 v0, v10, v0, s[18:19]
	v_cmp_gt_f32_e32 vcc, v0, v204
	s_cbranch_vccz .LBB0_974
	ds_bpermute_b32 v10, v225, v0
	v_max_f32_e32 v0, v0, v0
	s_waitcnt lgkmcnt(0)
	v_max_f32_e32 v10, v10, v10
	v_max_f32_e32 v0, v0, v10
	ds_bpermute_b32 v10, v224, v0
	s_waitcnt lgkmcnt(0)
	v_max3_f32 v10, v202, v0, v10
	v_sub_f32_e32 v0, v202, v10
	v_exp_f32_e32 v0, v0
	v_mov_b32_e32 v202, v10
	v_mul_f32_e32 v203, v203, v0
	v_pk_mul_f32 v[66:67], v[66:67], v[0:1] op_sel_hi:[1,0]
	v_pk_mul_f32 v[64:65], v[64:65], v[0:1] op_sel_hi:[1,0]
	v_pk_mul_f32 v[62:63], v[62:63], v[0:1] op_sel_hi:[1,0]
	v_pk_mul_f32 v[60:61], v[60:61], v[0:1] op_sel_hi:[1,0]
	v_pk_mul_f32 v[58:59], v[58:59], v[0:1] op_sel_hi:[1,0]
	v_pk_mul_f32 v[56:57], v[56:57], v[0:1] op_sel_hi:[1,0]
	v_pk_mul_f32 v[54:55], v[54:55], v[0:1] op_sel_hi:[1,0]
	v_pk_mul_f32 v[52:53], v[52:53], v[0:1] op_sel_hi:[1,0]
	v_pk_mul_f32 v[50:51], v[50:51], v[0:1] op_sel_hi:[1,0]
	v_pk_mul_f32 v[48:49], v[48:49], v[0:1] op_sel_hi:[1,0]
	v_pk_mul_f32 v[46:47], v[46:47], v[0:1] op_sel_hi:[1,0]
	v_pk_mul_f32 v[44:45], v[44:45], v[0:1] op_sel_hi:[1,0]
	v_pk_mul_f32 v[42:43], v[42:43], v[0:1] op_sel_hi:[1,0]
	v_pk_mul_f32 v[40:41], v[40:41], v[0:1] op_sel_hi:[1,0]
	v_pk_mul_f32 v[38:39], v[38:39], v[0:1] op_sel_hi:[1,0]
	v_pk_mul_f32 v[36:37], v[36:37], v[0:1] op_sel_hi:[1,0]
.LBB0_974:
	v_add_f32_e32 v0, -4.0, v202
	v_sub_f32_e32 v2, v2, v0
	v_exp_f32_e32 v2, v2
	v_sub_f32_e32 v6, v6, v0
	v_exp_f32_e32 v6, v6
	v_sub_f32_e32 v4, v4, v0
	v_cndmask_b32_e64 v28, 0, v2, s[16:17]
	v_sub_f32_e32 v2, v3, v0
	v_exp_f32_e32 v2, v2
	v_sub_f32_e32 v3, v7, v0
	v_exp_f32_e32 v3, v3
	v_sub_f32_e32 v7, v8, v0
	v_cndmask_b32_e64 v29, 0, v2, s[12:13]
	v_sub_f32_e32 v2, v5, v0
	v_sub_f32_e32 v0, v9, v0
	v_cndmask_b32_e64 v6, 0, v6, s[24:25]
	v_exp_f32_e32 v4, v4
	v_exp_f32_e32 v7, v7
	v_cndmask_b32_e64 v30, 0, v3, s[20:21]
	v_exp_f32_e32 v5, v2
	v_exp_f32_e32 v0, v0
	v_mov_b32_e32 v2, v1
	v_mov_b32_e32 v3, v1
	v_cvt_pk_fp8_f32 v2, v28, v29
	v_cvt_pk_fp8_f32 v3, v6, v30
	v_cndmask_b32_e64 v4, 0, v4, s[14:15]
	v_cndmask_b32_e64 v7, 0, v7, s[22:23]
	v_cndmask_b32_e64 v5, 0, v5, s[10:11]
	v_cndmask_b32_e64 v0, 0, v0, s[18:19]
	v_cvt_pk_fp8_f32 v2, v4, v5 op_sel:[0,0,1]
	v_cvt_pk_fp8_f32 v3, v7, v0 op_sel:[0,0,1]
	v_add_f32_e32 v6, v28, v6
	v_add_f32_e32 v6, 0, v6
	v_add_f32_e32 v28, v29, v30
	v_add_f32_e32 v6, v28, v6
	v_add_f32_e32 v4, v4, v7
	v_add_f32_e32 v4, v4, v6
	v_add_f32_e32 v0, v5, v0
	s_waitcnt vmcnt(19)
	v_mfma_f32_16x16x32_fp8_fp8 v[8:11], v[90:91], v[2:3], v[64:67]
	v_add_f32_e32 v0, v0, v4
	v_add_f32_e32 v133, v203, v0
	v_mov_b32_e32 v0, v202
	v_mfma_f32_16x16x32_fp8_fp8 v[12:15], v[92:93], v[2:3], v[60:63]
	s_waitcnt vmcnt(18)
	v_mfma_f32_16x16x32_fp8_fp8 v[16:19], v[94:95], v[2:3], v[56:59]
	v_mfma_f32_16x16x32_fp8_fp8 v[20:23], v[96:97], v[2:3], v[52:55]
	s_waitcnt vmcnt(17)
	v_mfma_f32_16x16x32_fp8_fp8 v[24:27], v[98:99], v[2:3], v[48:51]
	v_mfma_f32_16x16x32_fp8_fp8 v[32:35], v[100:101], v[2:3], v[44:47]
	s_waitcnt vmcnt(16)
	v_mfma_f32_16x16x32_fp8_fp8 v[28:31], v[102:103], v[2:3], v[40:43]
	v_mfma_f32_16x16x32_fp8_fp8 v[4:7], v[104:105], v[2:3], v[36:39]
	s_nop 1
	s_add_i32 s10, s56, -3
	s_cmp_ge_u32 s10, s54
	s_mov_b64 s[10:11], -1
	s_cbranch_scc0 .LBB0_966

; template <bool SLC, bool NOMASK> ...
;     const int kq = lane >> 4;
;     const int pos0 = SLC ? (dcur & 0xfffff) : dcur;
;     const int lo = SLC ? ((((dcur >> 20) == qi) | ((dcur >> 20) == 4)) ? 0 : (1 << 30)) : lo_in;
;     load_frag8(nxt, KF, VF, SLC ? (dnext & 0xfffff) : dnext, lane);
;     f32x4 sa[2] = {(f32x4){0.f, 0.f, 0.f, 0.f}, (f32x4){0.f, 0.f, 0.f, 0.f}};
; #pragma unroll
;     for (int T = 0; T < 2; ++T)
; #pragma unroll
;         for (int s2 = 0; s2 < 4; ++s2) sa[T] = __builtin_amdgcn_mfma_f32_16x16x32_fp8_fp8(cur.k[T][s2], qf[s2], sa[T], 0, 0, 0);
;     float sc[8]; bool vd[8]; float mx = -1e30f;
;     const bool act = lo == 0 || !SLC;
;     if (NOMASK) {
; #pragma unroll
;         for (int j = 0; j < 8; ++j) { sc[j] = sa[j >> 2][j & 3]; vd[j] = act; }
;         mx = fmaxf(fmaxf(fmaxf(sc[0], sc[1]), fmaxf(sc[2], sc[3])), fmaxf(fmaxf(sc[4], sc[5]), fmaxf(sc[6], sc[7])));
;         mx = act ? mx : -1e30f;
;     } else {
; #pragma unroll
;         for (int T = 0; T < 2; ++T)
; #pragma unroll
;             for (int r = 0; r < 4; ++r) { const int p = pos0 + 16 * T + 4 * kq + r; const bool v = (p >= lo) & (p <= hi); const float x = sa[T][r];
;                 sc[4 * T + r] = x; vd[4 * T + r] = v; mx = v ? fmaxf(mx, x) : mx; }
;     }
;     if (__builtin_amdgcn_ballot_w64(mx > st.m + 4.f) != 0ull) {
;         mx = fmaxf(mx, __shfl_xor(mx, 16)); mx = fmaxf(mx, __shfl_xor(mx, 32));
;         const float mn = fmaxf(st.m, mx), alpha = __builtin_amdgcn_exp2f(st.m - mn); st.m = mn; st.l *= alpha;
; #pragma unroll
;         for (int j = 0; j < 8; ++j) st.o[j] = st.o[j] * alpha;
;     }
;     f32x4 pa, pb; float ps = 0.f;
;     const float mref = st.m - 4.f;
;     if (NOMASK) {
; #pragma unroll
;         for (int j = 0; j < 4; ++j) { pa[j] = __builtin_amdgcn_exp2f(sc[j] - mref); pb[j] = __builtin_amdgcn_exp2f(sc[4 + j] - mref); }
;         if (SLC) {
; #pragma unroll
;             for (int j = 0; j < 4; ++j) { pa[j] = act ? pa[j] : 0.f; pb[j] = act ? pb[j] : 0.f; }
;         }
; #pragma unroll
;         for (int j = 0; j < 4; ++j) ps += pa[j] + pb[j];
;     } else {
; #pragma unroll
;         for (int j = 0; j < 4; ++j) { pa[j] = vd[j] ? __builtin_amdgcn_exp2f(sc[j] - mref) : 0.f; pb[j] = vd[4 + j] ? __builtin_amdgcn_exp2f(sc[4 + j] - mref) : 0.f; ps += pa[j] + pb[j]; }
;     }
;     st.l += ps;
;     const u32x2 pw = pack8_fp8(pa, pb);
.LBB0_976:
	s_and_b32 s13, s12, 0xfffffbff
	s_cmp_eq_u32 s13, 4
	s_cselect_b64 s[10:11], -1, 0
	s_lshl_b32 s14, s57, 7
	s_and_b32 s50, s14, 0x7fff800
	v_lshl_add_u64 v[44:45], v[86:87], 0, s[50:51]
	s_and_b32 s50, s14, 0x7fff000
	v_lshl_add_u64 v[246:247], v[44:45], 0, v[120:121]
	global_load_dwordx4 v[138:141], v[246:247], off
	global_load_dwordx4 v[142:145], v[246:247], off offset:1024
	global_load_dwordx4 v[146:149], v[246:247], off offset:2048
	global_load_dwordx4 v[150:153], v[246:247], off offset:3072
	v_lshl_add_u64 v[44:45], v[88:89], 0, s[50:51]
	v_lshl_add_u64 v[244:245], v[44:45], 0, v[120:121]
	global_load_dwordx4 v[90:93], v[244:245], off
	global_load_dwordx4 v[94:97], v[244:245], off offset:1024
	global_load_dwordx4 v[98:101], v[244:245], off offset:2048
	global_load_dwordx4 v[102:105], v[244:245], off offset:3072
	s_waitcnt vmcnt(20)
	v_mfma_f32_16x16x32_fp8_fp8 v[36:39], v[154:155], v[78:79], 0
	v_cmp_eq_u32_e32 vcc, s13, v209
	s_or_b64 s[10:11], s[10:11], vcc
	v_mov_b64_e32 v[74:75], v[6:7]
	v_mfma_f32_16x16x32_fp8_fp8 v[40:43], v[162:163], v[78:79], 0
	v_mov_b64_e32 v[70:71], v[30:31]
	v_mov_b64_e32 v[66:67], v[34:35]
	v_mov_b64_e32 v[62:63], v[26:27]
	v_mfma_f32_16x16x32_fp8_fp8 v[36:39], v[156:157], v[80:81], v[36:39]
	v_mov_b64_e32 v[58:59], v[22:23]
	v_mov_b64_e32 v[54:55], v[18:19]
	v_mov_b64_e32 v[50:51], v[14:15]
	v_mfma_f32_16x16x32_fp8_fp8 v[40:43], v[164:165], v[80:81], v[40:43]
	v_mov_b32_e32 v203, v0
	v_mov_b64_e32 v[72:73], v[4:5]
	v_mov_b64_e32 v[68:69], v[28:29]
	v_mfma_f32_16x16x32_fp8_fp8 v[36:39], v[158:159], v[82:83], v[36:39]
	v_mov_b64_e32 v[64:65], v[32:33]
	v_mov_b64_e32 v[60:61], v[24:25]
	v_mov_b64_e32 v[56:57], v[20:21]
	v_mfma_f32_16x16x32_fp8_fp8 v[40:43], v[166:167], v[82:83], v[40:43]
	v_mov_b64_e32 v[52:53], v[16:17]
	v_mov_b64_e32 v[48:49], v[12:13]
	v_mfma_f32_16x16x32_fp8_fp8 v[36:39], v[160:161], v[84:85], v[36:39]
	v_mfma_f32_16x16x32_fp8_fp8 v[40:43], v[168:169], v[84:85], v[40:43]
	s_nop 6
	v_max_f32_e32 v3, v37, v37
	v_max_f32_e32 v44, v36, v36
	v_max_f32_e32 v3, v44, v3
	v_max_f32_e32 v44, v39, v39
	v_max_f32_e32 v45, v38, v38
	v_max_f32_e32 v44, v45, v44
	v_max_f32_e32 v45, v43, v43
	v_max_f32_e32 v46, v42, v42
	v_max_f32_e32 v45, v46, v45
	v_max3_f32 v45, v40, v41, v45
	v_max3_f32 v3, v3, v44, v45
	v_cndmask_b32_e64 v202, v220, v3, s[10:11]
	v_mov_b64_e32 v[46:47], v[10:11]
	v_cmp_gt_f32_e32 vcc, v202, v2
	v_mov_b64_e32 v[44:45], v[8:9]
	v_mov_b32_e32 v3, v133
	s_cbranch_vccz .LBB0_978
	ds_bpermute_b32 v3, v225, v202
	v_max_f32_e32 v44, v202, v202
	s_waitcnt lgkmcnt(0)
	v_max_f32_e32 v3, v3, v3
	v_max_f32_e32 v3, v44, v3
	ds_bpermute_b32 v44, v224, v3
	s_waitcnt lgkmcnt(0)
	v_max3_f32 v203, v0, v3, v44
	v_sub_f32_e32 v3, v0, v203
	v_exp_f32_e32 v72, v3
	s_nop 0
	v_mul_f32_e32 v3, v133, v72
	v_pk_mul_f32 v[46:47], v[10:11], v[72:73] op_sel_hi:[1,0]
	v_pk_mul_f32 v[44:45], v[8:9], v[72:73] op_sel_hi:[1,0]
	v_pk_mul_f32 v[50:51], v[14:15], v[72:73] op_sel_hi:[1,0]
	v_pk_mul_f32 v[48:49], v[12:13], v[72:73] op_sel_hi:[1,0]
	v_pk_mul_f32 v[54:55], v[18:19], v[72:73] op_sel_hi:[1,0]
	v_pk_mul_f32 v[52:53], v[16:17], v[72:73] op_sel_hi:[1,0]
	v_pk_mul_f32 v[58:59], v[22:23], v[72:73] op_sel_hi:[1,0]
	v_pk_mul_f32 v[56:57], v[20:21], v[72:73] op_sel_hi:[1,0]
	v_pk_mul_f32 v[62:63], v[26:27], v[72:73] op_sel_hi:[1,0]
	v_pk_mul_f32 v[60:61], v[24:25], v[72:73] op_sel_hi:[1,0]
	v_pk_mul_f32 v[66:67], v[34:35], v[72:73] op_sel_hi:[1,0]
	v_pk_mul_f32 v[64:65], v[32:33], v[72:73] op_sel_hi:[1,0]
	v_pk_mul_f32 v[70:71], v[30:31], v[72:73] op_sel_hi:[1,0]
	v_pk_mul_f32 v[68:69], v[28:29], v[72:73] op_sel_hi:[1,0]
	v_pk_mul_f32 v[74:75], v[6:7], v[72:73] op_sel_hi:[1,0]
	v_pk_mul_f32 v[72:73], v[4:5], v[72:73] op_sel_hi:[1,0]
.LBB0_978:
	v_add_f32_e32 v202, -4.0, v203
	v_sub_f32_e32 v36, v36, v202
	v_sub_f32_e32 v40, v40, v202
	v_sub_f32_e32 v37, v37, v202
	v_sub_f32_e32 v41, v41, v202
	v_exp_f32_e32 v36, v36
	v_exp_f32_e32 v40, v40
	v_exp_f32_e32 v37, v37
	v_exp_f32_e32 v41, v41
	v_sub_f32_e32 v38, v38, v202
	v_sub_f32_e32 v42, v42, v202
	v_sub_f32_e32 v39, v39, v202
	v_sub_f32_e32 v43, v43, v202
	v_exp_f32_e32 v38, v38
	v_exp_f32_e32 v42, v42
	v_exp_f32_e32 v39, v39
	v_exp_f32_e32 v43, v43
	v_cndmask_b32_e64 v202, 0, v36, s[10:11]
	v_cndmask_b32_e64 v204, 0, v40, s[10:11]
	v_cndmask_b32_e64 v205, 0, v37, s[10:11]
	v_cndmask_b32_e64 v227, 0, v41, s[10:11]
	v_mov_b32_e32 v228, v1
	v_mov_b32_e32 v229, v1
	v_cvt_pk_fp8_f32 v228, v202, v205
	v_cvt_pk_fp8_f32 v229, v204, v227
	v_cndmask_b32_e64 v230, 0, v38, s[10:11]
	v_cndmask_b32_e64 v231, 0, v42, s[10:11]
	v_cndmask_b32_e64 v232, 0, v39, s[10:11]
	v_cndmask_b32_e64 v233, 0, v43, s[10:11]
	v_cvt_pk_fp8_f32 v228, v230, v232 op_sel:[0,0,1]
	v_cvt_pk_fp8_f32 v229, v231, v233 op_sel:[0,0,1]
	s_nop 0
	s_waitcnt vmcnt(19)
	v_mfma_f32_16x16x32_fp8_fp8 v[40:43], v[108:109], v[228:229], v[48:51]
	v_mfma_f32_16x16x32_fp8_fp8 v[48:51], v[112:113], v[228:229], v[56:59]
	s_nop 2
	v_add_f32_e32 v56, v202, v204
	s_waitcnt vmcnt(18)
	v_mfma_f32_16x16x32_fp8_fp8 v[36:39], v[106:107], v[228:229], v[44:47]
	v_mfma_f32_16x16x32_fp8_fp8 v[44:47], v[110:111], v[228:229], v[52:55]
	s_waitcnt vmcnt(17)
	v_mfma_f32_16x16x32_fp8_fp8 v[52:55], v[114:115], v[228:229], v[60:63]
	s_nop 2
	v_add_f32_e32 v60, 0, v56
	v_add_f32_e32 v61, v205, v227
	v_add_f32_e32 v60, v61, v60
	v_add_f32_e32 v61, v230, v231
	v_mfma_f32_16x16x32_fp8_fp8 v[56:59], v[116:117], v[228:229], v[64:67]
	s_nop 2
	v_add_f32_e32 v64, v61, v60
	v_add_f32_e32 v65, v232, v233
	v_add_f32_e32 v64, v65, v64
	s_waitcnt vmcnt(16)
	v_mfma_f32_16x16x32_fp8_fp8 v[60:63], v[134:135], v[228:229], v[68:71]
	v_add_f32_e32 v204, v3, v64
	v_mfma_f32_16x16x32_fp8_fp8 v[64:67], v[136:137], v[228:229], v[72:75]
	s_nop 1
	s_branch .LBB0_968
; template <bool SLC, bool NOMASK> ...
;     const int kq = lane >> 4;
;     const int pos0 = SLC ? (dcur & 0xfffff) : dcur;
;     const int lo = SLC ? ((((dcur >> 20) == qi) | ((dcur >> 20) == 4)) ? 0 : (1 << 30)) : lo_in;
;     load_frag8(nxt, KF, VF, SLC ? (dnext & 0xfffff) : dnext, lane);
;     f32x4 sa[2] = {(f32x4){0.f, 0.f, 0.f, 0.f}, (f32x4){0.f, 0.f, 0.f, 0.f}};
; #pragma unroll
;     for (int T = 0; T < 2; ++T)
; #pragma unroll
;         for (int s2 = 0; s2 < 4; ++s2) sa[T] = __builtin_amdgcn_mfma_f32_16x16x32_fp8_fp8(cur.k[T][s2], qf[s2], sa[T], 0, 0, 0);
;     float sc[8]; bool vd[8]; float mx = -1e30f;
;     const bool act = lo == 0 || !SLC;
;     if (NOMASK) {
; #pragma unroll
;         for (int j = 0; j < 8; ++j) { sc[j] = sa[j >> 2][j & 3]; vd[j] = act; }
;         mx = fmaxf(fmaxf(fmaxf(sc[0], sc[1]), fmaxf(sc[2], sc[3])), fmaxf(fmaxf(sc[4], sc[5]), fmaxf(sc[6], sc[7])));
;         mx = act ? mx : -1e30f;
;     } else {
; #pragma unroll
;         for (int T = 0; T < 2; ++T)
; #pragma unroll
;             for (int r = 0; r < 4; ++r) { const int p = pos0 + 16 * T + 4 * kq + r; const bool v = (p >= lo) & (p <= hi); const float x = sa[T][r];
;                 sc[4 * T + r] = x; vd[4 * T + r] = v; mx = v ? fmaxf(mx, x) : mx; }
;     }
;     if (__builtin_amdgcn_ballot_w64(mx > st.m + 4.f) != 0ull) {
;         mx = fmaxf(mx, __shfl_xor(mx, 16)); mx = fmaxf(mx, __shfl_xor(mx, 32));
;         const float mn = fmaxf(st.m, mx), alpha = __builtin_amdgcn_exp2f(st.m - mn); st.m = mn; st.l *= alpha;
; #pragma unroll
;         for (int j = 0; j < 8; ++j) st.o[j] = st.o[j] * alpha;
;     }
.LBB0_979:
	s_cmp_eq_u32 s12, 4
	s_cselect_b64 s[10:11], -1, 0
	s_lshl_b32 s13, s57, 7
	s_and_b32 s50, s13, 0x7fff800
	v_lshl_add_u64 v[44:45], v[86:87], 0, s[50:51]
	s_and_b32 s50, s13, 0x7fff000
	v_lshl_add_u64 v[246:247], v[44:45], 0, v[120:121]
	global_load_dwordx4 v[138:141], v[246:247], off
	global_load_dwordx4 v[142:145], v[246:247], off offset:1024
	global_load_dwordx4 v[146:149], v[246:247], off offset:2048
	global_load_dwordx4 v[150:153], v[246:247], off offset:3072
	v_lshl_add_u64 v[44:45], v[88:89], 0, s[50:51]
	v_lshl_add_u64 v[244:245], v[44:45], 0, v[120:121]
	global_load_dwordx4 v[90:93], v[244:245], off
	global_load_dwordx4 v[94:97], v[244:245], off offset:1024
	global_load_dwordx4 v[98:101], v[244:245], off offset:2048
	global_load_dwordx4 v[102:105], v[244:245], off offset:3072
	s_waitcnt vmcnt(20)
	v_mfma_f32_16x16x32_fp8_fp8 v[36:39], v[154:155], v[78:79], 0
	s_and_b32 s13, s92, 0xfffff
	v_cmp_eq_u32_e32 vcc, s12, v209
	v_add_u32_e32 v3, s13, v210
	v_mfma_f32_16x16x32_fp8_fp8 v[36:39], v[156:157], v[80:81], v[36:39]
	s_or_b64 s[18:19], s[10:11], vcc
	v_cmp_le_i32_e32 vcc, v3, v132
	s_and_b64 s[16:17], s[18:19], vcc
	v_mfma_f32_16x16x32_fp8_fp8 v[36:39], v[158:159], v[82:83], v[36:39]
	v_cmp_lt_i32_e32 vcc, v3, v132
	s_and_b64 s[12:13], s[18:19], vcc
	v_mfma_f32_16x16x32_fp8_fp8 v[40:43], v[162:163], v[78:79], 0
	v_mfma_f32_16x16x32_fp8_fp8 v[36:39], v[160:161], v[84:85], v[36:39]
	v_mfma_f32_16x16x32_fp8_fp8 v[40:43], v[164:165], v[80:81], v[40:43]
	v_mfma_f32_16x16x32_fp8_fp8 v[40:43], v[166:167], v[82:83], v[40:43]
	s_nop 5
	v_max_f32_e32 v44, v36, v36
	v_max_f32_e32 v44, 0xf149f2ca, v44
	v_cndmask_b32_e64 v44, v220, v44, s[16:17]
	v_max_f32_e32 v45, v37, v37
	v_max_f32_e32 v45, v44, v45
	v_cndmask_b32_e64 v44, v44, v45, s[12:13]
	v_add_u32_e32 v45, 2, v3
	v_cmp_le_i32_e32 vcc, v45, v132
	v_max_f32_e32 v45, v38, v38
	v_max_f32_e32 v45, v44, v45
	s_and_b64 s[14:15], s[18:19], vcc
	v_mfma_f32_16x16x32_fp8_fp8 v[40:43], v[168:169], v[84:85], v[40:43]
	v_cndmask_b32_e64 v44, v44, v45, s[14:15]
	v_add_u32_e32 v45, 3, v3
	v_cmp_le_i32_e32 vcc, v45, v132
	v_max_f32_e32 v45, v39, v39
	v_max_f32_e32 v45, v44, v45
	s_and_b64 s[10:11], s[18:19], vcc
	v_cndmask_b32_e64 v44, v44, v45, s[10:11]
	v_add_u32_e32 v45, 16, v3
	v_cmp_le_i32_e32 vcc, v45, v132
	v_max_f32_e32 v45, v40, v40
	v_max_f32_e32 v45, v44, v45
	s_and_b64 s[24:25], s[18:19], vcc
	v_cndmask_b32_e64 v44, v44, v45, s[24:25]
	v_add_u32_e32 v45, 17, v3
	v_cmp_le_i32_e32 vcc, v45, v132
	v_max_f32_e32 v45, v44, v44
	v_max_f32_e32 v46, v41, v41
	v_max_f32_e32 v45, v45, v46
	s_and_b64 s[20:21], s[18:19], vcc
	v_cndmask_b32_e64 v44, v44, v45, s[20:21]
	v_add_u32_e32 v45, 18, v3
	v_cmp_le_i32_e32 vcc, v45, v132
	v_max_f32_e32 v45, v44, v44
	v_max_f32_e32 v46, v42, v42
	v_max_f32_e32 v45, v45, v46
	s_and_b64 s[22:23], s[18:19], vcc
	v_cndmask_b32_e64 v44, v44, v45, s[22:23]
	v_add_u32_e32 v3, 19, v3
	v_cmp_le_i32_e32 vcc, v3, v132
	v_max_f32_e32 v3, v44, v44
	v_max_f32_e32 v45, v43, v43
	v_max_f32_e32 v3, v3, v45
	s_and_b64 s[18:19], s[18:19], vcc
	v_cndmask_b32_e64 v3, v44, v3, s[18:19]
	v_cmp_gt_f32_e32 vcc, v3, v2
	s_cbranch_vccz .LBB0_981
	ds_bpermute_b32 v2, v225, v3
	v_max_f32_e32 v3, v3, v3
	s_waitcnt lgkmcnt(0)
	v_max_f32_e32 v2, v2, v2
	v_max_f32_e32 v2, v3, v2
	ds_bpermute_b32 v3, v224, v2
	s_waitcnt lgkmcnt(0)
	v_max3_f32 v2, v0, v2, v3
	v_sub_f32_e32 v0, v0, v2
	v_exp_f32_e32 v0, v0
	s_nop 0
	v_mul_f32_e32 v133, v133, v0
	v_pk_mul_f32 v[10:11], v[10:11], v[0:1] op_sel_hi:[1,0]
	v_pk_mul_f32 v[8:9], v[8:9], v[0:1] op_sel_hi:[1,0]
	v_pk_mul_f32 v[14:15], v[14:15], v[0:1] op_sel_hi:[1,0]
	v_pk_mul_f32 v[12:13], v[12:13], v[0:1] op_sel_hi:[1,0]
	v_pk_mul_f32 v[18:19], v[18:19], v[0:1] op_sel_hi:[1,0]
	v_pk_mul_f32 v[16:17], v[16:17], v[0:1] op_sel_hi:[1,0]
	v_pk_mul_f32 v[22:23], v[22:23], v[0:1] op_sel_hi:[1,0]
	v_pk_mul_f32 v[20:21], v[20:21], v[0:1] op_sel_hi:[1,0]
	v_pk_mul_f32 v[26:27], v[26:27], v[0:1] op_sel_hi:[1,0]
	v_pk_mul_f32 v[24:25], v[24:25], v[0:1] op_sel_hi:[1,0]
	v_pk_mul_f32 v[34:35], v[34:35], v[0:1] op_sel_hi:[1,0]
	v_pk_mul_f32 v[32:33], v[32:33], v[0:1] op_sel_hi:[1,0]
	v_pk_mul_f32 v[30:31], v[30:31], v[0:1] op_sel_hi:[1,0]
	v_pk_mul_f32 v[28:29], v[28:29], v[0:1] op_sel_hi:[1,0]
	v_pk_mul_f32 v[6:7], v[6:7], v[0:1] op_sel_hi:[1,0]
	v_pk_mul_f32 v[4:5], v[4:5], v[0:1] op_sel_hi:[1,0]
	v_mov_b32_e32 v0, v2

; template <bool SLC, bool NOMASK> ...
;     const int kq = lane >> 4;
;     const int pos0 = SLC ? (dcur & 0xfffff) : dcur;
;     const int lo = SLC ? ((((dcur >> 20) == qi) | ((dcur >> 20) == 4)) ? 0 : (1 << 30)) : lo_in;
;     load_frag8(nxt, KF, VF, SLC ? (dnext & 0xfffff) : dnext, lane);
;     f32x4 sa[2] = {(f32x4){0.f, 0.f, 0.f, 0.f}, (f32x4){0.f, 0.f, 0.f, 0.f}};
; #pragma unroll
;     for (int T = 0; T < 2; ++T)
; #pragma unroll
;         for (int s2 = 0; s2 < 4; ++s2) sa[T] = __builtin_amdgcn_mfma_f32_16x16x32_fp8_fp8(cur.k[T][s2], qf[s2], sa[T], 0, 0, 0);
;     float sc[8]; bool vd[8]; float mx = -1e30f;
;     const bool act = lo == 0 || !SLC;
;     if (NOMASK) {
; #pragma unroll
;         for (int j = 0; j < 8; ++j) { sc[j] = sa[j >> 2][j & 3]; vd[j] = act; }
;         mx = fmaxf(fmaxf(fmaxf(sc[0], sc[1]), fmaxf(sc[2], sc[3])), fmaxf(fmaxf(sc[4], sc[5]), fmaxf(sc[6], sc[7])));
;         mx = act ? mx : -1e30f;
;     } else {
; #pragma unroll
;         for (int T = 0; T < 2; ++T)
; #pragma unroll
;             for (int r = 0; r < 4; ++r) { const int p = pos0 + 16 * T + 4 * kq + r; const bool v = (p >= lo) & (p <= hi); const float x = sa[T][r];
;                 sc[4 * T + r] = x; vd[4 * T + r] = v; mx = v ? fmaxf(mx, x) : mx; }
;     }
;     if (__builtin_amdgcn_ballot_w64(mx > st.m + 4.f) != 0ull) {
;         mx = fmaxf(mx, __shfl_xor(mx, 16)); mx = fmaxf(mx, __shfl_xor(mx, 32));
;         const float mn = fmaxf(st.m, mx), alpha = __builtin_amdgcn_exp2f(st.m - mn); st.m = mn; st.l *= alpha;
; #pragma unroll
;         for (int j = 0; j < 8; ++j) st.o[j] = st.o[j] * alpha;
;     }
;     f32x4 pa, pb; float ps = 0.f;
;     const float mref = st.m - 4.f;
;     if (NOMASK) {
; #pragma unroll
;         for (int j = 0; j < 4; ++j) { pa[j] = __builtin_amdgcn_exp2f(sc[j] - mref); pb[j] = __builtin_amdgcn_exp2f(sc[4 + j] - mref); }
;         if (SLC) {
; #pragma unroll
;             for (int j = 0; j < 4; ++j) { pa[j] = act ? pa[j] : 0.f; pb[j] = act ? pb[j] : 0.f; }
;         }
; #pragma unroll
;         for (int j = 0; j < 4; ++j) ps += pa[j] + pb[j];
;     } else {
; #pragma unroll
;         for (int j = 0; j < 4; ++j) { pa[j] = vd[j] ? __builtin_amdgcn_exp2f(sc[j] - mref) : 0.f; pb[j] = vd[4 + j] ? __builtin_amdgcn_exp2f(sc[4 + j] - mref) : 0.f; ps += pa[j] + pb[j]; }
;     }
;     st.l += ps;
;     const u32x2 pw = pack8_fp8(pa, pb);
.LBB0_982:
	s_cmp_lt_u32 s56, s54
	s_cselect_b32 s10, s56, s55
	s_lshl_b32 s10, s10, 2
	s_add_i32 s10, s3, s10
	v_mov_b32_e32 v0, s10
	ds_read_b32 v0, v0 offset:13632
	s_and_b32 s13, s66, 2.0
	s_ashr_i32 s12, s66, 20
	s_mov_b64 s[10:11], -1
	s_cmp_eq_u32 s13, 0
	s_waitcnt lgkmcnt(0)
	v_readfirstlane_b32 s92, v0
	v_add_f32_e32 v0, 4.0, v203
	s_cbranch_scc1 .LBB0_986
	s_and_b32 s13, s12, 0xfffffbff
	s_cmp_eq_u32 s13, 4
	s_cselect_b64 s[10:11], -1, 0
	s_lshl_b32 s14, s92, 7
	s_and_b32 s50, s14, 0x7fff800
	v_lshl_add_u64 v[10:11], v[86:87], 0, s[50:51]
	s_and_b32 s50, s14, 0x7fff000
	v_lshl_add_u64 v[246:247], v[10:11], 0, v[120:121]
	global_load_dwordx4 v[154:157], v[246:247], off
	global_load_dwordx4 v[158:161], v[246:247], off offset:1024
	global_load_dwordx4 v[162:165], v[246:247], off offset:2048
	global_load_dwordx4 v[166:169], v[246:247], off offset:3072
	v_lshl_add_u64 v[10:11], v[88:89], 0, s[50:51]
	v_lshl_add_u64 v[244:245], v[10:11], 0, v[120:121]
	global_load_dwordx4 v[106:109], v[244:245], off
	global_load_dwordx4 v[110:113], v[244:245], off offset:1024
	global_load_dwordx4 v[114:117], v[244:245], off offset:2048
	global_load_dwordx4 v[134:137], v[244:245], off offset:3072
	s_waitcnt vmcnt(20)
	v_mfma_f32_16x16x32_fp8_fp8 v[2:5], v[186:187], v[78:79], 0
	v_cmp_eq_u32_e32 vcc, s13, v209
	s_or_b64 s[10:11], s[10:11], vcc
	v_mov_b64_e32 v[74:75], v[66:67]
	v_mfma_f32_16x16x32_fp8_fp8 v[6:9], v[194:195], v[78:79], 0
	v_mov_b64_e32 v[70:71], v[62:63]
	v_mov_b64_e32 v[30:31], v[56:57]
	v_mov_b64_e32 v[26:27], v[52:53]
	v_mfma_f32_16x16x32_fp8_fp8 v[2:5], v[188:189], v[80:81], v[2:5]
	v_mov_b64_e32 v[22:23], v[48:49]
	v_mov_b64_e32 v[18:19], v[44:45]
	v_mov_b64_e32 v[14:15], v[40:41]
	v_mfma_f32_16x16x32_fp8_fp8 v[6:9], v[196:197], v[80:81], v[6:9]
	v_mov_b32_e32 v202, v203
	v_mov_b64_e32 v[72:73], v[64:65]
	v_mov_b64_e32 v[68:69], v[60:61]
	v_mfma_f32_16x16x32_fp8_fp8 v[2:5], v[190:191], v[82:83], v[2:5]
	v_mov_b64_e32 v[32:33], v[58:59]
	v_mov_b64_e32 v[28:29], v[54:55]
	v_mov_b64_e32 v[24:25], v[50:51]
	v_mfma_f32_16x16x32_fp8_fp8 v[6:9], v[198:199], v[82:83], v[6:9]
	v_mov_b64_e32 v[20:21], v[46:47]
	v_mov_b64_e32 v[16:17], v[42:43]
	v_mov_b32_e32 v133, v204
	v_mfma_f32_16x16x32_fp8_fp8 v[2:5], v[192:193], v[84:85], v[2:5]
	v_mfma_f32_16x16x32_fp8_fp8 v[6:9], v[200:201], v[84:85], v[6:9]
	s_nop 6
	v_max_f32_e32 v10, v3, v3
	v_max_f32_e32 v11, v2, v2
	v_max_f32_e32 v10, v11, v10
	v_max_f32_e32 v11, v5, v5
	v_max_f32_e32 v12, v4, v4
	v_max_f32_e32 v11, v12, v11
	v_max_f32_e32 v12, v9, v9
	v_max_f32_e32 v13, v8, v8
	v_max_f32_e32 v12, v13, v12
	v_max3_f32 v12, v6, v7, v12
	v_max3_f32 v10, v10, v11, v12
	v_cndmask_b32_e64 v34, v220, v10, s[10:11]
	v_mov_b64_e32 v[10:11], v[36:37]
	v_cmp_gt_f32_e32 vcc, v34, v0
	v_mov_b64_e32 v[12:13], v[38:39]
	s_cbranch_vccz .LBB0_985
	ds_bpermute_b32 v10, v225, v34
	v_max_f32_e32 v11, v34, v34
	s_waitcnt lgkmcnt(0)
	v_max_f32_e32 v10, v10, v10
	v_max_f32_e32 v10, v11, v10
	ds_bpermute_b32 v11, v224, v10
	s_waitcnt lgkmcnt(0)
	v_max3_f32 v202, v203, v10, v11
	v_sub_f32_e32 v10, v203, v202
	v_exp_f32_e32 v34, v10
	s_nop 0
	v_mul_f32_e32 v133, v204, v34
	v_pk_mul_f32 v[12:13], v[38:39], v[34:35] op_sel_hi:[1,0]
	v_pk_mul_f32 v[10:11], v[36:37], v[34:35] op_sel_hi:[1,0]
	v_pk_mul_f32 v[16:17], v[42:43], v[34:35] op_sel_hi:[1,0]
	v_pk_mul_f32 v[14:15], v[40:41], v[34:35] op_sel_hi:[1,0]
	v_pk_mul_f32 v[20:21], v[46:47], v[34:35] op_sel_hi:[1,0]
	v_pk_mul_f32 v[18:19], v[44:45], v[34:35] op_sel_hi:[1,0]
	v_pk_mul_f32 v[24:25], v[50:51], v[34:35] op_sel_hi:[1,0]
	v_pk_mul_f32 v[22:23], v[48:49], v[34:35] op_sel_hi:[1,0]
	v_pk_mul_f32 v[28:29], v[54:55], v[34:35] op_sel_hi:[1,0]
	v_pk_mul_f32 v[26:27], v[52:53], v[34:35] op_sel_hi:[1,0]
	v_pk_mul_f32 v[32:33], v[58:59], v[34:35] op_sel_hi:[1,0]
	v_pk_mul_f32 v[30:31], v[56:57], v[34:35] op_sel_hi:[1,0]
	v_pk_mul_f32 v[70:71], v[62:63], v[34:35] op_sel_hi:[1,0]
	v_pk_mul_f32 v[68:69], v[60:61], v[34:35] op_sel_hi:[1,0]
	v_pk_mul_f32 v[74:75], v[66:67], v[34:35] op_sel_hi:[1,0]
	v_pk_mul_f32 v[72:73], v[64:65], v[34:35] op_sel_hi:[1,0]
.LBB0_985:
	v_add_f32_e32 v34, -4.0, v202
	v_sub_f32_e32 v2, v2, v34
	v_sub_f32_e32 v6, v6, v34
	v_sub_f32_e32 v3, v3, v34
	v_sub_f32_e32 v7, v7, v34
	v_exp_f32_e32 v2, v2
	v_exp_f32_e32 v6, v6
	v_exp_f32_e32 v3, v3
	v_exp_f32_e32 v7, v7
	v_sub_f32_e32 v4, v4, v34
	v_sub_f32_e32 v8, v8, v34
	v_sub_f32_e32 v5, v5, v34
	v_sub_f32_e32 v9, v9, v34
	v_exp_f32_e32 v4, v4
	v_exp_f32_e32 v8, v8
	v_exp_f32_e32 v5, v5
	v_exp_f32_e32 v9, v9
	v_cndmask_b32_e64 v34, 0, v2, s[10:11]
	v_cndmask_b32_e64 v6, 0, v6, s[10:11]
	v_cndmask_b32_e64 v35, 0, v3, s[10:11]
	v_cndmask_b32_e64 v7, 0, v7, s[10:11]
	v_mov_b32_e32 v2, v1
	v_mov_b32_e32 v3, v1
	v_cvt_pk_fp8_f32 v2, v34, v35
	v_cvt_pk_fp8_f32 v3, v6, v7
	v_cndmask_b32_e64 v4, 0, v4, s[10:11]
	v_cndmask_b32_e64 v205, 0, v8, s[10:11]
	v_cndmask_b32_e64 v5, 0, v5, s[10:11]
	v_cndmask_b32_e64 v227, 0, v9, s[10:11]
	v_add_f32_e32 v6, v34, v6
	v_cvt_pk_fp8_f32 v2, v4, v5 op_sel:[0,0,1]
	v_cvt_pk_fp8_f32 v3, v205, v227 op_sel:[0,0,1]
	v_add_f32_e32 v6, 0, v6
	v_add_f32_e32 v7, v35, v7
	v_add_f32_e32 v6, v7, v6
	v_add_f32_e32 v4, v4, v205
	v_add_f32_e32 v4, v4, v6
	v_add_f32_e32 v5, v5, v227
	v_add_f32_e32 v4, v5, v4
	s_waitcnt vmcnt(19)
	v_mfma_f32_16x16x32_fp8_fp8 v[8:11], v[170:171], v[2:3], v[10:13]
	v_add_f32_e32 v133, v133, v4
	s_mov_b64 s[10:11], 0
	v_mfma_f32_16x16x32_fp8_fp8 v[12:15], v[172:173], v[2:3], v[14:17]
	s_waitcnt vmcnt(18)
	v_mfma_f32_16x16x32_fp8_fp8 v[16:19], v[174:175], v[2:3], v[18:21]
	v_mfma_f32_16x16x32_fp8_fp8 v[20:23], v[176:177], v[2:3], v[22:25]
	s_waitcnt vmcnt(17)
	v_mfma_f32_16x16x32_fp8_fp8 v[24:27], v[178:179], v[2:3], v[26:29]
	v_mfma_f32_16x16x32_fp8_fp8 v[32:35], v[180:181], v[2:3], v[30:33]
	s_waitcnt vmcnt(16)
	v_mfma_f32_16x16x32_fp8_fp8 v[28:31], v[182:183], v[2:3], v[68:71]
	v_mfma_f32_16x16x32_fp8_fp8 v[4:7], v[184:185], v[2:3], v[72:75]
	s_nop 1
; template <bool SLC, bool NOMASK> ...
;     const int kq = lane >> 4;
;     const int pos0 = SLC ? (dcur & 0xfffff) : dcur;
;     const int lo = SLC ? ((((dcur >> 20) == qi) | ((dcur >> 20) == 4)) ? 0 : (1 << 30)) : lo_in;
;     load_frag8(nxt, KF, VF, SLC ? (dnext & 0xfffff) : dnext, lane);
;     f32x4 sa[2] = {(f32x4){0.f, 0.f, 0.f, 0.f}, (f32x4){0.f, 0.f, 0.f, 0.f}};
; #pragma unroll
;     for (int T = 0; T < 2; ++T)
; #pragma unroll
;         for (int s2 = 0; s2 < 4; ++s2) sa[T] = __builtin_amdgcn_mfma_f32_16x16x32_fp8_fp8(cur.k[T][s2], qf[s2], sa[T], 0, 0, 0);
;     float sc[8]; bool vd[8]; float mx = -1e30f;
;     const bool act = lo == 0 || !SLC;
;     if (NOMASK) {
; #pragma unroll
;         for (int j = 0; j < 8; ++j) { sc[j] = sa[j >> 2][j & 3]; vd[j] = act; }
;         mx = fmaxf(fmaxf(fmaxf(sc[0], sc[1]), fmaxf(sc[2], sc[3])), fmaxf(fmaxf(sc[4], sc[5]), fmaxf(sc[6], sc[7])));
;         mx = act ? mx : -1e30f;
;     } else {
; #pragma unroll
;         for (int T = 0; T < 2; ++T)
; #pragma unroll
;             for (int r = 0; r < 4; ++r) { const int p = pos0 + 16 * T + 4 * kq + r; const bool v = (p >= lo) & (p <= hi); const float x = sa[T][r];
;                 sc[4 * T + r] = x; vd[4 * T + r] = v; mx = v ? fmaxf(mx, x) : mx; }
;     }
;     if (__builtin_amdgcn_ballot_w64(mx > st.m + 4.f) != 0ull) {
;         mx = fmaxf(mx, __shfl_xor(mx, 16)); mx = fmaxf(mx, __shfl_xor(mx, 32));
;         const float mn = fmaxf(st.m, mx), alpha = __builtin_amdgcn_exp2f(st.m - mn); st.m = mn; st.l *= alpha;
; #pragma unroll
;         for (int j = 0; j < 8; ++j) st.o[j] = st.o[j] * alpha;
;     }
.LBB0_986:
	s_and_b64 vcc, exec, s[10:11]
	s_cbranch_vccz .LBB0_990
	s_cmp_eq_u32 s12, 4
	s_cselect_b64 s[10:11], -1, 0
	s_lshl_b32 s13, s92, 7
	s_and_b32 s50, s13, 0x7fff800
	v_lshl_add_u64 v[10:11], v[86:87], 0, s[50:51]
	s_and_b32 s50, s13, 0x7fff000
	v_lshl_add_u64 v[246:247], v[10:11], 0, v[120:121]
	global_load_dwordx4 v[154:157], v[246:247], off
	global_load_dwordx4 v[158:161], v[246:247], off offset:1024
	global_load_dwordx4 v[162:165], v[246:247], off offset:2048
	global_load_dwordx4 v[166:169], v[246:247], off offset:3072
	v_lshl_add_u64 v[10:11], v[88:89], 0, s[50:51]
	v_lshl_add_u64 v[244:245], v[10:11], 0, v[120:121]
	global_load_dwordx4 v[106:109], v[244:245], off
	global_load_dwordx4 v[110:113], v[244:245], off offset:1024
	global_load_dwordx4 v[114:117], v[244:245], off offset:2048
	global_load_dwordx4 v[134:137], v[244:245], off offset:3072
	s_waitcnt vmcnt(20)
	v_mfma_f32_16x16x32_fp8_fp8 v[2:5], v[186:187], v[78:79], 0
	s_and_b32 s13, s66, 0xfffff
	v_cmp_eq_u32_e32 vcc, s12, v209
	v_add_u32_e32 v10, s13, v210
	v_mfma_f32_16x16x32_fp8_fp8 v[2:5], v[188:189], v[80:81], v[2:5]
	s_or_b64 s[18:19], s[10:11], vcc
	v_cmp_le_i32_e32 vcc, v10, v132
	s_and_b64 s[16:17], s[18:19], vcc
	v_mfma_f32_16x16x32_fp8_fp8 v[2:5], v[190:191], v[82:83], v[2:5]
	v_cmp_lt_i32_e32 vcc, v10, v132
	s_and_b64 s[12:13], s[18:19], vcc
	v_mfma_f32_16x16x32_fp8_fp8 v[6:9], v[194:195], v[78:79], 0
	v_mfma_f32_16x16x32_fp8_fp8 v[2:5], v[192:193], v[84:85], v[2:5]
	v_mfma_f32_16x16x32_fp8_fp8 v[6:9], v[196:197], v[80:81], v[6:9]
	v_mfma_f32_16x16x32_fp8_fp8 v[6:9], v[198:199], v[82:83], v[6:9]
	s_nop 5
	v_max_f32_e32 v11, v2, v2
	v_max_f32_e32 v11, 0xf149f2ca, v11
	v_cndmask_b32_e64 v11, v220, v11, s[16:17]
	v_max_f32_e32 v12, v3, v3
	v_max_f32_e32 v12, v11, v12
	v_cndmask_b32_e64 v11, v11, v12, s[12:13]
	v_add_u32_e32 v12, 2, v10
	v_cmp_le_i32_e32 vcc, v12, v132
	v_max_f32_e32 v12, v4, v4
	v_max_f32_e32 v12, v11, v12
	s_and_b64 s[14:15], s[18:19], vcc
	v_mfma_f32_16x16x32_fp8_fp8 v[6:9], v[200:201], v[84:85], v[6:9]
	v_cndmask_b32_e64 v11, v11, v12, s[14:15]
	v_add_u32_e32 v12, 3, v10
	v_cmp_le_i32_e32 vcc, v12, v132
	v_max_f32_e32 v12, v5, v5
	v_max_f32_e32 v12, v11, v12
	s_and_b64 s[10:11], s[18:19], vcc
	v_cndmask_b32_e64 v11, v11, v12, s[10:11]
	v_add_u32_e32 v12, 16, v10
	v_cmp_le_i32_e32 vcc, v12, v132
	v_max_f32_e32 v12, v6, v6
	v_max_f32_e32 v12, v11, v12
	s_and_b64 s[24:25], s[18:19], vcc
	v_cndmask_b32_e64 v11, v11, v12, s[24:25]
	v_add_u32_e32 v12, 17, v10
	v_cmp_le_i32_e32 vcc, v12, v132
	v_max_f32_e32 v12, v11, v11
	v_max_f32_e32 v13, v7, v7
	v_max_f32_e32 v12, v12, v13
	s_and_b64 s[20:21], s[18:19], vcc
	v_cndmask_b32_e64 v11, v11, v12, s[20:21]
	v_add_u32_e32 v12, 18, v10
	v_cmp_le_i32_e32 vcc, v12, v132
	v_max_f32_e32 v12, v11, v11
	v_max_f32_e32 v13, v8, v8
	v_max_f32_e32 v12, v12, v13
	s_and_b64 s[22:23], s[18:19], vcc
	v_cndmask_b32_e64 v11, v11, v12, s[22:23]
	v_add_u32_e32 v10, 19, v10
	v_cmp_le_i32_e32 vcc, v10, v132
	v_max_f32_e32 v10, v11, v11
	v_max_f32_e32 v12, v9, v9
	v_max_f32_e32 v10, v10, v12
	s_and_b64 s[18:19], s[18:19], vcc
	v_cndmask_b32_e64 v10, v11, v10, s[18:19]
	v_cmp_gt_f32_e32 vcc, v10, v0
	s_cbranch_vccz .LBB0_989
	ds_bpermute_b32 v0, v225, v10
	v_max_f32_e32 v10, v10, v10
	s_waitcnt lgkmcnt(0)
	v_max_f32_e32 v0, v0, v0
	v_max_f32_e32 v0, v10, v0
	ds_bpermute_b32 v10, v224, v0
	s_waitcnt lgkmcnt(0)
	v_max3_f32 v10, v203, v0, v10
	v_sub_f32_e32 v0, v203, v10
	v_exp_f32_e32 v0, v0
	v_mov_b32_e32 v203, v10
	v_mul_f32_e32 v204, v204, v0
	v_pk_mul_f32 v[38:39], v[38:39], v[0:1] op_sel_hi:[1,0]
	v_pk_mul_f32 v[36:37], v[36:37], v[0:1] op_sel_hi:[1,0]
	v_pk_mul_f32 v[42:43], v[42:43], v[0:1] op_sel_hi:[1,0]
	v_pk_mul_f32 v[40:41], v[40:41], v[0:1] op_sel_hi:[1,0]
	v_pk_mul_f32 v[46:47], v[46:47], v[0:1] op_sel_hi:[1,0]
	v_pk_mul_f32 v[44:45], v[44:45], v[0:1] op_sel_hi:[1,0]
	v_pk_mul_f32 v[50:51], v[50:51], v[0:1] op_sel_hi:[1,0]
	v_pk_mul_f32 v[48:49], v[48:49], v[0:1] op_sel_hi:[1,0]
	v_pk_mul_f32 v[54:55], v[54:55], v[0:1] op_sel_hi:[1,0]
	v_pk_mul_f32 v[52:53], v[52:53], v[0:1] op_sel_hi:[1,0]
	v_pk_mul_f32 v[58:59], v[58:59], v[0:1] op_sel_hi:[1,0]
	v_pk_mul_f32 v[56:57], v[56:57], v[0:1] op_sel_hi:[1,0]
	v_pk_mul_f32 v[62:63], v[62:63], v[0:1] op_sel_hi:[1,0]
	v_pk_mul_f32 v[60:61], v[60:61], v[0:1] op_sel_hi:[1,0]
	v_pk_mul_f32 v[66:67], v[66:67], v[0:1] op_sel_hi:[1,0]
	v_pk_mul_f32 v[64:65], v[64:65], v[0:1] op_sel_hi:[1,0]

; template <bool SLC, bool NOMASK> ...
;     const int kq = lane >> 4;
;     const int pos0 = SLC ? (dcur & 0xfffff) : dcur;
;     const int lo = SLC ? ((((dcur >> 20) == qi) | ((dcur >> 20) == 4)) ? 0 : (1 << 30)) : lo_in;
;     load_frag8(nxt, KF, VF, SLC ? (dnext & 0xfffff) : dnext, lane);
;     f32x4 sa[2] = {(f32x4){0.f, 0.f, 0.f, 0.f}, (f32x4){0.f, 0.f, 0.f, 0.f}};
; #pragma unroll
;     for (int T = 0; T < 2; ++T)
; #pragma unroll
;         for (int s2 = 0; s2 < 4; ++s2) sa[T] = __builtin_amdgcn_mfma_f32_16x16x32_fp8_fp8(cur.k[T][s2], qf[s2], sa[T], 0, 0, 0);
;     float sc[8]; bool vd[8]; float mx = -1e30f;
;     const bool act = lo == 0 || !SLC;
;     if (NOMASK) {
; #pragma unroll
;         for (int j = 0; j < 8; ++j) { sc[j] = sa[j >> 2][j & 3]; vd[j] = act; }
;         mx = fmaxf(fmaxf(fmaxf(sc[0], sc[1]), fmaxf(sc[2], sc[3])), fmaxf(fmaxf(sc[4], sc[5]), fmaxf(sc[6], sc[7])));
;         mx = act ? mx : -1e30f;
;     } else {
; #pragma unroll
;         for (int T = 0; T < 2; ++T)
; #pragma unroll
;             for (int r = 0; r < 4; ++r) { const int p = pos0 + 16 * T + 4 * kq + r; const bool v = (p >= lo) & (p <= hi); const float x = sa[T][r];
;                 sc[4 * T + r] = x; vd[4 * T + r] = v; mx = v ? fmaxf(mx, x) : mx; }
;     }
;     if (__builtin_amdgcn_ballot_w64(mx > st.m + 4.f) != 0ull) {
;         mx = fmaxf(mx, __shfl_xor(mx, 16)); mx = fmaxf(mx, __shfl_xor(mx, 32));
;         const float mn = fmaxf(st.m, mx), alpha = __builtin_amdgcn_exp2f(st.m - mn); st.m = mn; st.l *= alpha;
; #pragma unroll
;         for (int j = 0; j < 8; ++j) st.o[j] = st.o[j] * alpha;
;     }
;     f32x4 pa, pb; float ps = 0.f;
;     const float mref = st.m - 4.f;
;     if (NOMASK) {
; #pragma unroll
;         for (int j = 0; j < 4; ++j) { pa[j] = __builtin_amdgcn_exp2f(sc[j] - mref); pb[j] = __builtin_amdgcn_exp2f(sc[4 + j] - mref); }
;         if (SLC) {
; #pragma unroll
;             for (int j = 0; j < 4; ++j) { pa[j] = act ? pa[j] : 0.f; pb[j] = act ? pb[j] : 0.f; }
;         }
; #pragma unroll
;         for (int j = 0; j < 4; ++j) ps += pa[j] + pb[j];
;     } else {
; #pragma unroll
;         for (int j = 0; j < 4; ++j) { pa[j] = vd[j] ? __builtin_amdgcn_exp2f(sc[j] - mref) : 0.f; pb[j] = vd[4 + j] ? __builtin_amdgcn_exp2f(sc[4 + j] - mref) : 0.f; ps += pa[j] + pb[j]; }
;     }
;     st.l += ps;
;     const u32x2 pw = pack8_fp8(pa, pb);
.LBB0_1002:
	v_lshl_add_u64 v[246:247], v[204:205], 0, v[120:121]
	global_load_dwordx4 v[186:189], v[246:247], off
	global_load_dwordx4 v[190:193], v[246:247], off offset:1024
	global_load_dwordx4 v[194:197], v[246:247], off offset:2048
	global_load_dwordx4 v[198:201], v[246:247], off offset:3072
	v_lshl_add_u64 v[244:245], v[202:203], 0, v[120:121]
	global_load_dwordx4 v[170:173], v[244:245], off
	global_load_dwordx4 v[174:177], v[244:245], off offset:1024
	global_load_dwordx4 v[178:181], v[244:245], off offset:2048
	global_load_dwordx4 v[182:185], v[244:245], off offset:3072
	s_waitcnt vmcnt(20)
	v_mfma_f32_16x16x32_fp8_fp8 v[2:5], v[138:139], v[78:79], 0
	v_mov_b64_e32 v[74:75], v[38:39]
	v_mov_b64_e32 v[70:71], v[42:43]
	v_mov_b64_e32 v[30:31], v[44:45]
	v_mfma_f32_16x16x32_fp8_fp8 v[6:9], v[146:147], v[78:79], 0
	v_mov_b64_e32 v[26:27], v[48:49]
	v_mov_b64_e32 v[22:23], v[52:53]
	v_mov_b64_e32 v[18:19], v[56:57]
	v_mfma_f32_16x16x32_fp8_fp8 v[2:5], v[140:141], v[80:81], v[2:5]
	v_mov_b64_e32 v[14:15], v[60:61]
	v_mov_b32_e32 v228, v133
	v_mov_b64_e32 v[72:73], v[36:37]
	v_mfma_f32_16x16x32_fp8_fp8 v[6:9], v[148:149], v[80:81], v[6:9]
	v_mov_b64_e32 v[68:69], v[40:41]
	v_mov_b64_e32 v[32:33], v[46:47]
	v_mov_b64_e32 v[28:29], v[50:51]
	v_mfma_f32_16x16x32_fp8_fp8 v[2:5], v[142:143], v[82:83], v[2:5]
	v_mov_b64_e32 v[24:25], v[54:55]
	v_mov_b64_e32 v[20:21], v[58:59]
	v_mov_b64_e32 v[16:17], v[62:63]
	v_mfma_f32_16x16x32_fp8_fp8 v[6:9], v[150:151], v[82:83], v[6:9]
	v_mov_b32_e32 v34, v227
	v_mfma_f32_16x16x32_fp8_fp8 v[2:5], v[144:145], v[84:85], v[2:5]
	v_mfma_f32_16x16x32_fp8_fp8 v[6:9], v[152:153], v[84:85], v[6:9]
	s_nop 6
	v_max_f32_e32 v0, v3, v3
	v_max_f32_e32 v10, v2, v2
	v_max_f32_e32 v0, v10, v0
	v_max_f32_e32 v10, v5, v5
	v_max_f32_e32 v11, v4, v4
	v_max_f32_e32 v10, v11, v10
	v_max_f32_e32 v11, v9, v9
	v_max_f32_e32 v12, v8, v8
	v_max_f32_e32 v11, v12, v11
	v_max3_f32 v11, v6, v7, v11
	v_max3_f32 v0, v0, v10, v11
	v_add_f32_e32 v10, 4.0, v133
	v_cmp_gt_f32_e32 vcc, v0, v10
	v_mov_b64_e32 v[10:11], v[64:65]
	v_mov_b64_e32 v[12:13], v[66:67]
	s_cbranch_vccz .LBB0_1004
	ds_bpermute_b32 v10, v225, v0
	v_max_f32_e32 v0, v0, v0
	s_waitcnt lgkmcnt(0)
	v_max_f32_e32 v10, v10, v10
	v_max_f32_e32 v0, v0, v10
	ds_bpermute_b32 v10, v224, v0
	s_waitcnt lgkmcnt(0)
	v_max3_f32 v228, v133, v0, v10
	v_sub_f32_e32 v0, v133, v228
	v_exp_f32_e32 v0, v0
	s_nop 0
	v_mul_f32_e32 v34, v227, v0
	v_pk_mul_f32 v[12:13], v[66:67], v[0:1] op_sel_hi:[1,0]
	v_pk_mul_f32 v[10:11], v[64:65], v[0:1] op_sel_hi:[1,0]
	v_pk_mul_f32 v[16:17], v[62:63], v[0:1] op_sel_hi:[1,0]
	v_pk_mul_f32 v[14:15], v[60:61], v[0:1] op_sel_hi:[1,0]
	v_pk_mul_f32 v[20:21], v[58:59], v[0:1] op_sel_hi:[1,0]
	v_pk_mul_f32 v[18:19], v[56:57], v[0:1] op_sel_hi:[1,0]
	v_pk_mul_f32 v[24:25], v[54:55], v[0:1] op_sel_hi:[1,0]
	v_pk_mul_f32 v[22:23], v[52:53], v[0:1] op_sel_hi:[1,0]
	v_pk_mul_f32 v[28:29], v[50:51], v[0:1] op_sel_hi:[1,0]
	v_pk_mul_f32 v[26:27], v[48:49], v[0:1] op_sel_hi:[1,0]
	v_pk_mul_f32 v[32:33], v[46:47], v[0:1] op_sel_hi:[1,0]
	v_pk_mul_f32 v[30:31], v[44:45], v[0:1] op_sel_hi:[1,0]
	v_pk_mul_f32 v[70:71], v[42:43], v[0:1] op_sel_hi:[1,0]
	v_pk_mul_f32 v[68:69], v[40:41], v[0:1] op_sel_hi:[1,0]
	v_pk_mul_f32 v[74:75], v[38:39], v[0:1] op_sel_hi:[1,0]
	v_pk_mul_f32 v[72:73], v[36:37], v[0:1] op_sel_hi:[1,0]
.LBB0_1004:
	v_add_f32_e32 v229, -4.0, v228
	v_sub_f32_e32 v0, v2, v229
	v_exp_f32_e32 v231, v0
	v_sub_f32_e32 v0, v6, v229
	v_exp_f32_e32 v234, v0
	v_sub_f32_e32 v0, v3, v229
	v_exp_f32_e32 v2, v0
	v_sub_f32_e32 v0, v7, v229
	v_exp_f32_e32 v0, v0
	v_sub_f32_e32 v3, v4, v229
	v_exp_f32_e32 v235, v3
	v_sub_f32_e32 v3, v8, v229
	v_exp_f32_e32 v236, v3
	v_sub_f32_e32 v3, v5, v229
	v_exp_f32_e32 v4, v3
	v_sub_f32_e32 v3, v9, v229
	v_mov_b32_e32 v232, v1
	v_mov_b32_e32 v233, v1
	v_exp_f32_e32 v230, v3
	v_cvt_pk_fp8_f32 v232, v231, v2
	v_cvt_pk_fp8_f32 v233, v234, v0
	v_add_f32_e32 v3, v231, v234
	v_pk_add_f32 v[2:3], v[2:3], v[0:1]
	v_cvt_pk_fp8_f32 v232, v235, v4 op_sel:[0,0,1]
	v_cvt_pk_fp8_f32 v233, v236, v230 op_sel:[0,0,1]
	v_pk_add_f32 v[2:3], v[2:3], v[2:3] op_sel_hi:[0,1]
	v_add_f32_e32 v5, v235, v236
	v_mov_b32_e32 v231, v3
	v_pk_add_f32 v[2:3], v[4:5], v[230:231]
	s_waitcnt vmcnt(19)
	v_mfma_f32_16x16x32_fp8_fp8 v[6:9], v[90:91], v[232:233], v[10:13]
	v_add_f32_e32 v0, v2, v3
	v_add_f32_e32 v34, v0, v34
	v_mfma_f32_16x16x32_fp8_fp8 v[10:13], v[92:93], v[232:233], v[14:17]
	s_waitcnt vmcnt(18)
	v_mfma_f32_16x16x32_fp8_fp8 v[14:17], v[94:95], v[232:233], v[18:21]
	v_mfma_f32_16x16x32_fp8_fp8 v[18:21], v[96:97], v[232:233], v[22:25]
	s_waitcnt vmcnt(17)
	v_mfma_f32_16x16x32_fp8_fp8 v[22:25], v[98:99], v[232:233], v[26:29]
	v_mfma_f32_16x16x32_fp8_fp8 v[26:29], v[100:101], v[232:233], v[30:33]
	s_waitcnt vmcnt(16)
	v_mfma_f32_16x16x32_fp8_fp8 v[30:33], v[102:103], v[232:233], v[68:71]
	v_mfma_f32_16x16x32_fp8_fp8 v[2:5], v[104:105], v[232:233], v[72:75]
	s_nop 1
	s_branch .LBB0_998
; template <bool SLC, bool NOMASK> ...
;     const int kq = lane >> 4;
;     const int pos0 = SLC ? (dcur & 0xfffff) : dcur;
;     const int lo = SLC ? ((((dcur >> 20) == qi) | ((dcur >> 20) == 4)) ? 0 : (1 << 30)) : lo_in;
;     load_frag8(nxt, KF, VF, SLC ? (dnext & 0xfffff) : dnext, lane);
;     f32x4 sa[2] = {(f32x4){0.f, 0.f, 0.f, 0.f}, (f32x4){0.f, 0.f, 0.f, 0.f}};
; #pragma unroll
;     for (int T = 0; T < 2; ++T)
; #pragma unroll
;         for (int s2 = 0; s2 < 4; ++s2) sa[T] = __builtin_amdgcn_mfma_f32_16x16x32_fp8_fp8(cur.k[T][s2], qf[s2], sa[T], 0, 0, 0);
;     float sc[8]; bool vd[8]; float mx = -1e30f;
;     const bool act = lo == 0 || !SLC;
;     if (NOMASK) {
; #pragma unroll
;         for (int j = 0; j < 8; ++j) { sc[j] = sa[j >> 2][j & 3]; vd[j] = act; }
;         mx = fmaxf(fmaxf(fmaxf(sc[0], sc[1]), fmaxf(sc[2], sc[3])), fmaxf(fmaxf(sc[4], sc[5]), fmaxf(sc[6], sc[7])));
;         mx = act ? mx : -1e30f;
;     } else {
; #pragma unroll
;         for (int T = 0; T < 2; ++T)
; #pragma unroll
;             for (int r = 0; r < 4; ++r) { const int p = pos0 + 16 * T + 4 * kq + r; const bool v = (p >= lo) & (p <= hi); const float x = sa[T][r];
;                 sc[4 * T + r] = x; vd[4 * T + r] = v; mx = v ? fmaxf(mx, x) : mx; }
;     }
;     if (__builtin_amdgcn_ballot_w64(mx > st.m + 4.f) != 0ull) {
;         mx = fmaxf(mx, __shfl_xor(mx, 16)); mx = fmaxf(mx, __shfl_xor(mx, 32));
;         const float mn = fmaxf(st.m, mx), alpha = __builtin_amdgcn_exp2f(st.m - mn); st.m = mn; st.l *= alpha;
; #pragma unroll
;         for (int j = 0; j < 8; ++j) st.o[j] = st.o[j] * alpha;
;     }
;     f32x4 pa, pb; float ps = 0.f;
;     const float mref = st.m - 4.f;
;     if (NOMASK) {
; #pragma unroll
;         for (int j = 0; j < 4; ++j) { pa[j] = __builtin_amdgcn_exp2f(sc[j] - mref); pb[j] = __builtin_amdgcn_exp2f(sc[4 + j] - mref); }
;         if (SLC) {
; #pragma unroll
;             for (int j = 0; j < 4; ++j) { pa[j] = act ? pa[j] : 0.f; pb[j] = act ? pb[j] : 0.f; }
;         }
; #pragma unroll
;         for (int j = 0; j < 4; ++j) ps += pa[j] + pb[j];
;     } else {
; #pragma unroll
;         for (int j = 0; j < 4; ++j) { pa[j] = vd[j] ? __builtin_amdgcn_exp2f(sc[j] - mref) : 0.f; pb[j] = vd[4 + j] ? __builtin_amdgcn_exp2f(sc[4 + j] - mref) : 0.f; ps += pa[j] + pb[j]; }
;     }
;     st.l += ps;
;     const u32x2 pw = pack8_fp8(pa, pb);
.LBB0_1005:
	v_lshl_add_u64 v[246:247], v[204:205], 0, v[120:121]
	global_load_dwordx4 v[186:189], v[246:247], off
	global_load_dwordx4 v[190:193], v[246:247], off offset:1024
	global_load_dwordx4 v[194:197], v[246:247], off offset:2048
	global_load_dwordx4 v[198:201], v[246:247], off offset:3072
	v_lshl_add_u64 v[244:245], v[202:203], 0, v[120:121]
	global_load_dwordx4 v[170:173], v[244:245], off
	global_load_dwordx4 v[174:177], v[244:245], off offset:1024
	global_load_dwordx4 v[178:181], v[244:245], off offset:2048
	global_load_dwordx4 v[182:185], v[244:245], off offset:3072
	s_waitcnt vmcnt(20)
	v_mfma_f32_16x16x32_fp8_fp8 v[2:5], v[138:139], v[78:79], 0
	v_add_u32_e32 v0, s14, v210
	v_cmp_ge_i32_e32 vcc, v0, v35
	v_cmp_le_i32_e64 s[10:11], v0, v132
	v_mfma_f32_16x16x32_fp8_fp8 v[2:5], v[140:141], v[80:81], v[2:5]
	s_and_b64 s[16:17], vcc, s[10:11]
	v_add_u32_e32 v11, 1, v0
	v_cmp_ge_i32_e32 vcc, v11, v35
	v_mfma_f32_16x16x32_fp8_fp8 v[2:5], v[142:143], v[82:83], v[2:5]
	v_cmp_lt_i32_e64 s[10:11], v0, v132
	s_and_b64 s[12:13], s[10:11], vcc
	v_mfma_f32_16x16x32_fp8_fp8 v[6:9], v[146:147], v[78:79], 0
	v_mfma_f32_16x16x32_fp8_fp8 v[2:5], v[144:145], v[84:85], v[2:5]
	v_mfma_f32_16x16x32_fp8_fp8 v[6:9], v[148:149], v[80:81], v[6:9]
	v_mfma_f32_16x16x32_fp8_fp8 v[6:9], v[150:151], v[82:83], v[6:9]
	s_nop 5
	v_max_f32_e32 v10, v2, v2
	v_max_f32_e32 v10, 0xf149f2ca, v10
	v_cndmask_b32_e64 v10, v220, v10, s[16:17]
	v_max_f32_e32 v11, v3, v3
	v_max_f32_e32 v11, v10, v11
	v_cndmask_b32_e64 v10, v10, v11, s[12:13]
	v_add_u32_e32 v11, 2, v0
	v_cmp_ge_i32_e32 vcc, v11, v35
	v_cmp_le_i32_e64 s[10:11], v11, v132
	v_max_f32_e32 v11, v4, v4
	v_max_f32_e32 v11, v10, v11
	s_and_b64 s[14:15], vcc, s[10:11]
	v_mfma_f32_16x16x32_fp8_fp8 v[6:9], v[152:153], v[84:85], v[6:9]
	v_cndmask_b32_e64 v10, v10, v11, s[14:15]
	v_add_u32_e32 v11, 3, v0
	v_cmp_ge_i32_e32 vcc, v11, v35
	v_cmp_le_i32_e64 s[10:11], v11, v132
	v_max_f32_e32 v11, v5, v5
	v_max_f32_e32 v11, v10, v11
	s_and_b64 s[10:11], vcc, s[10:11]
	v_cndmask_b32_e64 v10, v10, v11, s[10:11]
	v_add_u32_e32 v11, 16, v0
	v_cmp_ge_i32_e32 vcc, v11, v35
	v_cmp_le_i32_e64 s[18:19], v11, v132
	v_max_f32_e32 v11, v6, v6
	v_max_f32_e32 v11, v10, v11
	s_and_b64 s[24:25], vcc, s[18:19]
	v_cndmask_b32_e64 v10, v10, v11, s[24:25]
	v_add_u32_e32 v11, 17, v0
	v_cmp_ge_i32_e32 vcc, v11, v35
	v_cmp_le_i32_e64 s[18:19], v11, v132
	v_max_f32_e32 v11, v10, v10
	v_max_f32_e32 v12, v7, v7
	v_max_f32_e32 v11, v11, v12
	s_and_b64 s[20:21], vcc, s[18:19]
	v_cndmask_b32_e64 v10, v10, v11, s[20:21]
	v_add_u32_e32 v11, 18, v0
	v_cmp_ge_i32_e32 vcc, v11, v35
	v_cmp_le_i32_e64 s[18:19], v11, v132
	v_max_f32_e32 v11, v10, v10
	v_max_f32_e32 v12, v8, v8
	v_max_f32_e32 v11, v11, v12
	s_and_b64 s[22:23], vcc, s[18:19]
	v_cndmask_b32_e64 v10, v10, v11, s[22:23]
	v_add_u32_e32 v0, 19, v0
	v_cmp_ge_i32_e32 vcc, v0, v35
	v_cmp_le_i32_e64 s[18:19], v0, v132
	v_max_f32_e32 v0, v10, v10
	v_max_f32_e32 v11, v9, v9
	v_max_f32_e32 v0, v0, v11
	s_and_b64 s[18:19], vcc, s[18:19]
	v_cndmask_b32_e64 v0, v10, v0, s[18:19]
	v_add_f32_e32 v10, 4.0, v133
	v_cmp_gt_f32_e32 vcc, v0, v10
	s_cbranch_vccz .LBB0_1007
	ds_bpermute_b32 v10, v225, v0
	v_max_f32_e32 v0, v0, v0
	s_waitcnt lgkmcnt(0)
	v_max_f32_e32 v10, v10, v10
	v_max_f32_e32 v0, v0, v10
	ds_bpermute_b32 v10, v224, v0
	s_waitcnt lgkmcnt(0)
	v_max3_f32 v10, v133, v0, v10
	v_sub_f32_e32 v0, v133, v10
	v_exp_f32_e32 v0, v0
	v_mov_b32_e32 v133, v10
	v_mul_f32_e32 v227, v227, v0
	v_pk_mul_f32 v[66:67], v[66:67], v[0:1] op_sel_hi:[1,0]
	v_pk_mul_f32 v[64:65], v[64:65], v[0:1] op_sel_hi:[1,0]
	v_pk_mul_f32 v[62:63], v[62:63], v[0:1] op_sel_hi:[1,0]
	v_pk_mul_f32 v[60:61], v[60:61], v[0:1] op_sel_hi:[1,0]
	v_pk_mul_f32 v[58:59], v[58:59], v[0:1] op_sel_hi:[1,0]
	v_pk_mul_f32 v[56:57], v[56:57], v[0:1] op_sel_hi:[1,0]
	v_pk_mul_f32 v[54:55], v[54:55], v[0:1] op_sel_hi:[1,0]
	v_pk_mul_f32 v[52:53], v[52:53], v[0:1] op_sel_hi:[1,0]
	v_pk_mul_f32 v[50:51], v[50:51], v[0:1] op_sel_hi:[1,0]
	v_pk_mul_f32 v[48:49], v[48:49], v[0:1] op_sel_hi:[1,0]
	v_pk_mul_f32 v[46:47], v[46:47], v[0:1] op_sel_hi:[1,0]
	v_pk_mul_f32 v[44:45], v[44:45], v[0:1] op_sel_hi:[1,0]
	v_pk_mul_f32 v[42:43], v[42:43], v[0:1] op_sel_hi:[1,0]
	v_pk_mul_f32 v[40:41], v[40:41], v[0:1] op_sel_hi:[1,0]
	v_pk_mul_f32 v[38:39], v[38:39], v[0:1] op_sel_hi:[1,0]
	v_pk_mul_f32 v[36:37], v[36:37], v[0:1] op_sel_hi:[1,0]
.LBB0_1007:
	v_add_f32_e32 v0, -4.0, v133
	v_sub_f32_e32 v2, v2, v0
	v_exp_f32_e32 v2, v2
	v_sub_f32_e32 v6, v6, v0
	v_exp_f32_e32 v6, v6
	v_sub_f32_e32 v4, v4, v0
	v_cndmask_b32_e64 v26, 0, v2, s[16:17]
	v_sub_f32_e32 v2, v3, v0
	v_exp_f32_e32 v2, v2
	v_sub_f32_e32 v3, v7, v0
	v_exp_f32_e32 v3, v3
	v_cndmask_b32_e64 v27, 0, v6, s[24:25]
	v_sub_f32_e32 v6, v8, v0
	v_cndmask_b32_e64 v28, 0, v2, s[12:13]
	v_sub_f32_e32 v2, v5, v0
	v_sub_f32_e32 v0, v9, v0
	v_exp_f32_e32 v4, v4
	v_exp_f32_e32 v6, v6
	v_cndmask_b32_e64 v29, 0, v3, s[20:21]
	v_exp_f32_e32 v5, v2
	v_exp_f32_e32 v0, v0
	v_mov_b32_e32 v2, v1
	v_mov_b32_e32 v3, v1
	v_cvt_pk_fp8_f32 v2, v26, v28
	v_cvt_pk_fp8_f32 v3, v27, v29
	v_cndmask_b32_e64 v4, 0, v4, s[14:15]
	v_cndmask_b32_e64 v30, 0, v6, s[22:23]
	v_cndmask_b32_e64 v5, 0, v5, s[10:11]
	v_cndmask_b32_e64 v0, 0, v0, s[18:19]
	v_cvt_pk_fp8_f32 v2, v4, v5 op_sel:[0,0,1]
	v_cvt_pk_fp8_f32 v3, v30, v0 op_sel:[0,0,1]
	v_add_f32_e32 v26, v26, v27
	v_add_f32_e32 v31, 0, v26
	v_add_f32_e32 v32, v28, v29
	v_add_f32_e32 v31, v32, v31
	v_add_f32_e32 v4, v4, v30
	v_add_f32_e32 v4, v4, v31
	v_add_f32_e32 v0, v5, v0
	s_waitcnt vmcnt(19)
	v_mfma_f32_16x16x32_fp8_fp8 v[6:9], v[90:91], v[2:3], v[64:67]
	v_add_f32_e32 v0, v0, v4
	v_add_f32_e32 v34, v227, v0
	v_mov_b32_e32 v228, v133
	v_mfma_f32_16x16x32_fp8_fp8 v[10:13], v[92:93], v[2:3], v[60:63]
	s_waitcnt vmcnt(18)
	v_mfma_f32_16x16x32_fp8_fp8 v[14:17], v[94:95], v[2:3], v[56:59]
	v_mfma_f32_16x16x32_fp8_fp8 v[18:21], v[96:97], v[2:3], v[52:55]
	s_waitcnt vmcnt(17)
	v_mfma_f32_16x16x32_fp8_fp8 v[22:25], v[98:99], v[2:3], v[48:51]
	v_mfma_f32_16x16x32_fp8_fp8 v[26:29], v[100:101], v[2:3], v[44:47]
	s_waitcnt vmcnt(16)
	v_mfma_f32_16x16x32_fp8_fp8 v[30:33], v[102:103], v[2:3], v[40:43]
	v_mfma_f32_16x16x32_fp8_fp8 v[2:5], v[104:105], v[2:3], v[36:39]
	s_nop 1
	s_cmp_ge_i32 s56, s27
	s_mov_b64 s[10:11], -1
	s_cbranch_scc0 .LBB0_999

; template <bool SLC, bool NOMASK> ...
;     const int kq = lane >> 4;
;     const int pos0 = SLC ? (dcur & 0xfffff) : dcur;
;     const int lo = SLC ? ((((dcur >> 20) == qi) | ((dcur >> 20) == 4)) ? 0 : (1 << 30)) : lo_in;
;     load_frag8(nxt, KF, VF, SLC ? (dnext & 0xfffff) : dnext, lane);
;     f32x4 sa[2] = {(f32x4){0.f, 0.f, 0.f, 0.f}, (f32x4){0.f, 0.f, 0.f, 0.f}};
; #pragma unroll
;     for (int T = 0; T < 2; ++T)
; #pragma unroll
;         for (int s2 = 0; s2 < 4; ++s2) sa[T] = __builtin_amdgcn_mfma_f32_16x16x32_fp8_fp8(cur.k[T][s2], qf[s2], sa[T], 0, 0, 0);
;     float sc[8]; bool vd[8]; float mx = -1e30f;
;     const bool act = lo == 0 || !SLC;
;     if (NOMASK) {
; #pragma unroll
;         for (int j = 0; j < 8; ++j) { sc[j] = sa[j >> 2][j & 3]; vd[j] = act; }
;         mx = fmaxf(fmaxf(fmaxf(sc[0], sc[1]), fmaxf(sc[2], sc[3])), fmaxf(fmaxf(sc[4], sc[5]), fmaxf(sc[6], sc[7])));
;         mx = act ? mx : -1e30f;
;     } else {
; #pragma unroll
;         for (int T = 0; T < 2; ++T)
; #pragma unroll
;             for (int r = 0; r < 4; ++r) { const int p = pos0 + 16 * T + 4 * kq + r; const bool v = (p >= lo) & (p <= hi); const float x = sa[T][r];
;                 sc[4 * T + r] = x; vd[4 * T + r] = v; mx = v ? fmaxf(mx, x) : mx; }
;     }
;     if (__builtin_amdgcn_ballot_w64(mx > st.m + 4.f) != 0ull) {
;         mx = fmaxf(mx, __shfl_xor(mx, 16)); mx = fmaxf(mx, __shfl_xor(mx, 32));
;         const float mn = fmaxf(st.m, mx), alpha = __builtin_amdgcn_exp2f(st.m - mn); st.m = mn; st.l *= alpha;
; #pragma unroll
;         for (int j = 0; j < 8; ++j) st.o[j] = st.o[j] * alpha;
;     }
;     f32x4 pa, pb; float ps = 0.f;
;     const float mref = st.m - 4.f;
;     if (NOMASK) {
; #pragma unroll
;         for (int j = 0; j < 4; ++j) { pa[j] = __builtin_amdgcn_exp2f(sc[j] - mref); pb[j] = __builtin_amdgcn_exp2f(sc[4 + j] - mref); }
;         if (SLC) {
; #pragma unroll
;             for (int j = 0; j < 4; ++j) { pa[j] = act ? pa[j] : 0.f; pb[j] = act ? pb[j] : 0.f; }
;         }
; #pragma unroll
;         for (int j = 0; j < 4; ++j) ps += pa[j] + pb[j];
;     } else {
; #pragma unroll
;         for (int j = 0; j < 4; ++j) { pa[j] = vd[j] ? __builtin_amdgcn_exp2f(sc[j] - mref) : 0.f; pb[j] = vd[4 + j] ? __builtin_amdgcn_exp2f(sc[4 + j] - mref) : 0.f; ps += pa[j] + pb[j]; }
;     }
;     st.l += ps;
;     const u32x2 pw = pack8_fp8(pa, pb);
.LBB0_1009:
	v_lshl_add_u64 v[246:247], v[204:205], 0, v[120:121]
	global_load_dwordx4 v[138:141], v[246:247], off
	global_load_dwordx4 v[142:145], v[246:247], off offset:1024
	global_load_dwordx4 v[146:149], v[246:247], off offset:2048
	global_load_dwordx4 v[150:153], v[246:247], off offset:3072
	v_lshl_add_u64 v[244:245], v[202:203], 0, v[120:121]
	global_load_dwordx4 v[90:93], v[244:245], off
	global_load_dwordx4 v[94:97], v[244:245], off offset:1024
	global_load_dwordx4 v[98:101], v[244:245], off offset:2048
	global_load_dwordx4 v[102:105], v[244:245], off offset:3072
	s_waitcnt vmcnt(20)
	v_mfma_f32_16x16x32_fp8_fp8 v[36:39], v[154:155], v[78:79], 0
	v_mov_b64_e32 v[74:75], v[4:5]
	v_mov_b64_e32 v[70:71], v[32:33]
	v_mov_b64_e32 v[66:67], v[28:29]
	v_mfma_f32_16x16x32_fp8_fp8 v[40:43], v[162:163], v[78:79], 0
	v_mov_b64_e32 v[62:63], v[24:25]
	v_mov_b64_e32 v[58:59], v[20:21]
	v_mov_b64_e32 v[54:55], v[16:17]
	v_mfma_f32_16x16x32_fp8_fp8 v[36:39], v[156:157], v[80:81], v[36:39]
	v_mov_b64_e32 v[50:51], v[12:13]
	v_mov_b32_e32 v227, v228
	v_mov_b64_e32 v[72:73], v[2:3]
	v_mfma_f32_16x16x32_fp8_fp8 v[40:43], v[164:165], v[80:81], v[40:43]
	v_mov_b64_e32 v[68:69], v[30:31]
	v_mov_b64_e32 v[64:65], v[26:27]
	v_mov_b64_e32 v[60:61], v[22:23]
	v_mfma_f32_16x16x32_fp8_fp8 v[36:39], v[158:159], v[82:83], v[36:39]
	v_mov_b64_e32 v[56:57], v[18:19]
	v_mov_b64_e32 v[52:53], v[14:15]
	v_mov_b64_e32 v[48:49], v[10:11]
	v_mfma_f32_16x16x32_fp8_fp8 v[40:43], v[166:167], v[82:83], v[40:43]
	v_mov_b32_e32 v229, v34
	v_mfma_f32_16x16x32_fp8_fp8 v[36:39], v[160:161], v[84:85], v[36:39]
	v_mfma_f32_16x16x32_fp8_fp8 v[40:43], v[168:169], v[84:85], v[40:43]
	s_nop 6
	v_max_f32_e32 v0, v37, v37
	v_max_f32_e32 v44, v36, v36
	v_max_f32_e32 v0, v44, v0
	v_max_f32_e32 v44, v39, v39
	v_max_f32_e32 v45, v38, v38
	v_max_f32_e32 v44, v45, v44
	v_max_f32_e32 v45, v43, v43
	v_max_f32_e32 v46, v42, v42
	v_max_f32_e32 v45, v46, v45
	v_max3_f32 v45, v40, v41, v45
	v_max3_f32 v0, v0, v44, v45
	v_mov_b64_e32 v[46:47], v[8:9]
	v_cmp_gt_f32_e32 vcc, v0, v133
	v_mov_b64_e32 v[44:45], v[6:7]
	s_cbranch_vccz .LBB0_1011
	ds_bpermute_b32 v44, v225, v0
	v_max_f32_e32 v0, v0, v0
	s_waitcnt lgkmcnt(0)
	v_max_f32_e32 v44, v44, v44
	v_max_f32_e32 v0, v0, v44
	ds_bpermute_b32 v44, v224, v0
	s_waitcnt lgkmcnt(0)
	v_max3_f32 v227, v228, v0, v44
	v_sub_f32_e32 v0, v228, v227
	v_exp_f32_e32 v0, v0
	s_nop 0
	v_mul_f32_e32 v229, v34, v0
	v_pk_mul_f32 v[46:47], v[8:9], v[0:1] op_sel_hi:[1,0]
	v_pk_mul_f32 v[44:45], v[6:7], v[0:1] op_sel_hi:[1,0]
	v_pk_mul_f32 v[50:51], v[12:13], v[0:1] op_sel_hi:[1,0]
	v_pk_mul_f32 v[48:49], v[10:11], v[0:1] op_sel_hi:[1,0]
	v_pk_mul_f32 v[54:55], v[16:17], v[0:1] op_sel_hi:[1,0]
	v_pk_mul_f32 v[52:53], v[14:15], v[0:1] op_sel_hi:[1,0]
	v_pk_mul_f32 v[58:59], v[20:21], v[0:1] op_sel_hi:[1,0]
	v_pk_mul_f32 v[56:57], v[18:19], v[0:1] op_sel_hi:[1,0]
	v_pk_mul_f32 v[62:63], v[24:25], v[0:1] op_sel_hi:[1,0]
	v_pk_mul_f32 v[60:61], v[22:23], v[0:1] op_sel_hi:[1,0]
	v_pk_mul_f32 v[66:67], v[28:29], v[0:1] op_sel_hi:[1,0]
	v_pk_mul_f32 v[64:65], v[26:27], v[0:1] op_sel_hi:[1,0]
	v_pk_mul_f32 v[70:71], v[32:33], v[0:1] op_sel_hi:[1,0]
	v_pk_mul_f32 v[68:69], v[30:31], v[0:1] op_sel_hi:[1,0]
	v_pk_mul_f32 v[74:75], v[4:5], v[0:1] op_sel_hi:[1,0]
	v_pk_mul_f32 v[72:73], v[2:3], v[0:1] op_sel_hi:[1,0]
.LBB0_1011:
	v_add_f32_e32 v231, -4.0, v227
	v_sub_f32_e32 v0, v36, v231
	v_exp_f32_e32 v233, v0
	v_sub_f32_e32 v0, v40, v231
	v_exp_f32_e32 v235, v0
	v_sub_f32_e32 v0, v37, v231
	v_exp_f32_e32 v230, v0
	v_sub_f32_e32 v0, v41, v231
	v_exp_f32_e32 v0, v0
	v_sub_f32_e32 v36, v38, v231
	v_exp_f32_e32 v238, v36
	v_sub_f32_e32 v36, v42, v231
	v_exp_f32_e32 v239, v36
	v_sub_f32_e32 v36, v39, v231
	v_exp_f32_e32 v232, v36
	v_sub_f32_e32 v36, v43, v231
	v_mov_b32_e32 v236, v1
	v_mov_b32_e32 v237, v1
	v_exp_f32_e32 v234, v36
	v_cvt_pk_fp8_f32 v236, v233, v230
	v_cvt_pk_fp8_f32 v237, v235, v0
	v_add_f32_e32 v231, v233, v235
	v_add_f32_e32 v233, v238, v239
	v_cvt_pk_fp8_f32 v236, v238, v232 op_sel:[0,0,1]
	v_cvt_pk_fp8_f32 v237, v239, v234 op_sel:[0,0,1]
	s_nop 0
	s_waitcnt vmcnt(19)
	v_mfma_f32_16x16x32_fp8_fp8 v[36:39], v[106:107], v[236:237], v[44:47]
	v_mfma_f32_16x16x32_fp8_fp8 v[44:47], v[110:111], v[236:237], v[52:55]
	s_waitcnt vmcnt(18)
	v_mfma_f32_16x16x32_fp8_fp8 v[52:55], v[114:115], v[236:237], v[60:63]
	s_nop 2
	v_add_f32_e64 v60, v230, v0
	v_add_f32_e64 v61, v231, v1
	v_mfma_f32_16x16x32_fp8_fp8 v[40:43], v[108:109], v[236:237], v[48:51]
	v_pk_add_f32 v[60:61], v[60:61], v[60:61] op_sel_hi:[0,1]
	v_mov_b32_e32 v235, v61
	s_waitcnt vmcnt(17)
	v_mfma_f32_16x16x32_fp8_fp8 v[48:51], v[112:113], v[236:237], v[56:59]
	v_mfma_f32_16x16x32_fp8_fp8 v[56:59], v[116:117], v[236:237], v[64:67]
	s_nop 2
	v_add_f32_e64 v64, v232, v234
	v_add_f32_e64 v65, v233, v235
	s_waitcnt vmcnt(16)
	v_mfma_f32_16x16x32_fp8_fp8 v[60:63], v[134:135], v[236:237], v[68:71]
	v_add_f32_e32 v0, v64, v65
	v_add_f32_e32 v229, v0, v229
	v_mfma_f32_16x16x32_fp8_fp8 v[64:67], v[136:137], v[236:237], v[72:75]
	s_nop 1
	s_branch .LBB0_1001
; template <bool SLC, bool NOMASK> ...
;     const int kq = lane >> 4;
;     const int pos0 = SLC ? (dcur & 0xfffff) : dcur;
;     const int lo = SLC ? ((((dcur >> 20) == qi) | ((dcur >> 20) == 4)) ? 0 : (1 << 30)) : lo_in;
;     load_frag8(nxt, KF, VF, SLC ? (dnext & 0xfffff) : dnext, lane);
;     f32x4 sa[2] = {(f32x4){0.f, 0.f, 0.f, 0.f}, (f32x4){0.f, 0.f, 0.f, 0.f}};
; #pragma unroll
;     for (int T = 0; T < 2; ++T)
; #pragma unroll
;         for (int s2 = 0; s2 < 4; ++s2) sa[T] = __builtin_amdgcn_mfma_f32_16x16x32_fp8_fp8(cur.k[T][s2], qf[s2], sa[T], 0, 0, 0);
;     float sc[8]; bool vd[8]; float mx = -1e30f;
;     const bool act = lo == 0 || !SLC;
;     if (NOMASK) {
; #pragma unroll
;         for (int j = 0; j < 8; ++j) { sc[j] = sa[j >> 2][j & 3]; vd[j] = act; }
;         mx = fmaxf(fmaxf(fmaxf(sc[0], sc[1]), fmaxf(sc[2], sc[3])), fmaxf(fmaxf(sc[4], sc[5]), fmaxf(sc[6], sc[7])));
;         mx = act ? mx : -1e30f;
;     } else {
; #pragma unroll
;         for (int T = 0; T < 2; ++T)
; #pragma unroll
;             for (int r = 0; r < 4; ++r) { const int p = pos0 + 16 * T + 4 * kq + r; const bool v = (p >= lo) & (p <= hi); const float x = sa[T][r];
;                 sc[4 * T + r] = x; vd[4 * T + r] = v; mx = v ? fmaxf(mx, x) : mx; }
;     }
;     if (__builtin_amdgcn_ballot_w64(mx > st.m + 4.f) != 0ull) {
;         mx = fmaxf(mx, __shfl_xor(mx, 16)); mx = fmaxf(mx, __shfl_xor(mx, 32));
;         const float mn = fmaxf(st.m, mx), alpha = __builtin_amdgcn_exp2f(st.m - mn); st.m = mn; st.l *= alpha;
; #pragma unroll
;         for (int j = 0; j < 8; ++j) st.o[j] = st.o[j] * alpha;
;     }
;     f32x4 pa, pb; float ps = 0.f;
;     const float mref = st.m - 4.f;
;     if (NOMASK) {
; #pragma unroll
;         for (int j = 0; j < 4; ++j) { pa[j] = __builtin_amdgcn_exp2f(sc[j] - mref); pb[j] = __builtin_amdgcn_exp2f(sc[4 + j] - mref); }
;         if (SLC) {
; #pragma unroll
;             for (int j = 0; j < 4; ++j) { pa[j] = act ? pa[j] : 0.f; pb[j] = act ? pb[j] : 0.f; }
;         }
; #pragma unroll
;         for (int j = 0; j < 4; ++j) ps += pa[j] + pb[j];
;     } else {
; #pragma unroll
;         for (int j = 0; j < 4; ++j) { pa[j] = vd[j] ? __builtin_amdgcn_exp2f(sc[j] - mref) : 0.f; pb[j] = vd[4 + j] ? __builtin_amdgcn_exp2f(sc[4 + j] - mref) : 0.f; ps += pa[j] + pb[j]; }
;     }
;     st.l += ps;
;     const u32x2 pw = pack8_fp8(pa, pb);
.LBB0_1012:
	v_lshl_add_u64 v[246:247], v[204:205], 0, v[120:121]
	global_load_dwordx4 v[138:141], v[246:247], off
	global_load_dwordx4 v[142:145], v[246:247], off offset:1024
	global_load_dwordx4 v[146:149], v[246:247], off offset:2048
	global_load_dwordx4 v[150:153], v[246:247], off offset:3072
	v_lshl_add_u64 v[244:245], v[202:203], 0, v[120:121]
	global_load_dwordx4 v[90:93], v[244:245], off
	global_load_dwordx4 v[94:97], v[244:245], off offset:1024
	global_load_dwordx4 v[98:101], v[244:245], off offset:2048
	global_load_dwordx4 v[102:105], v[244:245], off offset:3072
	s_waitcnt vmcnt(20)
	v_mfma_f32_16x16x32_fp8_fp8 v[36:39], v[154:155], v[78:79], 0
	v_add_u32_e32 v0, s66, v210
	v_cmp_ge_i32_e32 vcc, v0, v35
	v_cmp_le_i32_e64 s[10:11], v0, v132
	v_mfma_f32_16x16x32_fp8_fp8 v[36:39], v[156:157], v[80:81], v[36:39]
	s_and_b64 s[16:17], vcc, s[10:11]
	v_add_u32_e32 v45, 1, v0
	v_cmp_ge_i32_e32 vcc, v45, v35
	v_mfma_f32_16x16x32_fp8_fp8 v[36:39], v[158:159], v[82:83], v[36:39]
	v_cmp_lt_i32_e64 s[10:11], v0, v132
	s_and_b64 s[12:13], s[10:11], vcc
	v_mfma_f32_16x16x32_fp8_fp8 v[40:43], v[162:163], v[78:79], 0
	v_mfma_f32_16x16x32_fp8_fp8 v[36:39], v[160:161], v[84:85], v[36:39]
	v_mfma_f32_16x16x32_fp8_fp8 v[40:43], v[164:165], v[80:81], v[40:43]
	v_mfma_f32_16x16x32_fp8_fp8 v[40:43], v[166:167], v[82:83], v[40:43]
	s_nop 5
	v_max_f32_e32 v44, v36, v36
	v_max_f32_e32 v44, 0xf149f2ca, v44
	v_cndmask_b32_e64 v44, v220, v44, s[16:17]
	v_max_f32_e32 v45, v37, v37
	v_max_f32_e32 v45, v44, v45
	v_cndmask_b32_e64 v44, v44, v45, s[12:13]
	v_add_u32_e32 v45, 2, v0
	v_cmp_ge_i32_e32 vcc, v45, v35
	v_cmp_le_i32_e64 s[10:11], v45, v132
	v_max_f32_e32 v45, v38, v38
	v_max_f32_e32 v45, v44, v45
	s_and_b64 s[14:15], vcc, s[10:11]
	v_mfma_f32_16x16x32_fp8_fp8 v[40:43], v[168:169], v[84:85], v[40:43]
	v_cndmask_b32_e64 v44, v44, v45, s[14:15]
	v_add_u32_e32 v45, 3, v0
	v_cmp_ge_i32_e32 vcc, v45, v35
	v_cmp_le_i32_e64 s[10:11], v45, v132
	v_max_f32_e32 v45, v39, v39
	v_max_f32_e32 v45, v44, v45
	s_and_b64 s[10:11], vcc, s[10:11]
	v_cndmask_b32_e64 v44, v44, v45, s[10:11]
	v_add_u32_e32 v45, 16, v0
	v_cmp_ge_i32_e32 vcc, v45, v35
	v_cmp_le_i32_e64 s[18:19], v45, v132
	v_max_f32_e32 v45, v40, v40
	v_max_f32_e32 v45, v44, v45
	s_and_b64 s[24:25], vcc, s[18:19]
	v_cndmask_b32_e64 v44, v44, v45, s[24:25]
	v_add_u32_e32 v45, 17, v0
	v_cmp_ge_i32_e32 vcc, v45, v35
	v_cmp_le_i32_e64 s[18:19], v45, v132
	v_max_f32_e32 v45, v44, v44
	v_max_f32_e32 v46, v41, v41
	v_max_f32_e32 v45, v45, v46
	s_and_b64 s[20:21], vcc, s[18:19]
	v_cndmask_b32_e64 v44, v44, v45, s[20:21]
	v_add_u32_e32 v45, 18, v0
	v_cmp_ge_i32_e32 vcc, v45, v35
	v_cmp_le_i32_e64 s[18:19], v45, v132
	v_max_f32_e32 v45, v44, v44
	v_max_f32_e32 v46, v42, v42
	v_max_f32_e32 v45, v45, v46
	s_and_b64 s[22:23], vcc, s[18:19]
	v_cndmask_b32_e64 v44, v44, v45, s[22:23]
	v_add_u32_e32 v0, 19, v0
	v_cmp_ge_i32_e32 vcc, v0, v35
	v_cmp_le_i32_e64 s[18:19], v0, v132
	v_max_f32_e32 v0, v44, v44
	v_max_f32_e32 v45, v43, v43
	v_max_f32_e32 v0, v0, v45
	s_and_b64 s[18:19], vcc, s[18:19]
	v_cndmask_b32_e64 v0, v44, v0, s[18:19]
	v_cmp_gt_f32_e32 vcc, v0, v133
	s_cbranch_vccz .LBB0_1014
	ds_bpermute_b32 v44, v225, v0
	v_max_f32_e32 v0, v0, v0
	s_waitcnt lgkmcnt(0)
	v_max_f32_e32 v44, v44, v44
	v_max_f32_e32 v0, v0, v44
	ds_bpermute_b32 v44, v224, v0
	s_waitcnt lgkmcnt(0)
	v_max3_f32 v44, v228, v0, v44
	v_sub_f32_e32 v0, v228, v44
	v_exp_f32_e32 v0, v0
	v_mov_b32_e32 v228, v44
	v_mul_f32_e32 v34, v34, v0
	v_pk_mul_f32 v[8:9], v[8:9], v[0:1] op_sel_hi:[1,0]
	v_pk_mul_f32 v[6:7], v[6:7], v[0:1] op_sel_hi:[1,0]
	v_pk_mul_f32 v[12:13], v[12:13], v[0:1] op_sel_hi:[1,0]
	v_pk_mul_f32 v[10:11], v[10:11], v[0:1] op_sel_hi:[1,0]
	v_pk_mul_f32 v[16:17], v[16:17], v[0:1] op_sel_hi:[1,0]
	v_pk_mul_f32 v[14:15], v[14:15], v[0:1] op_sel_hi:[1,0]
	v_pk_mul_f32 v[20:21], v[20:21], v[0:1] op_sel_hi:[1,0]
	v_pk_mul_f32 v[18:19], v[18:19], v[0:1] op_sel_hi:[1,0]
	v_pk_mul_f32 v[24:25], v[24:25], v[0:1] op_sel_hi:[1,0]
	v_pk_mul_f32 v[22:23], v[22:23], v[0:1] op_sel_hi:[1,0]
	v_pk_mul_f32 v[28:29], v[28:29], v[0:1] op_sel_hi:[1,0]
	v_pk_mul_f32 v[26:27], v[26:27], v[0:1] op_sel_hi:[1,0]
	v_pk_mul_f32 v[32:33], v[32:33], v[0:1] op_sel_hi:[1,0]
	v_pk_mul_f32 v[30:31], v[30:31], v[0:1] op_sel_hi:[1,0]
	v_pk_mul_f32 v[4:5], v[4:5], v[0:1] op_sel_hi:[1,0]
	v_pk_mul_f32 v[2:3], v[2:3], v[0:1] op_sel_hi:[1,0]
.LBB0_1014:
	v_add_f32_e32 v0, -4.0, v228
	v_sub_f32_e32 v36, v36, v0
	v_exp_f32_e32 v36, v36
	v_sub_f32_e32 v40, v40, v0
	v_exp_f32_e32 v40, v40
	v_sub_f32_e32 v38, v38, v0
	v_cndmask_b32_e64 v56, 0, v36, s[16:17]
	v_sub_f32_e32 v36, v37, v0
	v_exp_f32_e32 v36, v36
	v_sub_f32_e32 v37, v41, v0
	v_exp_f32_e32 v37, v37
	v_cndmask_b32_e64 v57, 0, v40, s[24:25]
	v_sub_f32_e32 v40, v42, v0
	v_cndmask_b32_e64 v58, 0, v36, s[12:13]
	v_sub_f32_e32 v36, v39, v0
	v_sub_f32_e32 v0, v43, v0
	v_exp_f32_e32 v38, v38
	v_exp_f32_e32 v40, v40
	v_cndmask_b32_e64 v59, 0, v37, s[20:21]
	v_exp_f32_e32 v36, v36
	v_exp_f32_e32 v0, v0
	v_mov_b32_e32 v64, v1
	v_mov_b32_e32 v65, v1
	v_cvt_pk_fp8_f32 v64, v56, v58
	v_cvt_pk_fp8_f32 v65, v57, v59
	v_cndmask_b32_e64 v60, 0, v38, s[14:15]
	v_cndmask_b32_e64 v61, 0, v40, s[22:23]
	v_cndmask_b32_e64 v66, 0, v36, s[10:11]
	v_cndmask_b32_e64 v0, 0, v0, s[18:19]
	v_cvt_pk_fp8_f32 v64, v60, v66 op_sel:[0,0,1]
	v_cvt_pk_fp8_f32 v65, v61, v0 op_sel:[0,0,1]
	v_add_f32_e32 v0, v66, v0
	v_mov_b32_e32 v227, v228
	s_waitcnt vmcnt(19)
	v_mfma_f32_16x16x32_fp8_fp8 v[36:39], v[106:107], v[64:65], v[6:9]
	s_nop 2
	v_add_f32_e32 v6, v56, v57
	v_add_f32_e32 v6, 0, v6
	v_add_f32_e32 v7, v58, v59
	v_mfma_f32_16x16x32_fp8_fp8 v[40:43], v[108:109], v[64:65], v[10:13]
	v_add_f32_e32 v6, v7, v6
	v_add_f32_e32 v7, v60, v61
	v_add_f32_e32 v6, v7, v6
	s_waitcnt vmcnt(18)
	v_mfma_f32_16x16x32_fp8_fp8 v[44:47], v[110:111], v[64:65], v[14:17]
	v_add_f32_e32 v0, v0, v6
	v_add_f32_e32 v229, v34, v0
	v_mfma_f32_16x16x32_fp8_fp8 v[48:51], v[112:113], v[64:65], v[18:21]
	s_waitcnt vmcnt(17)
	v_mfma_f32_16x16x32_fp8_fp8 v[52:55], v[114:115], v[64:65], v[22:25]
	v_mfma_f32_16x16x32_fp8_fp8 v[56:59], v[116:117], v[64:65], v[26:29]
	s_waitcnt vmcnt(16)
	v_mfma_f32_16x16x32_fp8_fp8 v[60:63], v[134:135], v[64:65], v[30:33]
	v_mfma_f32_16x16x32_fp8_fp8 v[64:67], v[136:137], v[64:65], v[2:5]
	s_nop 1
	s_cmp_gt_i32 s55, s27
	s_mov_b64 s[10:11], -1
	s_cbranch_scc1 .LBB0_994
; template <bool SLC, bool NOMASK> ...
;     const int kq = lane >> 4;
;     const int pos0 = SLC ? (dcur & 0xfffff) : dcur;
;     const int lo = SLC ? ((((dcur >> 20) == qi) | ((dcur >> 20) == 4)) ? 0 : (1 << 30)) : lo_in;
;     load_frag8(nxt, KF, VF, SLC ? (dnext & 0xfffff) : dnext, lane);
;     f32x4 sa[2] = {(f32x4){0.f, 0.f, 0.f, 0.f}, (f32x4){0.f, 0.f, 0.f, 0.f}};
; #pragma unroll
;     for (int T = 0; T < 2; ++T)
; #pragma unroll
;         for (int s2 = 0; s2 < 4; ++s2) sa[T] = __builtin_amdgcn_mfma_f32_16x16x32_fp8_fp8(cur.k[T][s2], qf[s2], sa[T], 0, 0, 0);
;     float sc[8]; bool vd[8]; float mx = -1e30f;
;     const bool act = lo == 0 || !SLC;
;     if (NOMASK) {
; #pragma unroll
;         for (int j = 0; j < 8; ++j) { sc[j] = sa[j >> 2][j & 3]; vd[j] = act; }
;         mx = fmaxf(fmaxf(fmaxf(sc[0], sc[1]), fmaxf(sc[2], sc[3])), fmaxf(fmaxf(sc[4], sc[5]), fmaxf(sc[6], sc[7])));
;         mx = act ? mx : -1e30f;
;     } else {
; #pragma unroll
;         for (int T = 0; T < 2; ++T)
; #pragma unroll
;             for (int r = 0; r < 4; ++r) { const int p = pos0 + 16 * T + 4 * kq + r; const bool v = (p >= lo) & (p <= hi); const float x = sa[T][r];
;                 sc[4 * T + r] = x; vd[4 * T + r] = v; mx = v ? fmaxf(mx, x) : mx; }
;     }
;     if (__builtin_amdgcn_ballot_w64(mx > st.m + 4.f) != 0ull) {
;         mx = fmaxf(mx, __shfl_xor(mx, 16)); mx = fmaxf(mx, __shfl_xor(mx, 32));
;         const float mn = fmaxf(st.m, mx), alpha = __builtin_amdgcn_exp2f(st.m - mn); st.m = mn; st.l *= alpha;
; #pragma unroll
;         for (int j = 0; j < 8; ++j) st.o[j] = st.o[j] * alpha;
;     }
;     f32x4 pa, pb; float ps = 0.f;
;     const float mref = st.m - 4.f;
;     if (NOMASK) {
; #pragma unroll
;         for (int j = 0; j < 4; ++j) { pa[j] = __builtin_amdgcn_exp2f(sc[j] - mref); pb[j] = __builtin_amdgcn_exp2f(sc[4 + j] - mref); }
;         if (SLC) {
; #pragma unroll
;             for (int j = 0; j < 4; ++j) { pa[j] = act ? pa[j] : 0.f; pb[j] = act ? pb[j] : 0.f; }
;         }
; #pragma unroll
;         for (int j = 0; j < 4; ++j) ps += pa[j] + pb[j];
;     } else {
; #pragma unroll
;         for (int j = 0; j < 4; ++j) { pa[j] = vd[j] ? __builtin_amdgcn_exp2f(sc[j] - mref) : 0.f; pb[j] = vd[4 + j] ? __builtin_amdgcn_exp2f(sc[4 + j] - mref) : 0.f; ps += pa[j] + pb[j]; }
;     }
;     st.l += ps;
;     const u32x2 pw = pack8_fp8(pa, pb);
.LBB0_1015:
	s_cmp_lt_i32 s57, s54
	s_cselect_b64 s[10:11], -1, 0
	s_or_b32 s12, s57, 31
	s_cmp_gt_i32 s12, s90
	s_cselect_b64 s[12:13], -1, 0
	s_or_b64 s[10:11], s[10:11], s[12:13]
	s_and_b64 s[10:11], s[10:11], exec
	s_cselect_b32 s10, 0, 2.0
	s_add_i32 s56, s56, 4
	s_or_b32 s14, s10, s57
	s_min_i32 s10, s56, s27
	s_add_i32 s12, s10, s26
	s_lshl_b32 s43, s12, 5
	s_and_b32 s10, s43, 0x3fffffe0
	s_lshr_b32 s50, s10, 4
	s_lshl_b64 s[10:11], s[50:51], 11
	s_and_b32 s50, s12, 0x1ffffff
	s_lshl_b64 s[12:13], s[50:51], 12
	s_cmp_lt_u32 s14, 2.0
	v_lshl_add_u64 v[204:205], v[86:87], 0, s[10:11]
	v_lshl_add_u64 v[202:203], v[88:89], 0, s[12:13]
	s_mov_b64 s[10:11], -1
	v_add_f32_e32 v228, 4.0, v227
	s_cbranch_scc1 .LBB0_1019
	v_lshl_add_u64 v[246:247], v[204:205], 0, v[120:121]
	global_load_dwordx4 v[154:157], v[246:247], off
	global_load_dwordx4 v[158:161], v[246:247], off offset:1024
	global_load_dwordx4 v[162:165], v[246:247], off offset:2048
	global_load_dwordx4 v[166:169], v[246:247], off offset:3072
	v_lshl_add_u64 v[244:245], v[202:203], 0, v[120:121]
	global_load_dwordx4 v[106:109], v[244:245], off
	global_load_dwordx4 v[110:113], v[244:245], off offset:1024
	global_load_dwordx4 v[114:117], v[244:245], off offset:2048
	global_load_dwordx4 v[134:137], v[244:245], off offset:3072
	s_waitcnt vmcnt(20)
	v_mfma_f32_16x16x32_fp8_fp8 v[2:5], v[186:187], v[78:79], 0
	v_mov_b64_e32 v[74:75], v[66:67]
	v_mov_b64_e32 v[70:71], v[62:63]
	v_mov_b64_e32 v[30:31], v[56:57]
	v_mfma_f32_16x16x32_fp8_fp8 v[6:9], v[194:195], v[78:79], 0
	v_mov_b64_e32 v[26:27], v[52:53]
	v_mov_b64_e32 v[22:23], v[48:49]
	v_mov_b64_e32 v[18:19], v[44:45]
	v_mfma_f32_16x16x32_fp8_fp8 v[2:5], v[188:189], v[80:81], v[2:5]
	v_mov_b64_e32 v[14:15], v[40:41]
	v_mov_b32_e32 v133, v227
	v_mov_b64_e32 v[72:73], v[64:65]
	v_mfma_f32_16x16x32_fp8_fp8 v[6:9], v[196:197], v[80:81], v[6:9]
	v_mov_b64_e32 v[68:69], v[60:61]
	v_mov_b64_e32 v[32:33], v[58:59]
	v_mov_b64_e32 v[28:29], v[54:55]
	v_mfma_f32_16x16x32_fp8_fp8 v[2:5], v[190:191], v[82:83], v[2:5]
	v_mov_b64_e32 v[24:25], v[50:51]
	v_mov_b64_e32 v[20:21], v[46:47]
	v_mov_b64_e32 v[16:17], v[42:43]
	v_mfma_f32_16x16x32_fp8_fp8 v[6:9], v[198:199], v[82:83], v[6:9]
	v_mov_b32_e32 v34, v229
	v_mfma_f32_16x16x32_fp8_fp8 v[2:5], v[192:193], v[84:85], v[2:5]
	v_mfma_f32_16x16x32_fp8_fp8 v[6:9], v[200:201], v[84:85], v[6:9]
	s_nop 6
	v_max_f32_e32 v0, v3, v3
	v_max_f32_e32 v10, v2, v2
	v_max_f32_e32 v0, v10, v0
	v_max_f32_e32 v10, v5, v5
	v_max_f32_e32 v11, v4, v4
	v_max_f32_e32 v10, v11, v10
	v_max_f32_e32 v11, v9, v9
	v_max_f32_e32 v12, v8, v8
	v_max_f32_e32 v11, v12, v11
	v_max3_f32 v11, v6, v7, v11
	v_max3_f32 v0, v0, v10, v11
	v_mov_b64_e32 v[10:11], v[36:37]
	v_cmp_gt_f32_e32 vcc, v0, v228
	v_mov_b64_e32 v[12:13], v[38:39]
	s_cbranch_vccz .LBB0_1018
	ds_bpermute_b32 v10, v225, v0
	v_max_f32_e32 v0, v0, v0
	s_waitcnt lgkmcnt(0)
	v_max_f32_e32 v10, v10, v10
	v_max_f32_e32 v0, v0, v10
	ds_bpermute_b32 v10, v224, v0
	s_waitcnt lgkmcnt(0)
	v_max3_f32 v133, v227, v0, v10
	v_sub_f32_e32 v0, v227, v133
	v_exp_f32_e32 v0, v0
	s_nop 0
	v_mul_f32_e32 v34, v229, v0
	v_pk_mul_f32 v[12:13], v[38:39], v[0:1] op_sel_hi:[1,0]
	v_pk_mul_f32 v[10:11], v[36:37], v[0:1] op_sel_hi:[1,0]
	v_pk_mul_f32 v[16:17], v[42:43], v[0:1] op_sel_hi:[1,0]
	v_pk_mul_f32 v[14:15], v[40:41], v[0:1] op_sel_hi:[1,0]
	v_pk_mul_f32 v[20:21], v[46:47], v[0:1] op_sel_hi:[1,0]
	v_pk_mul_f32 v[18:19], v[44:45], v[0:1] op_sel_hi:[1,0]
	v_pk_mul_f32 v[24:25], v[50:51], v[0:1] op_sel_hi:[1,0]
	v_pk_mul_f32 v[22:23], v[48:49], v[0:1] op_sel_hi:[1,0]
	v_pk_mul_f32 v[28:29], v[54:55], v[0:1] op_sel_hi:[1,0]
	v_pk_mul_f32 v[26:27], v[52:53], v[0:1] op_sel_hi:[1,0]
	v_pk_mul_f32 v[32:33], v[58:59], v[0:1] op_sel_hi:[1,0]
	v_pk_mul_f32 v[30:31], v[56:57], v[0:1] op_sel_hi:[1,0]
	v_pk_mul_f32 v[70:71], v[62:63], v[0:1] op_sel_hi:[1,0]
	v_pk_mul_f32 v[68:69], v[60:61], v[0:1] op_sel_hi:[1,0]
	v_pk_mul_f32 v[74:75], v[66:67], v[0:1] op_sel_hi:[1,0]
	v_pk_mul_f32 v[72:73], v[64:65], v[0:1] op_sel_hi:[1,0]
.LBB0_1018:
	v_add_f32_e32 v230, -4.0, v133
	v_sub_f32_e32 v0, v2, v230
	v_exp_f32_e32 v231, v0
	v_sub_f32_e32 v0, v6, v230
	v_exp_f32_e32 v234, v0
	v_sub_f32_e32 v0, v3, v230
	v_exp_f32_e32 v2, v0
	v_sub_f32_e32 v0, v7, v230
	v_exp_f32_e32 v0, v0
	v_sub_f32_e32 v3, v4, v230
	v_exp_f32_e32 v235, v3
	v_sub_f32_e32 v3, v8, v230
	v_exp_f32_e32 v236, v3
	v_sub_f32_e32 v3, v5, v230
	v_exp_f32_e32 v4, v3
	v_sub_f32_e32 v3, v9, v230
	v_mov_b32_e32 v232, v1
	v_mov_b32_e32 v233, v1
	v_exp_f32_e32 v230, v3
	v_cvt_pk_fp8_f32 v232, v231, v2
	v_cvt_pk_fp8_f32 v233, v234, v0
	v_add_f32_e32 v3, v231, v234
	v_pk_add_f32 v[2:3], v[2:3], v[0:1]
	v_cvt_pk_fp8_f32 v232, v235, v4 op_sel:[0,0,1]
	v_cvt_pk_fp8_f32 v233, v236, v230 op_sel:[0,0,1]
	v_pk_add_f32 v[2:3], v[2:3], v[2:3] op_sel_hi:[0,1]
	v_add_f32_e32 v5, v235, v236
	v_mov_b32_e32 v231, v3
	v_pk_add_f32 v[2:3], v[4:5], v[230:231]
	s_waitcnt vmcnt(19)
	v_mfma_f32_16x16x32_fp8_fp8 v[6:9], v[170:171], v[232:233], v[10:13]
	v_add_f32_e32 v0, v2, v3
	v_add_f32_e32 v34, v0, v34
	s_mov_b64 s[10:11], 0
	v_mfma_f32_16x16x32_fp8_fp8 v[10:13], v[172:173], v[232:233], v[14:17]
	s_waitcnt vmcnt(18)
	v_mfma_f32_16x16x32_fp8_fp8 v[14:17], v[174:175], v[232:233], v[18:21]
	v_mfma_f32_16x16x32_fp8_fp8 v[18:21], v[176:177], v[232:233], v[22:25]
	s_waitcnt vmcnt(17)
	v_mfma_f32_16x16x32_fp8_fp8 v[22:25], v[178:179], v[232:233], v[26:29]
	v_mfma_f32_16x16x32_fp8_fp8 v[26:29], v[180:181], v[232:233], v[30:33]
	s_waitcnt vmcnt(16)
	v_mfma_f32_16x16x32_fp8_fp8 v[30:33], v[182:183], v[232:233], v[68:71]
	v_mfma_f32_16x16x32_fp8_fp8 v[2:5], v[184:185], v[232:233], v[72:75]
	s_nop 1
; template <bool SLC, bool NOMASK> ...
;     const int kq = lane >> 4;
;     const int pos0 = SLC ? (dcur & 0xfffff) : dcur;
;     const int lo = SLC ? ((((dcur >> 20) == qi) | ((dcur >> 20) == 4)) ? 0 : (1 << 30)) : lo_in;
;     load_frag8(nxt, KF, VF, SLC ? (dnext & 0xfffff) : dnext, lane);
;     f32x4 sa[2] = {(f32x4){0.f, 0.f, 0.f, 0.f}, (f32x4){0.f, 0.f, 0.f, 0.f}};
; #pragma unroll
;     for (int T = 0; T < 2; ++T)
; #pragma unroll
;         for (int s2 = 0; s2 < 4; ++s2) sa[T] = __builtin_amdgcn_mfma_f32_16x16x32_fp8_fp8(cur.k[T][s2], qf[s2], sa[T], 0, 0, 0);
;     float sc[8]; bool vd[8]; float mx = -1e30f;
;     const bool act = lo == 0 || !SLC;
;     if (NOMASK) {
; #pragma unroll
;         for (int j = 0; j < 8; ++j) { sc[j] = sa[j >> 2][j & 3]; vd[j] = act; }
;         mx = fmaxf(fmaxf(fmaxf(sc[0], sc[1]), fmaxf(sc[2], sc[3])), fmaxf(fmaxf(sc[4], sc[5]), fmaxf(sc[6], sc[7])));
;         mx = act ? mx : -1e30f;
;     } else {
; #pragma unroll
;         for (int T = 0; T < 2; ++T)
; #pragma unroll
;             for (int r = 0; r < 4; ++r) { const int p = pos0 + 16 * T + 4 * kq + r; const bool v = (p >= lo) & (p <= hi); const float x = sa[T][r];
;                 sc[4 * T + r] = x; vd[4 * T + r] = v; mx = v ? fmaxf(mx, x) : mx; }
;     }
;     if (__builtin_amdgcn_ballot_w64(mx > st.m + 4.f) != 0ull) {
;         mx = fmaxf(mx, __shfl_xor(mx, 16)); mx = fmaxf(mx, __shfl_xor(mx, 32));
;         const float mn = fmaxf(st.m, mx), alpha = __builtin_amdgcn_exp2f(st.m - mn); st.m = mn; st.l *= alpha;
; #pragma unroll
;         for (int j = 0; j < 8; ++j) st.o[j] = st.o[j] * alpha;
;     }
;     f32x4 pa, pb; float ps = 0.f;
;     const float mref = st.m - 4.f;
;     if (NOMASK) {
; #pragma unroll
;         for (int j = 0; j < 4; ++j) { pa[j] = __builtin_amdgcn_exp2f(sc[j] - mref); pb[j] = __builtin_amdgcn_exp2f(sc[4 + j] - mref); }
;         if (SLC) {
; #pragma unroll
;             for (int j = 0; j < 4; ++j) { pa[j] = act ? pa[j] : 0.f; pb[j] = act ? pb[j] : 0.f; }
;         }
; #pragma unroll
;         for (int j = 0; j < 4; ++j) ps += pa[j] + pb[j];
;     } else {
; #pragma unroll
;         for (int j = 0; j < 4; ++j) { pa[j] = vd[j] ? __builtin_amdgcn_exp2f(sc[j] - mref) : 0.f; pb[j] = vd[4 + j] ? __builtin_amdgcn_exp2f(sc[4 + j] - mref) : 0.f; ps += pa[j] + pb[j]; }
;     }
;     st.l += ps;
;     const u32x2 pw = pack8_fp8(pa, pb);
.LBB0_1019:
	s_and_b64 vcc, exec, s[10:11]
	s_cbranch_vccz .LBB0_1023
	v_lshl_add_u64 v[246:247], v[204:205], 0, v[120:121]
	global_load_dwordx4 v[154:157], v[246:247], off
	global_load_dwordx4 v[158:161], v[246:247], off offset:1024
	global_load_dwordx4 v[162:165], v[246:247], off offset:2048
	global_load_dwordx4 v[166:169], v[246:247], off offset:3072
	v_lshl_add_u64 v[244:245], v[202:203], 0, v[120:121]
	global_load_dwordx4 v[106:109], v[244:245], off
	global_load_dwordx4 v[110:113], v[244:245], off offset:1024
	global_load_dwordx4 v[114:117], v[244:245], off offset:2048
	global_load_dwordx4 v[134:137], v[244:245], off offset:3072
	s_waitcnt vmcnt(20)
	v_mfma_f32_16x16x32_fp8_fp8 v[2:5], v[186:187], v[78:79], 0
	v_or_b32_e32 v0, s57, v210
	v_cmp_ge_i32_e32 vcc, v0, v35
	v_cmp_le_i32_e64 s[10:11], v0, v132
	v_mfma_f32_16x16x32_fp8_fp8 v[2:5], v[188:189], v[80:81], v[2:5]
	s_and_b64 s[16:17], vcc, s[10:11]
	v_or_b32_e32 v11, 1, v0
	v_cmp_ge_i32_e32 vcc, v11, v35
	v_mfma_f32_16x16x32_fp8_fp8 v[2:5], v[190:191], v[82:83], v[2:5]
	v_cmp_lt_i32_e64 s[10:11], v0, v132
	s_and_b64 s[12:13], s[10:11], vcc
	v_mfma_f32_16x16x32_fp8_fp8 v[6:9], v[194:195], v[78:79], 0
	v_mfma_f32_16x16x32_fp8_fp8 v[2:5], v[192:193], v[84:85], v[2:5]
	v_mfma_f32_16x16x32_fp8_fp8 v[6:9], v[196:197], v[80:81], v[6:9]
	v_mfma_f32_16x16x32_fp8_fp8 v[6:9], v[198:199], v[82:83], v[6:9]
	s_nop 5
	v_max_f32_e32 v10, v2, v2
	v_max_f32_e32 v10, 0xf149f2ca, v10
	v_cndmask_b32_e64 v10, v220, v10, s[16:17]
	v_max_f32_e32 v11, v3, v3
	v_max_f32_e32 v11, v10, v11
	v_cndmask_b32_e64 v10, v10, v11, s[12:13]
	v_or_b32_e32 v11, 2, v0
	v_cmp_ge_i32_e32 vcc, v11, v35
	v_cmp_le_i32_e64 s[10:11], v11, v132
	v_max_f32_e32 v11, v4, v4
	v_max_f32_e32 v11, v10, v11
	s_and_b64 s[14:15], vcc, s[10:11]
	v_mfma_f32_16x16x32_fp8_fp8 v[6:9], v[200:201], v[84:85], v[6:9]
	v_cndmask_b32_e64 v10, v10, v11, s[14:15]
	v_or_b32_e32 v11, 3, v0
	v_cmp_ge_i32_e32 vcc, v11, v35
	v_cmp_le_i32_e64 s[10:11], v11, v132
	v_max_f32_e32 v11, v5, v5
	v_max_f32_e32 v11, v10, v11
	s_and_b64 s[10:11], vcc, s[10:11]
	v_cndmask_b32_e64 v10, v10, v11, s[10:11]
	v_or_b32_e32 v11, 16, v0
	v_cmp_ge_i32_e32 vcc, v11, v35
	v_cmp_le_i32_e64 s[18:19], v11, v132
	v_max_f32_e32 v11, v6, v6
	v_max_f32_e32 v11, v10, v11
	s_and_b64 s[24:25], vcc, s[18:19]
	v_cndmask_b32_e64 v10, v10, v11, s[24:25]
	v_or_b32_e32 v11, 17, v0
	v_cmp_ge_i32_e32 vcc, v11, v35
	v_cmp_le_i32_e64 s[18:19], v11, v132
	v_max_f32_e32 v11, v10, v10
	v_max_f32_e32 v12, v7, v7
	v_max_f32_e32 v11, v11, v12
	s_and_b64 s[20:21], vcc, s[18:19]
	v_cndmask_b32_e64 v10, v10, v11, s[20:21]
	v_or_b32_e32 v11, 18, v0
	v_cmp_ge_i32_e32 vcc, v11, v35
	v_cmp_le_i32_e64 s[18:19], v11, v132
	v_max_f32_e32 v11, v10, v10
	v_max_f32_e32 v12, v8, v8
	v_max_f32_e32 v11, v11, v12
	s_and_b64 s[22:23], vcc, s[18:19]
	v_cndmask_b32_e64 v10, v10, v11, s[22:23]
	v_or_b32_e32 v0, 19, v0
	v_cmp_ge_i32_e32 vcc, v0, v35
	v_cmp_le_i32_e64 s[18:19], v0, v132
	v_max_f32_e32 v0, v10, v10
	v_max_f32_e32 v11, v9, v9
	v_max_f32_e32 v0, v0, v11
	s_and_b64 s[18:19], vcc, s[18:19]
	v_cndmask_b32_e64 v0, v10, v0, s[18:19]
	v_cmp_gt_f32_e32 vcc, v0, v228
	s_cbranch_vccz .LBB0_1022
	ds_bpermute_b32 v10, v225, v0
	v_max_f32_e32 v0, v0, v0
	s_waitcnt lgkmcnt(0)
	v_max_f32_e32 v10, v10, v10
	v_max_f32_e32 v0, v0, v10
	ds_bpermute_b32 v10, v224, v0
	s_waitcnt lgkmcnt(0)
	v_max3_f32 v10, v227, v0, v10
	v_sub_f32_e32 v0, v227, v10
	v_exp_f32_e32 v0, v0
	v_mov_b32_e32 v227, v10
	v_mul_f32_e32 v229, v229, v0
	v_pk_mul_f32 v[38:39], v[38:39], v[0:1] op_sel_hi:[1,0]
	v_pk_mul_f32 v[36:37], v[36:37], v[0:1] op_sel_hi:[1,0]
	v_pk_mul_f32 v[42:43], v[42:43], v[0:1] op_sel_hi:[1,0]
	v_pk_mul_f32 v[40:41], v[40:41], v[0:1] op_sel_hi:[1,0]
	v_pk_mul_f32 v[46:47], v[46:47], v[0:1] op_sel_hi:[1,0]
	v_pk_mul_f32 v[44:45], v[44:45], v[0:1] op_sel_hi:[1,0]
	v_pk_mul_f32 v[50:51], v[50:51], v[0:1] op_sel_hi:[1,0]
	v_pk_mul_f32 v[48:49], v[48:49], v[0:1] op_sel_hi:[1,0]
	v_pk_mul_f32 v[54:55], v[54:55], v[0:1] op_sel_hi:[1,0]
	v_pk_mul_f32 v[52:53], v[52:53], v[0:1] op_sel_hi:[1,0]
	v_pk_mul_f32 v[58:59], v[58:59], v[0:1] op_sel_hi:[1,0]
	v_pk_mul_f32 v[56:57], v[56:57], v[0:1] op_sel_hi:[1,0]
	v_pk_mul_f32 v[62:63], v[62:63], v[0:1] op_sel_hi:[1,0]
	v_pk_mul_f32 v[60:61], v[60:61], v[0:1] op_sel_hi:[1,0]
	v_pk_mul_f32 v[66:67], v[66:67], v[0:1] op_sel_hi:[1,0]
	v_pk_mul_f32 v[64:65], v[64:65], v[0:1] op_sel_hi:[1,0]
.LBB0_1022:
	v_add_f32_e32 v0, -4.0, v227
	v_sub_f32_e32 v2, v2, v0
	v_exp_f32_e32 v2, v2
	v_sub_f32_e32 v6, v6, v0
	v_exp_f32_e32 v6, v6
	v_sub_f32_e32 v4, v4, v0
	v_cndmask_b32_e64 v26, 0, v2, s[16:17]
	v_sub_f32_e32 v2, v3, v0
	v_exp_f32_e32 v2, v2
	v_sub_f32_e32 v3, v7, v0
	v_exp_f32_e32 v3, v3
	v_cndmask_b32_e64 v27, 0, v6, s[24:25]
	v_sub_f32_e32 v6, v8, v0
	v_cndmask_b32_e64 v28, 0, v2, s[12:13]
	v_sub_f32_e32 v2, v5, v0
	v_sub_f32_e32 v0, v9, v0
	v_exp_f32_e32 v4, v4
	v_exp_f32_e32 v6, v6
	v_cndmask_b32_e64 v29, 0, v3, s[20:21]
	v_exp_f32_e32 v5, v2
	v_exp_f32_e32 v0, v0
	v_mov_b32_e32 v2, v1
	v_mov_b32_e32 v3, v1
	v_cvt_pk_fp8_f32 v2, v26, v28
	v_cvt_pk_fp8_f32 v3, v27, v29
	v_cndmask_b32_e64 v4, 0, v4, s[14:15]
	v_cndmask_b32_e64 v30, 0, v6, s[22:23]
	v_cndmask_b32_e64 v5, 0, v5, s[10:11]
	v_cndmask_b32_e64 v0, 0, v0, s[18:19]
	v_cvt_pk_fp8_f32 v2, v4, v5 op_sel:[0,0,1]
	v_cvt_pk_fp8_f32 v3, v30, v0 op_sel:[0,0,1]
	v_add_f32_e32 v26, v26, v27
	v_add_f32_e32 v31, 0, v26
	v_add_f32_e32 v32, v28, v29
	v_add_f32_e32 v31, v32, v31
	v_add_f32_e32 v4, v4, v30
	v_add_f32_e32 v4, v4, v31
	v_add_f32_e32 v0, v5, v0
	s_waitcnt vmcnt(19)
	v_mfma_f32_16x16x32_fp8_fp8 v[6:9], v[170:171], v[2:3], v[36:39]
	v_add_f32_e32 v0, v0, v4
	v_add_f32_e32 v34, v229, v0
	v_mov_b32_e32 v133, v227
	v_mfma_f32_16x16x32_fp8_fp8 v[10:13], v[172:173], v[2:3], v[40:43]
	s_waitcnt vmcnt(18)
	v_mfma_f32_16x16x32_fp8_fp8 v[14:17], v[174:175], v[2:3], v[44:47]
	v_mfma_f32_16x16x32_fp8_fp8 v[18:21], v[176:177], v[2:3], v[48:51]
	s_waitcnt vmcnt(17)
	v_mfma_f32_16x16x32_fp8_fp8 v[22:25], v[178:179], v[2:3], v[52:55]
	v_mfma_f32_16x16x32_fp8_fp8 v[26:29], v[180:181], v[2:3], v[56:59]
	s_waitcnt vmcnt(16)
	v_mfma_f32_16x16x32_fp8_fp8 v[30:33], v[182:183], v[2:3], v[60:63]
	v_mfma_f32_16x16x32_fp8_fp8 v[2:5], v[184:185], v[2:3], v[64:67]
	s_nop 1
